# LDS-DMA GEMM staging for FFN_GU, SSD_IN, QKV unrolled bodies (XOR-swizzled linear LDS image); scan look-ahead; attention LDS read pipelining
# speedup vs baseline: 1.0342x; 1.0342x over previous
; DEVI void phase_rk_scan(const Params& p, char* smem) {
;     ...
;       const int nstep = min(32, L - s * 32);
;       for (int q0 = 0; q0 < nstep; q0 += 16) {
; #pragma unroll
;         for (int g8 = 0; g8 < 16; g8 += 8) {
;           float r_[8], w_[8], k_[8], kk_[8], bv_[8], v_[8];
; #pragma unroll
;           for (int u = 0; u < 8; ++u) {
;             const int q = q0 + g8 + u;
;             r_[u] = st[(0 * 32 + q) * 64 + lane]; w_[u] = st[(1 * 32 + q) * 64 + lane]; k_[u] = st[(2 * 32 + q) * 64 + lane];
;             kk_[u] = st[(3 * 32 + q) * 64 + lane]; bv_[u] = st[(4 * 32 + q) * 64 + lane]; v_[u] = st[(5 * 32 + q) * 64 + row];
;           }
; #pragma unroll
.LBB0_226:
	s_lshl_b32 s4, s34, 5
	s_sub_i32 s4, s29, s4
	s_cmp_lt_i32 s4, 1
	s_cbranch_scc1 .LBB0_231
	s_min_i32 s34, s4, 32
	s_mov_b32 s35, 0
	v_mov_b32_e32 v55, v10
	v_mov_b32_e32 v56, v54
	v_mov_b64_e32 v[42:43], v[28:29]
	ds_read2st64_b32 v[106:107], v55 offset0:96 offset1:97
	ds_read2st64_b32 v[102:103], v55 offset0:32 offset1:33
	ds_read2st64_b32 v[104:105], v55 offset0:64 offset1:65
	ds_read2st64_b32 v[110:111], v56 offset1:1
	ds_read2st64_b32 v[108:109], v55 offset0:128 offset1:129
	ds_read2st64_b32 v[100:101], v55 offset1:1
	ds_read2st64_b32 v[118:119], v55 offset0:98 offset1:99
	ds_read2st64_b32 v[114:115], v55 offset0:34 offset1:35
	ds_read2st64_b32 v[116:117], v55 offset0:66 offset1:67
	ds_read2st64_b32 v[122:123], v56 offset0:2 offset1:3
	ds_read2st64_b32 v[120:121], v55 offset0:130 offset1:131
	ds_read2st64_b32 v[112:113], v55 offset0:2 offset1:3
	s_branch .LBB0_229

; DEVI void phase_rk_scan(const Params& p, char* smem) {
;     ...
;           for (int u = 0; u < 8; ++u) {
;             const int q = q0 + g8 + u;
;             r_[u] = st[(0 * 32 + q) * 64 + lane]; w_[u] = st[(1 * 32 + q) * 64 + lane]; k_[u] = st[(2 * 32 + q) * 64 + lane];
;             kk_[u] = st[(3 * 32 + q) * 64 + lane]; bv_[u] = st[(4 * 32 + q) * 64 + lane]; v_[u] = st[(5 * 32 + q) * 64 + row];
;           }
; #pragma unroll
;           for (int u = 0; u < 8; ++u) {
;             const float base = S * w_[u] + v_[u] * k_[u];
;             const float sa = wave_sum63(S * kk_[u]);
;             S = base - sa * bv_[u];
;             yb[(g8 + u) * 68 + lane] = S * r_[u];
;           }
.LBB0_229:
	v_add_u32_e32 v58, 0xc000, v47
	v_add_u32_e32 v59, 0xc400, v47
	v_add_u32_e32 v60, 0xc800, v47
	v_add_u32_e32 v61, 0xcc00, v47
	s_waitcnt lgkmcnt(6)
	v_pk_mul_f32 v[62:63], v[110:111], v[104:105]
	v_mul_f32_e32 v68, v40, v106
	v_fma_f32 v71, v40, v102, v62
	v_mul_f32_e32 v70, v108, v107
	v_mul_f32_e32 v69, v71, v107
	v_add_f32_dpp v68, v68, v68 quad_perm:[1,0,3,2] row_mask:0xf bank_mask:0xf bound_ctrl:1
	v_add_f32_dpp v70, v70, v70 quad_perm:[1,0,3,2] row_mask:0xf bank_mask:0xf bound_ctrl:1
	v_add_f32_dpp v69, v69, v69 quad_perm:[1,0,3,2] row_mask:0xf bank_mask:0xf bound_ctrl:1
	v_add_f32_dpp v68, v68, v68 quad_perm:[2,3,0,1] row_mask:0xf bank_mask:0xf bound_ctrl:1
	v_add_f32_dpp v70, v70, v70 quad_perm:[2,3,0,1] row_mask:0xf bank_mask:0xf bound_ctrl:1
	v_add_f32_dpp v69, v69, v69 quad_perm:[2,3,0,1] row_mask:0xf bank_mask:0xf bound_ctrl:1
	v_add_f32_dpp v68, v68, v68 row_half_mirror row_mask:0xf bank_mask:0xf bound_ctrl:1
	v_add_f32_dpp v70, v70, v70 row_half_mirror row_mask:0xf bank_mask:0xf bound_ctrl:1
	v_add_f32_dpp v69, v69, v69 row_half_mirror row_mask:0xf bank_mask:0xf bound_ctrl:1
	v_add_f32_dpp v68, v68, v68 row_mirror row_mask:0xf bank_mask:0xf bound_ctrl:1
	v_add_f32_dpp v70, v70, v70 row_mirror row_mask:0xf bank_mask:0xf bound_ctrl:1
	v_add_f32_dpp v69, v69, v69 row_mirror row_mask:0xf bank_mask:0xf bound_ctrl:1
	v_add_f32_dpp v68, v68, v68 row_bcast:15 row_mask:0xa bank_mask:0xf
	v_add_f32_dpp v70, v70, v70 row_bcast:15 row_mask:0xa bank_mask:0xf
	v_add_f32_dpp v69, v69, v69 row_bcast:15 row_mask:0xa bank_mask:0xf
	v_add_f32_dpp v68, v68, v68 row_bcast:31 row_mask:0xc bank_mask:0xf
	v_add_f32_dpp v70, v70, v70 row_bcast:31 row_mask:0xc bank_mask:0xf
	v_add_f32_dpp v69, v69, v69 row_bcast:31 row_mask:0xc bank_mask:0xf
	v_fma_f32 v73, -v68, v70, v69
	v_readlane_b32 s4, v68, 63
	v_readlane_b32 s5, v73, 63
	ds_read2st64_b32 v[130:131], v55 offset0:100 offset1:101
	ds_read2st64_b32 v[126:127], v55 offset0:36 offset1:37
	ds_read2st64_b32 v[128:129], v55 offset0:68 offset1:69
	ds_read2st64_b32 v[134:135], v56 offset0:4 offset1:5
	ds_read2st64_b32 v[132:133], v55 offset0:132 offset1:133
	ds_read2st64_b32 v[124:125], v55 offset0:4 offset1:5
	v_fma_f32 v64, -s4, v108, v71
	v_fma_f32 v72, v64, v103, v63
	v_fma_f32 v65, -s5, v109, v72
	v_pk_mul_f32 v[66:67], v[64:65], v[100:101]
	ds_write2_b32 v58, v66, v67 offset1:68
	s_waitcnt lgkmcnt(7)
	v_pk_mul_f32 v[78:79], v[122:123], v[116:117]
	v_mul_f32_e32 v84, v65, v118
	v_fma_f32 v87, v65, v114, v78
	v_mul_f32_e32 v86, v120, v119
	v_mul_f32_e32 v85, v87, v119
	v_add_f32_dpp v84, v84, v84 quad_perm:[1,0,3,2] row_mask:0xf bank_mask:0xf bound_ctrl:1
	v_add_f32_dpp v86, v86, v86 quad_perm:[1,0,3,2] row_mask:0xf bank_mask:0xf bound_ctrl:1
	v_add_f32_dpp v85, v85, v85 quad_perm:[1,0,3,2] row_mask:0xf bank_mask:0xf bound_ctrl:1
	v_add_f32_dpp v84, v84, v84 quad_perm:[2,3,0,1] row_mask:0xf bank_mask:0xf bound_ctrl:1
	v_add_f32_dpp v86, v86, v86 quad_perm:[2,3,0,1] row_mask:0xf bank_mask:0xf bound_ctrl:1
	v_add_f32_dpp v85, v85, v85 quad_perm:[2,3,0,1] row_mask:0xf bank_mask:0xf bound_ctrl:1
	v_add_f32_dpp v84, v84, v84 row_half_mirror row_mask:0xf bank_mask:0xf bound_ctrl:1
	v_add_f32_dpp v86, v86, v86 row_half_mirror row_mask:0xf bank_mask:0xf bound_ctrl:1
	v_add_f32_dpp v85, v85, v85 row_half_mirror row_mask:0xf bank_mask:0xf bound_ctrl:1
	v_add_f32_dpp v84, v84, v84 row_mirror row_mask:0xf bank_mask:0xf bound_ctrl:1
	v_add_f32_dpp v86, v86, v86 row_mirror row_mask:0xf bank_mask:0xf bound_ctrl:1
	v_add_f32_dpp v85, v85, v85 row_mirror row_mask:0xf bank_mask:0xf bound_ctrl:1
	v_add_f32_dpp v84, v84, v84 row_bcast:15 row_mask:0xa bank_mask:0xf
	v_add_f32_dpp v86, v86, v86 row_bcast:15 row_mask:0xa bank_mask:0xf
	v_add_f32_dpp v85, v85, v85 row_bcast:15 row_mask:0xa bank_mask:0xf
	v_add_f32_dpp v84, v84, v84 row_bcast:31 row_mask:0xc bank_mask:0xf
	v_add_f32_dpp v86, v86, v86 row_bcast:31 row_mask:0xc bank_mask:0xf
	v_add_f32_dpp v85, v85, v85 row_bcast:31 row_mask:0xc bank_mask:0xf
	v_fma_f32 v89, -v84, v86, v85
	v_readlane_b32 s4, v84, 63
	v_readlane_b32 s5, v89, 63
	ds_read2st64_b32 v[106:107], v55 offset0:102 offset1:103
	ds_read2st64_b32 v[102:103], v55 offset0:38 offset1:39
	ds_read2st64_b32 v[104:105], v55 offset0:70 offset1:71
	ds_read2st64_b32 v[110:111], v56 offset0:6 offset1:7
	ds_read2st64_b32 v[108:109], v55 offset0:134 offset1:135
	ds_read2st64_b32 v[100:101], v55 offset0:6 offset1:7
	v_fma_f32 v80, -s4, v120, v87
	v_fma_f32 v88, v80, v115, v79
	v_fma_f32 v81, -s5, v121, v88
	v_pk_mul_f32 v[82:83], v[80:81], v[112:113]
	ds_write2_b32 v58, v82, v83 offset0:136 offset1:204
	s_waitcnt lgkmcnt(8)
; DEVI void phase_rk_scan(const Params& p, char* smem) {
;     ...
;           for (int u = 0; u < 8; ++u) {
;             const int q = q0 + g8 + u;
;             r_[u] = st[(0 * 32 + q) * 64 + lane]; w_[u] = st[(1 * 32 + q) * 64 + lane]; k_[u] = st[(2 * 32 + q) * 64 + lane];
;             kk_[u] = st[(3 * 32 + q) * 64 + lane]; bv_[u] = st[(4 * 32 + q) * 64 + lane]; v_[u] = st[(5 * 32 + q) * 64 + row];
;           }
; #pragma unroll
;           for (int u = 0; u < 8; ++u) {
;             const float base = S * w_[u] + v_[u] * k_[u];
;             const float sa = wave_sum63(S * kk_[u]);
;             S = base - sa * bv_[u];
;             yb[(g8 + u) * 68 + lane] = S * r_[u];
;           }
	v_pk_mul_f32 v[62:63], v[134:135], v[128:129]
	v_mul_f32_e32 v68, v81, v130
	v_fma_f32 v71, v81, v126, v62
	v_mul_f32_e32 v70, v132, v131
	v_mul_f32_e32 v69, v71, v131
	v_add_f32_dpp v68, v68, v68 quad_perm:[1,0,3,2] row_mask:0xf bank_mask:0xf bound_ctrl:1
	v_add_f32_dpp v70, v70, v70 quad_perm:[1,0,3,2] row_mask:0xf bank_mask:0xf bound_ctrl:1
	v_add_f32_dpp v69, v69, v69 quad_perm:[1,0,3,2] row_mask:0xf bank_mask:0xf bound_ctrl:1
	v_add_f32_dpp v68, v68, v68 quad_perm:[2,3,0,1] row_mask:0xf bank_mask:0xf bound_ctrl:1
	v_add_f32_dpp v70, v70, v70 quad_perm:[2,3,0,1] row_mask:0xf bank_mask:0xf bound_ctrl:1
	v_add_f32_dpp v69, v69, v69 quad_perm:[2,3,0,1] row_mask:0xf bank_mask:0xf bound_ctrl:1
	v_add_f32_dpp v68, v68, v68 row_half_mirror row_mask:0xf bank_mask:0xf bound_ctrl:1
	v_add_f32_dpp v70, v70, v70 row_half_mirror row_mask:0xf bank_mask:0xf bound_ctrl:1
	v_add_f32_dpp v69, v69, v69 row_half_mirror row_mask:0xf bank_mask:0xf bound_ctrl:1
	v_add_f32_dpp v68, v68, v68 row_mirror row_mask:0xf bank_mask:0xf bound_ctrl:1
	v_add_f32_dpp v70, v70, v70 row_mirror row_mask:0xf bank_mask:0xf bound_ctrl:1
	v_add_f32_dpp v69, v69, v69 row_mirror row_mask:0xf bank_mask:0xf bound_ctrl:1
	v_add_f32_dpp v68, v68, v68 row_bcast:15 row_mask:0xa bank_mask:0xf
	v_add_f32_dpp v70, v70, v70 row_bcast:15 row_mask:0xa bank_mask:0xf
	v_add_f32_dpp v69, v69, v69 row_bcast:15 row_mask:0xa bank_mask:0xf
	v_add_f32_dpp v68, v68, v68 row_bcast:31 row_mask:0xc bank_mask:0xf
	v_add_f32_dpp v70, v70, v70 row_bcast:31 row_mask:0xc bank_mask:0xf
	v_add_f32_dpp v69, v69, v69 row_bcast:31 row_mask:0xc bank_mask:0xf
	v_fma_f32 v73, -v68, v70, v69
	v_readlane_b32 s4, v68, 63
	v_readlane_b32 s5, v73, 63
	ds_read2st64_b32 v[118:119], v55 offset0:104 offset1:105
	ds_read2st64_b32 v[114:115], v55 offset0:40 offset1:41
	ds_read2st64_b32 v[116:117], v55 offset0:72 offset1:73
	ds_read2st64_b32 v[122:123], v56 offset0:8 offset1:9
	ds_read2st64_b32 v[120:121], v55 offset0:136 offset1:137
	ds_read2st64_b32 v[112:113], v55 offset0:8 offset1:9
	v_fma_f32 v64, -s4, v132, v71
	v_fma_f32 v72, v64, v127, v63
	v_fma_f32 v65, -s5, v133, v72
	v_pk_mul_f32 v[66:67], v[64:65], v[124:125]
	ds_write2_b32 v59, v66, v67 offset0:16 offset1:84
	s_waitcnt lgkmcnt(8)
	v_pk_mul_f32 v[78:79], v[110:111], v[104:105]
	v_mul_f32_e32 v84, v65, v106
	v_fma_f32 v87, v65, v102, v78
	v_mul_f32_e32 v86, v108, v107
	v_mul_f32_e32 v85, v87, v107
	v_add_f32_dpp v84, v84, v84 quad_perm:[1,0,3,2] row_mask:0xf bank_mask:0xf bound_ctrl:1
	v_add_f32_dpp v86, v86, v86 quad_perm:[1,0,3,2] row_mask:0xf bank_mask:0xf bound_ctrl:1
	v_add_f32_dpp v85, v85, v85 quad_perm:[1,0,3,2] row_mask:0xf bank_mask:0xf bound_ctrl:1
	v_add_f32_dpp v84, v84, v84 quad_perm:[2,3,0,1] row_mask:0xf bank_mask:0xf bound_ctrl:1
	v_add_f32_dpp v86, v86, v86 quad_perm:[2,3,0,1] row_mask:0xf bank_mask:0xf bound_ctrl:1
	v_add_f32_dpp v85, v85, v85 quad_perm:[2,3,0,1] row_mask:0xf bank_mask:0xf bound_ctrl:1
	v_add_f32_dpp v84, v84, v84 row_half_mirror row_mask:0xf bank_mask:0xf bound_ctrl:1
	v_add_f32_dpp v86, v86, v86 row_half_mirror row_mask:0xf bank_mask:0xf bound_ctrl:1
	v_add_f32_dpp v85, v85, v85 row_half_mirror row_mask:0xf bank_mask:0xf bound_ctrl:1
	v_add_f32_dpp v84, v84, v84 row_mirror row_mask:0xf bank_mask:0xf bound_ctrl:1
	v_add_f32_dpp v86, v86, v86 row_mirror row_mask:0xf bank_mask:0xf bound_ctrl:1
	v_add_f32_dpp v85, v85, v85 row_mirror row_mask:0xf bank_mask:0xf bound_ctrl:1
	v_add_f32_dpp v84, v84, v84 row_bcast:15 row_mask:0xa bank_mask:0xf
	v_add_f32_dpp v86, v86, v86 row_bcast:15 row_mask:0xa bank_mask:0xf
	v_add_f32_dpp v85, v85, v85 row_bcast:15 row_mask:0xa bank_mask:0xf
	v_add_f32_dpp v84, v84, v84 row_bcast:31 row_mask:0xc bank_mask:0xf
	v_add_f32_dpp v86, v86, v86 row_bcast:31 row_mask:0xc bank_mask:0xf
	v_add_f32_dpp v85, v85, v85 row_bcast:31 row_mask:0xc bank_mask:0xf
	v_fma_f32 v89, -v84, v86, v85
	v_readlane_b32 s4, v84, 63
	v_readlane_b32 s5, v89, 63
	ds_read2st64_b32 v[130:131], v55 offset0:106 offset1:107
	ds_read2st64_b32 v[126:127], v55 offset0:42 offset1:43
	ds_read2st64_b32 v[128:129], v55 offset0:74 offset1:75
	ds_read2st64_b32 v[134:135], v56 offset0:10 offset1:11
	ds_read2st64_b32 v[132:133], v55 offset0:138 offset1:139
	ds_read2st64_b32 v[124:125], v55 offset0:10 offset1:11
	v_fma_f32 v80, -s4, v108, v87
	v_fma_f32 v88, v80, v103, v79
	v_fma_f32 v81, -s5, v109, v88
	v_pk_mul_f32 v[82:83], v[80:81], v[100:101]
	ds_write2_b32 v59, v82, v83 offset0:152 offset1:220
	s_waitcnt lgkmcnt(8)
	v_pk_mul_f32 v[62:63], v[122:123], v[116:117]
	v_mul_f32_e32 v68, v81, v118
	v_fma_f32 v71, v81, v114, v62
	v_mul_f32_e32 v70, v120, v119
	v_mul_f32_e32 v69, v71, v119
	v_add_f32_dpp v68, v68, v68 quad_perm:[1,0,3,2] row_mask:0xf bank_mask:0xf bound_ctrl:1
	v_add_f32_dpp v70, v70, v70 quad_perm:[1,0,3,2] row_mask:0xf bank_mask:0xf bound_ctrl:1
	v_add_f32_dpp v69, v69, v69 quad_perm:[1,0,3,2] row_mask:0xf bank_mask:0xf bound_ctrl:1
	v_add_f32_dpp v68, v68, v68 quad_perm:[2,3,0,1] row_mask:0xf bank_mask:0xf bound_ctrl:1
	v_add_f32_dpp v70, v70, v70 quad_perm:[2,3,0,1] row_mask:0xf bank_mask:0xf bound_ctrl:1
	v_add_f32_dpp v69, v69, v69 quad_perm:[2,3,0,1] row_mask:0xf bank_mask:0xf bound_ctrl:1
	v_add_f32_dpp v68, v68, v68 row_half_mirror row_mask:0xf bank_mask:0xf bound_ctrl:1
	v_add_f32_dpp v70, v70, v70 row_half_mirror row_mask:0xf bank_mask:0xf bound_ctrl:1
	v_add_f32_dpp v69, v69, v69 row_half_mirror row_mask:0xf bank_mask:0xf bound_ctrl:1
	v_add_f32_dpp v68, v68, v68 row_mirror row_mask:0xf bank_mask:0xf bound_ctrl:1
	v_add_f32_dpp v70, v70, v70 row_mirror row_mask:0xf bank_mask:0xf bound_ctrl:1
	v_add_f32_dpp v69, v69, v69 row_mirror row_mask:0xf bank_mask:0xf bound_ctrl:1
	v_add_f32_dpp v68, v68, v68 row_bcast:15 row_mask:0xa bank_mask:0xf
	v_add_f32_dpp v70, v70, v70 row_bcast:15 row_mask:0xa bank_mask:0xf
	v_add_f32_dpp v69, v69, v69 row_bcast:15 row_mask:0xa bank_mask:0xf
	v_add_f32_dpp v68, v68, v68 row_bcast:31 row_mask:0xc bank_mask:0xf
	v_add_f32_dpp v70, v70, v70 row_bcast:31 row_mask:0xc bank_mask:0xf
	v_add_f32_dpp v69, v69, v69 row_bcast:31 row_mask:0xc bank_mask:0xf
	v_fma_f32 v73, -v68, v70, v69
	v_readlane_b32 s4, v68, 63
	v_readlane_b32 s5, v73, 63
	ds_read2st64_b32 v[106:107], v55 offset0:108 offset1:109
	ds_read2st64_b32 v[102:103], v55 offset0:44 offset1:45
	ds_read2st64_b32 v[104:105], v55 offset0:76 offset1:77
	ds_read2st64_b32 v[110:111], v56 offset0:12 offset1:13
	ds_read2st64_b32 v[108:109], v55 offset0:140 offset1:141
	ds_read2st64_b32 v[100:101], v55 offset0:12 offset1:13
	v_fma_f32 v64, -s4, v120, v71
	v_fma_f32 v72, v64, v115, v63
	v_fma_f32 v65, -s5, v121, v72
	v_pk_mul_f32 v[66:67], v[64:65], v[112:113]
	ds_write2_b32 v60, v66, v67 offset0:32 offset1:100
	s_waitcnt lgkmcnt(8)
; DEVI void phase_rk_scan(const Params& p, char* smem) {
;     ...
;           for (int u = 0; u < 8; ++u) {
;             const int q = q0 + g8 + u;
;             r_[u] = st[(0 * 32 + q) * 64 + lane]; w_[u] = st[(1 * 32 + q) * 64 + lane]; k_[u] = st[(2 * 32 + q) * 64 + lane];
;             kk_[u] = st[(3 * 32 + q) * 64 + lane]; bv_[u] = st[(4 * 32 + q) * 64 + lane]; v_[u] = st[(5 * 32 + q) * 64 + row];
;           }
; #pragma unroll
;           for (int u = 0; u < 8; ++u) {
;             const float base = S * w_[u] + v_[u] * k_[u];
;             const float sa = wave_sum63(S * kk_[u]);
;             S = base - sa * bv_[u];
;             yb[(g8 + u) * 68 + lane] = S * r_[u];
;           }
	v_pk_mul_f32 v[78:79], v[134:135], v[128:129]
	v_mul_f32_e32 v84, v65, v130
	v_fma_f32 v87, v65, v126, v78
	v_mul_f32_e32 v86, v132, v131
	v_mul_f32_e32 v85, v87, v131
	v_add_f32_dpp v84, v84, v84 quad_perm:[1,0,3,2] row_mask:0xf bank_mask:0xf bound_ctrl:1
	v_add_f32_dpp v86, v86, v86 quad_perm:[1,0,3,2] row_mask:0xf bank_mask:0xf bound_ctrl:1
	v_add_f32_dpp v85, v85, v85 quad_perm:[1,0,3,2] row_mask:0xf bank_mask:0xf bound_ctrl:1
	v_add_f32_dpp v84, v84, v84 quad_perm:[2,3,0,1] row_mask:0xf bank_mask:0xf bound_ctrl:1
	v_add_f32_dpp v86, v86, v86 quad_perm:[2,3,0,1] row_mask:0xf bank_mask:0xf bound_ctrl:1
	v_add_f32_dpp v85, v85, v85 quad_perm:[2,3,0,1] row_mask:0xf bank_mask:0xf bound_ctrl:1
	v_add_f32_dpp v84, v84, v84 row_half_mirror row_mask:0xf bank_mask:0xf bound_ctrl:1
	v_add_f32_dpp v86, v86, v86 row_half_mirror row_mask:0xf bank_mask:0xf bound_ctrl:1
	v_add_f32_dpp v85, v85, v85 row_half_mirror row_mask:0xf bank_mask:0xf bound_ctrl:1
	v_add_f32_dpp v84, v84, v84 row_mirror row_mask:0xf bank_mask:0xf bound_ctrl:1
	v_add_f32_dpp v86, v86, v86 row_mirror row_mask:0xf bank_mask:0xf bound_ctrl:1
	v_add_f32_dpp v85, v85, v85 row_mirror row_mask:0xf bank_mask:0xf bound_ctrl:1
	v_add_f32_dpp v84, v84, v84 row_bcast:15 row_mask:0xa bank_mask:0xf
	v_add_f32_dpp v86, v86, v86 row_bcast:15 row_mask:0xa bank_mask:0xf
	v_add_f32_dpp v85, v85, v85 row_bcast:15 row_mask:0xa bank_mask:0xf
	v_add_f32_dpp v84, v84, v84 row_bcast:31 row_mask:0xc bank_mask:0xf
	v_add_f32_dpp v86, v86, v86 row_bcast:31 row_mask:0xc bank_mask:0xf
	v_add_f32_dpp v85, v85, v85 row_bcast:31 row_mask:0xc bank_mask:0xf
	v_fma_f32 v89, -v84, v86, v85
	v_readlane_b32 s4, v84, 63
	v_readlane_b32 s5, v89, 63
	ds_read2st64_b32 v[118:119], v55 offset0:110 offset1:111
	ds_read2st64_b32 v[114:115], v55 offset0:46 offset1:47
	ds_read2st64_b32 v[116:117], v55 offset0:78 offset1:79
	ds_read2st64_b32 v[122:123], v56 offset0:14 offset1:15
	ds_read2st64_b32 v[120:121], v55 offset0:142 offset1:143
	ds_read2st64_b32 v[112:113], v55 offset0:14 offset1:15
	v_fma_f32 v80, -s4, v132, v87
	v_fma_f32 v88, v80, v127, v79
	v_fma_f32 v81, -s5, v133, v88
	v_pk_mul_f32 v[82:83], v[80:81], v[124:125]
	ds_write2_b32 v60, v82, v83 offset0:168 offset1:236
	s_waitcnt lgkmcnt(8)
	v_pk_mul_f32 v[62:63], v[110:111], v[104:105]
	v_mul_f32_e32 v68, v81, v106
	v_fma_f32 v71, v81, v102, v62
	v_mul_f32_e32 v70, v108, v107
	v_mul_f32_e32 v69, v71, v107
	v_add_f32_dpp v68, v68, v68 quad_perm:[1,0,3,2] row_mask:0xf bank_mask:0xf bound_ctrl:1
	v_add_f32_dpp v70, v70, v70 quad_perm:[1,0,3,2] row_mask:0xf bank_mask:0xf bound_ctrl:1
	v_add_f32_dpp v69, v69, v69 quad_perm:[1,0,3,2] row_mask:0xf bank_mask:0xf bound_ctrl:1
	v_add_f32_dpp v68, v68, v68 quad_perm:[2,3,0,1] row_mask:0xf bank_mask:0xf bound_ctrl:1
	v_add_f32_dpp v70, v70, v70 quad_perm:[2,3,0,1] row_mask:0xf bank_mask:0xf bound_ctrl:1
	v_add_f32_dpp v69, v69, v69 quad_perm:[2,3,0,1] row_mask:0xf bank_mask:0xf bound_ctrl:1
	v_add_f32_dpp v68, v68, v68 row_half_mirror row_mask:0xf bank_mask:0xf bound_ctrl:1
	v_add_f32_dpp v70, v70, v70 row_half_mirror row_mask:0xf bank_mask:0xf bound_ctrl:1
	v_add_f32_dpp v69, v69, v69 row_half_mirror row_mask:0xf bank_mask:0xf bound_ctrl:1
	v_add_f32_dpp v68, v68, v68 row_mirror row_mask:0xf bank_mask:0xf bound_ctrl:1
	v_add_f32_dpp v70, v70, v70 row_mirror row_mask:0xf bank_mask:0xf bound_ctrl:1
	v_add_f32_dpp v69, v69, v69 row_mirror row_mask:0xf bank_mask:0xf bound_ctrl:1
	v_add_f32_dpp v68, v68, v68 row_bcast:15 row_mask:0xa bank_mask:0xf
	v_add_f32_dpp v70, v70, v70 row_bcast:15 row_mask:0xa bank_mask:0xf
	v_add_f32_dpp v69, v69, v69 row_bcast:15 row_mask:0xa bank_mask:0xf
	v_add_f32_dpp v68, v68, v68 row_bcast:31 row_mask:0xc bank_mask:0xf
	v_add_f32_dpp v70, v70, v70 row_bcast:31 row_mask:0xc bank_mask:0xf
	v_add_f32_dpp v69, v69, v69 row_bcast:31 row_mask:0xc bank_mask:0xf
	v_fma_f32 v73, -v68, v70, v69
	v_readlane_b32 s4, v68, 63
	v_readlane_b32 s5, v73, 63
	s_nop 1
	v_fma_f32 v64, -s4, v108, v71
	v_fma_f32 v72, v64, v103, v63
	v_fma_f32 v65, -s5, v109, v72
	v_pk_mul_f32 v[66:67], v[64:65], v[100:101]
	ds_write2_b32 v61, v66, v67 offset0:48 offset1:116
	s_waitcnt lgkmcnt(2)
; DEVI void phase_rk_scan(const Params& p, char* smem) {
;     ...
;           for (int u = 0; u < 8; ++u) {
;             const float base = S * w_[u] + v_[u] * k_[u];
;             const float sa = wave_sum63(S * kk_[u]);
;             S = base - sa * bv_[u];
;             yb[(g8 + u) * 68 + lane] = S * r_[u];
;           }
;         }
;         if (lane < 16) {
;           const float* yr = yb + lane * 68;
;           f32x4 acc = *(const f32x4*)yr;
; #pragma unroll
;           for (int j = 1; j < 16; ++j) acc += *(const f32x4*)(yr + 4 * j);
;           Y[(size_t)(mbase + s * 32 + q0 + lane) * 1024 + h * 64 + row] = (acc[0] + acc[1]) + (acc[2] + acc[3]);
;         }
	v_pk_mul_f32 v[78:79], v[122:123], v[116:117]
	v_mul_f32_e32 v84, v65, v118
	v_fma_f32 v87, v65, v114, v78
	v_mul_f32_e32 v86, v120, v119
	v_mul_f32_e32 v85, v87, v119
	v_add_f32_dpp v84, v84, v84 quad_perm:[1,0,3,2] row_mask:0xf bank_mask:0xf bound_ctrl:1
	v_add_f32_dpp v86, v86, v86 quad_perm:[1,0,3,2] row_mask:0xf bank_mask:0xf bound_ctrl:1
	v_add_f32_dpp v85, v85, v85 quad_perm:[1,0,3,2] row_mask:0xf bank_mask:0xf bound_ctrl:1
	v_add_f32_dpp v84, v84, v84 quad_perm:[2,3,0,1] row_mask:0xf bank_mask:0xf bound_ctrl:1
	v_add_f32_dpp v86, v86, v86 quad_perm:[2,3,0,1] row_mask:0xf bank_mask:0xf bound_ctrl:1
	v_add_f32_dpp v85, v85, v85 quad_perm:[2,3,0,1] row_mask:0xf bank_mask:0xf bound_ctrl:1
	v_add_f32_dpp v84, v84, v84 row_half_mirror row_mask:0xf bank_mask:0xf bound_ctrl:1
	v_add_f32_dpp v86, v86, v86 row_half_mirror row_mask:0xf bank_mask:0xf bound_ctrl:1
	v_add_f32_dpp v85, v85, v85 row_half_mirror row_mask:0xf bank_mask:0xf bound_ctrl:1
	v_add_f32_dpp v84, v84, v84 row_mirror row_mask:0xf bank_mask:0xf bound_ctrl:1
	v_add_f32_dpp v86, v86, v86 row_mirror row_mask:0xf bank_mask:0xf bound_ctrl:1
	v_add_f32_dpp v85, v85, v85 row_mirror row_mask:0xf bank_mask:0xf bound_ctrl:1
	v_add_f32_dpp v84, v84, v84 row_bcast:15 row_mask:0xa bank_mask:0xf
	v_add_f32_dpp v86, v86, v86 row_bcast:15 row_mask:0xa bank_mask:0xf
	v_add_f32_dpp v85, v85, v85 row_bcast:15 row_mask:0xa bank_mask:0xf
	v_add_f32_dpp v84, v84, v84 row_bcast:31 row_mask:0xc bank_mask:0xf
	v_add_f32_dpp v86, v86, v86 row_bcast:31 row_mask:0xc bank_mask:0xf
	v_add_f32_dpp v85, v85, v85 row_bcast:31 row_mask:0xc bank_mask:0xf
	v_fma_f32 v89, -v84, v86, v85
	v_readlane_b32 s4, v84, 63
	v_readlane_b32 s5, v89, 63
	s_nop 1
	v_fma_f32 v80, -s4, v120, v87
	v_fma_f32 v88, v80, v115, v79
	v_fma_f32 v81, -s5, v121, v88
	v_pk_mul_f32 v[82:83], v[80:81], v[112:113]
	ds_write2_b32 v61, v82, v83 offset0:184 offset1:252
	v_mov_b32_e32 v40, v81
	v_and_b32_e32 v156, 15, v8
	v_lshrrev_b32_e32 v157, 4, v8
	v_mul_u32_u24_e32 v156, 0x110, v156
	v_lshl_add_u32 v156, v157, 6, v156
	v_sub_u32_e32 v136, v47, v10
	v_add_u32_e32 v136, v136, v156
	ds_read_b128 v[140:143], v136 offset:49152
	ds_read_b128 v[144:147], v136 offset:49168
	ds_read_b128 v[148:151], v136 offset:49184
	ds_read_b128 v[152:155], v136 offset:49200
	ds_read2st64_b32 v[106:107], v55 offset0:112 offset1:113
	ds_read2st64_b32 v[102:103], v55 offset0:48 offset1:49
	ds_read2st64_b32 v[104:105], v55 offset0:80 offset1:81
	ds_read2st64_b32 v[110:111], v56 offset0:16 offset1:17
	ds_read2st64_b32 v[108:109], v55 offset0:144 offset1:145
	ds_read2st64_b32 v[100:101], v55 offset0:16 offset1:17
	ds_read2st64_b32 v[118:119], v55 offset0:114 offset1:115
	ds_read2st64_b32 v[114:115], v55 offset0:50 offset1:51
	ds_read2st64_b32 v[116:117], v55 offset0:82 offset1:83
	ds_read2st64_b32 v[122:123], v56 offset0:18 offset1:19
	ds_read2st64_b32 v[120:121], v55 offset0:146 offset1:147
	ds_read2st64_b32 v[112:113], v55 offset0:18 offset1:19
	s_waitcnt lgkmcnt(14)
	v_pk_add_f32 v[140:141], v[140:141], v[144:145]
	v_pk_add_f32 v[142:143], v[142:143], v[146:147]
	s_waitcnt lgkmcnt(12)
	v_pk_add_f32 v[148:149], v[148:149], v[152:153]
	v_pk_add_f32 v[150:151], v[150:151], v[154:155]
	v_pk_add_f32 v[140:141], v[140:141], v[148:149]
	v_pk_add_f32 v[142:143], v[142:143], v[150:151]
	v_pk_add_f32 v[140:141], v[140:141], v[142:143]
	v_add_f32_e32 v156, v140, v141
	v_mov_b32_e32 v157, v156
	s_nop 1
	v_permlane32_swap_b32_e32 v156, v157
	v_add_f32_e32 v156, v156, v157
	v_mov_b32_e32 v157, v156
	s_nop 1
	v_permlane16_swap_b32_e32 v156, v157
	v_add_f32_e32 v41, v156, v157
	s_and_saveexec_b64 s[4:5], s[6:7]
	s_cbranch_execz .LBB0_228
	global_store_dword v[42:43], v41, off
	s_branch .LBB0_228

; DEVI f32x16 mfma32(bf16x8 a, bf16x8 b, f32x16 c) { return __builtin_amdgcn_mfma_f32_32x32x16_bf16(a, b, c, 0, 0, 0); }
; DEVI void attn_item(const Params& p, int seq, int qt, int h, float lam, char* smem) {
;     ...
; #pragma unroll
;     for (int kt2 = 0; kt2 < 2; ++kt2) {
;       S[kt2] = zero16();
; #pragma unroll
;       for (int ks = 0; ks < 4; ++ks) {
;         const bf16x8 a = *(const bf16x8*)(Kc + (c * 64 + kt2 * 32 + (lane & 31)) * 72 + ks * 16 + hl * 8);
;         S[kt2] = mfma32(a, qf[ks], S[kt2]);
;       }
;       __builtin_amdgcn_sched_barrier(0);
;     }
.LBB0_1504:
	s_mul_i32 s3, s3, 0x8c00
	v_lshl_or_b32 v64, v152, 1, s3
	v_add_u32_e32 v96, v64, v155
	ds_read_b128 v[64:67], v96
	ds_read_b128 v[68:71], v96 offset:32
	ds_read_b128 v[72:75], v96 offset:64
	ds_read_b128 v[76:79], v96 offset:96
	ds_read_b128 v[202:205], v96 offset:4608
	ds_read_b128 v[230:233], v96 offset:4640
	ds_read_b128 v[240:243], v96 offset:4672
	s_waitcnt lgkmcnt(6)
	v_mfma_f32_32x32x16_bf16 v[80:95], v[64:67], v[130:133], 0
	s_waitcnt lgkmcnt(5)
	v_mfma_f32_32x32x16_bf16 v[80:95], v[68:71], v[134:137], v[80:95]
	s_waitcnt lgkmcnt(4)
	v_mfma_f32_32x32x16_bf16 v[80:95], v[72:75], v[138:141], v[80:95]
	s_waitcnt lgkmcnt(3)
	v_mfma_f32_32x32x16_bf16 v[80:95], v[76:79], v[142:145], v[80:95]
	s_waitcnt lgkmcnt(2)
	v_mfma_f32_32x32x16_bf16 v[64:79], v[202:205], v[130:133], 0
	ds_read_b128 v[202:205], v96 offset:4704
	s_waitcnt lgkmcnt(2)
	v_mfma_f32_32x32x16_bf16 v[64:79], v[230:233], v[134:137], v[64:79]
	s_waitcnt lgkmcnt(1)
	v_mfma_f32_32x32x16_bf16 v[64:79], v[240:243], v[138:141], v[64:79]
	s_waitcnt lgkmcnt(0)
	v_mfma_f32_32x32x16_bf16 v[64:79], v[202:205], v[142:145], v[64:79]
	s_nop 2
	v_max3_f32 v96, v80, s5, v81
	v_max3_f32 v96, v96, v82, v83
	v_max3_f32 v96, v96, v84, v85
	v_max3_f32 v96, v96, v86, v87
	v_max3_f32 v96, v96, v88, v89
	v_max3_f32 v96, v96, v90, v91
	v_max3_f32 v96, v96, v92, v93
	v_max3_f32 v96, v96, v94, v95
	s_nop 3
	v_max3_f32 v96, v96, v64, v65
	v_max3_f32 v96, v96, v66, v67
	v_max3_f32 v96, v96, v68, v69
	v_max3_f32 v96, v96, v70, v71
	v_max3_f32 v96, v96, v72, v73
	v_max3_f32 v96, v96, v74, v75
	v_max3_f32 v96, v96, v76, v77
	v_max3_f32 v96, v96, v78, v79
	ds_bpermute_b32 v202, v149, v96
	s_waitcnt lgkmcnt(0)
	v_max3_f32 v96, v175, v96, v202
	v_cmp_gt_f32_e32 vcc, v96, v175
	s_cbranch_vccz .LBB0_1506
	v_sub_f32_e32 v175, v175, v96
	v_mul_f32_e32 v175, 0x3e38aa3b, v175
	v_exp_f32_e32 v202, v175
	s_nop 0
	v_pk_mul_f32 v[46:47], v[46:47], v[202:203] op_sel_hi:[1,0]
	v_pk_mul_f32 v[44:45], v[44:45], v[202:203] op_sel_hi:[1,0]
	v_pk_mul_f32 v[42:43], v[42:43], v[202:203] op_sel_hi:[1,0]
	v_pk_mul_f32 v[40:41], v[40:41], v[202:203] op_sel_hi:[1,0]
	v_pk_mul_f32 v[38:39], v[38:39], v[202:203] op_sel_hi:[1,0]
	v_pk_mul_f32 v[36:37], v[36:37], v[202:203] op_sel_hi:[1,0]
	v_pk_mul_f32 v[34:35], v[34:35], v[202:203] op_sel_hi:[1,0]
	v_pk_mul_f32 v[32:33], v[32:33], v[202:203] op_sel_hi:[1,0]
	v_pk_mul_f32 v[62:63], v[62:63], v[202:203] op_sel_hi:[1,0]
	v_pk_mul_f32 v[60:61], v[60:61], v[202:203] op_sel_hi:[1,0]
	v_pk_mul_f32 v[58:59], v[58:59], v[202:203] op_sel_hi:[1,0]
	v_pk_mul_f32 v[56:57], v[56:57], v[202:203] op_sel_hi:[1,0]
	v_pk_mul_f32 v[54:55], v[54:55], v[202:203] op_sel_hi:[1,0]
	v_pk_mul_f32 v[52:53], v[52:53], v[202:203] op_sel_hi:[1,0]
	v_pk_mul_f32 v[50:51], v[50:51], v[202:203] op_sel_hi:[1,0]
	v_pk_mul_f32 v[48:49], v[48:49], v[202:203] op_sel_hi:[1,0]
	v_pk_mul_f32 v[30:31], v[30:31], v[202:203] op_sel_hi:[1,0]
	v_pk_mul_f32 v[28:29], v[28:29], v[202:203] op_sel_hi:[1,0]
	v_pk_mul_f32 v[26:27], v[26:27], v[202:203] op_sel_hi:[1,0]
	v_pk_mul_f32 v[24:25], v[24:25], v[202:203] op_sel_hi:[1,0]
	v_pk_mul_f32 v[22:23], v[22:23], v[202:203] op_sel_hi:[1,0]
	v_pk_mul_f32 v[20:21], v[20:21], v[202:203] op_sel_hi:[1,0]
	v_pk_mul_f32 v[18:19], v[18:19], v[202:203] op_sel_hi:[1,0]
	v_pk_mul_f32 v[16:17], v[16:17], v[202:203] op_sel_hi:[1,0]
	v_pk_mul_f32 v[14:15], v[14:15], v[202:203] op_sel_hi:[1,0]
	v_pk_mul_f32 v[12:13], v[12:13], v[202:203] op_sel_hi:[1,0]
	v_pk_mul_f32 v[10:11], v[10:11], v[202:203] op_sel_hi:[1,0]
	v_pk_mul_f32 v[8:9], v[8:9], v[202:203] op_sel_hi:[1,0]
	v_pk_mul_f32 v[6:7], v[6:7], v[202:203] op_sel_hi:[1,0]
	v_pk_mul_f32 v[4:5], v[4:5], v[202:203] op_sel_hi:[1,0]
	v_pk_mul_f32 v[2:3], v[2:3], v[202:203] op_sel_hi:[1,0]
	v_pk_mul_f32 v[0:1], v[0:1], v[202:203] op_sel_hi:[1,0]
	v_mul_f32_e32 v174, v174, v202
; DEVI f32x16 mfma32(bf16x8 a, bf16x8 b, f32x16 c) { return __builtin_amdgcn_mfma_f32_32x32x16_bf16(a, b, c, 0, 0, 0); }
; DEVI void attn_item(const Params& p, int seq, int qt, int h, float lam, char* smem) {
;     ...
; #pragma unroll
;     for (int kt2 = 0; kt2 < 2; ++kt2)
; #pragma unroll
;       for (int r = 0; r < 16; ++r) {
;         const float pv = __builtin_amdgcn_exp2f(S[kt2][r] * sc - msc);
;         S[kt2][r] = pv;
;         ps += pv;
;       }
;     if (__any(mnew > mrun)) {
;       const float alpha = __builtin_amdgcn_exp2f((mrun - mnew) * sc);
;       lrun *= alpha;
; #pragma unroll
;       for (int et = 0; et < 4; ++et)
; #pragma unroll
;         for (int r = 0; r < 16; ++r) O[et][r] *= alpha;
;     }
;     mrun = mnew;
;     lrun += ps;
;     bf16x8 pf[4];
; #pragma unroll
;     for (int s = 0; s < 4; ++s) {
;       union { u32x4 q; bf16x8 v; } cvp;
; #pragma unroll
;       for (int e = 0; e < 4; ++e) cvp.q[e] = pack2(S[s >> 1][(s & 1) * 8 + 2 * e], S[s >> 1][(s & 1) * 8 + 2 * e + 1]);
;       pf[s] = cvp.v;
;     }
; #pragma unroll
;     for (int et = 0; et < 4; ++et) {
; #pragma unroll
;       for (int s = 0; s < 4; ++s) {
;         const bf16* vp = Vc + (et * 32 + (lane & 31)) * 68 + 16 * s + 4 * hl;
;         const uint2 v0 = *(const uint2*)vp, v1 = *(const uint2*)(vp + 8);
;         union { uint4 q; bf16x8 v; } cv;
;         cv.q = make_uint4(v0.x, v0.y, v1.x, v1.y);
;         O[et] = mfma32(cv.v, pf[s], O[et]);
;       }
;       __builtin_amdgcn_sched_barrier(0);
;     }
.LBB0_1506:
	v_mul_f32_e32 v175, 0x3e38aa3b, v96
	v_fma_f32 v80, v80, s82, -v175
	v_exp_f32_e32 v80, v80
	v_fma_f32 v81, v81, s82, -v175
	v_exp_f32_e32 v81, v81
	v_fma_f32 v82, v82, s82, -v175
	v_exp_f32_e32 v82, v82
	v_fma_f32 v83, v83, s82, -v175
	v_exp_f32_e32 v83, v83
	v_fma_f32 v84, v84, s82, -v175
	v_add_f32_e32 v202, 0, v80
	v_exp_f32_e32 v84, v84
	v_fma_f32 v85, v85, s82, -v175
	v_add_f32_e32 v202, v81, v202
	v_exp_f32_e32 v85, v85
	v_fma_f32 v86, v86, s82, -v175
	v_add_f32_e32 v202, v82, v202
	v_exp_f32_e32 v86, v86
	v_fma_f32 v87, v87, s82, -v175
	v_add_f32_e32 v202, v83, v202
	v_exp_f32_e32 v87, v87
	v_fma_f32 v88, v88, s82, -v175
	v_add_f32_e32 v202, v84, v202
	v_exp_f32_e32 v88, v88
	v_fma_f32 v89, v89, s82, -v175
	v_add_f32_e32 v202, v85, v202
	v_exp_f32_e32 v89, v89
	v_fma_f32 v90, v90, s82, -v175
	v_add_f32_e32 v202, v86, v202
	v_exp_f32_e32 v90, v90
	v_fma_f32 v91, v91, s82, -v175
	v_add_f32_e32 v202, v87, v202
	v_exp_f32_e32 v91, v91
	v_fma_f32 v92, v92, s82, -v175
	v_add_f32_e32 v202, v88, v202
	v_exp_f32_e32 v92, v92
	v_fma_f32 v93, v93, s82, -v175
	v_add_f32_e32 v202, v89, v202
	v_exp_f32_e32 v93, v93
	v_fma_f32 v94, v94, s82, -v175
	v_add_f32_e32 v202, v90, v202
	v_exp_f32_e32 v94, v94
	v_fma_f32 v95, v95, s82, -v175
	v_add_f32_e32 v202, v91, v202
	v_exp_f32_e32 v95, v95
	v_fma_f32 v64, v64, s82, -v175
	v_add_f32_e32 v202, v92, v202
	v_exp_f32_e32 v64, v64
	v_fma_f32 v65, v65, s82, -v175
	v_add_f32_e32 v202, v93, v202
	v_exp_f32_e32 v65, v65
	v_fma_f32 v66, v66, s82, -v175
	v_add_f32_e32 v202, v94, v202
	v_exp_f32_e32 v66, v66
	v_fma_f32 v67, v67, s82, -v175
	v_add_f32_e32 v202, v95, v202
	v_exp_f32_e32 v67, v67
	v_fma_f32 v68, v68, s82, -v175
	v_add_f32_e32 v202, v64, v202
	v_exp_f32_e32 v203, v68
	v_add_f32_e32 v202, v65, v202
	v_add_f32_e32 v202, v66, v202
	v_add_f32_e32 v202, v67, v202
	v_fma_f32 v69, v69, s82, -v175
	v_add_f32_e32 v68, v203, v202
	v_exp_f32_e32 v202, v69
	v_fma_f32 v69, v70, s82, -v175
	v_exp_f32_e32 v204, v69
	v_fma_f32 v69, v71, s82, -v175
	v_exp_f32_e32 v71, v69
	v_fma_f32 v69, v72, s82, -v175
	v_exp_f32_e32 v205, v69
	v_fma_f32 v69, v73, s82, -v175
	v_exp_f32_e32 v206, v69
	v_fma_f32 v69, v74, s82, -v175
	v_exp_f32_e32 v207, v69
	v_fma_f32 v69, v75, s82, -v175
	v_exp_f32_e32 v229, v69
	v_fma_f32 v69, v76, s82, -v175
	v_exp_f32_e32 v230, v69
	v_fma_f32 v69, v77, s82, -v175
	v_cvt_pk_bf16_f32 v72, v88, v89
	v_add3_u32 v88, s3, v152, v201
	v_exp_f32_e32 v231, v69
	v_fma_f32 v69, v78, s82, -v175
	v_add_u32_e32 v89, 0x4800, v88
	v_exp_f32_e32 v232, v69
	v_fma_f32 v69, v79, s82, -v175
	v_cvt_pk_bf16_f32 v76, v80, v81
	v_cvt_pk_bf16_f32 v77, v82, v83
	v_cvt_pk_bf16_f32 v78, v84, v85
	v_cvt_pk_bf16_f32 v79, v86, v87
	ds_read2_b64 v[80:83], v89 offset1:2
	ds_read2_b64 v[84:87], v89 offset0:4 offset1:6
	s_waitcnt lgkmcnt(1)
	v_mfma_f32_32x32x16_bf16 v[32:47], v[80:83], v[76:79], v[32:47]
	v_add_f32_e32 v68, v202, v68
	v_add_f32_e32 v68, v204, v68
	v_add_f32_e32 v68, v71, v68
	v_cvt_pk_bf16_f32 v73, v90, v91
	v_cvt_pk_bf16_f32 v74, v92, v93
	v_cvt_pk_bf16_f32 v75, v94, v95
	ds_read2_b64 v[80:83], v89 offset0:8 offset1:10
	v_add_f32_e32 v68, v205, v68
	s_waitcnt lgkmcnt(1)
	v_mfma_f32_32x32x16_bf16 v[32:47], v[84:87], v[72:75], v[32:47]
	v_add_f32_e32 v68, v206, v68
	v_add_f32_e32 v68, v207, v68
	v_add_f32_e32 v68, v229, v68
	v_exp_f32_e32 v175, v69
	v_add_f32_e32 v68, v230, v68
	v_add_f32_e32 v68, v231, v68
	v_add_f32_e32 v68, v232, v68
	v_add_f32_e32 v233, v175, v68
	v_cvt_pk_bf16_f32 v68, v64, v65
	v_cvt_pk_bf16_f32 v69, v66, v67
	v_cvt_pk_bf16_f32 v70, v203, v202
	v_cvt_pk_bf16_f32 v71, v204, v71
	v_cvt_pk_bf16_f32 v64, v205, v206
	v_cvt_pk_bf16_f32 v65, v207, v229
	s_waitcnt lgkmcnt(0)
	v_mfma_f32_32x32x16_bf16 v[32:47], v[80:83], v[68:71], v[32:47]
	v_cvt_pk_bf16_f32 v66, v230, v231
	v_cvt_pk_bf16_f32 v67, v232, v175
	v_add_u32_e32 v202, 0x5800, v88
	v_add_u32_e32 v203, 0x6800, v88
	v_add_u32_e32 v204, 0x7800, v88
	ds_read2_b64 v[80:83], v89 offset0:12 offset1:14
	ds_read2_b64 v[84:87], v202 offset0:32 offset1:34
	ds_read2_b64 v[92:95], v202 offset0:36 offset1:38
	ds_read2_b64 v[88:91], v202 offset0:40 offset1:42
	s_waitcnt lgkmcnt(3)
	v_mfma_f32_32x32x16_bf16 v[32:47], v[80:83], v[64:67], v[32:47]
	ds_read2_b64 v[80:83], v202 offset0:44 offset1:46
	s_waitcnt lgkmcnt(3)
	v_mfma_f32_32x32x16_bf16 v[48:63], v[84:87], v[76:79], v[48:63]
	ds_read2_b64 v[84:87], v203 offset0:64 offset1:66
	s_waitcnt lgkmcnt(3)
	v_mfma_f32_32x32x16_bf16 v[48:63], v[92:95], v[72:75], v[48:63]
	ds_read2_b64 v[92:95], v203 offset0:68 offset1:70
	s_waitcnt lgkmcnt(3)
	v_mfma_f32_32x32x16_bf16 v[48:63], v[88:91], v[68:71], v[48:63]
	ds_read2_b64 v[88:91], v203 offset0:72 offset1:74
	s_waitcnt lgkmcnt(3)
	v_mfma_f32_32x32x16_bf16 v[48:63], v[80:83], v[64:67], v[48:63]
	ds_read2_b64 v[80:83], v203 offset0:76 offset1:78
	s_waitcnt lgkmcnt(3)
	v_mfma_f32_32x32x16_bf16 v[16:31], v[84:87], v[76:79], v[16:31]
	ds_read2_b64 v[84:87], v204 offset0:96 offset1:98
	s_waitcnt lgkmcnt(3)
	v_mfma_f32_32x32x16_bf16 v[16:31], v[92:95], v[72:75], v[16:31]
	ds_read2_b64 v[92:95], v204 offset0:100 offset1:102
	s_waitcnt lgkmcnt(3)
	v_mfma_f32_32x32x16_bf16 v[16:31], v[88:91], v[68:71], v[16:31]
	ds_read2_b64 v[88:91], v204 offset0:104 offset1:106
	s_waitcnt lgkmcnt(3)
	v_mfma_f32_32x32x16_bf16 v[16:31], v[80:83], v[64:67], v[16:31]
	ds_read2_b64 v[80:83], v204 offset0:108 offset1:110
	s_waitcnt lgkmcnt(3)
	v_mfma_f32_32x32x16_bf16 v[0:15], v[84:87], v[76:79], v[0:15]
	s_waitcnt lgkmcnt(2)
	v_mfma_f32_32x32x16_bf16 v[0:15], v[92:95], v[72:75], v[0:15]
	s_waitcnt lgkmcnt(1)
	v_mfma_f32_32x32x16_bf16 v[0:15], v[88:91], v[68:71], v[0:15]
	s_waitcnt lgkmcnt(0)
	v_mfma_f32_32x32x16_bf16 v[0:15], v[80:83], v[64:67], v[0:15]
	s_add_i32 s76, s76, 64
	s_add_i32 s3, s2, 1
	v_add_f32_e32 v174, v233, v174
	s_cmp_eq_u32 s2, s19
	s_barrier
	s_cbranch_scc0 .LBB0_1500

;     ...
;   const int lrow = tid >> 3, lkc = (tid & 7) * 8;
;   const bf16* Ag = jb.A + (size_t)max(m0 + lrow, 0) * jb.lda + lkc;
;   const bf16* Ag1 = jb.A + (ptrdiff_t)(m0 + lrow) * jb.lda + lkc;
;   const bf16* Bg = jb.Bt + (size_t)(n0 + lrow) * jb.K + lkc;
;   const size_t astep = (size_t)32 * jb.lda, bstep = (size_t)32 * jb.K;
;   if (kt1 < 0) kt1 = jb.K >> 6;
;   const int nk = kt1 - kt0;
;   Ag += (size_t)kt0 * 64; Ag1 += (size_t)kt0 * 64; Bg += (size_t)kt0 * 64;
;   u32x4 ra0[4], rb0[4], ra1[4], rb1[4];
;     ...
;   bf16* As1 = As + 2 * 128 * 72;
;   bf16* Bs1 = As1 + 128 * 72;
;   G_LOAD(ra0, rb0, 0);
;   if (nk > 1) G_LOAD(ra1, rb1, 1);
;   G_STORE(ra0, rb0, As, Bs);
;   __syncthreads();
.LBB0_1557:
	s_cmpk_gt_i32 s17, 0xc47
	s_cbranch_scc1 .LBB0_1814
	s_mul_hi_i32 s2, s17, 0x2aaaaaab
	s_lshr_b32 s3, s2, 31
	s_ashr_i32 s2, s2, 6
	s_add_i32 s2, s2, s3
	s_lshl_b32 s3, s2, 4
	s_sub_i32 s4, 0x83, s3
	s_min_u32 s4, s4, 16
	v_cvt_f32_ubyte0_e32 v0, s4
	v_rcp_iflag_f32_e32 v0, v0
	s_sub_i32 s7, 0, s4
	s_mulk_i32 s2, 0xfe80
	s_add_i32 s5, s17, s2
	v_mul_f32_e32 v0, 0x4f7ffffe, v0
	v_cvt_u32_f32_e32 v0, v0
	s_abs_i32 s6, s5
	s_ashr_i32 s2, s5, 31
	v_mov_b32_e32 v85, v208
	v_readfirstlane_b32 s8, v0
	s_mul_i32 s7, s7, s8
	s_mul_hi_u32 s7, s8, s7
	s_add_i32 s8, s8, s7
	s_mul_hi_u32 s7, s6, s8
	s_mul_i32 s8, s7, s4
	s_sub_i32 s6, s6, s8
	s_add_i32 s8, s7, 1
	s_sub_i32 s9, s6, s4
	s_cmp_ge_u32 s6, s4
	s_cselect_b32 s7, s8, s7
	s_cselect_b32 s6, s9, s6
	s_add_i32 s8, s7, 1
	s_cmp_ge_u32 s6, s4
	s_cselect_b32 s6, s8, s7
	s_xor_b32 s6, s6, s2
	s_sub_i32 s2, s6, s2
	s_mul_i32 s4, s2, s4
	s_sub_i32 s4, s5, s4
	s_add_i32 s3, s3, s4
	s_lshl_b32 s3, s3, 7
	s_lshl_b32 s4, s2, 7
	v_ashrrev_i32_e32 v82, 3, v85
	v_add_u32_e32 v0, s3, v82
	v_max_i32_e32 v96, 0, v0
	v_lshlrev_b32_e32 v1, 4, v85
	v_lshlrev_b64 v[2:3], 11, v[96:97]
	v_and_b32_e32 v96, 0x70, v1
	s_mov_b64 s[96:97], 0x80
	v_lshrrev_b32_e32 v178, 4, v208
	v_and_b32_e32 v178, 7, v178
	v_lshlrev_b32_e32 v178, 4, v178
	v_xor_b32_e32 v96, v96, v178
	v_lshrrev_b32_e32 v179, 6, v208
	v_lshlrev_b32_e32 v179, 10, v179
	v_lshrrev_b32_e32 v180, 5, v208
	v_lshrrev_b32_e32 v181, 1, v208
	v_xor_b32_e32 v180, v180, v181
	v_readfirstlane_b32 s94, v179
	v_and_b32_e32 v180, 1, v180
	v_lshlrev_b32_e32 v180, 4, v180
	v_and_b32_e32 v181, 31, v208
	v_lshlrev_b32_e32 v181, 7, v181
	v_or_b32_e32 v180, v180, v181
	v_lshrrev_b32_e32 v181, 7, v208
	v_lshlrev_b32_e32 v181, 13, v181
	v_or_b32_e32 v194, v180, v181
	v_bfe_u32 v181, v208, 6, 1
	v_lshlrev_b32_e32 v181, 13, v181
	v_or_b32_e32 v195, v180, v181
	v_bfe_u32 v178, v208, 2, 2
	v_xor_b32_e32 v179, 0, v178
	v_lshlrev_b32_e32 v179, 5, v179
	v_or_b32_e32 v170, v194, v179
	v_or_b32_e32 v174, v195, v179
	v_xor_b32_e32 v179, 1, v178
	v_lshlrev_b32_e32 v179, 5, v179
	v_or_b32_e32 v171, v194, v179
	v_or_b32_e32 v175, v195, v179
	v_xor_b32_e32 v179, 2, v178
	v_lshlrev_b32_e32 v179, 5, v179
	v_or_b32_e32 v172, v194, v179
	v_or_b32_e32 v176, v195, v179
	v_xor_b32_e32 v179, 3, v178
	v_lshlrev_b32_e32 v179, 5, v179
	v_or_b32_e32 v173, v194, v179
	v_or_b32_e32 v177, v195, v179
	v_ashrrev_i32_e32 v1, 31, v0
	v_lshlrev_b64 v[0:1], 11, v[0:1]
	v_lshl_add_u64 v[0:1], s[12:13], 0, v[0:1]
	v_lshl_add_u64 v[28:29], v[0:1], 0, v[96:97]
	v_add_u32_e32 v0, s4, v82
	v_ashrrev_i32_e32 v1, 31, v0
	v_lshlrev_b64 v[0:1], 11, v[0:1]
	v_lshl_add_u64 v[0:1], s[14:15], 0, v[0:1]
	v_add_co_u32_e32 v70, vcc, s63, v28
	v_lshl_add_u64 v[68:69], v[0:1], 0, v[96:97]
	s_nop 0
	v_addc_co_u32_e32 v71, vcc, 0, v29, vcc
	v_add_co_u32_e32 v72, vcc, s63, v68
	v_lshl_add_u64 v[2:3], s[12:13], 0, v[2:3]
	s_nop 0
	v_addc_co_u32_e32 v73, vcc, 0, v69, vcc
	v_add_co_u32_e32 v74, vcc, s64, v28
	v_lshl_add_u64 v[66:67], v[2:3], 0, v[96:97]
	s_nop 0
	v_addc_co_u32_e32 v75, vcc, 0, v29, vcc
	v_add_co_u32_e32 v76, vcc, s64, v68
	v_addc_co_u32_e32 v77, vcc, 0, v69, vcc
	v_add_co_u32_e32 v78, vcc, s65, v68
	s_nop 0
	v_addc_co_u32_e32 v79, vcc, 0, v69, vcc
	v_add_co_u32_e32 v80, vcc, s65, v28
	s_nop 0
	v_addc_co_u32_e32 v81, vcc, 0, v29, vcc
	v_ashrrev_i32_e32 v64, 1, v85
	v_and_b32_e32 v84, 31, v85
	v_lshrrev_b32_e32 v65, 1, v85
	v_and_b32_e32 v86, 0xffffffc0, v64
	v_and_b32_e32 v88, 16, v65
	v_or_b32_e32 v64, v86, v84
	v_mad_u64_u32 v[82:83], s[6:7], v82, s91, v[96:97]
	v_mad_u64_u32 v[64:65], s[6:7], v64, s91, v[88:89]
	v_add_u32_e32 v83, 0xd800, v82
	s_ashr_i32 s5, s2, 3
	s_and_b32 s2, s4, 0x380
	s_mov_b64 s[22:23], s[74:75]
	s_mov_b64 s[6:7], 0x1e05c060
	s_add_u32 m0, s94, 0x4000
	s_nop 1
	global_load_lds_dwordx4 v[68:69], off
	s_add_u32 m0, s94, 0x0
	s_nop 1
	global_load_lds_dwordx4 v[66:67], off
	s_add_u32 m0, s94, 0x5000
	s_nop 1
	global_load_lds_dwordx4 v[72:73], off
	s_add_u32 m0, s94, 0x6000
	s_nop 1
	global_load_lds_dwordx4 v[76:77], off
	s_add_u32 m0, s94, 0x7000
	s_nop 1
	global_load_lds_dwordx4 v[78:79], off
	s_add_u32 m0, s94, 0x1000
	s_nop 1
	global_load_lds_dwordx4 v[70:71], off
	s_add_u32 m0, s94, 0x2000
	s_nop 1
	global_load_lds_dwordx4 v[74:75], off
	s_add_u32 m0, s94, 0x3000
	s_nop 1
	global_load_lds_dwordx4 v[80:81], off
	s_waitcnt lgkmcnt(0)
	s_waitcnt vmcnt(0)
	s_barrier
;     ...
;   bf16* As1 = As + 2 * 128 * 72;
;   bf16* Bs1 = As1 + 128 * 72;
;   G_LOAD(ra0, rb0, 0);
;   if (nk > 1) G_LOAD(ra1, rb1, 1);
;   G_STORE(ra0, rb0, As, Bs);
;   __syncthreads();
;   for (int kt = 0; kt < nk; kt += 2) {
;     if (kt + 2 < nk) G_LOAD(ra0, rb0, kt + 2);
;     if (kt + 1 < nk) G_STORE(ra1, rb1, As1, Bs1);
;     G_COMPUTE(As, Bs);
;     __syncthreads();
;     if (kt + 1 < nk) {
;       if (kt + 3 < nk) G_LOAD(ra1, rb1, kt + 3);
;       if (kt + 2 < nk) G_STORE(ra0, rb0, As, Bs);
;       G_COMPUTE(As1, Bs1);
;       __syncthreads();
;     }
;   }
	v_lshl_add_u64 v[66:67], v[66:67], 0, s[96:97]
	s_add_u32 m0, s94, 0x8000
	s_nop 1
	global_load_lds_dwordx4 v[66:67], off
	v_lshl_add_u64 v[68:69], v[68:69], 0, s[96:97]
	s_add_u32 m0, s94, 0xc000
	s_nop 1
	global_load_lds_dwordx4 v[68:69], off
	v_lshl_add_u64 v[70:71], v[70:71], 0, s[96:97]
	s_add_u32 m0, s94, 0x9000
	s_nop 1
	global_load_lds_dwordx4 v[70:71], off
	v_lshl_add_u64 v[72:73], v[72:73], 0, s[96:97]
	s_add_u32 m0, s94, 0xd000
	s_nop 1
	global_load_lds_dwordx4 v[72:73], off
	v_lshl_add_u64 v[74:75], v[74:75], 0, s[96:97]
	s_add_u32 m0, s94, 0xa000
	s_nop 1
	global_load_lds_dwordx4 v[74:75], off
	v_lshl_add_u64 v[76:77], v[76:77], 0, s[96:97]
	s_add_u32 m0, s94, 0xe000
	s_nop 1
	global_load_lds_dwordx4 v[76:77], off
	v_lshl_add_u64 v[80:81], v[80:81], 0, s[96:97]
	s_add_u32 m0, s94, 0xb000
	s_nop 1
	global_load_lds_dwordx4 v[80:81], off
	v_lshl_add_u64 v[78:79], v[78:79], 0, s[96:97]
	s_add_u32 m0, s94, 0xf000
	s_nop 1
	global_load_lds_dwordx4 v[78:79], off
	ds_read_b128 v[0:3], v170 offset:0
	v_and_b32_e32 v4, 0x5f, v85
	v_mad_u32_u24 v65, v4, s91, v88
	ds_read_b128 v[4:7], v174 offset:16384
	ds_read_b128 v[88:91], v171 offset:0
	ds_read_b128 v[92:95], v175 offset:16384
	ds_read_b128 v[16:19], v174 offset:20480
	ds_read_b128 v[98:101], v175 offset:20480
	s_waitcnt lgkmcnt(4)
	v_mfma_f32_32x32x16_bf16 v[32:47], v[0:3], v[4:7], 0
	ds_read_b128 v[20:23], v170 offset:4096
	ds_read_b128 v[102:105], v171 offset:4096
	s_waitcnt lgkmcnt(3)
	v_mfma_f32_32x32x16_bf16 v[48:63], v[0:3], v[16:19], 0
	s_waitcnt lgkmcnt(1)
	v_mfma_f32_32x32x16_bf16 v[0:15], v[20:23], v[4:7], 0
	v_mfma_f32_32x32x16_bf16 v[16:31], v[20:23], v[16:19], 0
	v_mfma_f32_32x32x16_bf16 v[32:47], v[88:91], v[92:95], v[32:47]
	v_mfma_f32_32x32x16_bf16 v[48:63], v[88:91], v[98:101], v[48:63]
	s_waitcnt lgkmcnt(0)
	v_mfma_f32_32x32x16_bf16 v[0:15], v[102:105], v[92:95], v[0:15]
	v_mfma_f32_32x32x16_bf16 v[16:31], v[102:105], v[98:101], v[16:31]
	ds_read_b128 v[88:91], v172 offset:0
	ds_read_b128 v[92:95], v176 offset:16384
	ds_read_b128 v[98:101], v173 offset:0
	ds_read_b128 v[102:105], v177 offset:16384
	ds_read_b128 v[106:109], v176 offset:20480
	ds_read_b128 v[110:113], v177 offset:20480
	s_waitcnt lgkmcnt(4)
	v_mfma_f32_32x32x16_bf16 v[32:47], v[88:91], v[92:95], v[32:47]
	s_waitcnt lgkmcnt(1)
	v_mfma_f32_32x32x16_bf16 v[48:63], v[88:91], v[106:109], v[48:63]
	ds_read_b128 v[88:91], v172 offset:4096
	ds_read_b128 v[114:117], v173 offset:4096
	s_waitcnt lgkmcnt(1)
	v_mfma_f32_32x32x16_bf16 v[0:15], v[88:91], v[92:95], v[0:15]
	v_mfma_f32_32x32x16_bf16 v[16:31], v[88:91], v[106:109], v[16:31]
	v_mfma_f32_32x32x16_bf16 v[32:47], v[98:101], v[102:105], v[32:47]
	v_mfma_f32_32x32x16_bf16 v[48:63], v[98:101], v[110:113], v[48:63]
	s_waitcnt lgkmcnt(0)
	v_mfma_f32_32x32x16_bf16 v[0:15], v[114:117], v[102:105], v[0:15]
	s_waitcnt vmcnt(0)
	s_barrier
	v_lshl_add_u64 v[66:67], v[66:67], 0, s[96:97]
	s_add_u32 m0, s94, 0x0
	s_nop 1
	global_load_lds_dwordx4 v[66:67], off
	v_lshl_add_u64 v[68:69], v[68:69], 0, s[96:97]
	s_add_u32 m0, s94, 0x4000
	s_nop 1
	global_load_lds_dwordx4 v[68:69], off
	v_lshl_add_u64 v[70:71], v[70:71], 0, s[96:97]
	s_add_u32 m0, s94, 0x1000
	s_nop 1
	global_load_lds_dwordx4 v[70:71], off
	v_lshl_add_u64 v[72:73], v[72:73], 0, s[96:97]
	s_add_u32 m0, s94, 0x5000
	s_nop 1
	global_load_lds_dwordx4 v[72:73], off
	v_lshl_add_u64 v[74:75], v[74:75], 0, s[96:97]
	s_add_u32 m0, s94, 0x2000
	s_nop 1
	global_load_lds_dwordx4 v[74:75], off
	v_lshl_add_u64 v[76:77], v[76:77], 0, s[96:97]
	s_add_u32 m0, s94, 0x6000
	s_nop 1
	global_load_lds_dwordx4 v[76:77], off
	v_lshl_add_u64 v[80:81], v[80:81], 0, s[96:97]
	s_add_u32 m0, s94, 0x3000
	s_nop 1
	global_load_lds_dwordx4 v[80:81], off
	v_lshl_add_u64 v[78:79], v[78:79], 0, s[96:97]
	s_add_u32 m0, s94, 0x7000
	s_nop 1
	global_load_lds_dwordx4 v[78:79], off
	v_mfma_f32_32x32x16_bf16 v[16:31], v[114:117], v[110:113], v[16:31]
	ds_read_b128 v[88:91], v170 offset:32768
	ds_read_b128 v[92:95], v174 offset:49152
	ds_read_b128 v[98:101], v171 offset:32768
	ds_read_b128 v[102:105], v175 offset:49152
	ds_read_b128 v[106:109], v174 offset:53248
	ds_read_b128 v[110:113], v175 offset:53248
	s_waitcnt lgkmcnt(4)
	v_mfma_f32_32x32x16_bf16 v[32:47], v[88:91], v[92:95], v[32:47]
	s_waitcnt lgkmcnt(1)
	v_mfma_f32_32x32x16_bf16 v[48:63], v[88:91], v[106:109], v[48:63]
	ds_read_b128 v[88:91], v170 offset:36864
	ds_read_b128 v[114:117], v171 offset:36864
	s_waitcnt lgkmcnt(1)
	v_mfma_f32_32x32x16_bf16 v[0:15], v[88:91], v[92:95], v[0:15]
	v_mfma_f32_32x32x16_bf16 v[16:31], v[88:91], v[106:109], v[16:31]
	v_mfma_f32_32x32x16_bf16 v[32:47], v[98:101], v[102:105], v[32:47]
	v_mfma_f32_32x32x16_bf16 v[48:63], v[98:101], v[110:113], v[48:63]
	s_waitcnt lgkmcnt(0)
	v_mfma_f32_32x32x16_bf16 v[0:15], v[114:117], v[102:105], v[0:15]
	ds_read_b128 v[88:91], v172 offset:32768
	ds_read_b128 v[92:95], v176 offset:49152
	ds_read_b128 v[98:101], v173 offset:32768
	ds_read_b128 v[102:105], v177 offset:49152
	v_mfma_f32_32x32x16_bf16 v[16:31], v[114:117], v[110:113], v[16:31]
	ds_read_b128 v[106:109], v176 offset:53248
	ds_read_b128 v[110:113], v177 offset:53248
	s_waitcnt lgkmcnt(4)
	v_mfma_f32_32x32x16_bf16 v[32:47], v[88:91], v[92:95], v[32:47]
	s_waitcnt lgkmcnt(1)
	v_mfma_f32_32x32x16_bf16 v[48:63], v[88:91], v[106:109], v[48:63]
	ds_read_b128 v[88:91], v172 offset:36864
	ds_read_b128 v[114:117], v173 offset:36864
	s_waitcnt lgkmcnt(1)
	v_mfma_f32_32x32x16_bf16 v[0:15], v[88:91], v[92:95], v[0:15]
	v_mfma_f32_32x32x16_bf16 v[16:31], v[88:91], v[106:109], v[16:31]
	v_mfma_f32_32x32x16_bf16 v[32:47], v[98:101], v[102:105], v[32:47]
	v_mfma_f32_32x32x16_bf16 v[48:63], v[98:101], v[110:113], v[48:63]
	s_waitcnt lgkmcnt(0)
	v_mfma_f32_32x32x16_bf16 v[0:15], v[114:117], v[102:105], v[0:15]
	s_waitcnt vmcnt(0)
	s_barrier
;     ...
;   bf16* As1 = As + 2 * 128 * 72;
;   bf16* Bs1 = As1 + 128 * 72;
;   G_LOAD(ra0, rb0, 0);
;   if (nk > 1) G_LOAD(ra1, rb1, 1);
;   G_STORE(ra0, rb0, As, Bs);
;   __syncthreads();
;   for (int kt = 0; kt < nk; kt += 2) {
;     if (kt + 2 < nk) G_LOAD(ra0, rb0, kt + 2);
;     if (kt + 1 < nk) G_STORE(ra1, rb1, As1, Bs1);
;     G_COMPUTE(As, Bs);
;     __syncthreads();
;     if (kt + 1 < nk) {
;       if (kt + 3 < nk) G_LOAD(ra1, rb1, kt + 3);
;       if (kt + 2 < nk) G_STORE(ra0, rb0, As, Bs);
;       G_COMPUTE(As1, Bs1);
;       __syncthreads();
;     }
;   }
	v_lshl_add_u64 v[66:67], v[66:67], 0, s[96:97]
	s_add_u32 m0, s94, 0x8000
	s_nop 1
	global_load_lds_dwordx4 v[66:67], off
	v_lshl_add_u64 v[68:69], v[68:69], 0, s[96:97]
	s_add_u32 m0, s94, 0xc000
	s_nop 1
	global_load_lds_dwordx4 v[68:69], off
	v_lshl_add_u64 v[70:71], v[70:71], 0, s[96:97]
	s_add_u32 m0, s94, 0x9000
	s_nop 1
	global_load_lds_dwordx4 v[70:71], off
	v_lshl_add_u64 v[72:73], v[72:73], 0, s[96:97]
	s_add_u32 m0, s94, 0xd000
	s_nop 1
	global_load_lds_dwordx4 v[72:73], off
	v_lshl_add_u64 v[74:75], v[74:75], 0, s[96:97]
	s_add_u32 m0, s94, 0xa000
	s_nop 1
	global_load_lds_dwordx4 v[74:75], off
	v_lshl_add_u64 v[76:77], v[76:77], 0, s[96:97]
	s_add_u32 m0, s94, 0xe000
	s_nop 1
	global_load_lds_dwordx4 v[76:77], off
	v_lshl_add_u64 v[80:81], v[80:81], 0, s[96:97]
	s_add_u32 m0, s94, 0xb000
	s_nop 1
	global_load_lds_dwordx4 v[80:81], off
	v_lshl_add_u64 v[78:79], v[78:79], 0, s[96:97]
	s_add_u32 m0, s94, 0xf000
	s_nop 1
	global_load_lds_dwordx4 v[78:79], off
	v_mfma_f32_32x32x16_bf16 v[16:31], v[114:117], v[110:113], v[16:31]
	ds_read_b128 v[88:91], v170 offset:0
	ds_read_b128 v[92:95], v174 offset:16384
	ds_read_b128 v[98:101], v171 offset:0
	ds_read_b128 v[102:105], v175 offset:16384
	ds_read_b128 v[106:109], v174 offset:20480
	ds_read_b128 v[110:113], v175 offset:20480
	s_waitcnt lgkmcnt(4)
	v_mfma_f32_32x32x16_bf16 v[32:47], v[88:91], v[92:95], v[32:47]
	s_waitcnt lgkmcnt(1)
	v_mfma_f32_32x32x16_bf16 v[48:63], v[88:91], v[106:109], v[48:63]
	ds_read_b128 v[88:91], v170 offset:4096
	ds_read_b128 v[114:117], v171 offset:4096
	s_waitcnt lgkmcnt(1)
	v_mfma_f32_32x32x16_bf16 v[0:15], v[88:91], v[92:95], v[0:15]
	v_mfma_f32_32x32x16_bf16 v[16:31], v[88:91], v[106:109], v[16:31]
	v_mfma_f32_32x32x16_bf16 v[32:47], v[98:101], v[102:105], v[32:47]
	v_mfma_f32_32x32x16_bf16 v[48:63], v[98:101], v[110:113], v[48:63]
	s_waitcnt lgkmcnt(0)
	v_mfma_f32_32x32x16_bf16 v[0:15], v[114:117], v[102:105], v[0:15]
	ds_read_b128 v[88:91], v172 offset:0
	ds_read_b128 v[92:95], v176 offset:16384
	ds_read_b128 v[98:101], v173 offset:0
	ds_read_b128 v[102:105], v177 offset:16384
	v_mfma_f32_32x32x16_bf16 v[16:31], v[114:117], v[110:113], v[16:31]
	ds_read_b128 v[106:109], v176 offset:20480
	ds_read_b128 v[110:113], v177 offset:20480
	s_waitcnt lgkmcnt(4)
	v_mfma_f32_32x32x16_bf16 v[32:47], v[88:91], v[92:95], v[32:47]
	s_waitcnt lgkmcnt(1)
	v_mfma_f32_32x32x16_bf16 v[48:63], v[88:91], v[106:109], v[48:63]
	ds_read_b128 v[88:91], v172 offset:4096
	ds_read_b128 v[114:117], v173 offset:4096
	s_waitcnt lgkmcnt(1)
	v_mfma_f32_32x32x16_bf16 v[0:15], v[88:91], v[92:95], v[0:15]
	v_mfma_f32_32x32x16_bf16 v[16:31], v[88:91], v[106:109], v[16:31]
	v_mfma_f32_32x32x16_bf16 v[32:47], v[98:101], v[102:105], v[32:47]
	v_mfma_f32_32x32x16_bf16 v[48:63], v[98:101], v[110:113], v[48:63]
	s_waitcnt lgkmcnt(0)
	v_mfma_f32_32x32x16_bf16 v[0:15], v[114:117], v[102:105], v[0:15]
	s_waitcnt vmcnt(0)
	s_barrier
	v_lshl_add_u64 v[66:67], v[66:67], 0, s[96:97]
	s_add_u32 m0, s94, 0x0
	s_nop 1
	global_load_lds_dwordx4 v[66:67], off
	v_lshl_add_u64 v[68:69], v[68:69], 0, s[96:97]
	s_add_u32 m0, s94, 0x4000
	s_nop 1
	global_load_lds_dwordx4 v[68:69], off
	v_lshl_add_u64 v[70:71], v[70:71], 0, s[96:97]
	s_add_u32 m0, s94, 0x1000
	s_nop 1
	global_load_lds_dwordx4 v[70:71], off
	v_lshl_add_u64 v[72:73], v[72:73], 0, s[96:97]
	s_add_u32 m0, s94, 0x5000
	s_nop 1
	global_load_lds_dwordx4 v[72:73], off
	v_lshl_add_u64 v[74:75], v[74:75], 0, s[96:97]
	s_add_u32 m0, s94, 0x2000
	s_nop 1
	global_load_lds_dwordx4 v[74:75], off
	v_lshl_add_u64 v[76:77], v[76:77], 0, s[96:97]
	s_add_u32 m0, s94, 0x6000
	s_nop 1
	global_load_lds_dwordx4 v[76:77], off
	v_lshl_add_u64 v[80:81], v[80:81], 0, s[96:97]
	s_add_u32 m0, s94, 0x3000
	s_nop 1
	global_load_lds_dwordx4 v[80:81], off
	v_lshl_add_u64 v[78:79], v[78:79], 0, s[96:97]
	s_add_u32 m0, s94, 0x7000
	s_nop 1
	global_load_lds_dwordx4 v[78:79], off
	v_mfma_f32_32x32x16_bf16 v[16:31], v[114:117], v[110:113], v[16:31]
	ds_read_b128 v[88:91], v170 offset:32768
	ds_read_b128 v[92:95], v174 offset:49152
	ds_read_b128 v[98:101], v171 offset:32768
	ds_read_b128 v[102:105], v175 offset:49152
	ds_read_b128 v[106:109], v174 offset:53248
	ds_read_b128 v[110:113], v175 offset:53248
	s_waitcnt lgkmcnt(4)
	v_mfma_f32_32x32x16_bf16 v[32:47], v[88:91], v[92:95], v[32:47]
	s_waitcnt lgkmcnt(1)
	v_mfma_f32_32x32x16_bf16 v[48:63], v[88:91], v[106:109], v[48:63]
	ds_read_b128 v[88:91], v170 offset:36864
	ds_read_b128 v[114:117], v171 offset:36864
	s_waitcnt lgkmcnt(1)
	v_mfma_f32_32x32x16_bf16 v[0:15], v[88:91], v[92:95], v[0:15]
	v_mfma_f32_32x32x16_bf16 v[16:31], v[88:91], v[106:109], v[16:31]
	v_mfma_f32_32x32x16_bf16 v[32:47], v[98:101], v[102:105], v[32:47]
	v_mfma_f32_32x32x16_bf16 v[48:63], v[98:101], v[110:113], v[48:63]
	s_waitcnt lgkmcnt(0)
	v_mfma_f32_32x32x16_bf16 v[0:15], v[114:117], v[102:105], v[0:15]
	ds_read_b128 v[88:91], v172 offset:32768
	ds_read_b128 v[92:95], v176 offset:49152
	ds_read_b128 v[98:101], v173 offset:32768
	ds_read_b128 v[102:105], v177 offset:49152
	v_mfma_f32_32x32x16_bf16 v[16:31], v[114:117], v[110:113], v[16:31]
	ds_read_b128 v[106:109], v176 offset:53248
	ds_read_b128 v[110:113], v177 offset:53248
	s_waitcnt lgkmcnt(4)
	v_mfma_f32_32x32x16_bf16 v[32:47], v[88:91], v[92:95], v[32:47]
	s_waitcnt lgkmcnt(1)
	v_mfma_f32_32x32x16_bf16 v[48:63], v[88:91], v[106:109], v[48:63]
	ds_read_b128 v[88:91], v172 offset:36864
	ds_read_b128 v[114:117], v173 offset:36864
	s_waitcnt lgkmcnt(1)
	v_mfma_f32_32x32x16_bf16 v[0:15], v[88:91], v[92:95], v[0:15]
	v_mfma_f32_32x32x16_bf16 v[16:31], v[88:91], v[106:109], v[16:31]
	v_mfma_f32_32x32x16_bf16 v[32:47], v[98:101], v[102:105], v[32:47]
	v_mfma_f32_32x32x16_bf16 v[48:63], v[98:101], v[110:113], v[48:63]
	s_waitcnt lgkmcnt(0)
	v_mfma_f32_32x32x16_bf16 v[0:15], v[114:117], v[102:105], v[0:15]
	s_waitcnt vmcnt(0)
	s_barrier
;     ...
;   bf16* As1 = As + 2 * 128 * 72;
;   bf16* Bs1 = As1 + 128 * 72;
;   G_LOAD(ra0, rb0, 0);
;   if (nk > 1) G_LOAD(ra1, rb1, 1);
;   G_STORE(ra0, rb0, As, Bs);
;   __syncthreads();
;   for (int kt = 0; kt < nk; kt += 2) {
;     if (kt + 2 < nk) G_LOAD(ra0, rb0, kt + 2);
;     if (kt + 1 < nk) G_STORE(ra1, rb1, As1, Bs1);
;     G_COMPUTE(As, Bs);
;     __syncthreads();
;     if (kt + 1 < nk) {
;       if (kt + 3 < nk) G_LOAD(ra1, rb1, kt + 3);
;       if (kt + 2 < nk) G_STORE(ra0, rb0, As, Bs);
;       G_COMPUTE(As1, Bs1);
;       __syncthreads();
;     }
;   }
	v_lshl_add_u64 v[66:67], v[66:67], 0, s[96:97]
	s_add_u32 m0, s94, 0x8000
	s_nop 1
	global_load_lds_dwordx4 v[66:67], off
	v_lshl_add_u64 v[68:69], v[68:69], 0, s[96:97]
	s_add_u32 m0, s94, 0xc000
	s_nop 1
	global_load_lds_dwordx4 v[68:69], off
	v_lshl_add_u64 v[70:71], v[70:71], 0, s[96:97]
	s_add_u32 m0, s94, 0x9000
	s_nop 1
	global_load_lds_dwordx4 v[70:71], off
	v_lshl_add_u64 v[72:73], v[72:73], 0, s[96:97]
	s_add_u32 m0, s94, 0xd000
	s_nop 1
	global_load_lds_dwordx4 v[72:73], off
	v_lshl_add_u64 v[74:75], v[74:75], 0, s[96:97]
	s_add_u32 m0, s94, 0xa000
	s_nop 1
	global_load_lds_dwordx4 v[74:75], off
	v_lshl_add_u64 v[76:77], v[76:77], 0, s[96:97]
	s_add_u32 m0, s94, 0xe000
	s_nop 1
	global_load_lds_dwordx4 v[76:77], off
	v_lshl_add_u64 v[80:81], v[80:81], 0, s[96:97]
	s_add_u32 m0, s94, 0xb000
	s_nop 1
	global_load_lds_dwordx4 v[80:81], off
	v_lshl_add_u64 v[78:79], v[78:79], 0, s[96:97]
	s_add_u32 m0, s94, 0xf000
	s_nop 1
	global_load_lds_dwordx4 v[78:79], off
	v_mfma_f32_32x32x16_bf16 v[16:31], v[114:117], v[110:113], v[16:31]
	ds_read_b128 v[88:91], v170 offset:0
	ds_read_b128 v[92:95], v174 offset:16384
	ds_read_b128 v[98:101], v171 offset:0
	ds_read_b128 v[102:105], v175 offset:16384
	ds_read_b128 v[106:109], v174 offset:20480
	ds_read_b128 v[110:113], v175 offset:20480
	s_waitcnt lgkmcnt(4)
	v_mfma_f32_32x32x16_bf16 v[32:47], v[88:91], v[92:95], v[32:47]
	s_waitcnt lgkmcnt(1)
	v_mfma_f32_32x32x16_bf16 v[48:63], v[88:91], v[106:109], v[48:63]
	ds_read_b128 v[88:91], v170 offset:4096
	ds_read_b128 v[114:117], v171 offset:4096
	s_waitcnt lgkmcnt(1)
	v_mfma_f32_32x32x16_bf16 v[0:15], v[88:91], v[92:95], v[0:15]
	v_mfma_f32_32x32x16_bf16 v[16:31], v[88:91], v[106:109], v[16:31]
	v_mfma_f32_32x32x16_bf16 v[32:47], v[98:101], v[102:105], v[32:47]
	v_mfma_f32_32x32x16_bf16 v[48:63], v[98:101], v[110:113], v[48:63]
	s_waitcnt lgkmcnt(0)
	v_mfma_f32_32x32x16_bf16 v[0:15], v[114:117], v[102:105], v[0:15]
	ds_read_b128 v[88:91], v172 offset:0
	ds_read_b128 v[92:95], v176 offset:16384
	ds_read_b128 v[98:101], v173 offset:0
	ds_read_b128 v[102:105], v177 offset:16384
	v_mfma_f32_32x32x16_bf16 v[16:31], v[114:117], v[110:113], v[16:31]
	ds_read_b128 v[106:109], v176 offset:20480
	ds_read_b128 v[110:113], v177 offset:20480
	s_waitcnt lgkmcnt(4)
	v_mfma_f32_32x32x16_bf16 v[32:47], v[88:91], v[92:95], v[32:47]
	s_waitcnt lgkmcnt(1)
	v_mfma_f32_32x32x16_bf16 v[48:63], v[88:91], v[106:109], v[48:63]
	ds_read_b128 v[88:91], v172 offset:4096
	ds_read_b128 v[114:117], v173 offset:4096
	s_waitcnt lgkmcnt(1)
	v_mfma_f32_32x32x16_bf16 v[0:15], v[88:91], v[92:95], v[0:15]
	v_mfma_f32_32x32x16_bf16 v[16:31], v[88:91], v[106:109], v[16:31]
	v_mfma_f32_32x32x16_bf16 v[32:47], v[98:101], v[102:105], v[32:47]
	v_mfma_f32_32x32x16_bf16 v[48:63], v[98:101], v[110:113], v[48:63]
	s_waitcnt lgkmcnt(0)
	v_mfma_f32_32x32x16_bf16 v[0:15], v[114:117], v[102:105], v[0:15]
	s_waitcnt vmcnt(0)
	s_barrier
	v_lshl_add_u64 v[66:67], v[66:67], 0, s[96:97]
	s_add_u32 m0, s94, 0x0
	s_nop 1
	global_load_lds_dwordx4 v[66:67], off
	v_lshl_add_u64 v[68:69], v[68:69], 0, s[96:97]
	s_add_u32 m0, s94, 0x4000
	s_nop 1
	global_load_lds_dwordx4 v[68:69], off
	v_lshl_add_u64 v[70:71], v[70:71], 0, s[96:97]
	s_add_u32 m0, s94, 0x1000
	s_nop 1
	global_load_lds_dwordx4 v[70:71], off
	v_lshl_add_u64 v[72:73], v[72:73], 0, s[96:97]
	s_add_u32 m0, s94, 0x5000
	s_nop 1
	global_load_lds_dwordx4 v[72:73], off
	v_lshl_add_u64 v[74:75], v[74:75], 0, s[96:97]
	s_add_u32 m0, s94, 0x2000
	s_nop 1
	global_load_lds_dwordx4 v[74:75], off
	v_lshl_add_u64 v[76:77], v[76:77], 0, s[96:97]
	s_add_u32 m0, s94, 0x6000
	s_nop 1
	global_load_lds_dwordx4 v[76:77], off
	v_lshl_add_u64 v[80:81], v[80:81], 0, s[96:97]
	s_add_u32 m0, s94, 0x3000
	s_nop 1
	global_load_lds_dwordx4 v[80:81], off
	v_lshl_add_u64 v[78:79], v[78:79], 0, s[96:97]
	s_add_u32 m0, s94, 0x7000
	s_nop 1
	global_load_lds_dwordx4 v[78:79], off
	v_mfma_f32_32x32x16_bf16 v[16:31], v[114:117], v[110:113], v[16:31]
	ds_read_b128 v[88:91], v170 offset:32768
	ds_read_b128 v[92:95], v174 offset:49152
	ds_read_b128 v[98:101], v171 offset:32768
	ds_read_b128 v[102:105], v175 offset:49152
	ds_read_b128 v[106:109], v174 offset:53248
	ds_read_b128 v[110:113], v175 offset:53248
	s_waitcnt lgkmcnt(4)
	v_mfma_f32_32x32x16_bf16 v[32:47], v[88:91], v[92:95], v[32:47]
	s_waitcnt lgkmcnt(1)
	v_mfma_f32_32x32x16_bf16 v[48:63], v[88:91], v[106:109], v[48:63]
	ds_read_b128 v[88:91], v170 offset:36864
	ds_read_b128 v[114:117], v171 offset:36864
	s_waitcnt lgkmcnt(1)
	v_mfma_f32_32x32x16_bf16 v[0:15], v[88:91], v[92:95], v[0:15]
	v_mfma_f32_32x32x16_bf16 v[16:31], v[88:91], v[106:109], v[16:31]
	v_mfma_f32_32x32x16_bf16 v[32:47], v[98:101], v[102:105], v[32:47]
	v_mfma_f32_32x32x16_bf16 v[48:63], v[98:101], v[110:113], v[48:63]
	s_waitcnt lgkmcnt(0)
	v_mfma_f32_32x32x16_bf16 v[0:15], v[114:117], v[102:105], v[0:15]
	ds_read_b128 v[88:91], v172 offset:32768
	ds_read_b128 v[92:95], v176 offset:49152
	ds_read_b128 v[98:101], v173 offset:32768
	ds_read_b128 v[102:105], v177 offset:49152
	v_mfma_f32_32x32x16_bf16 v[16:31], v[114:117], v[110:113], v[16:31]
	ds_read_b128 v[106:109], v176 offset:53248
	ds_read_b128 v[110:113], v177 offset:53248
	s_waitcnt lgkmcnt(4)
	v_mfma_f32_32x32x16_bf16 v[32:47], v[88:91], v[92:95], v[32:47]
	s_waitcnt lgkmcnt(1)
	v_mfma_f32_32x32x16_bf16 v[48:63], v[88:91], v[106:109], v[48:63]
	ds_read_b128 v[88:91], v172 offset:36864
	ds_read_b128 v[114:117], v173 offset:36864
	s_waitcnt lgkmcnt(1)
	v_mfma_f32_32x32x16_bf16 v[0:15], v[88:91], v[92:95], v[0:15]
	v_mfma_f32_32x32x16_bf16 v[16:31], v[88:91], v[106:109], v[16:31]
	v_mfma_f32_32x32x16_bf16 v[32:47], v[98:101], v[102:105], v[32:47]
	v_mfma_f32_32x32x16_bf16 v[48:63], v[98:101], v[110:113], v[48:63]
	s_waitcnt lgkmcnt(0)
	v_mfma_f32_32x32x16_bf16 v[0:15], v[114:117], v[102:105], v[0:15]
	s_waitcnt vmcnt(0)
	s_barrier
;     ...
;   bf16* As1 = As + 2 * 128 * 72;
;   bf16* Bs1 = As1 + 128 * 72;
;   G_LOAD(ra0, rb0, 0);
;   if (nk > 1) G_LOAD(ra1, rb1, 1);
;   G_STORE(ra0, rb0, As, Bs);
;   __syncthreads();
;   for (int kt = 0; kt < nk; kt += 2) {
;     if (kt + 2 < nk) G_LOAD(ra0, rb0, kt + 2);
;     if (kt + 1 < nk) G_STORE(ra1, rb1, As1, Bs1);
;     G_COMPUTE(As, Bs);
;     __syncthreads();
;     if (kt + 1 < nk) {
;       if (kt + 3 < nk) G_LOAD(ra1, rb1, kt + 3);
;       if (kt + 2 < nk) G_STORE(ra0, rb0, As, Bs);
;       G_COMPUTE(As1, Bs1);
;       __syncthreads();
;     }
;   }
	v_lshl_add_u64 v[66:67], v[66:67], 0, s[96:97]
	s_add_u32 m0, s94, 0x8000
	s_nop 1
	global_load_lds_dwordx4 v[66:67], off
	v_lshl_add_u64 v[68:69], v[68:69], 0, s[96:97]
	s_add_u32 m0, s94, 0xc000
	s_nop 1
	global_load_lds_dwordx4 v[68:69], off
	v_lshl_add_u64 v[70:71], v[70:71], 0, s[96:97]
	s_add_u32 m0, s94, 0x9000
	s_nop 1
	global_load_lds_dwordx4 v[70:71], off
	v_lshl_add_u64 v[72:73], v[72:73], 0, s[96:97]
	s_add_u32 m0, s94, 0xd000
	s_nop 1
	global_load_lds_dwordx4 v[72:73], off
	v_lshl_add_u64 v[74:75], v[74:75], 0, s[96:97]
	s_add_u32 m0, s94, 0xa000
	s_nop 1
	global_load_lds_dwordx4 v[74:75], off
	v_lshl_add_u64 v[76:77], v[76:77], 0, s[96:97]
	s_add_u32 m0, s94, 0xe000
	s_nop 1
	global_load_lds_dwordx4 v[76:77], off
	v_lshl_add_u64 v[80:81], v[80:81], 0, s[96:97]
	s_add_u32 m0, s94, 0xb000
	s_nop 1
	global_load_lds_dwordx4 v[80:81], off
	v_lshl_add_u64 v[78:79], v[78:79], 0, s[96:97]
	s_add_u32 m0, s94, 0xf000
	s_nop 1
	global_load_lds_dwordx4 v[78:79], off
	v_mfma_f32_32x32x16_bf16 v[16:31], v[114:117], v[110:113], v[16:31]
	ds_read_b128 v[88:91], v170 offset:0
	ds_read_b128 v[92:95], v174 offset:16384
	ds_read_b128 v[98:101], v171 offset:0
	ds_read_b128 v[102:105], v175 offset:16384
	ds_read_b128 v[106:109], v174 offset:20480
	ds_read_b128 v[110:113], v175 offset:20480
	s_waitcnt lgkmcnt(4)
	v_mfma_f32_32x32x16_bf16 v[32:47], v[88:91], v[92:95], v[32:47]
	s_waitcnt lgkmcnt(1)
	v_mfma_f32_32x32x16_bf16 v[48:63], v[88:91], v[106:109], v[48:63]
	ds_read_b128 v[88:91], v170 offset:4096
	ds_read_b128 v[114:117], v171 offset:4096
	s_waitcnt lgkmcnt(1)
	v_mfma_f32_32x32x16_bf16 v[0:15], v[88:91], v[92:95], v[0:15]
	v_mfma_f32_32x32x16_bf16 v[16:31], v[88:91], v[106:109], v[16:31]
	v_mfma_f32_32x32x16_bf16 v[32:47], v[98:101], v[102:105], v[32:47]
	v_mfma_f32_32x32x16_bf16 v[48:63], v[98:101], v[110:113], v[48:63]
	s_waitcnt lgkmcnt(0)
	v_mfma_f32_32x32x16_bf16 v[0:15], v[114:117], v[102:105], v[0:15]
	ds_read_b128 v[88:91], v172 offset:0
	ds_read_b128 v[92:95], v176 offset:16384
	ds_read_b128 v[98:101], v173 offset:0
	ds_read_b128 v[102:105], v177 offset:16384
	v_mfma_f32_32x32x16_bf16 v[16:31], v[114:117], v[110:113], v[16:31]
	ds_read_b128 v[106:109], v176 offset:20480
	ds_read_b128 v[110:113], v177 offset:20480
	s_waitcnt lgkmcnt(4)
	v_mfma_f32_32x32x16_bf16 v[32:47], v[88:91], v[92:95], v[32:47]
	s_waitcnt lgkmcnt(1)
	v_mfma_f32_32x32x16_bf16 v[48:63], v[88:91], v[106:109], v[48:63]
	ds_read_b128 v[88:91], v172 offset:4096
	ds_read_b128 v[114:117], v173 offset:4096
	s_waitcnt lgkmcnt(1)
	v_mfma_f32_32x32x16_bf16 v[0:15], v[88:91], v[92:95], v[0:15]
	v_mfma_f32_32x32x16_bf16 v[16:31], v[88:91], v[106:109], v[16:31]
	v_mfma_f32_32x32x16_bf16 v[32:47], v[98:101], v[102:105], v[32:47]
	v_mfma_f32_32x32x16_bf16 v[48:63], v[98:101], v[110:113], v[48:63]
	s_waitcnt lgkmcnt(0)
	v_mfma_f32_32x32x16_bf16 v[0:15], v[114:117], v[102:105], v[0:15]
	s_waitcnt vmcnt(0)
	s_barrier
	v_lshl_add_u64 v[66:67], v[66:67], 0, s[96:97]
	s_add_u32 m0, s94, 0x0
	s_nop 1
	global_load_lds_dwordx4 v[66:67], off
	v_lshl_add_u64 v[68:69], v[68:69], 0, s[96:97]
	s_add_u32 m0, s94, 0x4000
	s_nop 1
	global_load_lds_dwordx4 v[68:69], off
	v_lshl_add_u64 v[70:71], v[70:71], 0, s[96:97]
	s_add_u32 m0, s94, 0x1000
	s_nop 1
	global_load_lds_dwordx4 v[70:71], off
	v_lshl_add_u64 v[72:73], v[72:73], 0, s[96:97]
	s_add_u32 m0, s94, 0x5000
	s_nop 1
	global_load_lds_dwordx4 v[72:73], off
	v_lshl_add_u64 v[74:75], v[74:75], 0, s[96:97]
	s_add_u32 m0, s94, 0x2000
	s_nop 1
	global_load_lds_dwordx4 v[74:75], off
	v_lshl_add_u64 v[76:77], v[76:77], 0, s[96:97]
	s_add_u32 m0, s94, 0x6000
	s_nop 1
	global_load_lds_dwordx4 v[76:77], off
	v_lshl_add_u64 v[80:81], v[80:81], 0, s[96:97]
	s_add_u32 m0, s94, 0x3000
	s_nop 1
	global_load_lds_dwordx4 v[80:81], off
	v_lshl_add_u64 v[78:79], v[78:79], 0, s[96:97]
	s_add_u32 m0, s94, 0x7000
	s_nop 1
	global_load_lds_dwordx4 v[78:79], off
	v_mfma_f32_32x32x16_bf16 v[16:31], v[114:117], v[110:113], v[16:31]
	ds_read_b128 v[88:91], v170 offset:32768
	ds_read_b128 v[92:95], v174 offset:49152
	ds_read_b128 v[98:101], v171 offset:32768
	ds_read_b128 v[102:105], v175 offset:49152
	ds_read_b128 v[106:109], v174 offset:53248
	ds_read_b128 v[110:113], v175 offset:53248
	s_waitcnt lgkmcnt(4)
	v_mfma_f32_32x32x16_bf16 v[32:47], v[88:91], v[92:95], v[32:47]
	s_waitcnt lgkmcnt(1)
	v_mfma_f32_32x32x16_bf16 v[48:63], v[88:91], v[106:109], v[48:63]
	ds_read_b128 v[88:91], v170 offset:36864
	ds_read_b128 v[114:117], v171 offset:36864
	s_waitcnt lgkmcnt(1)
	v_mfma_f32_32x32x16_bf16 v[0:15], v[88:91], v[92:95], v[0:15]
	v_mfma_f32_32x32x16_bf16 v[16:31], v[88:91], v[106:109], v[16:31]
	v_mfma_f32_32x32x16_bf16 v[32:47], v[98:101], v[102:105], v[32:47]
	v_mfma_f32_32x32x16_bf16 v[48:63], v[98:101], v[110:113], v[48:63]
	s_waitcnt lgkmcnt(0)
	v_mfma_f32_32x32x16_bf16 v[0:15], v[114:117], v[102:105], v[0:15]
	ds_read_b128 v[88:91], v172 offset:32768
	ds_read_b128 v[92:95], v176 offset:49152
	ds_read_b128 v[98:101], v173 offset:32768
	ds_read_b128 v[102:105], v177 offset:49152
	v_mfma_f32_32x32x16_bf16 v[16:31], v[114:117], v[110:113], v[16:31]
	ds_read_b128 v[106:109], v176 offset:53248
	ds_read_b128 v[110:113], v177 offset:53248
	s_waitcnt lgkmcnt(4)
	v_mfma_f32_32x32x16_bf16 v[32:47], v[88:91], v[92:95], v[32:47]
	s_waitcnt lgkmcnt(1)
	v_mfma_f32_32x32x16_bf16 v[48:63], v[88:91], v[106:109], v[48:63]
	ds_read_b128 v[88:91], v172 offset:36864
	ds_read_b128 v[114:117], v173 offset:36864
	s_waitcnt lgkmcnt(1)
	v_mfma_f32_32x32x16_bf16 v[0:15], v[88:91], v[92:95], v[0:15]
	v_mfma_f32_32x32x16_bf16 v[16:31], v[88:91], v[106:109], v[16:31]
	v_mfma_f32_32x32x16_bf16 v[32:47], v[98:101], v[102:105], v[32:47]
	v_mfma_f32_32x32x16_bf16 v[48:63], v[98:101], v[110:113], v[48:63]
	s_waitcnt lgkmcnt(0)
	v_mfma_f32_32x32x16_bf16 v[0:15], v[114:117], v[102:105], v[0:15]
	s_waitcnt vmcnt(0)
	s_barrier
;     ...
;   bf16* As1 = As + 2 * 128 * 72;
;   bf16* Bs1 = As1 + 128 * 72;
;   G_LOAD(ra0, rb0, 0);
;   if (nk > 1) G_LOAD(ra1, rb1, 1);
;   G_STORE(ra0, rb0, As, Bs);
;   __syncthreads();
;   for (int kt = 0; kt < nk; kt += 2) {
;     if (kt + 2 < nk) G_LOAD(ra0, rb0, kt + 2);
;     if (kt + 1 < nk) G_STORE(ra1, rb1, As1, Bs1);
;     G_COMPUTE(As, Bs);
;     __syncthreads();
;     if (kt + 1 < nk) {
;       if (kt + 3 < nk) G_LOAD(ra1, rb1, kt + 3);
;       if (kt + 2 < nk) G_STORE(ra0, rb0, As, Bs);
;       G_COMPUTE(As1, Bs1);
;       __syncthreads();
;     }
;   }
	v_lshl_add_u64 v[66:67], v[66:67], 0, s[96:97]
	s_add_u32 m0, s94, 0x8000
	s_nop 1
	global_load_lds_dwordx4 v[66:67], off
	v_lshl_add_u64 v[68:69], v[68:69], 0, s[96:97]
	s_add_u32 m0, s94, 0xc000
	s_nop 1
	global_load_lds_dwordx4 v[68:69], off
	v_lshl_add_u64 v[70:71], v[70:71], 0, s[96:97]
	s_add_u32 m0, s94, 0x9000
	s_nop 1
	global_load_lds_dwordx4 v[70:71], off
	v_lshl_add_u64 v[72:73], v[72:73], 0, s[96:97]
	s_add_u32 m0, s94, 0xd000
	s_nop 1
	global_load_lds_dwordx4 v[72:73], off
	v_lshl_add_u64 v[74:75], v[74:75], 0, s[96:97]
	s_add_u32 m0, s94, 0xa000
	s_nop 1
	global_load_lds_dwordx4 v[74:75], off
	v_lshl_add_u64 v[76:77], v[76:77], 0, s[96:97]
	s_add_u32 m0, s94, 0xe000
	s_nop 1
	global_load_lds_dwordx4 v[76:77], off
	v_lshl_add_u64 v[80:81], v[80:81], 0, s[96:97]
	s_add_u32 m0, s94, 0xb000
	s_nop 1
	global_load_lds_dwordx4 v[80:81], off
	v_lshl_add_u64 v[78:79], v[78:79], 0, s[96:97]
	s_add_u32 m0, s94, 0xf000
	s_nop 1
	global_load_lds_dwordx4 v[78:79], off
	v_mfma_f32_32x32x16_bf16 v[16:31], v[114:117], v[110:113], v[16:31]
	ds_read_b128 v[88:91], v170 offset:0
	ds_read_b128 v[92:95], v174 offset:16384
	ds_read_b128 v[98:101], v171 offset:0
	ds_read_b128 v[102:105], v175 offset:16384
	ds_read_b128 v[106:109], v174 offset:20480
	ds_read_b128 v[110:113], v175 offset:20480
	s_waitcnt lgkmcnt(4)
	v_mfma_f32_32x32x16_bf16 v[32:47], v[88:91], v[92:95], v[32:47]
	s_waitcnt lgkmcnt(1)
	v_mfma_f32_32x32x16_bf16 v[48:63], v[88:91], v[106:109], v[48:63]
	ds_read_b128 v[88:91], v170 offset:4096
	ds_read_b128 v[114:117], v171 offset:4096
	s_waitcnt lgkmcnt(1)
	v_mfma_f32_32x32x16_bf16 v[0:15], v[88:91], v[92:95], v[0:15]
	v_mfma_f32_32x32x16_bf16 v[16:31], v[88:91], v[106:109], v[16:31]
	v_mfma_f32_32x32x16_bf16 v[32:47], v[98:101], v[102:105], v[32:47]
	v_mfma_f32_32x32x16_bf16 v[48:63], v[98:101], v[110:113], v[48:63]
	s_waitcnt lgkmcnt(0)
	v_mfma_f32_32x32x16_bf16 v[0:15], v[114:117], v[102:105], v[0:15]
	ds_read_b128 v[88:91], v172 offset:0
	ds_read_b128 v[92:95], v176 offset:16384
	ds_read_b128 v[98:101], v173 offset:0
	ds_read_b128 v[102:105], v177 offset:16384
	v_mfma_f32_32x32x16_bf16 v[16:31], v[114:117], v[110:113], v[16:31]
	ds_read_b128 v[106:109], v176 offset:20480
	ds_read_b128 v[110:113], v177 offset:20480
	s_waitcnt lgkmcnt(4)
	v_mfma_f32_32x32x16_bf16 v[32:47], v[88:91], v[92:95], v[32:47]
	s_waitcnt lgkmcnt(1)
	v_mfma_f32_32x32x16_bf16 v[48:63], v[88:91], v[106:109], v[48:63]
	ds_read_b128 v[88:91], v172 offset:4096
	ds_read_b128 v[114:117], v173 offset:4096
	s_waitcnt lgkmcnt(1)
	v_mfma_f32_32x32x16_bf16 v[0:15], v[88:91], v[92:95], v[0:15]
	v_mfma_f32_32x32x16_bf16 v[16:31], v[88:91], v[106:109], v[16:31]
	v_mfma_f32_32x32x16_bf16 v[32:47], v[98:101], v[102:105], v[32:47]
	v_mfma_f32_32x32x16_bf16 v[48:63], v[98:101], v[110:113], v[48:63]
	s_waitcnt lgkmcnt(0)
	v_mfma_f32_32x32x16_bf16 v[0:15], v[114:117], v[102:105], v[0:15]
	s_waitcnt vmcnt(0)
	s_barrier
	v_lshl_add_u64 v[66:67], v[66:67], 0, s[96:97]
	s_add_u32 m0, s94, 0x0
	s_nop 1
	global_load_lds_dwordx4 v[66:67], off
	v_lshl_add_u64 v[68:69], v[68:69], 0, s[96:97]
	s_add_u32 m0, s94, 0x4000
	s_nop 1
	global_load_lds_dwordx4 v[68:69], off
	v_lshl_add_u64 v[70:71], v[70:71], 0, s[96:97]
	s_add_u32 m0, s94, 0x1000
	s_nop 1
	global_load_lds_dwordx4 v[70:71], off
	v_lshl_add_u64 v[72:73], v[72:73], 0, s[96:97]
	s_add_u32 m0, s94, 0x5000
	s_nop 1
	global_load_lds_dwordx4 v[72:73], off
	v_lshl_add_u64 v[74:75], v[74:75], 0, s[96:97]
	s_add_u32 m0, s94, 0x2000
	s_nop 1
	global_load_lds_dwordx4 v[74:75], off
	v_lshl_add_u64 v[76:77], v[76:77], 0, s[96:97]
	s_add_u32 m0, s94, 0x6000
	s_nop 1
	global_load_lds_dwordx4 v[76:77], off
	v_lshl_add_u64 v[80:81], v[80:81], 0, s[96:97]
	s_add_u32 m0, s94, 0x3000
	s_nop 1
	global_load_lds_dwordx4 v[80:81], off
	v_lshl_add_u64 v[78:79], v[78:79], 0, s[96:97]
	s_add_u32 m0, s94, 0x7000
	s_nop 1
	global_load_lds_dwordx4 v[78:79], off
	v_mfma_f32_32x32x16_bf16 v[16:31], v[114:117], v[110:113], v[16:31]
	ds_read_b128 v[88:91], v170 offset:32768
	ds_read_b128 v[92:95], v174 offset:49152
	ds_read_b128 v[98:101], v171 offset:32768
	ds_read_b128 v[102:105], v175 offset:49152
	ds_read_b128 v[106:109], v174 offset:53248
	ds_read_b128 v[110:113], v175 offset:53248
	s_waitcnt lgkmcnt(4)
	v_mfma_f32_32x32x16_bf16 v[32:47], v[88:91], v[92:95], v[32:47]
	s_waitcnt lgkmcnt(1)
	v_mfma_f32_32x32x16_bf16 v[48:63], v[88:91], v[106:109], v[48:63]
	ds_read_b128 v[88:91], v170 offset:36864
	ds_read_b128 v[114:117], v171 offset:36864
	s_waitcnt lgkmcnt(1)
	v_mfma_f32_32x32x16_bf16 v[0:15], v[88:91], v[92:95], v[0:15]
	v_mfma_f32_32x32x16_bf16 v[16:31], v[88:91], v[106:109], v[16:31]
	v_mfma_f32_32x32x16_bf16 v[32:47], v[98:101], v[102:105], v[32:47]
	v_mfma_f32_32x32x16_bf16 v[48:63], v[98:101], v[110:113], v[48:63]
	s_waitcnt lgkmcnt(0)
	v_mfma_f32_32x32x16_bf16 v[0:15], v[114:117], v[102:105], v[0:15]
	ds_read_b128 v[88:91], v172 offset:32768
	ds_read_b128 v[92:95], v176 offset:49152
	ds_read_b128 v[98:101], v173 offset:32768
	ds_read_b128 v[102:105], v177 offset:49152
	v_mfma_f32_32x32x16_bf16 v[16:31], v[114:117], v[110:113], v[16:31]
	ds_read_b128 v[106:109], v176 offset:53248
	ds_read_b128 v[110:113], v177 offset:53248
	s_waitcnt lgkmcnt(4)
	v_mfma_f32_32x32x16_bf16 v[32:47], v[88:91], v[92:95], v[32:47]
	s_waitcnt lgkmcnt(1)
	v_mfma_f32_32x32x16_bf16 v[48:63], v[88:91], v[106:109], v[48:63]
	ds_read_b128 v[88:91], v172 offset:36864
	ds_read_b128 v[114:117], v173 offset:36864
	s_waitcnt lgkmcnt(1)
	v_mfma_f32_32x32x16_bf16 v[0:15], v[88:91], v[92:95], v[0:15]
	v_mfma_f32_32x32x16_bf16 v[16:31], v[88:91], v[106:109], v[16:31]
	v_mfma_f32_32x32x16_bf16 v[32:47], v[98:101], v[102:105], v[32:47]
	v_mfma_f32_32x32x16_bf16 v[48:63], v[98:101], v[110:113], v[48:63]
	s_waitcnt lgkmcnt(0)
	v_mfma_f32_32x32x16_bf16 v[0:15], v[114:117], v[102:105], v[0:15]
	s_waitcnt vmcnt(0)
	s_barrier
;     ...
;   bf16* As1 = As + 2 * 128 * 72;
;   bf16* Bs1 = As1 + 128 * 72;
;   G_LOAD(ra0, rb0, 0);
;   if (nk > 1) G_LOAD(ra1, rb1, 1);
;   G_STORE(ra0, rb0, As, Bs);
;   __syncthreads();
;   for (int kt = 0; kt < nk; kt += 2) {
;     if (kt + 2 < nk) G_LOAD(ra0, rb0, kt + 2);
;     if (kt + 1 < nk) G_STORE(ra1, rb1, As1, Bs1);
;     G_COMPUTE(As, Bs);
;     __syncthreads();
;     if (kt + 1 < nk) {
;       if (kt + 3 < nk) G_LOAD(ra1, rb1, kt + 3);
;       if (kt + 2 < nk) G_STORE(ra0, rb0, As, Bs);
;       G_COMPUTE(As1, Bs1);
;       __syncthreads();
;     }
;   }
	v_lshl_add_u64 v[66:67], v[66:67], 0, s[96:97]
	s_add_u32 m0, s94, 0x8000
	s_nop 1
	global_load_lds_dwordx4 v[66:67], off
	v_lshl_add_u64 v[68:69], v[68:69], 0, s[96:97]
	s_add_u32 m0, s94, 0xc000
	s_nop 1
	global_load_lds_dwordx4 v[68:69], off
	v_lshl_add_u64 v[70:71], v[70:71], 0, s[96:97]
	s_add_u32 m0, s94, 0x9000
	s_nop 1
	global_load_lds_dwordx4 v[70:71], off
	v_lshl_add_u64 v[72:73], v[72:73], 0, s[96:97]
	s_add_u32 m0, s94, 0xd000
	s_nop 1
	global_load_lds_dwordx4 v[72:73], off
	v_lshl_add_u64 v[74:75], v[74:75], 0, s[96:97]
	s_add_u32 m0, s94, 0xa000
	s_nop 1
	global_load_lds_dwordx4 v[74:75], off
	v_lshl_add_u64 v[76:77], v[76:77], 0, s[96:97]
	s_add_u32 m0, s94, 0xe000
	s_nop 1
	global_load_lds_dwordx4 v[76:77], off
	v_lshl_add_u64 v[80:81], v[80:81], 0, s[96:97]
	s_add_u32 m0, s94, 0xb000
	s_nop 1
	global_load_lds_dwordx4 v[80:81], off
	v_lshl_add_u64 v[78:79], v[78:79], 0, s[96:97]
	s_add_u32 m0, s94, 0xf000
	s_nop 1
	global_load_lds_dwordx4 v[78:79], off
	v_mfma_f32_32x32x16_bf16 v[16:31], v[114:117], v[110:113], v[16:31]
	ds_read_b128 v[88:91], v170 offset:0
	ds_read_b128 v[92:95], v174 offset:16384
	ds_read_b128 v[98:101], v171 offset:0
	ds_read_b128 v[102:105], v175 offset:16384
	ds_read_b128 v[106:109], v174 offset:20480
	ds_read_b128 v[110:113], v175 offset:20480
	s_waitcnt lgkmcnt(4)
	v_mfma_f32_32x32x16_bf16 v[32:47], v[88:91], v[92:95], v[32:47]
	s_waitcnt lgkmcnt(1)
	v_mfma_f32_32x32x16_bf16 v[48:63], v[88:91], v[106:109], v[48:63]
	ds_read_b128 v[88:91], v170 offset:4096
	ds_read_b128 v[114:117], v171 offset:4096
	s_waitcnt lgkmcnt(1)
	v_mfma_f32_32x32x16_bf16 v[0:15], v[88:91], v[92:95], v[0:15]
	v_mfma_f32_32x32x16_bf16 v[16:31], v[88:91], v[106:109], v[16:31]
	v_mfma_f32_32x32x16_bf16 v[32:47], v[98:101], v[102:105], v[32:47]
	v_mfma_f32_32x32x16_bf16 v[48:63], v[98:101], v[110:113], v[48:63]
	s_waitcnt lgkmcnt(0)
	v_mfma_f32_32x32x16_bf16 v[0:15], v[114:117], v[102:105], v[0:15]
	ds_read_b128 v[88:91], v172 offset:0
	ds_read_b128 v[92:95], v176 offset:16384
	ds_read_b128 v[98:101], v173 offset:0
	ds_read_b128 v[102:105], v177 offset:16384
	v_mfma_f32_32x32x16_bf16 v[16:31], v[114:117], v[110:113], v[16:31]
	ds_read_b128 v[106:109], v176 offset:20480
	ds_read_b128 v[110:113], v177 offset:20480
	s_waitcnt lgkmcnt(4)
	v_mfma_f32_32x32x16_bf16 v[32:47], v[88:91], v[92:95], v[32:47]
	s_waitcnt lgkmcnt(1)
	v_mfma_f32_32x32x16_bf16 v[48:63], v[88:91], v[106:109], v[48:63]
	ds_read_b128 v[88:91], v172 offset:4096
	ds_read_b128 v[114:117], v173 offset:4096
	s_waitcnt lgkmcnt(1)
	v_mfma_f32_32x32x16_bf16 v[0:15], v[88:91], v[92:95], v[0:15]
	v_mfma_f32_32x32x16_bf16 v[16:31], v[88:91], v[106:109], v[16:31]
	v_mfma_f32_32x32x16_bf16 v[32:47], v[98:101], v[102:105], v[32:47]
	v_mfma_f32_32x32x16_bf16 v[48:63], v[98:101], v[110:113], v[48:63]
	s_waitcnt lgkmcnt(0)
	v_mfma_f32_32x32x16_bf16 v[0:15], v[114:117], v[102:105], v[0:15]
	s_waitcnt vmcnt(0)
	s_barrier
	v_lshl_add_u64 v[66:67], v[66:67], 0, s[96:97]
	s_add_u32 m0, s94, 0x0
	s_nop 1
	global_load_lds_dwordx4 v[66:67], off
	v_lshl_add_u64 v[68:69], v[68:69], 0, s[96:97]
	s_add_u32 m0, s94, 0x4000
	s_nop 1
	global_load_lds_dwordx4 v[68:69], off
	v_lshl_add_u64 v[70:71], v[70:71], 0, s[96:97]
	s_add_u32 m0, s94, 0x1000
	s_nop 1
	global_load_lds_dwordx4 v[70:71], off
	v_lshl_add_u64 v[72:73], v[72:73], 0, s[96:97]
	s_add_u32 m0, s94, 0x5000
	s_nop 1
	global_load_lds_dwordx4 v[72:73], off
	v_lshl_add_u64 v[74:75], v[74:75], 0, s[96:97]
	s_add_u32 m0, s94, 0x2000
	s_nop 1
	global_load_lds_dwordx4 v[74:75], off
	v_lshl_add_u64 v[76:77], v[76:77], 0, s[96:97]
	s_add_u32 m0, s94, 0x6000
	s_nop 1
	global_load_lds_dwordx4 v[76:77], off
	v_lshl_add_u64 v[80:81], v[80:81], 0, s[96:97]
	s_add_u32 m0, s94, 0x3000
	s_nop 1
	global_load_lds_dwordx4 v[80:81], off
	v_lshl_add_u64 v[78:79], v[78:79], 0, s[96:97]
	s_add_u32 m0, s94, 0x7000
	s_nop 1
	global_load_lds_dwordx4 v[78:79], off
	v_mfma_f32_32x32x16_bf16 v[16:31], v[114:117], v[110:113], v[16:31]
	ds_read_b128 v[88:91], v170 offset:32768
	ds_read_b128 v[92:95], v174 offset:49152
	ds_read_b128 v[98:101], v171 offset:32768
	ds_read_b128 v[102:105], v175 offset:49152
	ds_read_b128 v[106:109], v174 offset:53248
	ds_read_b128 v[110:113], v175 offset:53248
	s_waitcnt lgkmcnt(4)
	v_mfma_f32_32x32x16_bf16 v[32:47], v[88:91], v[92:95], v[32:47]
	s_waitcnt lgkmcnt(1)
	v_mfma_f32_32x32x16_bf16 v[48:63], v[88:91], v[106:109], v[48:63]
	ds_read_b128 v[88:91], v170 offset:36864
	ds_read_b128 v[114:117], v171 offset:36864
	s_waitcnt lgkmcnt(1)
	v_mfma_f32_32x32x16_bf16 v[0:15], v[88:91], v[92:95], v[0:15]
	v_mfma_f32_32x32x16_bf16 v[16:31], v[88:91], v[106:109], v[16:31]
	v_mfma_f32_32x32x16_bf16 v[32:47], v[98:101], v[102:105], v[32:47]
	v_mfma_f32_32x32x16_bf16 v[48:63], v[98:101], v[110:113], v[48:63]
	s_waitcnt lgkmcnt(0)
	v_mfma_f32_32x32x16_bf16 v[0:15], v[114:117], v[102:105], v[0:15]
	ds_read_b128 v[88:91], v172 offset:32768
	ds_read_b128 v[92:95], v176 offset:49152
	ds_read_b128 v[98:101], v173 offset:32768
	ds_read_b128 v[102:105], v177 offset:49152
	v_mfma_f32_32x32x16_bf16 v[16:31], v[114:117], v[110:113], v[16:31]
	ds_read_b128 v[106:109], v176 offset:53248
	ds_read_b128 v[110:113], v177 offset:53248
	s_waitcnt lgkmcnt(4)
	v_mfma_f32_32x32x16_bf16 v[32:47], v[88:91], v[92:95], v[32:47]
	s_waitcnt lgkmcnt(1)
	v_mfma_f32_32x32x16_bf16 v[48:63], v[88:91], v[106:109], v[48:63]
	ds_read_b128 v[88:91], v172 offset:36864
	ds_read_b128 v[114:117], v173 offset:36864
	s_waitcnt lgkmcnt(1)
	v_mfma_f32_32x32x16_bf16 v[0:15], v[88:91], v[92:95], v[0:15]
	v_mfma_f32_32x32x16_bf16 v[16:31], v[88:91], v[106:109], v[16:31]
	v_mfma_f32_32x32x16_bf16 v[32:47], v[98:101], v[102:105], v[32:47]
	v_mfma_f32_32x32x16_bf16 v[48:63], v[98:101], v[110:113], v[48:63]
	s_waitcnt lgkmcnt(0)
	v_mfma_f32_32x32x16_bf16 v[0:15], v[114:117], v[102:105], v[0:15]
	s_waitcnt vmcnt(0)
	s_barrier
;     ...
;   bf16* As1 = As + 2 * 128 * 72;
;   bf16* Bs1 = As1 + 128 * 72;
;   G_LOAD(ra0, rb0, 0);
;   if (nk > 1) G_LOAD(ra1, rb1, 1);
;   G_STORE(ra0, rb0, As, Bs);
;   __syncthreads();
;   for (int kt = 0; kt < nk; kt += 2) {
;     if (kt + 2 < nk) G_LOAD(ra0, rb0, kt + 2);
;     if (kt + 1 < nk) G_STORE(ra1, rb1, As1, Bs1);
;     G_COMPUTE(As, Bs);
;     __syncthreads();
;     if (kt + 1 < nk) {
;       if (kt + 3 < nk) G_LOAD(ra1, rb1, kt + 3);
;       if (kt + 2 < nk) G_STORE(ra0, rb0, As, Bs);
;       G_COMPUTE(As1, Bs1);
;       __syncthreads();
;     }
;   }
	v_lshl_add_u64 v[66:67], v[66:67], 0, s[96:97]
	s_add_u32 m0, s94, 0x8000
	s_nop 1
	global_load_lds_dwordx4 v[66:67], off
	v_lshl_add_u64 v[68:69], v[68:69], 0, s[96:97]
	s_add_u32 m0, s94, 0xc000
	s_nop 1
	global_load_lds_dwordx4 v[68:69], off
	v_lshl_add_u64 v[70:71], v[70:71], 0, s[96:97]
	s_add_u32 m0, s94, 0x9000
	s_nop 1
	global_load_lds_dwordx4 v[70:71], off
	v_lshl_add_u64 v[72:73], v[72:73], 0, s[96:97]
	s_add_u32 m0, s94, 0xd000
	s_nop 1
	global_load_lds_dwordx4 v[72:73], off
	v_lshl_add_u64 v[74:75], v[74:75], 0, s[96:97]
	s_add_u32 m0, s94, 0xa000
	s_nop 1
	global_load_lds_dwordx4 v[74:75], off
	v_lshl_add_u64 v[76:77], v[76:77], 0, s[96:97]
	s_add_u32 m0, s94, 0xe000
	s_nop 1
	global_load_lds_dwordx4 v[76:77], off
	v_lshl_add_u64 v[80:81], v[80:81], 0, s[96:97]
	s_add_u32 m0, s94, 0xb000
	s_nop 1
	global_load_lds_dwordx4 v[80:81], off
	v_lshl_add_u64 v[78:79], v[78:79], 0, s[96:97]
	s_add_u32 m0, s94, 0xf000
	s_nop 1
	global_load_lds_dwordx4 v[78:79], off
	v_mfma_f32_32x32x16_bf16 v[16:31], v[114:117], v[110:113], v[16:31]
	ds_read_b128 v[88:91], v170 offset:0
	ds_read_b128 v[92:95], v174 offset:16384
	ds_read_b128 v[98:101], v171 offset:0
	ds_read_b128 v[102:105], v175 offset:16384
	ds_read_b128 v[106:109], v174 offset:20480
	ds_read_b128 v[110:113], v175 offset:20480
	s_waitcnt lgkmcnt(4)
	v_mfma_f32_32x32x16_bf16 v[32:47], v[88:91], v[92:95], v[32:47]
	s_waitcnt lgkmcnt(1)
	v_mfma_f32_32x32x16_bf16 v[48:63], v[88:91], v[106:109], v[48:63]
	ds_read_b128 v[88:91], v170 offset:4096
	ds_read_b128 v[114:117], v171 offset:4096
	s_waitcnt lgkmcnt(1)
	v_mfma_f32_32x32x16_bf16 v[0:15], v[88:91], v[92:95], v[0:15]
	v_mfma_f32_32x32x16_bf16 v[16:31], v[88:91], v[106:109], v[16:31]
	v_mfma_f32_32x32x16_bf16 v[32:47], v[98:101], v[102:105], v[32:47]
	v_mfma_f32_32x32x16_bf16 v[48:63], v[98:101], v[110:113], v[48:63]
	s_waitcnt lgkmcnt(0)
	v_mfma_f32_32x32x16_bf16 v[0:15], v[114:117], v[102:105], v[0:15]
	ds_read_b128 v[88:91], v172 offset:0
	ds_read_b128 v[92:95], v176 offset:16384
	ds_read_b128 v[98:101], v173 offset:0
	ds_read_b128 v[102:105], v177 offset:16384
	v_mfma_f32_32x32x16_bf16 v[16:31], v[114:117], v[110:113], v[16:31]
	ds_read_b128 v[106:109], v176 offset:20480
	ds_read_b128 v[110:113], v177 offset:20480
	s_waitcnt lgkmcnt(4)
	v_mfma_f32_32x32x16_bf16 v[32:47], v[88:91], v[92:95], v[32:47]
	s_waitcnt lgkmcnt(1)
	v_mfma_f32_32x32x16_bf16 v[48:63], v[88:91], v[106:109], v[48:63]
	ds_read_b128 v[88:91], v172 offset:4096
	ds_read_b128 v[114:117], v173 offset:4096
	s_waitcnt lgkmcnt(1)
	v_mfma_f32_32x32x16_bf16 v[0:15], v[88:91], v[92:95], v[0:15]
	v_mfma_f32_32x32x16_bf16 v[16:31], v[88:91], v[106:109], v[16:31]
	v_mfma_f32_32x32x16_bf16 v[32:47], v[98:101], v[102:105], v[32:47]
	v_mfma_f32_32x32x16_bf16 v[48:63], v[98:101], v[110:113], v[48:63]
	s_waitcnt lgkmcnt(0)
	v_mfma_f32_32x32x16_bf16 v[0:15], v[114:117], v[102:105], v[0:15]
	s_waitcnt vmcnt(0)
	s_barrier
	v_lshl_add_u64 v[66:67], v[66:67], 0, s[96:97]
	s_add_u32 m0, s94, 0x0
	s_nop 1
	global_load_lds_dwordx4 v[66:67], off
	v_lshl_add_u64 v[68:69], v[68:69], 0, s[96:97]
	s_add_u32 m0, s94, 0x4000
	s_nop 1
	global_load_lds_dwordx4 v[68:69], off
	v_lshl_add_u64 v[70:71], v[70:71], 0, s[96:97]
	s_add_u32 m0, s94, 0x1000
	s_nop 1
	global_load_lds_dwordx4 v[70:71], off
	v_lshl_add_u64 v[72:73], v[72:73], 0, s[96:97]
	s_add_u32 m0, s94, 0x5000
	s_nop 1
	global_load_lds_dwordx4 v[72:73], off
	v_lshl_add_u64 v[74:75], v[74:75], 0, s[96:97]
	s_add_u32 m0, s94, 0x2000
	s_nop 1
	global_load_lds_dwordx4 v[74:75], off
	v_lshl_add_u64 v[76:77], v[76:77], 0, s[96:97]
	s_add_u32 m0, s94, 0x6000
	s_nop 1
	global_load_lds_dwordx4 v[76:77], off
	v_lshl_add_u64 v[80:81], v[80:81], 0, s[96:97]
	s_add_u32 m0, s94, 0x3000
	s_nop 1
	global_load_lds_dwordx4 v[80:81], off
	v_lshl_add_u64 v[78:79], v[78:79], 0, s[96:97]
	s_add_u32 m0, s94, 0x7000
	s_nop 1
	global_load_lds_dwordx4 v[78:79], off
	v_mfma_f32_32x32x16_bf16 v[16:31], v[114:117], v[110:113], v[16:31]
	ds_read_b128 v[88:91], v170 offset:32768
	ds_read_b128 v[92:95], v174 offset:49152
	ds_read_b128 v[98:101], v171 offset:32768
	ds_read_b128 v[102:105], v175 offset:49152
	ds_read_b128 v[106:109], v174 offset:53248
	ds_read_b128 v[110:113], v175 offset:53248
	s_waitcnt lgkmcnt(4)
	v_mfma_f32_32x32x16_bf16 v[32:47], v[88:91], v[92:95], v[32:47]
	s_waitcnt lgkmcnt(1)
	v_mfma_f32_32x32x16_bf16 v[48:63], v[88:91], v[106:109], v[48:63]
	ds_read_b128 v[88:91], v170 offset:36864
	ds_read_b128 v[114:117], v171 offset:36864
	s_waitcnt lgkmcnt(1)
	v_mfma_f32_32x32x16_bf16 v[0:15], v[88:91], v[92:95], v[0:15]
	v_mfma_f32_32x32x16_bf16 v[16:31], v[88:91], v[106:109], v[16:31]
	v_mfma_f32_32x32x16_bf16 v[32:47], v[98:101], v[102:105], v[32:47]
	v_mfma_f32_32x32x16_bf16 v[48:63], v[98:101], v[110:113], v[48:63]
	s_waitcnt lgkmcnt(0)
	v_mfma_f32_32x32x16_bf16 v[0:15], v[114:117], v[102:105], v[0:15]
	ds_read_b128 v[88:91], v172 offset:32768
	ds_read_b128 v[92:95], v176 offset:49152
	ds_read_b128 v[98:101], v173 offset:32768
	ds_read_b128 v[102:105], v177 offset:49152
	v_mfma_f32_32x32x16_bf16 v[16:31], v[114:117], v[110:113], v[16:31]
	ds_read_b128 v[106:109], v176 offset:53248
	ds_read_b128 v[110:113], v177 offset:53248
	s_waitcnt lgkmcnt(4)
	v_mfma_f32_32x32x16_bf16 v[32:47], v[88:91], v[92:95], v[32:47]
	s_waitcnt lgkmcnt(1)
	v_mfma_f32_32x32x16_bf16 v[48:63], v[88:91], v[106:109], v[48:63]
	ds_read_b128 v[88:91], v172 offset:36864
	ds_read_b128 v[114:117], v173 offset:36864
	s_waitcnt lgkmcnt(1)
	v_mfma_f32_32x32x16_bf16 v[0:15], v[88:91], v[92:95], v[0:15]
	v_mfma_f32_32x32x16_bf16 v[16:31], v[88:91], v[106:109], v[16:31]
	v_mfma_f32_32x32x16_bf16 v[32:47], v[98:101], v[102:105], v[32:47]
	v_mfma_f32_32x32x16_bf16 v[48:63], v[98:101], v[110:113], v[48:63]
	s_nop 0
	s_nop 0
	s_nop 0
	s_nop 0
	s_nop 0
	s_nop 0
	s_nop 0
	s_waitcnt lgkmcnt(0)
	s_waitcnt vmcnt(0)
	s_barrier
; #define PW(T, off) ((T*)(lndp(p.ws) + (off)))
; DEVI void gemm_epi_qkv(const Params& p, f32x16 (&acc)[2][2], int rbase, int cbase, int lane) {
;   char* ar = PW(char, W_arena);
;   const int which = cbase >> 10, cc = cbase & 1023, d = lane & 31, hl = lane >> 5;
; #pragma unroll
;   for (int i = 0; i < 2; ++i) {
; #pragma unroll
;     for (int rq = 0; rq < 4; ++rq) {
;       const int row0 = rbase + i * 32 + 8 * rq + 4 * hl;
;       if (row0 >= M) continue;
;       const bool pr = row0 < TP;
;       const int b = pr ? 0 : (row0 - TP) >> 4, t0 = pr ? row0 : (row0 - TP) & 15;
;     ...
;   for (int kt = 0; kt < nk; kt += 2) {
;     if (kt + 2 < nk) G_LOAD(ra0, rb0, kt + 2);
;     if (kt + 1 < nk) G_STORE(ra1, rb1, As1, Bs1);
;     G_COMPUTE(As, Bs);
;     __syncthreads();
;     if (kt + 1 < nk) {
;       if (kt + 3 < nk) G_LOAD(ra1, rb1, kt + 3);
;       if (kt + 2 < nk) G_STORE(ra0, rb0, As, Bs);
;       G_COMPUTE(As1, Bs1);
;       __syncthreads();
;     }
;   }
	v_lshl_add_u64 v[66:67], v[66:67], 0, s[96:97]
	s_add_u32 m0, s94, 0x8000
	s_nop 1
	global_load_lds_dwordx4 v[66:67], off
	v_lshl_add_u64 v[68:69], v[68:69], 0, s[96:97]
	s_add_u32 m0, s94, 0xc000
	s_nop 1
	global_load_lds_dwordx4 v[68:69], off
	v_lshl_add_u64 v[70:71], v[70:71], 0, s[96:97]
	s_add_u32 m0, s94, 0x9000
	s_nop 1
	global_load_lds_dwordx4 v[70:71], off
	v_lshl_add_u64 v[72:73], v[72:73], 0, s[96:97]
	s_add_u32 m0, s94, 0xd000
	s_nop 1
	global_load_lds_dwordx4 v[72:73], off
	v_lshl_add_u64 v[74:75], v[74:75], 0, s[96:97]
	s_add_u32 m0, s94, 0xa000
	s_nop 1
	global_load_lds_dwordx4 v[74:75], off
	v_lshl_add_u64 v[76:77], v[76:77], 0, s[96:97]
	s_add_u32 m0, s94, 0xe000
	s_nop 1
	global_load_lds_dwordx4 v[76:77], off
	v_lshl_add_u64 v[80:81], v[80:81], 0, s[96:97]
	s_add_u32 m0, s94, 0xb000
	s_nop 1
	global_load_lds_dwordx4 v[80:81], off
	v_lshl_add_u64 v[78:79], v[78:79], 0, s[96:97]
	s_add_u32 m0, s94, 0xf000
	s_nop 1
	global_load_lds_dwordx4 v[78:79], off
	v_mfma_f32_32x32x16_bf16 v[0:15], v[114:117], v[102:105], v[0:15]
	ds_read_b128 v[66:69], v170 offset:0
	ds_read_b128 v[70:73], v174 offset:16384
	ds_read_b128 v[74:77], v171 offset:0
	ds_read_b128 v[78:81], v175 offset:16384
	ds_read_b128 v[88:91], v174 offset:20480
	ds_read_b128 v[92:95], v175 offset:20480
	v_mfma_f32_32x32x16_bf16 v[16:31], v[114:117], v[110:113], v[16:31]
	s_waitcnt lgkmcnt(4)
	v_mfma_f32_32x32x16_bf16 v[32:47], v[66:69], v[70:73], v[32:47]
	s_waitcnt lgkmcnt(1)
	v_mfma_f32_32x32x16_bf16 v[48:63], v[66:69], v[88:91], v[48:63]
	ds_read_b128 v[66:69], v170 offset:4096
	ds_read_b128 v[98:101], v171 offset:4096
	s_waitcnt lgkmcnt(1)
	v_mfma_f32_32x32x16_bf16 v[0:15], v[66:69], v[70:73], v[0:15]
	v_mfma_f32_32x32x16_bf16 v[16:31], v[66:69], v[88:91], v[16:31]
	v_mfma_f32_32x32x16_bf16 v[32:47], v[74:77], v[78:81], v[32:47]
	v_mfma_f32_32x32x16_bf16 v[48:63], v[74:77], v[92:95], v[48:63]
	s_waitcnt lgkmcnt(0)
	v_mfma_f32_32x32x16_bf16 v[0:15], v[98:101], v[78:81], v[0:15]
	ds_read_b128 v[66:69], v172 offset:0
	ds_read_b128 v[70:73], v176 offset:16384
	ds_read_b128 v[74:77], v173 offset:0
	ds_read_b128 v[78:81], v177 offset:16384
	v_mfma_f32_32x32x16_bf16 v[16:31], v[98:101], v[92:95], v[16:31]
	ds_read_b128 v[88:91], v176 offset:20480
	ds_read_b128 v[92:95], v177 offset:20480
	s_waitcnt lgkmcnt(4)
	v_mfma_f32_32x32x16_bf16 v[32:47], v[66:69], v[70:73], v[32:47]
	s_waitcnt lgkmcnt(1)
	v_mfma_f32_32x32x16_bf16 v[48:63], v[66:69], v[88:91], v[48:63]
	ds_read_b128 v[66:69], v172 offset:4096
	ds_read_b128 v[98:101], v173 offset:4096
	s_waitcnt lgkmcnt(0)
	s_waitcnt vmcnt(0)
	s_barrier
	v_mfma_f32_32x32x16_bf16 v[0:15], v[66:69], v[70:73], v[0:15]
	v_mfma_f32_32x32x16_bf16 v[32:47], v[74:77], v[78:81], v[32:47]
	v_mfma_f32_32x32x16_bf16 v[48:63], v[74:77], v[92:95], v[48:63]
	v_mfma_f32_32x32x16_bf16 v[16:31], v[66:69], v[88:91], v[16:31]
	v_mfma_f32_32x32x16_bf16 v[0:15], v[98:101], v[78:81], v[0:15]
	ds_read_b128 v[66:69], v170 offset:32768
	ds_read_b128 v[70:73], v174 offset:49152
	ds_read_b128 v[74:77], v175 offset:49152
	ds_read_b128 v[78:81], v171 offset:32768
	ds_read_b128 v[88:91], v174 offset:53248
	s_waitcnt lgkmcnt(3)
	v_mfma_f32_32x32x16_bf16 v[32:47], v[66:69], v[70:73], v[32:47]
	s_waitcnt lgkmcnt(0)
	v_mfma_f32_32x32x16_bf16 v[48:63], v[66:69], v[88:91], v[48:63]
	ds_read_b128 v[66:69], v170 offset:36864
	v_mfma_f32_32x32x16_bf16 v[16:31], v[98:101], v[92:95], v[16:31]
	s_waitcnt lgkmcnt(0)
	v_mfma_f32_32x32x16_bf16 v[0:15], v[66:69], v[70:73], v[0:15]
	ds_read_b128 v[70:73], v171 offset:36864
	v_mfma_f32_32x32x16_bf16 v[16:31], v[66:69], v[88:91], v[16:31]
	ds_read_b128 v[66:69], v175 offset:53248
	v_mfma_f32_32x32x16_bf16 v[32:47], v[78:81], v[74:77], v[32:47]
	s_waitcnt lgkmcnt(0)
	v_mfma_f32_32x32x16_bf16 v[48:63], v[78:81], v[66:69], v[48:63]
	v_and_or_b32 v80, v85, 64, s2
	v_or_b32_e32 v81, v80, v84
	v_mfma_f32_32x32x16_bf16 v[0:15], v[70:73], v[74:77], v[0:15]
	v_mfma_f32_32x32x16_bf16 v[16:31], v[70:73], v[66:69], v[16:31]
	ds_read_b128 v[66:69], v172 offset:32768
	ds_read_b128 v[70:73], v176 offset:49152
	ds_read_b128 v[74:77], v176 offset:53248
	s_waitcnt lgkmcnt(1)
	v_mfma_f32_32x32x16_bf16 v[32:47], v[66:69], v[70:73], v[32:47]
	s_waitcnt lgkmcnt(0)
	v_mfma_f32_32x32x16_bf16 v[48:63], v[66:69], v[74:77], v[48:63]
	ds_read_b128 v[66:69], v172 offset:36864
	s_waitcnt lgkmcnt(0)
	v_mfma_f32_32x32x16_bf16 v[0:15], v[66:69], v[70:73], v[0:15]
	ds_read_b128 v[88:91], v177 offset:53248
	ds_read_b128 v[92:95], v177 offset:49152
	ds_read_b128 v[70:73], v173 offset:32768
	v_lshrrev_b32_e32 v65, 3, v85
	v_and_b32_e32 v82, 4, v65
	v_mfma_f32_32x32x16_bf16 v[16:31], v[66:69], v[74:77], v[16:31]
	ds_read_b128 v[74:77], v173 offset:36864
	v_add_u32_e32 v64, s3, v86
	v_or_b32_e32 v68, v64, v82
	v_mul_u32_u24_e32 v64, 0x4040, v81
	v_lshlrev_b32_e32 v96, 1, v64
	s_waitcnt lgkmcnt(0)
	s_barrier
	v_mfma_f32_32x32x16_bf16 v[32:47], v[70:73], v[92:95], v[32:47]
	s_cmp_gt_i32 s5, 1
	s_cselect_b64 s[2:3], -1, 0
	v_lshl_add_u64 v[64:65], s[22:23], 0, v[96:97]
	v_lshlrev_b32_e32 v96, 1, v80
	s_cmpk_gt_u32 s4, 0x3ff
	s_cselect_b64 s[20:21], -1, 0
	v_mfma_f32_32x32x16_bf16 v[48:63], v[70:73], v[88:91], v[48:63]
	v_lshl_add_u64 v[70:71], v[64:65], 0, s[6:7]
	v_lshl_add_u64 v[64:65], s[22:23], 0, v[96:97]
	s_mov_b64 s[6:7], 0x13e3c000
	v_lshl_add_u64 v[66:67], v[64:65], 0, s[6:7]
	s_mov_b64 s[6:7], 0x11d7c000
	s_cmp_eq_u32 s5, 1
	v_lshl_add_u64 v[64:65], v[64:65], 0, s[6:7]
	v_mfma_f32_32x32x16_bf16 v[0:15], v[74:77], v[92:95], v[0:15]
	s_cselect_b64 s[18:19], -1, 0
	v_cmp_gt_i32_e32 vcc, s90, v68
	v_mfma_f32_32x32x16_bf16 v[16:31], v[74:77], v[88:91], v[16:31]
	s_and_saveexec_b64 s[4:5], vcc
	s_cbranch_execz .LBB0_1590
	s_movk_i32 s6, 0x400f
	v_add_u32_e32 v72, 0xffffbff0, v68
	v_cmp_lt_i32_e64 s[6:7], s6, v68
	v_ashrrev_i32_e32 v78, 4, v72
	s_mov_b64 s[8:9], -1
	s_and_b64 vcc, exec, s[2:3]
	s_cbranch_vccz .LBB0_1569
	s_and_saveexec_b64 s[8:9], s[6:7]
	s_xor_b64 s[8:9], exec, s[8:9]
	s_cbranch_execz .LBB0_1562
	s_mov_b64 s[10:11], s[72:73]
	s_add_u32 s10, s10, 0xc48f000
	v_mov_b32_e32 v73, v97
	s_addc_u32 s11, s11, 0
	v_mov_b64_e32 v[74:75], v[72:73]

; DEVI int TID() { int t = threadIdx.x; asm volatile("" : "+v"(t)); return t; }
;   bf16* As = (bf16*)smem;
;   bf16* Bs = As + 128 * 72;
;   const int tid = TID(), lane = tid & 63, wave = tid >> 6, wm = wave >> 1, wn = wave & 1;
;   f32x16 acc[2][2];
; #pragma unroll
;   for (int i = 0; i < 2; ++i)
; #pragma unroll
;     for (int j = 0; j < 2; ++j) acc[i][j] = zero16();
;   const int lrow = tid >> 3, lkc = (tid & 7) * 8;
;   const bf16* Ag = jb.A + (size_t)max(m0 + lrow, 0) * jb.lda + lkc;
;   const bf16* Ag1 = jb.A + (ptrdiff_t)(m0 + lrow) * jb.lda + lkc;
;   const bf16* Bg = jb.Bt + (size_t)(n0 + lrow) * jb.K + lkc;
;   const size_t astep = (size_t)32 * jb.lda, bstep = (size_t)32 * jb.K;
;   if (kt1 < 0) kt1 = jb.K >> 6;
;   const int nk = kt1 - kt0;
;   Ag += (size_t)kt0 * 64; Ag1 += (size_t)kt0 * 64; Bg += (size_t)kt0 * 64;
;   u32x4 ra0[4], rb0[4], ra1[4], rb1[4];
;     ...
;   bf16* As1 = As + 2 * 128 * 72;
;   bf16* Bs1 = As1 + 128 * 72;
;   G_LOAD(ra0, rb0, 0);
;   if (nk > 1) G_LOAD(ra1, rb1, 1);
;   G_STORE(ra0, rb0, As, Bs);
;   __syncthreads();
; DEVI void gemm_single(const Params& p, const GJob& jb, int nt, char* smem) {
;     ...
;     for (int t = lb; t < nmt * nnt; t += nlb) {
;       const int mt = m_lo + t / nnt, ntg = n_lo + t % nnt;
;       gemm_tile(p, jb, fused ? mt * 126 - 2 : mt * 128, ntg * 128, smem);
.LBB0_1819:
	s_abs_i32 s3, s22
	s_mul_hi_u32 s4, s3, s29
	s_mul_i32 s5, s4, s26
	s_ashr_i32 s2, s22, 31
	s_sub_i32 s3, s3, s5
	s_xor_b32 s2, s2, s28
	s_add_i32 s5, s4, 1
	s_sub_i32 s6, s3, s26
	s_cmp_ge_u32 s3, s26
	s_cselect_b32 s4, s5, s4
	s_cselect_b32 s3, s6, s3
	s_add_i32 s5, s4, 1
	s_cmp_ge_u32 s3, s26
	s_cselect_b32 s3, s5, s4
	s_xor_b32 s3, s3, s2
	s_sub_i32 s4, s3, s2
	s_mul_i32 s2, s2, 6
	s_mul_i32 s3, s3, 6
	s_add_i32 s4, s4, s24
	s_sub_i32 s2, s2, s3
	s_add_i32 s3, s23, s22
	v_mov_b32_e32 v85, v208
	s_add_i32 s2, s3, s2
	s_lshl_b32 s3, s4, 7
	s_lshl_b32 s4, s2, 7
	v_ashrrev_i32_e32 v64, 3, v85
	v_add_u32_e32 v0, s3, v64
	v_max_i32_e32 v96, 0, v0
	v_lshlrev_b32_e32 v1, 4, v85
	v_lshlrev_b64 v[2:3], 11, v[96:97]
	v_and_b32_e32 v96, 0x70, v1
	s_mov_b64 s[96:97], 0x80
	v_lshrrev_b32_e32 v178, 4, v208
	v_and_b32_e32 v178, 7, v178
	v_lshlrev_b32_e32 v178, 4, v178
	v_xor_b32_e32 v96, v96, v178
	v_lshrrev_b32_e32 v179, 6, v208
	v_lshlrev_b32_e32 v179, 10, v179
	v_lshrrev_b32_e32 v180, 5, v208
	v_lshrrev_b32_e32 v181, 1, v208
	v_xor_b32_e32 v180, v180, v181
	v_readfirstlane_b32 s94, v179
	v_and_b32_e32 v180, 1, v180
	v_lshlrev_b32_e32 v180, 4, v180
	v_and_b32_e32 v181, 31, v208
	v_lshlrev_b32_e32 v181, 7, v181
	v_or_b32_e32 v180, v180, v181
	v_lshrrev_b32_e32 v181, 7, v208
	v_lshlrev_b32_e32 v181, 13, v181
	v_or_b32_e32 v194, v180, v181
	v_bfe_u32 v181, v208, 6, 1
	v_lshlrev_b32_e32 v181, 13, v181
	v_or_b32_e32 v195, v180, v181
	v_bfe_u32 v178, v208, 2, 2
	v_xor_b32_e32 v179, 0, v178
	v_lshlrev_b32_e32 v179, 5, v179
	v_or_b32_e32 v170, v194, v179
	v_or_b32_e32 v174, v195, v179
	v_xor_b32_e32 v179, 1, v178
	v_lshlrev_b32_e32 v179, 5, v179
	v_or_b32_e32 v171, v194, v179
	v_or_b32_e32 v175, v195, v179
	v_xor_b32_e32 v179, 2, v178
	v_lshlrev_b32_e32 v179, 5, v179
	v_or_b32_e32 v172, v194, v179
	v_or_b32_e32 v176, v195, v179
	v_xor_b32_e32 v179, 3, v178
	v_lshlrev_b32_e32 v179, 5, v179
	v_or_b32_e32 v173, v194, v179
	v_or_b32_e32 v177, v195, v179
	v_ashrrev_i32_e32 v1, 31, v0
	v_lshlrev_b64 v[0:1], 11, v[0:1]
	v_lshl_add_u64 v[0:1], s[12:13], 0, v[0:1]
	v_lshl_add_u64 v[24:25], v[0:1], 0, v[96:97]
	v_add_u32_e32 v0, s4, v64
	v_ashrrev_i32_e32 v1, 31, v0
	v_lshlrev_b64 v[0:1], 11, v[0:1]
	v_lshl_add_u64 v[0:1], s[14:15], 0, v[0:1]
	v_add_co_u32_e32 v70, vcc, s63, v24
	v_lshl_add_u64 v[68:69], v[0:1], 0, v[96:97]
	s_nop 0
	v_addc_co_u32_e32 v71, vcc, 0, v25, vcc
	v_add_co_u32_e32 v72, vcc, s63, v68
	v_lshl_add_u64 v[2:3], s[12:13], 0, v[2:3]
	s_nop 0
	v_addc_co_u32_e32 v73, vcc, 0, v69, vcc
	v_add_co_u32_e32 v74, vcc, s64, v24
	v_lshl_add_u64 v[66:67], v[2:3], 0, v[96:97]
	s_nop 0
	v_addc_co_u32_e32 v75, vcc, 0, v25, vcc
	v_add_co_u32_e32 v76, vcc, s64, v68
	v_addc_co_u32_e32 v77, vcc, 0, v69, vcc
	v_add_co_u32_e32 v78, vcc, s65, v24
	s_nop 0
	v_addc_co_u32_e32 v79, vcc, 0, v25, vcc
	v_add_co_u32_e32 v80, vcc, s65, v68
	s_nop 0
	v_addc_co_u32_e32 v81, vcc, 0, v69, vcc
	v_ashrrev_i32_e32 v65, 1, v85
	v_and_b32_e32 v84, 31, v85
	v_lshrrev_b32_e32 v82, 1, v85
	v_and_b32_e32 v86, 0xffffffc0, v65
	v_and_b32_e32 v88, 16, v82
	v_or_b32_e32 v65, v86, v84
	v_mad_u64_u32 v[82:83], s[6:7], v64, s91, v[96:97]
	v_add_u32_e32 v87, 0xd800, v82
	v_mad_u64_u32 v[64:65], s[6:7], v65, s91, v[88:89]
	v_and_b32_e32 v65, 0x5f, v85
	v_mad_u32_u24 v83, v65, s91, v88
	s_and_b32 s6, s4, 0x380
	s_mov_b64 s[20:21], s[74:75]
	s_ashr_i32 s5, s2, 3
	s_add_u32 m0, s94, 0x0
	s_nop 1
	global_load_lds_dwordx4 v[66:67], off
	s_add_u32 m0, s94, 0x4000
	s_nop 1
	global_load_lds_dwordx4 v[68:69], off
	s_add_u32 m0, s94, 0x1000
	s_nop 1
	global_load_lds_dwordx4 v[70:71], off
	s_add_u32 m0, s94, 0x2000
	s_nop 1
	global_load_lds_dwordx4 v[74:75], off
	s_add_u32 m0, s94, 0x3000
	s_nop 1
	global_load_lds_dwordx4 v[78:79], off
	s_add_u32 m0, s94, 0x5000
	s_nop 1
	global_load_lds_dwordx4 v[72:73], off
	s_add_u32 m0, s94, 0x6000
	s_nop 1
	global_load_lds_dwordx4 v[76:77], off
	s_add_u32 m0, s94, 0x7000
	s_nop 1
	global_load_lds_dwordx4 v[80:81], off
	s_waitcnt lgkmcnt(0)
	s_waitcnt vmcnt(0)
	s_barrier
	v_lshl_add_u64 v[66:67], v[66:67], 0, s[96:97]
	s_add_u32 m0, s94, 0x8000
	s_nop 1
	global_load_lds_dwordx4 v[66:67], off
	v_lshl_add_u64 v[68:69], v[68:69], 0, s[96:97]
	s_add_u32 m0, s94, 0xc000
	s_nop 1
	global_load_lds_dwordx4 v[68:69], off
	v_lshl_add_u64 v[70:71], v[70:71], 0, s[96:97]
	s_add_u32 m0, s94, 0x9000
	s_nop 1
	global_load_lds_dwordx4 v[70:71], off
	v_lshl_add_u64 v[72:73], v[72:73], 0, s[96:97]
	s_add_u32 m0, s94, 0xd000
	s_nop 1
	global_load_lds_dwordx4 v[72:73], off
	v_lshl_add_u64 v[74:75], v[74:75], 0, s[96:97]
	s_add_u32 m0, s94, 0xa000
	s_nop 1
	global_load_lds_dwordx4 v[74:75], off
	v_lshl_add_u64 v[76:77], v[76:77], 0, s[96:97]
	s_add_u32 m0, s94, 0xe000
	s_nop 1
	global_load_lds_dwordx4 v[76:77], off
	v_lshl_add_u64 v[78:79], v[78:79], 0, s[96:97]
	s_add_u32 m0, s94, 0xb000
	s_nop 1
	global_load_lds_dwordx4 v[78:79], off
	v_lshl_add_u64 v[80:81], v[80:81], 0, s[96:97]
	s_add_u32 m0, s94, 0xf000
	s_nop 1
	global_load_lds_dwordx4 v[80:81], off
	ds_read_b128 v[0:3], v170 offset:0
	ds_read_b128 v[4:7], v174 offset:16384
	ds_read_b128 v[88:91], v171 offset:0
	ds_read_b128 v[92:95], v175 offset:16384
	ds_read_b128 v[16:19], v174 offset:20480
	ds_read_b128 v[98:101], v175 offset:20480
	s_waitcnt lgkmcnt(4)
	v_mfma_f32_32x32x16_bf16 v[32:47], v[0:3], v[4:7], 0
	ds_read_b128 v[20:23], v170 offset:4096
	ds_read_b128 v[102:105], v171 offset:4096
	s_waitcnt lgkmcnt(3)
	v_mfma_f32_32x32x16_bf16 v[48:63], v[0:3], v[16:19], 0
	s_waitcnt lgkmcnt(1)
	v_mfma_f32_32x32x16_bf16 v[0:15], v[20:23], v[4:7], 0
	v_mfma_f32_32x32x16_bf16 v[16:31], v[20:23], v[16:19], 0
	v_mfma_f32_32x32x16_bf16 v[32:47], v[88:91], v[92:95], v[32:47]
	v_mfma_f32_32x32x16_bf16 v[48:63], v[88:91], v[98:101], v[48:63]
	s_waitcnt lgkmcnt(0)
	v_mfma_f32_32x32x16_bf16 v[0:15], v[102:105], v[92:95], v[0:15]
	v_mfma_f32_32x32x16_bf16 v[16:31], v[102:105], v[98:101], v[16:31]
	ds_read_b128 v[88:91], v172 offset:0
	ds_read_b128 v[92:95], v176 offset:16384
	ds_read_b128 v[98:101], v173 offset:0
	ds_read_b128 v[102:105], v177 offset:16384
	ds_read_b128 v[106:109], v176 offset:20480
	ds_read_b128 v[110:113], v177 offset:20480
	s_waitcnt lgkmcnt(4)
	v_mfma_f32_32x32x16_bf16 v[32:47], v[88:91], v[92:95], v[32:47]
	s_waitcnt lgkmcnt(1)
	v_mfma_f32_32x32x16_bf16 v[48:63], v[88:91], v[106:109], v[48:63]
	ds_read_b128 v[88:91], v172 offset:4096
	ds_read_b128 v[114:117], v173 offset:4096
	s_waitcnt lgkmcnt(1)
	v_mfma_f32_32x32x16_bf16 v[0:15], v[88:91], v[92:95], v[0:15]
	v_mfma_f32_32x32x16_bf16 v[16:31], v[88:91], v[106:109], v[16:31]
	v_mfma_f32_32x32x16_bf16 v[32:47], v[98:101], v[102:105], v[32:47]
	v_mfma_f32_32x32x16_bf16 v[48:63], v[98:101], v[110:113], v[48:63]
	s_waitcnt lgkmcnt(0)
	v_mfma_f32_32x32x16_bf16 v[0:15], v[114:117], v[102:105], v[0:15]
	s_waitcnt vmcnt(0)
	s_barrier
;     ...
;   bf16* As1 = As + 2 * 128 * 72;
;   bf16* Bs1 = As1 + 128 * 72;
;   G_LOAD(ra0, rb0, 0);
;   if (nk > 1) G_LOAD(ra1, rb1, 1);
;   G_STORE(ra0, rb0, As, Bs);
;   __syncthreads();
;   for (int kt = 0; kt < nk; kt += 2) {
;     if (kt + 2 < nk) G_LOAD(ra0, rb0, kt + 2);
;     if (kt + 1 < nk) G_STORE(ra1, rb1, As1, Bs1);
;     G_COMPUTE(As, Bs);
;     __syncthreads();
;     if (kt + 1 < nk) {
;       if (kt + 3 < nk) G_LOAD(ra1, rb1, kt + 3);
;       if (kt + 2 < nk) G_STORE(ra0, rb0, As, Bs);
;       G_COMPUTE(As1, Bs1);
;       __syncthreads();
	v_lshl_add_u64 v[66:67], v[66:67], 0, s[96:97]
	s_add_u32 m0, s94, 0x0
	s_nop 1
	global_load_lds_dwordx4 v[66:67], off
	v_lshl_add_u64 v[68:69], v[68:69], 0, s[96:97]
	s_add_u32 m0, s94, 0x4000
	s_nop 1
	global_load_lds_dwordx4 v[68:69], off
	v_lshl_add_u64 v[70:71], v[70:71], 0, s[96:97]
	s_add_u32 m0, s94, 0x1000
	s_nop 1
	global_load_lds_dwordx4 v[70:71], off
	v_lshl_add_u64 v[72:73], v[72:73], 0, s[96:97]
	s_add_u32 m0, s94, 0x5000
	s_nop 1
	global_load_lds_dwordx4 v[72:73], off
	v_lshl_add_u64 v[74:75], v[74:75], 0, s[96:97]
	s_add_u32 m0, s94, 0x2000
	s_nop 1
	global_load_lds_dwordx4 v[74:75], off
	v_lshl_add_u64 v[76:77], v[76:77], 0, s[96:97]
	s_add_u32 m0, s94, 0x6000
	s_nop 1
	global_load_lds_dwordx4 v[76:77], off
	v_lshl_add_u64 v[78:79], v[78:79], 0, s[96:97]
	s_add_u32 m0, s94, 0x3000
	s_nop 1
	global_load_lds_dwordx4 v[78:79], off
	v_lshl_add_u64 v[80:81], v[80:81], 0, s[96:97]
	s_add_u32 m0, s94, 0x7000
	s_nop 1
	global_load_lds_dwordx4 v[80:81], off
	v_mfma_f32_32x32x16_bf16 v[16:31], v[114:117], v[110:113], v[16:31]
	ds_read_b128 v[88:91], v170 offset:32768
	ds_read_b128 v[92:95], v174 offset:49152
	ds_read_b128 v[98:101], v171 offset:32768
	ds_read_b128 v[102:105], v175 offset:49152
	ds_read_b128 v[106:109], v174 offset:53248
	ds_read_b128 v[110:113], v175 offset:53248
	s_waitcnt lgkmcnt(4)
	v_mfma_f32_32x32x16_bf16 v[32:47], v[88:91], v[92:95], v[32:47]
	s_waitcnt lgkmcnt(1)
	v_mfma_f32_32x32x16_bf16 v[48:63], v[88:91], v[106:109], v[48:63]
	ds_read_b128 v[88:91], v170 offset:36864
	ds_read_b128 v[114:117], v171 offset:36864
	s_waitcnt lgkmcnt(1)
	v_mfma_f32_32x32x16_bf16 v[0:15], v[88:91], v[92:95], v[0:15]
	v_mfma_f32_32x32x16_bf16 v[16:31], v[88:91], v[106:109], v[16:31]
	v_mfma_f32_32x32x16_bf16 v[32:47], v[98:101], v[102:105], v[32:47]
	v_mfma_f32_32x32x16_bf16 v[48:63], v[98:101], v[110:113], v[48:63]
	s_waitcnt lgkmcnt(0)
	v_mfma_f32_32x32x16_bf16 v[0:15], v[114:117], v[102:105], v[0:15]
	ds_read_b128 v[88:91], v172 offset:32768
	ds_read_b128 v[92:95], v176 offset:49152
	ds_read_b128 v[98:101], v173 offset:32768
	ds_read_b128 v[102:105], v177 offset:49152
	v_mfma_f32_32x32x16_bf16 v[16:31], v[114:117], v[110:113], v[16:31]
	ds_read_b128 v[106:109], v176 offset:53248
	ds_read_b128 v[110:113], v177 offset:53248
	s_waitcnt lgkmcnt(4)
	v_mfma_f32_32x32x16_bf16 v[32:47], v[88:91], v[92:95], v[32:47]
	s_waitcnt lgkmcnt(1)
	v_mfma_f32_32x32x16_bf16 v[48:63], v[88:91], v[106:109], v[48:63]
	ds_read_b128 v[88:91], v172 offset:36864
	ds_read_b128 v[114:117], v173 offset:36864
	s_waitcnt lgkmcnt(1)
	v_mfma_f32_32x32x16_bf16 v[0:15], v[88:91], v[92:95], v[0:15]
	v_mfma_f32_32x32x16_bf16 v[16:31], v[88:91], v[106:109], v[16:31]
	v_mfma_f32_32x32x16_bf16 v[32:47], v[98:101], v[102:105], v[32:47]
	v_mfma_f32_32x32x16_bf16 v[48:63], v[98:101], v[110:113], v[48:63]
	s_waitcnt lgkmcnt(0)
	v_mfma_f32_32x32x16_bf16 v[0:15], v[114:117], v[102:105], v[0:15]
	s_waitcnt vmcnt(0)
	s_barrier
	v_lshl_add_u64 v[66:67], v[66:67], 0, s[96:97]
	s_add_u32 m0, s94, 0x8000
	s_nop 1
	global_load_lds_dwordx4 v[66:67], off
	v_lshl_add_u64 v[68:69], v[68:69], 0, s[96:97]
	s_add_u32 m0, s94, 0xc000
	s_nop 1
	global_load_lds_dwordx4 v[68:69], off
	v_lshl_add_u64 v[70:71], v[70:71], 0, s[96:97]
	s_add_u32 m0, s94, 0x9000
	s_nop 1
	global_load_lds_dwordx4 v[70:71], off
	v_lshl_add_u64 v[72:73], v[72:73], 0, s[96:97]
	s_add_u32 m0, s94, 0xd000
	s_nop 1
	global_load_lds_dwordx4 v[72:73], off
	v_lshl_add_u64 v[74:75], v[74:75], 0, s[96:97]
	s_add_u32 m0, s94, 0xa000
	s_nop 1
	global_load_lds_dwordx4 v[74:75], off
	v_lshl_add_u64 v[76:77], v[76:77], 0, s[96:97]
	s_add_u32 m0, s94, 0xe000
	s_nop 1
	global_load_lds_dwordx4 v[76:77], off
	v_lshl_add_u64 v[78:79], v[78:79], 0, s[96:97]
	s_add_u32 m0, s94, 0xb000
	s_nop 1
	global_load_lds_dwordx4 v[78:79], off
	v_lshl_add_u64 v[80:81], v[80:81], 0, s[96:97]
	s_add_u32 m0, s94, 0xf000
	s_nop 1
	global_load_lds_dwordx4 v[80:81], off
	v_mfma_f32_32x32x16_bf16 v[16:31], v[114:117], v[110:113], v[16:31]
	ds_read_b128 v[88:91], v170 offset:0
	ds_read_b128 v[92:95], v174 offset:16384
	ds_read_b128 v[98:101], v171 offset:0
	ds_read_b128 v[102:105], v175 offset:16384
	ds_read_b128 v[106:109], v174 offset:20480
	ds_read_b128 v[110:113], v175 offset:20480
	s_waitcnt lgkmcnt(4)
	v_mfma_f32_32x32x16_bf16 v[32:47], v[88:91], v[92:95], v[32:47]
	s_waitcnt lgkmcnt(1)
	v_mfma_f32_32x32x16_bf16 v[48:63], v[88:91], v[106:109], v[48:63]
	ds_read_b128 v[88:91], v170 offset:4096
	ds_read_b128 v[114:117], v171 offset:4096
	s_waitcnt lgkmcnt(1)
	v_mfma_f32_32x32x16_bf16 v[0:15], v[88:91], v[92:95], v[0:15]
	v_mfma_f32_32x32x16_bf16 v[16:31], v[88:91], v[106:109], v[16:31]
	v_mfma_f32_32x32x16_bf16 v[32:47], v[98:101], v[102:105], v[32:47]
	v_mfma_f32_32x32x16_bf16 v[48:63], v[98:101], v[110:113], v[48:63]
	s_waitcnt lgkmcnt(0)
	v_mfma_f32_32x32x16_bf16 v[0:15], v[114:117], v[102:105], v[0:15]
	ds_read_b128 v[88:91], v172 offset:0
	ds_read_b128 v[92:95], v176 offset:16384
	ds_read_b128 v[98:101], v173 offset:0
	ds_read_b128 v[102:105], v177 offset:16384
	v_mfma_f32_32x32x16_bf16 v[16:31], v[114:117], v[110:113], v[16:31]
	ds_read_b128 v[106:109], v176 offset:20480
	ds_read_b128 v[110:113], v177 offset:20480
	s_waitcnt lgkmcnt(4)
	v_mfma_f32_32x32x16_bf16 v[32:47], v[88:91], v[92:95], v[32:47]
	s_waitcnt lgkmcnt(1)
	v_mfma_f32_32x32x16_bf16 v[48:63], v[88:91], v[106:109], v[48:63]
	ds_read_b128 v[88:91], v172 offset:4096
	ds_read_b128 v[114:117], v173 offset:4096
	s_waitcnt lgkmcnt(1)
	v_mfma_f32_32x32x16_bf16 v[0:15], v[88:91], v[92:95], v[0:15]
	v_mfma_f32_32x32x16_bf16 v[16:31], v[88:91], v[106:109], v[16:31]
	v_mfma_f32_32x32x16_bf16 v[32:47], v[98:101], v[102:105], v[32:47]
	v_mfma_f32_32x32x16_bf16 v[48:63], v[98:101], v[110:113], v[48:63]
	s_waitcnt lgkmcnt(0)
	v_mfma_f32_32x32x16_bf16 v[0:15], v[114:117], v[102:105], v[0:15]
	s_waitcnt vmcnt(0)
	s_barrier
;     ...
;   bf16* As1 = As + 2 * 128 * 72;
;   bf16* Bs1 = As1 + 128 * 72;
;   G_LOAD(ra0, rb0, 0);
;   if (nk > 1) G_LOAD(ra1, rb1, 1);
;   G_STORE(ra0, rb0, As, Bs);
;   __syncthreads();
;   for (int kt = 0; kt < nk; kt += 2) {
;     if (kt + 2 < nk) G_LOAD(ra0, rb0, kt + 2);
;     if (kt + 1 < nk) G_STORE(ra1, rb1, As1, Bs1);
;     G_COMPUTE(As, Bs);
;     __syncthreads();
;     if (kt + 1 < nk) {
;       if (kt + 3 < nk) G_LOAD(ra1, rb1, kt + 3);
;       if (kt + 2 < nk) G_STORE(ra0, rb0, As, Bs);
;       G_COMPUTE(As1, Bs1);
;       __syncthreads();
	v_lshl_add_u64 v[66:67], v[66:67], 0, s[96:97]
	s_add_u32 m0, s94, 0x0
	s_nop 1
	global_load_lds_dwordx4 v[66:67], off
	v_lshl_add_u64 v[68:69], v[68:69], 0, s[96:97]
	s_add_u32 m0, s94, 0x4000
	s_nop 1
	global_load_lds_dwordx4 v[68:69], off
	v_lshl_add_u64 v[70:71], v[70:71], 0, s[96:97]
	s_add_u32 m0, s94, 0x1000
	s_nop 1
	global_load_lds_dwordx4 v[70:71], off
	v_lshl_add_u64 v[72:73], v[72:73], 0, s[96:97]
	s_add_u32 m0, s94, 0x5000
	s_nop 1
	global_load_lds_dwordx4 v[72:73], off
	v_lshl_add_u64 v[74:75], v[74:75], 0, s[96:97]
	s_add_u32 m0, s94, 0x2000
	s_nop 1
	global_load_lds_dwordx4 v[74:75], off
	v_lshl_add_u64 v[76:77], v[76:77], 0, s[96:97]
	s_add_u32 m0, s94, 0x6000
	s_nop 1
	global_load_lds_dwordx4 v[76:77], off
	v_lshl_add_u64 v[78:79], v[78:79], 0, s[96:97]
	s_add_u32 m0, s94, 0x3000
	s_nop 1
	global_load_lds_dwordx4 v[78:79], off
	v_lshl_add_u64 v[80:81], v[80:81], 0, s[96:97]
	s_add_u32 m0, s94, 0x7000
	s_nop 1
	global_load_lds_dwordx4 v[80:81], off
	v_mfma_f32_32x32x16_bf16 v[16:31], v[114:117], v[110:113], v[16:31]
	ds_read_b128 v[88:91], v170 offset:32768
	ds_read_b128 v[92:95], v174 offset:49152
	ds_read_b128 v[98:101], v171 offset:32768
	ds_read_b128 v[102:105], v175 offset:49152
	ds_read_b128 v[106:109], v174 offset:53248
	ds_read_b128 v[110:113], v175 offset:53248
	s_waitcnt lgkmcnt(4)
	v_mfma_f32_32x32x16_bf16 v[32:47], v[88:91], v[92:95], v[32:47]
	s_waitcnt lgkmcnt(1)
	v_mfma_f32_32x32x16_bf16 v[48:63], v[88:91], v[106:109], v[48:63]
	ds_read_b128 v[88:91], v170 offset:36864
	ds_read_b128 v[114:117], v171 offset:36864
	s_waitcnt lgkmcnt(1)
	v_mfma_f32_32x32x16_bf16 v[0:15], v[88:91], v[92:95], v[0:15]
	v_mfma_f32_32x32x16_bf16 v[16:31], v[88:91], v[106:109], v[16:31]
	v_mfma_f32_32x32x16_bf16 v[32:47], v[98:101], v[102:105], v[32:47]
	v_mfma_f32_32x32x16_bf16 v[48:63], v[98:101], v[110:113], v[48:63]
	s_waitcnt lgkmcnt(0)
	v_mfma_f32_32x32x16_bf16 v[0:15], v[114:117], v[102:105], v[0:15]
	ds_read_b128 v[88:91], v172 offset:32768
	ds_read_b128 v[92:95], v176 offset:49152
	ds_read_b128 v[98:101], v173 offset:32768
	ds_read_b128 v[102:105], v177 offset:49152
	v_mfma_f32_32x32x16_bf16 v[16:31], v[114:117], v[110:113], v[16:31]
	ds_read_b128 v[106:109], v176 offset:53248
	ds_read_b128 v[110:113], v177 offset:53248
	s_waitcnt lgkmcnt(4)
	v_mfma_f32_32x32x16_bf16 v[32:47], v[88:91], v[92:95], v[32:47]
	s_waitcnt lgkmcnt(1)
	v_mfma_f32_32x32x16_bf16 v[48:63], v[88:91], v[106:109], v[48:63]
	ds_read_b128 v[88:91], v172 offset:36864
	ds_read_b128 v[114:117], v173 offset:36864
	s_waitcnt lgkmcnt(1)
	v_mfma_f32_32x32x16_bf16 v[0:15], v[88:91], v[92:95], v[0:15]
	v_mfma_f32_32x32x16_bf16 v[16:31], v[88:91], v[106:109], v[16:31]
	v_mfma_f32_32x32x16_bf16 v[32:47], v[98:101], v[102:105], v[32:47]
	v_mfma_f32_32x32x16_bf16 v[48:63], v[98:101], v[110:113], v[48:63]
	s_waitcnt lgkmcnt(0)
	v_mfma_f32_32x32x16_bf16 v[0:15], v[114:117], v[102:105], v[0:15]
	s_waitcnt vmcnt(0)
	s_barrier
	v_lshl_add_u64 v[66:67], v[66:67], 0, s[96:97]
	s_add_u32 m0, s94, 0x8000
	s_nop 1
	global_load_lds_dwordx4 v[66:67], off
	v_lshl_add_u64 v[68:69], v[68:69], 0, s[96:97]
	s_add_u32 m0, s94, 0xc000
	s_nop 1
	global_load_lds_dwordx4 v[68:69], off
	v_lshl_add_u64 v[70:71], v[70:71], 0, s[96:97]
	s_add_u32 m0, s94, 0x9000
	s_nop 1
	global_load_lds_dwordx4 v[70:71], off
	v_lshl_add_u64 v[72:73], v[72:73], 0, s[96:97]
	s_add_u32 m0, s94, 0xd000
	s_nop 1
	global_load_lds_dwordx4 v[72:73], off
	v_lshl_add_u64 v[74:75], v[74:75], 0, s[96:97]
	s_add_u32 m0, s94, 0xa000
	s_nop 1
	global_load_lds_dwordx4 v[74:75], off
	v_lshl_add_u64 v[76:77], v[76:77], 0, s[96:97]
	s_add_u32 m0, s94, 0xe000
	s_nop 1
	global_load_lds_dwordx4 v[76:77], off
	v_lshl_add_u64 v[78:79], v[78:79], 0, s[96:97]
	s_add_u32 m0, s94, 0xb000
	s_nop 1
	global_load_lds_dwordx4 v[78:79], off
	v_lshl_add_u64 v[80:81], v[80:81], 0, s[96:97]
	s_add_u32 m0, s94, 0xf000
	s_nop 1
	global_load_lds_dwordx4 v[80:81], off
	v_mfma_f32_32x32x16_bf16 v[16:31], v[114:117], v[110:113], v[16:31]
	ds_read_b128 v[88:91], v170 offset:0
	ds_read_b128 v[92:95], v174 offset:16384
	ds_read_b128 v[98:101], v171 offset:0
	ds_read_b128 v[102:105], v175 offset:16384
	ds_read_b128 v[106:109], v174 offset:20480
	ds_read_b128 v[110:113], v175 offset:20480
	s_waitcnt lgkmcnt(4)
	v_mfma_f32_32x32x16_bf16 v[32:47], v[88:91], v[92:95], v[32:47]
	s_waitcnt lgkmcnt(1)
	v_mfma_f32_32x32x16_bf16 v[48:63], v[88:91], v[106:109], v[48:63]
	ds_read_b128 v[88:91], v170 offset:4096
	ds_read_b128 v[114:117], v171 offset:4096
	s_waitcnt lgkmcnt(1)
	v_mfma_f32_32x32x16_bf16 v[0:15], v[88:91], v[92:95], v[0:15]
	v_mfma_f32_32x32x16_bf16 v[16:31], v[88:91], v[106:109], v[16:31]
	v_mfma_f32_32x32x16_bf16 v[32:47], v[98:101], v[102:105], v[32:47]
	v_mfma_f32_32x32x16_bf16 v[48:63], v[98:101], v[110:113], v[48:63]
	s_waitcnt lgkmcnt(0)
	v_mfma_f32_32x32x16_bf16 v[0:15], v[114:117], v[102:105], v[0:15]
	ds_read_b128 v[88:91], v172 offset:0
	ds_read_b128 v[92:95], v176 offset:16384
	ds_read_b128 v[98:101], v173 offset:0
	ds_read_b128 v[102:105], v177 offset:16384
	v_mfma_f32_32x32x16_bf16 v[16:31], v[114:117], v[110:113], v[16:31]
	ds_read_b128 v[106:109], v176 offset:20480
	ds_read_b128 v[110:113], v177 offset:20480
	s_waitcnt lgkmcnt(4)
	v_mfma_f32_32x32x16_bf16 v[32:47], v[88:91], v[92:95], v[32:47]
	s_waitcnt lgkmcnt(1)
	v_mfma_f32_32x32x16_bf16 v[48:63], v[88:91], v[106:109], v[48:63]
	ds_read_b128 v[88:91], v172 offset:4096
	ds_read_b128 v[114:117], v173 offset:4096
	s_waitcnt lgkmcnt(1)
	v_mfma_f32_32x32x16_bf16 v[0:15], v[88:91], v[92:95], v[0:15]
	v_mfma_f32_32x32x16_bf16 v[16:31], v[88:91], v[106:109], v[16:31]
	v_mfma_f32_32x32x16_bf16 v[32:47], v[98:101], v[102:105], v[32:47]
	v_mfma_f32_32x32x16_bf16 v[48:63], v[98:101], v[110:113], v[48:63]
	s_waitcnt lgkmcnt(0)
	v_mfma_f32_32x32x16_bf16 v[0:15], v[114:117], v[102:105], v[0:15]
	s_waitcnt vmcnt(0)
	s_barrier
;     ...
;   bf16* As1 = As + 2 * 128 * 72;
;   bf16* Bs1 = As1 + 128 * 72;
;   G_LOAD(ra0, rb0, 0);
;   if (nk > 1) G_LOAD(ra1, rb1, 1);
;   G_STORE(ra0, rb0, As, Bs);
;   __syncthreads();
;   for (int kt = 0; kt < nk; kt += 2) {
;     if (kt + 2 < nk) G_LOAD(ra0, rb0, kt + 2);
;     if (kt + 1 < nk) G_STORE(ra1, rb1, As1, Bs1);
;     G_COMPUTE(As, Bs);
;     __syncthreads();
;     if (kt + 1 < nk) {
;       if (kt + 3 < nk) G_LOAD(ra1, rb1, kt + 3);
;       if (kt + 2 < nk) G_STORE(ra0, rb0, As, Bs);
;       G_COMPUTE(As1, Bs1);
;       __syncthreads();
	v_lshl_add_u64 v[66:67], v[66:67], 0, s[96:97]
	s_add_u32 m0, s94, 0x0
	s_nop 1
	global_load_lds_dwordx4 v[66:67], off
	v_lshl_add_u64 v[68:69], v[68:69], 0, s[96:97]
	s_add_u32 m0, s94, 0x4000
	s_nop 1
	global_load_lds_dwordx4 v[68:69], off
	v_lshl_add_u64 v[70:71], v[70:71], 0, s[96:97]
	s_add_u32 m0, s94, 0x1000
	s_nop 1
	global_load_lds_dwordx4 v[70:71], off
	v_lshl_add_u64 v[72:73], v[72:73], 0, s[96:97]
	s_add_u32 m0, s94, 0x5000
	s_nop 1
	global_load_lds_dwordx4 v[72:73], off
	v_lshl_add_u64 v[74:75], v[74:75], 0, s[96:97]
	s_add_u32 m0, s94, 0x2000
	s_nop 1
	global_load_lds_dwordx4 v[74:75], off
	v_lshl_add_u64 v[76:77], v[76:77], 0, s[96:97]
	s_add_u32 m0, s94, 0x6000
	s_nop 1
	global_load_lds_dwordx4 v[76:77], off
	v_lshl_add_u64 v[78:79], v[78:79], 0, s[96:97]
	s_add_u32 m0, s94, 0x3000
	s_nop 1
	global_load_lds_dwordx4 v[78:79], off
	v_lshl_add_u64 v[80:81], v[80:81], 0, s[96:97]
	s_add_u32 m0, s94, 0x7000
	s_nop 1
	global_load_lds_dwordx4 v[80:81], off
	v_mfma_f32_32x32x16_bf16 v[16:31], v[114:117], v[110:113], v[16:31]
	ds_read_b128 v[88:91], v170 offset:32768
	ds_read_b128 v[92:95], v174 offset:49152
	ds_read_b128 v[98:101], v171 offset:32768
	ds_read_b128 v[102:105], v175 offset:49152
	ds_read_b128 v[106:109], v174 offset:53248
	ds_read_b128 v[110:113], v175 offset:53248
	s_waitcnt lgkmcnt(4)
	v_mfma_f32_32x32x16_bf16 v[32:47], v[88:91], v[92:95], v[32:47]
	s_waitcnt lgkmcnt(1)
	v_mfma_f32_32x32x16_bf16 v[48:63], v[88:91], v[106:109], v[48:63]
	ds_read_b128 v[88:91], v170 offset:36864
	ds_read_b128 v[114:117], v171 offset:36864
	s_waitcnt lgkmcnt(1)
	v_mfma_f32_32x32x16_bf16 v[0:15], v[88:91], v[92:95], v[0:15]
	v_mfma_f32_32x32x16_bf16 v[16:31], v[88:91], v[106:109], v[16:31]
	v_mfma_f32_32x32x16_bf16 v[32:47], v[98:101], v[102:105], v[32:47]
	v_mfma_f32_32x32x16_bf16 v[48:63], v[98:101], v[110:113], v[48:63]
	s_waitcnt lgkmcnt(0)
	v_mfma_f32_32x32x16_bf16 v[0:15], v[114:117], v[102:105], v[0:15]
	ds_read_b128 v[88:91], v172 offset:32768
	ds_read_b128 v[92:95], v176 offset:49152
	ds_read_b128 v[98:101], v173 offset:32768
	ds_read_b128 v[102:105], v177 offset:49152
	v_mfma_f32_32x32x16_bf16 v[16:31], v[114:117], v[110:113], v[16:31]
	ds_read_b128 v[106:109], v176 offset:53248
	ds_read_b128 v[110:113], v177 offset:53248
	s_waitcnt lgkmcnt(4)
	v_mfma_f32_32x32x16_bf16 v[32:47], v[88:91], v[92:95], v[32:47]
	s_waitcnt lgkmcnt(1)
	v_mfma_f32_32x32x16_bf16 v[48:63], v[88:91], v[106:109], v[48:63]
	ds_read_b128 v[88:91], v172 offset:36864
	ds_read_b128 v[114:117], v173 offset:36864
	s_waitcnt lgkmcnt(1)
	v_mfma_f32_32x32x16_bf16 v[0:15], v[88:91], v[92:95], v[0:15]
	v_mfma_f32_32x32x16_bf16 v[16:31], v[88:91], v[106:109], v[16:31]
	v_mfma_f32_32x32x16_bf16 v[32:47], v[98:101], v[102:105], v[32:47]
	v_mfma_f32_32x32x16_bf16 v[48:63], v[98:101], v[110:113], v[48:63]
	s_waitcnt lgkmcnt(0)
	v_mfma_f32_32x32x16_bf16 v[0:15], v[114:117], v[102:105], v[0:15]
	s_waitcnt vmcnt(0)
	s_barrier
	v_lshl_add_u64 v[66:67], v[66:67], 0, s[96:97]
	s_add_u32 m0, s94, 0x8000
	s_nop 1
	global_load_lds_dwordx4 v[66:67], off
	v_lshl_add_u64 v[68:69], v[68:69], 0, s[96:97]
	s_add_u32 m0, s94, 0xc000
	s_nop 1
	global_load_lds_dwordx4 v[68:69], off
	v_lshl_add_u64 v[70:71], v[70:71], 0, s[96:97]
	s_add_u32 m0, s94, 0x9000
	s_nop 1
	global_load_lds_dwordx4 v[70:71], off
	v_lshl_add_u64 v[72:73], v[72:73], 0, s[96:97]
	s_add_u32 m0, s94, 0xd000
	s_nop 1
	global_load_lds_dwordx4 v[72:73], off
	v_lshl_add_u64 v[74:75], v[74:75], 0, s[96:97]
	s_add_u32 m0, s94, 0xa000
	s_nop 1
	global_load_lds_dwordx4 v[74:75], off
	v_lshl_add_u64 v[76:77], v[76:77], 0, s[96:97]
	s_add_u32 m0, s94, 0xe000
	s_nop 1
	global_load_lds_dwordx4 v[76:77], off
	v_lshl_add_u64 v[78:79], v[78:79], 0, s[96:97]
	s_add_u32 m0, s94, 0xb000
	s_nop 1
	global_load_lds_dwordx4 v[78:79], off
	v_lshl_add_u64 v[80:81], v[80:81], 0, s[96:97]
	s_add_u32 m0, s94, 0xf000
	s_nop 1
	global_load_lds_dwordx4 v[80:81], off
	v_mfma_f32_32x32x16_bf16 v[16:31], v[114:117], v[110:113], v[16:31]
	ds_read_b128 v[88:91], v170 offset:0
	ds_read_b128 v[92:95], v174 offset:16384
	ds_read_b128 v[98:101], v171 offset:0
	ds_read_b128 v[102:105], v175 offset:16384
	ds_read_b128 v[106:109], v174 offset:20480
	ds_read_b128 v[110:113], v175 offset:20480
	s_waitcnt lgkmcnt(4)
	v_mfma_f32_32x32x16_bf16 v[32:47], v[88:91], v[92:95], v[32:47]
	s_waitcnt lgkmcnt(1)
	v_mfma_f32_32x32x16_bf16 v[48:63], v[88:91], v[106:109], v[48:63]
	ds_read_b128 v[88:91], v170 offset:4096
	ds_read_b128 v[114:117], v171 offset:4096
	s_waitcnt lgkmcnt(1)
	v_mfma_f32_32x32x16_bf16 v[0:15], v[88:91], v[92:95], v[0:15]
	v_mfma_f32_32x32x16_bf16 v[16:31], v[88:91], v[106:109], v[16:31]
	v_mfma_f32_32x32x16_bf16 v[32:47], v[98:101], v[102:105], v[32:47]
	v_mfma_f32_32x32x16_bf16 v[48:63], v[98:101], v[110:113], v[48:63]
	s_waitcnt lgkmcnt(0)
	v_mfma_f32_32x32x16_bf16 v[0:15], v[114:117], v[102:105], v[0:15]
	ds_read_b128 v[88:91], v172 offset:0
	ds_read_b128 v[92:95], v176 offset:16384
	ds_read_b128 v[98:101], v173 offset:0
	ds_read_b128 v[102:105], v177 offset:16384
	v_mfma_f32_32x32x16_bf16 v[16:31], v[114:117], v[110:113], v[16:31]
	ds_read_b128 v[106:109], v176 offset:20480
	ds_read_b128 v[110:113], v177 offset:20480
	s_waitcnt lgkmcnt(4)
	v_mfma_f32_32x32x16_bf16 v[32:47], v[88:91], v[92:95], v[32:47]
	s_waitcnt lgkmcnt(1)
	v_mfma_f32_32x32x16_bf16 v[48:63], v[88:91], v[106:109], v[48:63]
	ds_read_b128 v[88:91], v172 offset:4096
	ds_read_b128 v[114:117], v173 offset:4096
	s_waitcnt lgkmcnt(1)
	v_mfma_f32_32x32x16_bf16 v[0:15], v[88:91], v[92:95], v[0:15]
	v_mfma_f32_32x32x16_bf16 v[16:31], v[88:91], v[106:109], v[16:31]
	v_mfma_f32_32x32x16_bf16 v[32:47], v[98:101], v[102:105], v[32:47]
	v_mfma_f32_32x32x16_bf16 v[48:63], v[98:101], v[110:113], v[48:63]
	s_waitcnt lgkmcnt(0)
	v_mfma_f32_32x32x16_bf16 v[0:15], v[114:117], v[102:105], v[0:15]
	s_waitcnt vmcnt(0)
	s_barrier
;     ...
;   bf16* As1 = As + 2 * 128 * 72;
;   bf16* Bs1 = As1 + 128 * 72;
;   G_LOAD(ra0, rb0, 0);
;   if (nk > 1) G_LOAD(ra1, rb1, 1);
;   G_STORE(ra0, rb0, As, Bs);
;   __syncthreads();
;   for (int kt = 0; kt < nk; kt += 2) {
;     if (kt + 2 < nk) G_LOAD(ra0, rb0, kt + 2);
;     if (kt + 1 < nk) G_STORE(ra1, rb1, As1, Bs1);
;     G_COMPUTE(As, Bs);
;     __syncthreads();
;     if (kt + 1 < nk) {
;       if (kt + 3 < nk) G_LOAD(ra1, rb1, kt + 3);
;       if (kt + 2 < nk) G_STORE(ra0, rb0, As, Bs);
;       G_COMPUTE(As1, Bs1);
;       __syncthreads();
	v_lshl_add_u64 v[66:67], v[66:67], 0, s[96:97]
	s_add_u32 m0, s94, 0x0
	s_nop 1
	global_load_lds_dwordx4 v[66:67], off
	v_lshl_add_u64 v[68:69], v[68:69], 0, s[96:97]
	s_add_u32 m0, s94, 0x4000
	s_nop 1
	global_load_lds_dwordx4 v[68:69], off
	v_lshl_add_u64 v[70:71], v[70:71], 0, s[96:97]
	s_add_u32 m0, s94, 0x1000
	s_nop 1
	global_load_lds_dwordx4 v[70:71], off
	v_lshl_add_u64 v[72:73], v[72:73], 0, s[96:97]
	s_add_u32 m0, s94, 0x5000
	s_nop 1
	global_load_lds_dwordx4 v[72:73], off
	v_lshl_add_u64 v[74:75], v[74:75], 0, s[96:97]
	s_add_u32 m0, s94, 0x2000
	s_nop 1
	global_load_lds_dwordx4 v[74:75], off
	v_lshl_add_u64 v[76:77], v[76:77], 0, s[96:97]
	s_add_u32 m0, s94, 0x6000
	s_nop 1
	global_load_lds_dwordx4 v[76:77], off
	v_lshl_add_u64 v[78:79], v[78:79], 0, s[96:97]
	s_add_u32 m0, s94, 0x3000
	s_nop 1
	global_load_lds_dwordx4 v[78:79], off
	v_lshl_add_u64 v[80:81], v[80:81], 0, s[96:97]
	s_add_u32 m0, s94, 0x7000
	s_nop 1
	global_load_lds_dwordx4 v[80:81], off
	v_mfma_f32_32x32x16_bf16 v[16:31], v[114:117], v[110:113], v[16:31]
	ds_read_b128 v[88:91], v170 offset:32768
	ds_read_b128 v[92:95], v174 offset:49152
	ds_read_b128 v[98:101], v171 offset:32768
	ds_read_b128 v[102:105], v175 offset:49152
	ds_read_b128 v[106:109], v174 offset:53248
	ds_read_b128 v[110:113], v175 offset:53248
	s_waitcnt lgkmcnt(4)
	v_mfma_f32_32x32x16_bf16 v[32:47], v[88:91], v[92:95], v[32:47]
	s_waitcnt lgkmcnt(1)
	v_mfma_f32_32x32x16_bf16 v[48:63], v[88:91], v[106:109], v[48:63]
	ds_read_b128 v[88:91], v170 offset:36864
	ds_read_b128 v[114:117], v171 offset:36864
	s_waitcnt lgkmcnt(1)
	v_mfma_f32_32x32x16_bf16 v[0:15], v[88:91], v[92:95], v[0:15]
	v_mfma_f32_32x32x16_bf16 v[16:31], v[88:91], v[106:109], v[16:31]
	v_mfma_f32_32x32x16_bf16 v[32:47], v[98:101], v[102:105], v[32:47]
	v_mfma_f32_32x32x16_bf16 v[48:63], v[98:101], v[110:113], v[48:63]
	s_waitcnt lgkmcnt(0)
	v_mfma_f32_32x32x16_bf16 v[0:15], v[114:117], v[102:105], v[0:15]
	ds_read_b128 v[88:91], v172 offset:32768
	ds_read_b128 v[92:95], v176 offset:49152
	ds_read_b128 v[98:101], v173 offset:32768
	ds_read_b128 v[102:105], v177 offset:49152
	v_mfma_f32_32x32x16_bf16 v[16:31], v[114:117], v[110:113], v[16:31]
	ds_read_b128 v[106:109], v176 offset:53248
	ds_read_b128 v[110:113], v177 offset:53248
	s_waitcnt lgkmcnt(4)
	v_mfma_f32_32x32x16_bf16 v[32:47], v[88:91], v[92:95], v[32:47]
	s_waitcnt lgkmcnt(1)
	v_mfma_f32_32x32x16_bf16 v[48:63], v[88:91], v[106:109], v[48:63]
	ds_read_b128 v[88:91], v172 offset:36864
	ds_read_b128 v[114:117], v173 offset:36864
	s_waitcnt lgkmcnt(1)
	v_mfma_f32_32x32x16_bf16 v[0:15], v[88:91], v[92:95], v[0:15]
	v_mfma_f32_32x32x16_bf16 v[16:31], v[88:91], v[106:109], v[16:31]
	v_mfma_f32_32x32x16_bf16 v[32:47], v[98:101], v[102:105], v[32:47]
	v_mfma_f32_32x32x16_bf16 v[48:63], v[98:101], v[110:113], v[48:63]
	s_waitcnt lgkmcnt(0)
	v_mfma_f32_32x32x16_bf16 v[0:15], v[114:117], v[102:105], v[0:15]
	s_waitcnt vmcnt(0)
	s_barrier
	v_lshl_add_u64 v[66:67], v[66:67], 0, s[96:97]
	s_add_u32 m0, s94, 0x8000
	s_nop 1
	global_load_lds_dwordx4 v[66:67], off
	v_lshl_add_u64 v[68:69], v[68:69], 0, s[96:97]
	s_add_u32 m0, s94, 0xc000
	s_nop 1
	global_load_lds_dwordx4 v[68:69], off
	v_lshl_add_u64 v[70:71], v[70:71], 0, s[96:97]
	s_add_u32 m0, s94, 0x9000
	s_nop 1
	global_load_lds_dwordx4 v[70:71], off
	v_lshl_add_u64 v[72:73], v[72:73], 0, s[96:97]
	s_add_u32 m0, s94, 0xd000
	s_nop 1
	global_load_lds_dwordx4 v[72:73], off
	v_lshl_add_u64 v[74:75], v[74:75], 0, s[96:97]
	s_add_u32 m0, s94, 0xa000
	s_nop 1
	global_load_lds_dwordx4 v[74:75], off
	v_lshl_add_u64 v[76:77], v[76:77], 0, s[96:97]
	s_add_u32 m0, s94, 0xe000
	s_nop 1
	global_load_lds_dwordx4 v[76:77], off
	v_lshl_add_u64 v[78:79], v[78:79], 0, s[96:97]
	s_add_u32 m0, s94, 0xb000
	s_nop 1
	global_load_lds_dwordx4 v[78:79], off
	v_lshl_add_u64 v[80:81], v[80:81], 0, s[96:97]
	s_add_u32 m0, s94, 0xf000
	s_nop 1
	global_load_lds_dwordx4 v[80:81], off
	v_mfma_f32_32x32x16_bf16 v[16:31], v[114:117], v[110:113], v[16:31]
	ds_read_b128 v[88:91], v170 offset:0
	ds_read_b128 v[92:95], v174 offset:16384
	ds_read_b128 v[98:101], v171 offset:0
	ds_read_b128 v[102:105], v175 offset:16384
	ds_read_b128 v[106:109], v174 offset:20480
	ds_read_b128 v[110:113], v175 offset:20480
	s_waitcnt lgkmcnt(4)
	v_mfma_f32_32x32x16_bf16 v[32:47], v[88:91], v[92:95], v[32:47]
	s_waitcnt lgkmcnt(1)
	v_mfma_f32_32x32x16_bf16 v[48:63], v[88:91], v[106:109], v[48:63]
	ds_read_b128 v[88:91], v170 offset:4096
	ds_read_b128 v[114:117], v171 offset:4096
	s_waitcnt lgkmcnt(1)
	v_mfma_f32_32x32x16_bf16 v[0:15], v[88:91], v[92:95], v[0:15]
	v_mfma_f32_32x32x16_bf16 v[16:31], v[88:91], v[106:109], v[16:31]
	v_mfma_f32_32x32x16_bf16 v[32:47], v[98:101], v[102:105], v[32:47]
	v_mfma_f32_32x32x16_bf16 v[48:63], v[98:101], v[110:113], v[48:63]
	s_waitcnt lgkmcnt(0)
	v_mfma_f32_32x32x16_bf16 v[0:15], v[114:117], v[102:105], v[0:15]
	ds_read_b128 v[88:91], v172 offset:0
	ds_read_b128 v[92:95], v176 offset:16384
	ds_read_b128 v[98:101], v173 offset:0
	ds_read_b128 v[102:105], v177 offset:16384
	v_mfma_f32_32x32x16_bf16 v[16:31], v[114:117], v[110:113], v[16:31]
	ds_read_b128 v[106:109], v176 offset:20480
	ds_read_b128 v[110:113], v177 offset:20480
	s_waitcnt lgkmcnt(4)
	v_mfma_f32_32x32x16_bf16 v[32:47], v[88:91], v[92:95], v[32:47]
	s_waitcnt lgkmcnt(1)
	v_mfma_f32_32x32x16_bf16 v[48:63], v[88:91], v[106:109], v[48:63]
	ds_read_b128 v[88:91], v172 offset:4096
	ds_read_b128 v[114:117], v173 offset:4096
	s_waitcnt lgkmcnt(1)
	v_mfma_f32_32x32x16_bf16 v[0:15], v[88:91], v[92:95], v[0:15]
	v_mfma_f32_32x32x16_bf16 v[16:31], v[88:91], v[106:109], v[16:31]
	v_mfma_f32_32x32x16_bf16 v[32:47], v[98:101], v[102:105], v[32:47]
	v_mfma_f32_32x32x16_bf16 v[48:63], v[98:101], v[110:113], v[48:63]
	s_waitcnt lgkmcnt(0)
	v_mfma_f32_32x32x16_bf16 v[0:15], v[114:117], v[102:105], v[0:15]
	s_waitcnt vmcnt(0)
	s_barrier
;     ...
;   bf16* As1 = As + 2 * 128 * 72;
;   bf16* Bs1 = As1 + 128 * 72;
;   G_LOAD(ra0, rb0, 0);
;   if (nk > 1) G_LOAD(ra1, rb1, 1);
;   G_STORE(ra0, rb0, As, Bs);
;   __syncthreads();
;   for (int kt = 0; kt < nk; kt += 2) {
;     if (kt + 2 < nk) G_LOAD(ra0, rb0, kt + 2);
;     if (kt + 1 < nk) G_STORE(ra1, rb1, As1, Bs1);
;     G_COMPUTE(As, Bs);
;     __syncthreads();
;     if (kt + 1 < nk) {
;       if (kt + 3 < nk) G_LOAD(ra1, rb1, kt + 3);
;       if (kt + 2 < nk) G_STORE(ra0, rb0, As, Bs);
;       G_COMPUTE(As1, Bs1);
;       __syncthreads();
	v_lshl_add_u64 v[66:67], v[66:67], 0, s[96:97]
	s_add_u32 m0, s94, 0x0
	s_nop 1
	global_load_lds_dwordx4 v[66:67], off
	v_lshl_add_u64 v[68:69], v[68:69], 0, s[96:97]
	s_add_u32 m0, s94, 0x4000
	s_nop 1
	global_load_lds_dwordx4 v[68:69], off
	v_lshl_add_u64 v[70:71], v[70:71], 0, s[96:97]
	s_add_u32 m0, s94, 0x1000
	s_nop 1
	global_load_lds_dwordx4 v[70:71], off
	v_lshl_add_u64 v[72:73], v[72:73], 0, s[96:97]
	s_add_u32 m0, s94, 0x5000
	s_nop 1
	global_load_lds_dwordx4 v[72:73], off
	v_lshl_add_u64 v[74:75], v[74:75], 0, s[96:97]
	s_add_u32 m0, s94, 0x2000
	s_nop 1
	global_load_lds_dwordx4 v[74:75], off
	v_lshl_add_u64 v[76:77], v[76:77], 0, s[96:97]
	s_add_u32 m0, s94, 0x6000
	s_nop 1
	global_load_lds_dwordx4 v[76:77], off
	v_lshl_add_u64 v[78:79], v[78:79], 0, s[96:97]
	s_add_u32 m0, s94, 0x3000
	s_nop 1
	global_load_lds_dwordx4 v[78:79], off
	v_lshl_add_u64 v[80:81], v[80:81], 0, s[96:97]
	s_add_u32 m0, s94, 0x7000
	s_nop 1
	global_load_lds_dwordx4 v[80:81], off
	v_mfma_f32_32x32x16_bf16 v[16:31], v[114:117], v[110:113], v[16:31]
	ds_read_b128 v[88:91], v170 offset:32768
	ds_read_b128 v[92:95], v174 offset:49152
	ds_read_b128 v[98:101], v171 offset:32768
	ds_read_b128 v[102:105], v175 offset:49152
	ds_read_b128 v[106:109], v174 offset:53248
	ds_read_b128 v[110:113], v175 offset:53248
	s_waitcnt lgkmcnt(4)
	v_mfma_f32_32x32x16_bf16 v[32:47], v[88:91], v[92:95], v[32:47]
	s_waitcnt lgkmcnt(1)
	v_mfma_f32_32x32x16_bf16 v[48:63], v[88:91], v[106:109], v[48:63]
	ds_read_b128 v[88:91], v170 offset:36864
	ds_read_b128 v[114:117], v171 offset:36864
	s_waitcnt lgkmcnt(1)
	v_mfma_f32_32x32x16_bf16 v[0:15], v[88:91], v[92:95], v[0:15]
	v_mfma_f32_32x32x16_bf16 v[16:31], v[88:91], v[106:109], v[16:31]
	v_mfma_f32_32x32x16_bf16 v[32:47], v[98:101], v[102:105], v[32:47]
	v_mfma_f32_32x32x16_bf16 v[48:63], v[98:101], v[110:113], v[48:63]
	s_waitcnt lgkmcnt(0)
	v_mfma_f32_32x32x16_bf16 v[0:15], v[114:117], v[102:105], v[0:15]
	ds_read_b128 v[88:91], v172 offset:32768
	ds_read_b128 v[92:95], v176 offset:49152
	ds_read_b128 v[98:101], v173 offset:32768
	ds_read_b128 v[102:105], v177 offset:49152
	v_mfma_f32_32x32x16_bf16 v[16:31], v[114:117], v[110:113], v[16:31]
	ds_read_b128 v[106:109], v176 offset:53248
	ds_read_b128 v[110:113], v177 offset:53248
	s_waitcnt lgkmcnt(4)
	v_mfma_f32_32x32x16_bf16 v[32:47], v[88:91], v[92:95], v[32:47]
	s_waitcnt lgkmcnt(1)
	v_mfma_f32_32x32x16_bf16 v[48:63], v[88:91], v[106:109], v[48:63]
	ds_read_b128 v[88:91], v172 offset:36864
	ds_read_b128 v[114:117], v173 offset:36864
	s_waitcnt lgkmcnt(1)
	v_mfma_f32_32x32x16_bf16 v[0:15], v[88:91], v[92:95], v[0:15]
	v_mfma_f32_32x32x16_bf16 v[16:31], v[88:91], v[106:109], v[16:31]
	v_mfma_f32_32x32x16_bf16 v[32:47], v[98:101], v[102:105], v[32:47]
	v_mfma_f32_32x32x16_bf16 v[48:63], v[98:101], v[110:113], v[48:63]
	s_waitcnt lgkmcnt(0)
	v_mfma_f32_32x32x16_bf16 v[0:15], v[114:117], v[102:105], v[0:15]
	s_waitcnt vmcnt(0)
	s_barrier
	v_lshl_add_u64 v[66:67], v[66:67], 0, s[96:97]
	s_add_u32 m0, s94, 0x8000
	s_nop 1
	global_load_lds_dwordx4 v[66:67], off
	v_lshl_add_u64 v[68:69], v[68:69], 0, s[96:97]
	s_add_u32 m0, s94, 0xc000
	s_nop 1
	global_load_lds_dwordx4 v[68:69], off
	v_lshl_add_u64 v[70:71], v[70:71], 0, s[96:97]
	s_add_u32 m0, s94, 0x9000
	s_nop 1
	global_load_lds_dwordx4 v[70:71], off
	v_lshl_add_u64 v[72:73], v[72:73], 0, s[96:97]
	s_add_u32 m0, s94, 0xd000
	s_nop 1
	global_load_lds_dwordx4 v[72:73], off
	v_lshl_add_u64 v[74:75], v[74:75], 0, s[96:97]
	s_add_u32 m0, s94, 0xa000
	s_nop 1
	global_load_lds_dwordx4 v[74:75], off
	v_lshl_add_u64 v[76:77], v[76:77], 0, s[96:97]
	s_add_u32 m0, s94, 0xe000
	s_nop 1
	global_load_lds_dwordx4 v[76:77], off
	v_lshl_add_u64 v[78:79], v[78:79], 0, s[96:97]
	s_add_u32 m0, s94, 0xb000
	s_nop 1
	global_load_lds_dwordx4 v[78:79], off
	v_lshl_add_u64 v[80:81], v[80:81], 0, s[96:97]
	s_add_u32 m0, s94, 0xf000
	s_nop 1
	global_load_lds_dwordx4 v[80:81], off
	v_mfma_f32_32x32x16_bf16 v[16:31], v[114:117], v[110:113], v[16:31]
	ds_read_b128 v[88:91], v170 offset:0
	ds_read_b128 v[92:95], v174 offset:16384
	ds_read_b128 v[98:101], v171 offset:0
	ds_read_b128 v[102:105], v175 offset:16384
	ds_read_b128 v[106:109], v174 offset:20480
	ds_read_b128 v[110:113], v175 offset:20480
	s_waitcnt lgkmcnt(4)
	v_mfma_f32_32x32x16_bf16 v[32:47], v[88:91], v[92:95], v[32:47]
	s_waitcnt lgkmcnt(1)
	v_mfma_f32_32x32x16_bf16 v[48:63], v[88:91], v[106:109], v[48:63]
	ds_read_b128 v[88:91], v170 offset:4096
	ds_read_b128 v[114:117], v171 offset:4096
	s_waitcnt lgkmcnt(1)
	v_mfma_f32_32x32x16_bf16 v[0:15], v[88:91], v[92:95], v[0:15]
	v_mfma_f32_32x32x16_bf16 v[16:31], v[88:91], v[106:109], v[16:31]
	v_mfma_f32_32x32x16_bf16 v[32:47], v[98:101], v[102:105], v[32:47]
	v_mfma_f32_32x32x16_bf16 v[48:63], v[98:101], v[110:113], v[48:63]
	s_waitcnt lgkmcnt(0)
	v_mfma_f32_32x32x16_bf16 v[0:15], v[114:117], v[102:105], v[0:15]
	ds_read_b128 v[88:91], v172 offset:0
	ds_read_b128 v[92:95], v176 offset:16384
	ds_read_b128 v[98:101], v173 offset:0
	ds_read_b128 v[102:105], v177 offset:16384
	v_mfma_f32_32x32x16_bf16 v[16:31], v[114:117], v[110:113], v[16:31]
	ds_read_b128 v[106:109], v176 offset:20480
	ds_read_b128 v[110:113], v177 offset:20480
	s_waitcnt lgkmcnt(4)
	v_mfma_f32_32x32x16_bf16 v[32:47], v[88:91], v[92:95], v[32:47]
	s_waitcnt lgkmcnt(1)
	v_mfma_f32_32x32x16_bf16 v[48:63], v[88:91], v[106:109], v[48:63]
	ds_read_b128 v[88:91], v172 offset:4096
	ds_read_b128 v[114:117], v173 offset:4096
	s_waitcnt lgkmcnt(1)
	v_mfma_f32_32x32x16_bf16 v[0:15], v[88:91], v[92:95], v[0:15]
	v_mfma_f32_32x32x16_bf16 v[16:31], v[88:91], v[106:109], v[16:31]
	v_mfma_f32_32x32x16_bf16 v[32:47], v[98:101], v[102:105], v[32:47]
	v_mfma_f32_32x32x16_bf16 v[48:63], v[98:101], v[110:113], v[48:63]
	s_waitcnt lgkmcnt(0)
	v_mfma_f32_32x32x16_bf16 v[0:15], v[114:117], v[102:105], v[0:15]
	s_waitcnt vmcnt(0)
	s_barrier
;     ...
;   bf16* As1 = As + 2 * 128 * 72;
;   bf16* Bs1 = As1 + 128 * 72;
;   G_LOAD(ra0, rb0, 0);
;   if (nk > 1) G_LOAD(ra1, rb1, 1);
;   G_STORE(ra0, rb0, As, Bs);
;   __syncthreads();
;   for (int kt = 0; kt < nk; kt += 2) {
;     if (kt + 2 < nk) G_LOAD(ra0, rb0, kt + 2);
;     if (kt + 1 < nk) G_STORE(ra1, rb1, As1, Bs1);
;     G_COMPUTE(As, Bs);
;     __syncthreads();
;     if (kt + 1 < nk) {
;       if (kt + 3 < nk) G_LOAD(ra1, rb1, kt + 3);
;       if (kt + 2 < nk) G_STORE(ra0, rb0, As, Bs);
;       G_COMPUTE(As1, Bs1);
;       __syncthreads();
	v_lshl_add_u64 v[66:67], v[66:67], 0, s[96:97]
	s_add_u32 m0, s94, 0x0
	s_nop 1
	global_load_lds_dwordx4 v[66:67], off
	v_lshl_add_u64 v[68:69], v[68:69], 0, s[96:97]
	s_add_u32 m0, s94, 0x4000
	s_nop 1
	global_load_lds_dwordx4 v[68:69], off
	v_lshl_add_u64 v[70:71], v[70:71], 0, s[96:97]
	s_add_u32 m0, s94, 0x1000
	s_nop 1
	global_load_lds_dwordx4 v[70:71], off
	v_lshl_add_u64 v[72:73], v[72:73], 0, s[96:97]
	s_add_u32 m0, s94, 0x5000
	s_nop 1
	global_load_lds_dwordx4 v[72:73], off
	v_lshl_add_u64 v[74:75], v[74:75], 0, s[96:97]
	s_add_u32 m0, s94, 0x2000
	s_nop 1
	global_load_lds_dwordx4 v[74:75], off
	v_lshl_add_u64 v[76:77], v[76:77], 0, s[96:97]
	s_add_u32 m0, s94, 0x6000
	s_nop 1
	global_load_lds_dwordx4 v[76:77], off
	v_lshl_add_u64 v[78:79], v[78:79], 0, s[96:97]
	s_add_u32 m0, s94, 0x3000
	s_nop 1
	global_load_lds_dwordx4 v[78:79], off
	v_lshl_add_u64 v[80:81], v[80:81], 0, s[96:97]
	s_add_u32 m0, s94, 0x7000
	s_nop 1
	global_load_lds_dwordx4 v[80:81], off
	v_mfma_f32_32x32x16_bf16 v[16:31], v[114:117], v[110:113], v[16:31]
	ds_read_b128 v[88:91], v170 offset:32768
	ds_read_b128 v[92:95], v174 offset:49152
	ds_read_b128 v[98:101], v171 offset:32768
	ds_read_b128 v[102:105], v175 offset:49152
	ds_read_b128 v[106:109], v174 offset:53248
	ds_read_b128 v[110:113], v175 offset:53248
	s_waitcnt lgkmcnt(4)
	v_mfma_f32_32x32x16_bf16 v[32:47], v[88:91], v[92:95], v[32:47]
	s_waitcnt lgkmcnt(1)
	v_mfma_f32_32x32x16_bf16 v[48:63], v[88:91], v[106:109], v[48:63]
	ds_read_b128 v[88:91], v170 offset:36864
	ds_read_b128 v[114:117], v171 offset:36864
	s_waitcnt lgkmcnt(1)
	v_mfma_f32_32x32x16_bf16 v[0:15], v[88:91], v[92:95], v[0:15]
	v_mfma_f32_32x32x16_bf16 v[16:31], v[88:91], v[106:109], v[16:31]
	v_mfma_f32_32x32x16_bf16 v[32:47], v[98:101], v[102:105], v[32:47]
	v_mfma_f32_32x32x16_bf16 v[48:63], v[98:101], v[110:113], v[48:63]
	s_waitcnt lgkmcnt(0)
	v_mfma_f32_32x32x16_bf16 v[0:15], v[114:117], v[102:105], v[0:15]
	ds_read_b128 v[88:91], v172 offset:32768
	ds_read_b128 v[92:95], v176 offset:49152
	ds_read_b128 v[98:101], v173 offset:32768
	ds_read_b128 v[102:105], v177 offset:49152
	v_mfma_f32_32x32x16_bf16 v[16:31], v[114:117], v[110:113], v[16:31]
	ds_read_b128 v[106:109], v176 offset:53248
	ds_read_b128 v[110:113], v177 offset:53248
	s_waitcnt lgkmcnt(4)
	v_mfma_f32_32x32x16_bf16 v[32:47], v[88:91], v[92:95], v[32:47]
	s_waitcnt lgkmcnt(1)
	v_mfma_f32_32x32x16_bf16 v[48:63], v[88:91], v[106:109], v[48:63]
	ds_read_b128 v[88:91], v172 offset:36864
	ds_read_b128 v[114:117], v173 offset:36864
	s_waitcnt lgkmcnt(1)
	v_mfma_f32_32x32x16_bf16 v[0:15], v[88:91], v[92:95], v[0:15]
	v_mfma_f32_32x32x16_bf16 v[16:31], v[88:91], v[106:109], v[16:31]
	v_mfma_f32_32x32x16_bf16 v[32:47], v[98:101], v[102:105], v[32:47]
	v_mfma_f32_32x32x16_bf16 v[48:63], v[98:101], v[110:113], v[48:63]
	s_waitcnt lgkmcnt(0)
	v_mfma_f32_32x32x16_bf16 v[0:15], v[114:117], v[102:105], v[0:15]
	s_waitcnt vmcnt(0)
	s_barrier
	v_lshl_add_u64 v[66:67], v[66:67], 0, s[96:97]
	s_add_u32 m0, s94, 0x8000
	s_nop 1
	global_load_lds_dwordx4 v[66:67], off
	v_lshl_add_u64 v[68:69], v[68:69], 0, s[96:97]
	s_add_u32 m0, s94, 0xc000
	s_nop 1
	global_load_lds_dwordx4 v[68:69], off
	v_lshl_add_u64 v[70:71], v[70:71], 0, s[96:97]
	s_add_u32 m0, s94, 0x9000
	s_nop 1
	global_load_lds_dwordx4 v[70:71], off
	v_lshl_add_u64 v[72:73], v[72:73], 0, s[96:97]
	s_add_u32 m0, s94, 0xd000
	s_nop 1
	global_load_lds_dwordx4 v[72:73], off
	v_lshl_add_u64 v[74:75], v[74:75], 0, s[96:97]
	s_add_u32 m0, s94, 0xa000
	s_nop 1
	global_load_lds_dwordx4 v[74:75], off
	v_lshl_add_u64 v[76:77], v[76:77], 0, s[96:97]
	s_add_u32 m0, s94, 0xe000
	s_nop 1
	global_load_lds_dwordx4 v[76:77], off
	v_lshl_add_u64 v[78:79], v[78:79], 0, s[96:97]
	s_add_u32 m0, s94, 0xb000
	s_nop 1
	global_load_lds_dwordx4 v[78:79], off
	v_lshl_add_u64 v[80:81], v[80:81], 0, s[96:97]
	s_add_u32 m0, s94, 0xf000
	s_nop 1
	global_load_lds_dwordx4 v[80:81], off
	v_mfma_f32_32x32x16_bf16 v[16:31], v[114:117], v[110:113], v[16:31]
	ds_read_b128 v[88:91], v170 offset:0
	ds_read_b128 v[92:95], v174 offset:16384
	ds_read_b128 v[98:101], v171 offset:0
	ds_read_b128 v[102:105], v175 offset:16384
	ds_read_b128 v[106:109], v174 offset:20480
	ds_read_b128 v[110:113], v175 offset:20480
	s_waitcnt lgkmcnt(4)
	v_mfma_f32_32x32x16_bf16 v[32:47], v[88:91], v[92:95], v[32:47]
	s_waitcnt lgkmcnt(1)
	v_mfma_f32_32x32x16_bf16 v[48:63], v[88:91], v[106:109], v[48:63]
	ds_read_b128 v[88:91], v170 offset:4096
	ds_read_b128 v[114:117], v171 offset:4096
	s_waitcnt lgkmcnt(1)
	v_mfma_f32_32x32x16_bf16 v[0:15], v[88:91], v[92:95], v[0:15]
	v_mfma_f32_32x32x16_bf16 v[16:31], v[88:91], v[106:109], v[16:31]
	v_mfma_f32_32x32x16_bf16 v[32:47], v[98:101], v[102:105], v[32:47]
	v_mfma_f32_32x32x16_bf16 v[48:63], v[98:101], v[110:113], v[48:63]
	s_waitcnt lgkmcnt(0)
	v_mfma_f32_32x32x16_bf16 v[0:15], v[114:117], v[102:105], v[0:15]
	ds_read_b128 v[88:91], v172 offset:0
	ds_read_b128 v[92:95], v176 offset:16384
	ds_read_b128 v[98:101], v173 offset:0
	ds_read_b128 v[102:105], v177 offset:16384
	v_mfma_f32_32x32x16_bf16 v[16:31], v[114:117], v[110:113], v[16:31]
	ds_read_b128 v[106:109], v176 offset:20480
	ds_read_b128 v[110:113], v177 offset:20480
	s_waitcnt lgkmcnt(4)
	v_mfma_f32_32x32x16_bf16 v[32:47], v[88:91], v[92:95], v[32:47]
	s_waitcnt lgkmcnt(1)
	v_mfma_f32_32x32x16_bf16 v[48:63], v[88:91], v[106:109], v[48:63]
	ds_read_b128 v[88:91], v172 offset:4096
	ds_read_b128 v[114:117], v173 offset:4096
	s_waitcnt lgkmcnt(1)
	v_mfma_f32_32x32x16_bf16 v[0:15], v[88:91], v[92:95], v[0:15]
	v_mfma_f32_32x32x16_bf16 v[16:31], v[88:91], v[106:109], v[16:31]
	v_mfma_f32_32x32x16_bf16 v[32:47], v[98:101], v[102:105], v[32:47]
	v_mfma_f32_32x32x16_bf16 v[48:63], v[98:101], v[110:113], v[48:63]
	s_waitcnt lgkmcnt(0)
	v_mfma_f32_32x32x16_bf16 v[0:15], v[114:117], v[102:105], v[0:15]
	s_waitcnt vmcnt(0)
	s_barrier
;     ...
;   bf16* As1 = As + 2 * 128 * 72;
;   bf16* Bs1 = As1 + 128 * 72;
;   G_LOAD(ra0, rb0, 0);
;   if (nk > 1) G_LOAD(ra1, rb1, 1);
;   G_STORE(ra0, rb0, As, Bs);
;   __syncthreads();
;   for (int kt = 0; kt < nk; kt += 2) {
;     if (kt + 2 < nk) G_LOAD(ra0, rb0, kt + 2);
;     if (kt + 1 < nk) G_STORE(ra1, rb1, As1, Bs1);
;     G_COMPUTE(As, Bs);
;     __syncthreads();
;     if (kt + 1 < nk) {
;       if (kt + 3 < nk) G_LOAD(ra1, rb1, kt + 3);
;       if (kt + 2 < nk) G_STORE(ra0, rb0, As, Bs);
;       G_COMPUTE(As1, Bs1);
;       __syncthreads();
	v_lshl_add_u64 v[66:67], v[66:67], 0, s[96:97]
	s_add_u32 m0, s94, 0x0
	s_nop 1
	global_load_lds_dwordx4 v[66:67], off
	v_lshl_add_u64 v[68:69], v[68:69], 0, s[96:97]
	s_add_u32 m0, s94, 0x4000
	s_nop 1
	global_load_lds_dwordx4 v[68:69], off
	v_lshl_add_u64 v[70:71], v[70:71], 0, s[96:97]
	s_add_u32 m0, s94, 0x1000
	s_nop 1
	global_load_lds_dwordx4 v[70:71], off
	v_lshl_add_u64 v[72:73], v[72:73], 0, s[96:97]
	s_add_u32 m0, s94, 0x5000
	s_nop 1
	global_load_lds_dwordx4 v[72:73], off
	v_lshl_add_u64 v[74:75], v[74:75], 0, s[96:97]
	s_add_u32 m0, s94, 0x2000
	s_nop 1
	global_load_lds_dwordx4 v[74:75], off
	v_lshl_add_u64 v[76:77], v[76:77], 0, s[96:97]
	s_add_u32 m0, s94, 0x6000
	s_nop 1
	global_load_lds_dwordx4 v[76:77], off
	v_lshl_add_u64 v[78:79], v[78:79], 0, s[96:97]
	s_add_u32 m0, s94, 0x3000
	s_nop 1
	global_load_lds_dwordx4 v[78:79], off
	v_lshl_add_u64 v[80:81], v[80:81], 0, s[96:97]
	s_add_u32 m0, s94, 0x7000
	s_nop 1
	global_load_lds_dwordx4 v[80:81], off
	v_mfma_f32_32x32x16_bf16 v[16:31], v[114:117], v[110:113], v[16:31]
	ds_read_b128 v[88:91], v170 offset:32768
	ds_read_b128 v[92:95], v174 offset:49152
	ds_read_b128 v[98:101], v171 offset:32768
	ds_read_b128 v[102:105], v175 offset:49152
	ds_read_b128 v[106:109], v174 offset:53248
	ds_read_b128 v[110:113], v175 offset:53248
	s_waitcnt lgkmcnt(4)
	v_mfma_f32_32x32x16_bf16 v[32:47], v[88:91], v[92:95], v[32:47]
	s_waitcnt lgkmcnt(1)
	v_mfma_f32_32x32x16_bf16 v[48:63], v[88:91], v[106:109], v[48:63]
	ds_read_b128 v[88:91], v170 offset:36864
	ds_read_b128 v[114:117], v171 offset:36864
	s_waitcnt lgkmcnt(1)
	v_mfma_f32_32x32x16_bf16 v[0:15], v[88:91], v[92:95], v[0:15]
	v_mfma_f32_32x32x16_bf16 v[16:31], v[88:91], v[106:109], v[16:31]
	v_mfma_f32_32x32x16_bf16 v[32:47], v[98:101], v[102:105], v[32:47]
	v_mfma_f32_32x32x16_bf16 v[48:63], v[98:101], v[110:113], v[48:63]
	s_waitcnt lgkmcnt(0)
	v_mfma_f32_32x32x16_bf16 v[0:15], v[114:117], v[102:105], v[0:15]
	ds_read_b128 v[88:91], v172 offset:32768
	ds_read_b128 v[92:95], v176 offset:49152
	ds_read_b128 v[98:101], v173 offset:32768
	ds_read_b128 v[102:105], v177 offset:49152
	v_mfma_f32_32x32x16_bf16 v[16:31], v[114:117], v[110:113], v[16:31]
	ds_read_b128 v[106:109], v176 offset:53248
	ds_read_b128 v[110:113], v177 offset:53248
	s_waitcnt lgkmcnt(4)
	v_mfma_f32_32x32x16_bf16 v[32:47], v[88:91], v[92:95], v[32:47]
	s_waitcnt lgkmcnt(1)
	v_mfma_f32_32x32x16_bf16 v[48:63], v[88:91], v[106:109], v[48:63]
	ds_read_b128 v[88:91], v172 offset:36864
	ds_read_b128 v[114:117], v173 offset:36864
	s_waitcnt lgkmcnt(1)
	v_mfma_f32_32x32x16_bf16 v[0:15], v[88:91], v[92:95], v[0:15]
	v_mfma_f32_32x32x16_bf16 v[16:31], v[88:91], v[106:109], v[16:31]
	v_mfma_f32_32x32x16_bf16 v[32:47], v[98:101], v[102:105], v[32:47]
	v_mfma_f32_32x32x16_bf16 v[48:63], v[98:101], v[110:113], v[48:63]
	s_nop 0
	s_nop 0
	s_nop 0
	s_nop 0
	s_nop 0
	s_nop 0
	s_nop 0
	s_waitcnt lgkmcnt(0)
	s_waitcnt vmcnt(0)
	s_barrier
	v_lshl_add_u64 v[66:67], v[66:67], 0, s[96:97]
	s_add_u32 m0, s94, 0x8000
	s_nop 1
	global_load_lds_dwordx4 v[66:67], off
	v_lshl_add_u64 v[68:69], v[68:69], 0, s[96:97]
	s_add_u32 m0, s94, 0xc000
	s_nop 1
	global_load_lds_dwordx4 v[68:69], off
	v_lshl_add_u64 v[70:71], v[70:71], 0, s[96:97]
	s_add_u32 m0, s94, 0x9000
	s_nop 1
	global_load_lds_dwordx4 v[70:71], off
	v_lshl_add_u64 v[72:73], v[72:73], 0, s[96:97]
	s_add_u32 m0, s94, 0xd000
	s_nop 1
	global_load_lds_dwordx4 v[72:73], off
	v_lshl_add_u64 v[74:75], v[74:75], 0, s[96:97]
	s_add_u32 m0, s94, 0xa000
	s_nop 1
	global_load_lds_dwordx4 v[74:75], off
	v_lshl_add_u64 v[76:77], v[76:77], 0, s[96:97]
	s_add_u32 m0, s94, 0xe000
	s_nop 1
	global_load_lds_dwordx4 v[76:77], off
	v_lshl_add_u64 v[78:79], v[78:79], 0, s[96:97]
	s_add_u32 m0, s94, 0xb000
	s_nop 1
	global_load_lds_dwordx4 v[78:79], off
	v_lshl_add_u64 v[80:81], v[80:81], 0, s[96:97]
	s_add_u32 m0, s94, 0xf000
	s_nop 1
	global_load_lds_dwordx4 v[80:81], off
	v_mfma_f32_32x32x16_bf16 v[0:15], v[114:117], v[102:105], v[0:15]
	ds_read_b128 v[66:69], v170 offset:0
	ds_read_b128 v[70:73], v174 offset:16384
	ds_read_b128 v[74:77], v171 offset:0
	ds_read_b128 v[78:81], v175 offset:16384
	ds_read_b128 v[88:91], v174 offset:20480
	ds_read_b128 v[92:95], v175 offset:20480
	v_mfma_f32_32x32x16_bf16 v[16:31], v[114:117], v[110:113], v[16:31]
	s_waitcnt lgkmcnt(4)
	v_mfma_f32_32x32x16_bf16 v[32:47], v[66:69], v[70:73], v[32:47]
	s_waitcnt lgkmcnt(1)
	v_mfma_f32_32x32x16_bf16 v[48:63], v[66:69], v[88:91], v[48:63]
	ds_read_b128 v[66:69], v170 offset:4096
	ds_read_b128 v[98:101], v171 offset:4096
	s_waitcnt lgkmcnt(1)
	v_mfma_f32_32x32x16_bf16 v[0:15], v[66:69], v[70:73], v[0:15]
	v_mfma_f32_32x32x16_bf16 v[16:31], v[66:69], v[88:91], v[16:31]
	v_mfma_f32_32x32x16_bf16 v[32:47], v[74:77], v[78:81], v[32:47]
	v_mfma_f32_32x32x16_bf16 v[48:63], v[74:77], v[92:95], v[48:63]
	s_waitcnt lgkmcnt(0)
	v_mfma_f32_32x32x16_bf16 v[0:15], v[98:101], v[78:81], v[0:15]
	ds_read_b128 v[66:69], v172 offset:0
	ds_read_b128 v[70:73], v176 offset:16384
	ds_read_b128 v[74:77], v173 offset:0
	ds_read_b128 v[78:81], v177 offset:16384
	v_mfma_f32_32x32x16_bf16 v[16:31], v[98:101], v[92:95], v[16:31]
	ds_read_b128 v[88:91], v176 offset:20480
	ds_read_b128 v[92:95], v177 offset:20480
	s_waitcnt lgkmcnt(4)
	v_mfma_f32_32x32x16_bf16 v[32:47], v[66:69], v[70:73], v[32:47]
	s_waitcnt lgkmcnt(1)
	v_mfma_f32_32x32x16_bf16 v[48:63], v[66:69], v[88:91], v[48:63]
	ds_read_b128 v[66:69], v172 offset:4096
	ds_read_b128 v[98:101], v173 offset:4096
	s_waitcnt lgkmcnt(0)
	s_waitcnt vmcnt(0)
	s_barrier
; #define PW(T, off) ((T*)(lndp(p.ws) + (off)))
; DEVI void gemm_epi_qkv(const Params& p, f32x16 (&acc)[2][2], int rbase, int cbase, int lane) {
;   char* ar = PW(char, W_arena);
;   const int which = cbase >> 10, cc = cbase & 1023, d = lane & 31, hl = lane >> 5;
; #pragma unroll
;   for (int i = 0; i < 2; ++i) {
; #pragma unroll
;     for (int rq = 0; rq < 4; ++rq) {
;       const int row0 = rbase + i * 32 + 8 * rq + 4 * hl;
;       if (row0 >= M) continue;
;       const bool pr = row0 < TP;
;       const int b = pr ? 0 : (row0 - TP) >> 4, t0 = pr ? row0 : (row0 - TP) & 15;
;       if (which < 2) {
;     ...
;   for (int kt = 0; kt < nk; kt += 2) {
;     if (kt + 2 < nk) G_LOAD(ra0, rb0, kt + 2);
;     if (kt + 1 < nk) G_STORE(ra1, rb1, As1, Bs1);
;     G_COMPUTE(As, Bs);
;     __syncthreads();
;     if (kt + 1 < nk) {
;       if (kt + 3 < nk) G_LOAD(ra1, rb1, kt + 3);
;       if (kt + 2 < nk) G_STORE(ra0, rb0, As, Bs);
;       G_COMPUTE(As1, Bs1);
;       __syncthreads();
;     }
;   }
	v_mfma_f32_32x32x16_bf16 v[0:15], v[66:69], v[70:73], v[0:15]
	v_mfma_f32_32x32x16_bf16 v[32:47], v[74:77], v[78:81], v[32:47]
	v_mfma_f32_32x32x16_bf16 v[48:63], v[74:77], v[92:95], v[48:63]
	v_mfma_f32_32x32x16_bf16 v[16:31], v[66:69], v[88:91], v[16:31]
	v_mfma_f32_32x32x16_bf16 v[0:15], v[98:101], v[78:81], v[0:15]
	ds_read_b128 v[66:69], v170 offset:32768
	ds_read_b128 v[70:73], v174 offset:49152
	ds_read_b128 v[74:77], v175 offset:49152
	ds_read_b128 v[78:81], v171 offset:32768
	ds_read_b128 v[88:91], v174 offset:53248
	s_waitcnt lgkmcnt(3)
	v_mfma_f32_32x32x16_bf16 v[32:47], v[66:69], v[70:73], v[32:47]
	s_waitcnt lgkmcnt(0)
	v_mfma_f32_32x32x16_bf16 v[48:63], v[66:69], v[88:91], v[48:63]
	ds_read_b128 v[66:69], v170 offset:36864
	v_mfma_f32_32x32x16_bf16 v[16:31], v[98:101], v[92:95], v[16:31]
	s_waitcnt lgkmcnt(0)
	v_mfma_f32_32x32x16_bf16 v[0:15], v[66:69], v[70:73], v[0:15]
	ds_read_b128 v[70:73], v171 offset:36864
	v_mfma_f32_32x32x16_bf16 v[16:31], v[66:69], v[88:91], v[16:31]
	ds_read_b128 v[66:69], v175 offset:53248
	v_mfma_f32_32x32x16_bf16 v[32:47], v[78:81], v[74:77], v[32:47]
	s_waitcnt lgkmcnt(0)
	v_mfma_f32_32x32x16_bf16 v[48:63], v[78:81], v[66:69], v[48:63]
	v_or_b32_e32 v81, s6, v65
	v_and_or_b32 v80, v85, 64, s6
	s_mov_b64 s[6:7], 0x1e05c060
	v_mfma_f32_32x32x16_bf16 v[0:15], v[70:73], v[74:77], v[0:15]
	v_mfma_f32_32x32x16_bf16 v[16:31], v[70:73], v[66:69], v[16:31]
	ds_read_b128 v[66:69], v172 offset:32768
	ds_read_b128 v[70:73], v176 offset:49152
	ds_read_b128 v[74:77], v176 offset:53248
	s_waitcnt lgkmcnt(1)
	v_mfma_f32_32x32x16_bf16 v[32:47], v[66:69], v[70:73], v[32:47]
	s_waitcnt lgkmcnt(0)
	v_mfma_f32_32x32x16_bf16 v[48:63], v[66:69], v[74:77], v[48:63]
	ds_read_b128 v[66:69], v172 offset:36864
	s_waitcnt lgkmcnt(0)
	v_mfma_f32_32x32x16_bf16 v[0:15], v[66:69], v[70:73], v[0:15]
	ds_read_b128 v[88:91], v177 offset:53248
	ds_read_b128 v[92:95], v177 offset:49152
	ds_read_b128 v[70:73], v173 offset:32768
	v_mfma_f32_32x32x16_bf16 v[16:31], v[66:69], v[74:77], v[16:31]
	ds_read_b128 v[74:77], v173 offset:36864
	v_lshrrev_b32_e32 v66, 3, v85
	v_add_u32_e32 v64, s3, v86
	v_and_b32_e32 v82, 4, v66
	v_or_b32_e32 v68, v64, v82
	v_mul_u32_u24_e32 v64, 0x4040, v81
	v_lshlrev_b32_e32 v96, 1, v64
	s_waitcnt lgkmcnt(1)
	v_mfma_f32_32x32x16_bf16 v[32:47], v[70:73], v[92:95], v[32:47]
	s_waitcnt lgkmcnt(0)
	s_barrier
	s_cmp_gt_i32 s5, 1
	s_cselect_b64 s[2:3], -1, 0
	v_lshl_add_u64 v[64:65], s[20:21], 0, v[96:97]
	v_lshlrev_b32_e32 v96, 1, v80
	v_mfma_f32_32x32x16_bf16 v[48:63], v[70:73], v[88:91], v[48:63]
	v_lshl_add_u64 v[70:71], v[64:65], 0, s[6:7]
	s_cmpk_gt_u32 s4, 0x3ff
	v_lshl_add_u64 v[64:65], s[20:21], 0, v[96:97]
	s_mov_b64 s[6:7], 0x13e3c000
	s_cselect_b64 s[18:19], -1, 0
	v_lshl_add_u64 v[66:67], v[64:65], 0, s[6:7]
	s_mov_b64 s[6:7], 0x11d7c000
	v_mfma_f32_32x32x16_bf16 v[0:15], v[74:77], v[92:95], v[0:15]
	s_cmp_eq_u32 s5, 1
	v_lshl_add_u64 v[64:65], v[64:65], 0, s[6:7]
	s_cselect_b64 s[16:17], -1, 0
	v_cmp_gt_i32_e32 vcc, s90, v68
	v_mfma_f32_32x32x16_bf16 v[16:31], v[74:77], v[88:91], v[16:31]
	s_and_saveexec_b64 s[4:5], vcc
	s_cbranch_execz .LBB0_1851
	s_movk_i32 s6, 0x400f
	v_add_u32_e32 v72, 0xffffbff0, v68
	v_cmp_lt_i32_e64 s[6:7], s6, v68
	v_ashrrev_i32_e32 v78, 4, v72
	s_mov_b64 s[8:9], -1
	s_and_b64 vcc, exec, s[2:3]
	s_cbranch_vccz .LBB0_1830
	s_and_saveexec_b64 s[8:9], s[6:7]
	s_xor_b64 s[8:9], exec, s[8:9]
	s_cbranch_execz .LBB0_1823
	s_mov_b64 s[10:11], s[72:73]
	s_add_u32 s10, s10, 0xc48f000
	v_mov_b32_e32 v73, v97
	s_addc_u32 s11, s11, 0
	v_mov_b64_e32 v[74:75], v[72:73]

;     ...
;   const int lrow = tid >> 3, lkc = (tid & 7) * 8;
;   const bf16* Ag = jb.A + (size_t)max(m0 + lrow, 0) * jb.lda + lkc;
;   const bf16* Ag1 = jb.A + (ptrdiff_t)(m0 + lrow) * jb.lda + lkc;
;   const bf16* Bg = jb.Bt + (size_t)(n0 + lrow) * jb.K + lkc;
;   const size_t astep = (size_t)32 * jb.lda, bstep = (size_t)32 * jb.K;
;   if (kt1 < 0) kt1 = jb.K >> 6;
;   const int nk = kt1 - kt0;
;   Ag += (size_t)kt0 * 64; Ag1 += (size_t)kt0 * 64; Bg += (size_t)kt0 * 64;
;   u32x4 ra0[4], rb0[4], ra1[4], rb1[4];
;     ...
;   bf16* As1 = As + 2 * 128 * 72;
;   bf16* Bs1 = As1 + 128 * 72;
;   G_LOAD(ra0, rb0, 0);
;   if (nk > 1) G_LOAD(ra1, rb1, 1);
;   G_STORE(ra0, rb0, As, Bs);
;   __syncthreads();
.LBB0_2081:
	s_mul_hi_i32 s2, s17, 0x2aaaaaab
	s_lshr_b32 s3, s2, 31
	s_ashr_i32 s2, s2, 6
	s_add_i32 s2, s2, s3
	s_lshl_b32 s3, s2, 4
	s_sub_i32 s4, 0x83, s3
	s_min_u32 s4, s4, 16
	v_cvt_f32_ubyte0_e32 v0, s4
	v_rcp_iflag_f32_e32 v0, v0
	s_sub_i32 s7, 0, s4
	s_mulk_i32 s2, 0xfe80
	s_add_i32 s5, s17, s2
	v_mul_f32_e32 v0, 0x4f7ffffe, v0
	v_cvt_u32_f32_e32 v0, v0
	s_abs_i32 s6, s5
	s_ashr_i32 s2, s5, 31
	s_waitcnt vmcnt(2)
	v_mov_b32_e32 v85, v208
	v_readfirstlane_b32 s8, v0
	s_mul_i32 s7, s7, s8
	s_mul_hi_u32 s7, s8, s7
	s_add_i32 s8, s8, s7
	s_mul_hi_u32 s7, s6, s8
	s_mul_i32 s8, s7, s4
	s_sub_i32 s6, s6, s8
	s_add_i32 s8, s7, 1
	s_sub_i32 s9, s6, s4
	s_cmp_ge_u32 s6, s4
	s_cselect_b32 s7, s8, s7
	s_cselect_b32 s6, s9, s6
	s_add_i32 s8, s7, 1
	s_cmp_ge_u32 s6, s4
	s_cselect_b32 s6, s8, s7
	s_xor_b32 s6, s6, s2
	s_sub_i32 s2, s6, s2
	s_mul_i32 s4, s2, s4
	s_sub_i32 s4, s5, s4
	s_add_i32 s3, s3, s4
	s_lshl_b32 s3, s3, 7
	s_lshl_b32 s4, s2, 7
	v_ashrrev_i32_e32 v82, 3, v85
	v_add_u32_e32 v0, s3, v82
	v_max_i32_e32 v96, 0, v0
	v_lshlrev_b32_e32 v1, 4, v85
	v_lshlrev_b64 v[2:3], 11, v[96:97]
	v_and_b32_e32 v96, 0x70, v1
	s_mov_b64 s[96:97], 0x80
	v_lshrrev_b32_e32 v178, 4, v208
	v_and_b32_e32 v178, 7, v178
	v_lshlrev_b32_e32 v178, 4, v178
	v_xor_b32_e32 v96, v96, v178
	v_lshrrev_b32_e32 v179, 6, v208
	v_lshlrev_b32_e32 v179, 10, v179
	v_lshrrev_b32_e32 v180, 5, v208
	v_lshrrev_b32_e32 v181, 1, v208
	v_xor_b32_e32 v180, v180, v181
	v_readfirstlane_b32 s94, v179
	v_and_b32_e32 v180, 1, v180
	v_lshlrev_b32_e32 v180, 4, v180
	v_and_b32_e32 v181, 31, v208
	v_lshlrev_b32_e32 v181, 7, v181
	v_or_b32_e32 v180, v180, v181
	v_lshrrev_b32_e32 v181, 7, v208
	v_lshlrev_b32_e32 v181, 13, v181
	v_or_b32_e32 v194, v180, v181
	v_bfe_u32 v181, v208, 6, 1
	v_lshlrev_b32_e32 v181, 13, v181
	v_or_b32_e32 v195, v180, v181
	v_bfe_u32 v178, v208, 2, 2
	v_xor_b32_e32 v179, 0, v178
	v_lshlrev_b32_e32 v179, 5, v179
	v_or_b32_e32 v170, v194, v179
	v_or_b32_e32 v174, v195, v179
	v_xor_b32_e32 v179, 1, v178
	v_lshlrev_b32_e32 v179, 5, v179
	v_or_b32_e32 v171, v194, v179
	v_or_b32_e32 v175, v195, v179
	v_xor_b32_e32 v179, 2, v178
	v_lshlrev_b32_e32 v179, 5, v179
	v_or_b32_e32 v172, v194, v179
	v_or_b32_e32 v176, v195, v179
	v_xor_b32_e32 v179, 3, v178
	v_lshlrev_b32_e32 v179, 5, v179
	v_or_b32_e32 v173, v194, v179
	v_or_b32_e32 v177, v195, v179
	v_ashrrev_i32_e32 v1, 31, v0
	v_lshlrev_b64 v[0:1], 11, v[0:1]
	v_lshl_add_u64 v[0:1], s[12:13], 0, v[0:1]
	v_lshl_add_u64 v[28:29], v[0:1], 0, v[96:97]
	v_add_u32_e32 v0, s4, v82
	v_ashrrev_i32_e32 v1, 31, v0
	v_lshlrev_b64 v[0:1], 11, v[0:1]
	v_lshl_add_u64 v[0:1], s[14:15], 0, v[0:1]
	v_add_co_u32_e32 v70, vcc, s63, v28
	v_lshl_add_u64 v[68:69], v[0:1], 0, v[96:97]
	s_nop 0
	v_addc_co_u32_e32 v71, vcc, 0, v29, vcc
	v_add_co_u32_e32 v72, vcc, s63, v68
	v_lshl_add_u64 v[2:3], s[12:13], 0, v[2:3]
	s_nop 0
	v_addc_co_u32_e32 v73, vcc, 0, v69, vcc
	v_add_co_u32_e32 v74, vcc, s64, v28
	v_lshl_add_u64 v[66:67], v[2:3], 0, v[96:97]
	s_nop 0
	v_addc_co_u32_e32 v75, vcc, 0, v29, vcc
	v_add_co_u32_e32 v76, vcc, s64, v68
	v_addc_co_u32_e32 v77, vcc, 0, v69, vcc
	v_add_co_u32_e32 v78, vcc, s65, v68
	s_nop 0
	v_addc_co_u32_e32 v79, vcc, 0, v69, vcc
	v_add_co_u32_e32 v80, vcc, s65, v28
	s_nop 0
	v_addc_co_u32_e32 v81, vcc, 0, v29, vcc
	v_ashrrev_i32_e32 v64, 1, v85
	v_and_b32_e32 v84, 31, v85
	v_lshrrev_b32_e32 v65, 1, v85
	v_and_b32_e32 v86, 0xffffffc0, v64
	s_waitcnt vmcnt(0)
	v_and_b32_e32 v88, 16, v65
	v_or_b32_e32 v64, v86, v84
	v_mad_u64_u32 v[82:83], s[6:7], v82, s91, v[96:97]
	v_mad_u64_u32 v[64:65], s[6:7], v64, s91, v[88:89]
	v_add_u32_e32 v83, 0xd800, v82
	s_ashr_i32 s5, s2, 3
	s_and_b32 s2, s4, 0x380
	s_mov_b64 s[22:23], s[74:75]
	s_mov_b64 s[6:7], 0x1e05c060
	s_add_u32 m0, s94, 0x4000
	s_nop 1
	global_load_lds_dwordx4 v[68:69], off
	s_add_u32 m0, s94, 0x0
	s_nop 1
	global_load_lds_dwordx4 v[66:67], off
	s_add_u32 m0, s94, 0x5000
	s_nop 1
	global_load_lds_dwordx4 v[72:73], off
	s_add_u32 m0, s94, 0x6000
	s_nop 1
	global_load_lds_dwordx4 v[76:77], off
	s_add_u32 m0, s94, 0x7000
	s_nop 1
	global_load_lds_dwordx4 v[78:79], off
	s_add_u32 m0, s94, 0x1000
	s_nop 1
	global_load_lds_dwordx4 v[70:71], off
	s_add_u32 m0, s94, 0x2000
	s_nop 1
	global_load_lds_dwordx4 v[74:75], off
	s_add_u32 m0, s94, 0x3000
	s_nop 1
	global_load_lds_dwordx4 v[80:81], off
	s_waitcnt lgkmcnt(0)
	s_waitcnt vmcnt(0)
	s_barrier
;     ...
;   G_LOAD(ra0, rb0, 0);
;   if (nk > 1) G_LOAD(ra1, rb1, 1);
;   G_STORE(ra0, rb0, As, Bs);
;   __syncthreads();
;   for (int kt = 0; kt < nk; kt += 2) {
;     if (kt + 2 < nk) G_LOAD(ra0, rb0, kt + 2);
;     if (kt + 1 < nk) G_STORE(ra1, rb1, As1, Bs1);
;     G_COMPUTE(As, Bs);
;     __syncthreads();
;     if (kt + 1 < nk) {
;       if (kt + 3 < nk) G_LOAD(ra1, rb1, kt + 3);
;       if (kt + 2 < nk) G_STORE(ra0, rb0, As, Bs);
;       G_COMPUTE(As1, Bs1);
;       __syncthreads();
	v_lshl_add_u64 v[66:67], v[66:67], 0, s[96:97]
	s_add_u32 m0, s94, 0x8000
	s_nop 1
	global_load_lds_dwordx4 v[66:67], off
	v_lshl_add_u64 v[68:69], v[68:69], 0, s[96:97]
	s_add_u32 m0, s94, 0xc000
	s_nop 1
	global_load_lds_dwordx4 v[68:69], off
	v_lshl_add_u64 v[70:71], v[70:71], 0, s[96:97]
	s_add_u32 m0, s94, 0x9000
	s_nop 1
	global_load_lds_dwordx4 v[70:71], off
	v_lshl_add_u64 v[72:73], v[72:73], 0, s[96:97]
	s_add_u32 m0, s94, 0xd000
	s_nop 1
	global_load_lds_dwordx4 v[72:73], off
	v_lshl_add_u64 v[74:75], v[74:75], 0, s[96:97]
	s_add_u32 m0, s94, 0xa000
	s_nop 1
	global_load_lds_dwordx4 v[74:75], off
	v_lshl_add_u64 v[76:77], v[76:77], 0, s[96:97]
	s_add_u32 m0, s94, 0xe000
	s_nop 1
	global_load_lds_dwordx4 v[76:77], off
	v_lshl_add_u64 v[80:81], v[80:81], 0, s[96:97]
	s_add_u32 m0, s94, 0xb000
	s_nop 1
	global_load_lds_dwordx4 v[80:81], off
	v_lshl_add_u64 v[78:79], v[78:79], 0, s[96:97]
	s_add_u32 m0, s94, 0xf000
	s_nop 1
	global_load_lds_dwordx4 v[78:79], off
	ds_read_b128 v[0:3], v170 offset:0
	v_and_b32_e32 v4, 0x5f, v85
	v_mad_u32_u24 v65, v4, s91, v88
	ds_read_b128 v[4:7], v174 offset:16384
	ds_read_b128 v[88:91], v171 offset:0
	ds_read_b128 v[92:95], v175 offset:16384
	ds_read_b128 v[16:19], v174 offset:20480
	ds_read_b128 v[98:101], v175 offset:20480
	s_waitcnt lgkmcnt(4)
	v_mfma_f32_32x32x16_bf16 v[32:47], v[0:3], v[4:7], 0
	ds_read_b128 v[20:23], v170 offset:4096
	ds_read_b128 v[102:105], v171 offset:4096
	s_waitcnt lgkmcnt(3)
	v_mfma_f32_32x32x16_bf16 v[48:63], v[0:3], v[16:19], 0
	s_waitcnt lgkmcnt(1)
	v_mfma_f32_32x32x16_bf16 v[0:15], v[20:23], v[4:7], 0
	v_mfma_f32_32x32x16_bf16 v[16:31], v[20:23], v[16:19], 0
	v_mfma_f32_32x32x16_bf16 v[32:47], v[88:91], v[92:95], v[32:47]
	v_mfma_f32_32x32x16_bf16 v[48:63], v[88:91], v[98:101], v[48:63]
	s_waitcnt lgkmcnt(0)
	v_mfma_f32_32x32x16_bf16 v[0:15], v[102:105], v[92:95], v[0:15]
	v_mfma_f32_32x32x16_bf16 v[16:31], v[102:105], v[98:101], v[16:31]
	ds_read_b128 v[88:91], v172 offset:0
	ds_read_b128 v[92:95], v176 offset:16384
	ds_read_b128 v[98:101], v173 offset:0
	ds_read_b128 v[102:105], v177 offset:16384
	ds_read_b128 v[106:109], v176 offset:20480
	ds_read_b128 v[110:113], v177 offset:20480
	s_waitcnt lgkmcnt(4)
	v_mfma_f32_32x32x16_bf16 v[32:47], v[88:91], v[92:95], v[32:47]
	s_waitcnt lgkmcnt(1)
	v_mfma_f32_32x32x16_bf16 v[48:63], v[88:91], v[106:109], v[48:63]
	ds_read_b128 v[88:91], v172 offset:4096
	ds_read_b128 v[114:117], v173 offset:4096
	s_waitcnt lgkmcnt(1)
	v_mfma_f32_32x32x16_bf16 v[0:15], v[88:91], v[92:95], v[0:15]
	v_mfma_f32_32x32x16_bf16 v[16:31], v[88:91], v[106:109], v[16:31]
	v_mfma_f32_32x32x16_bf16 v[32:47], v[98:101], v[102:105], v[32:47]
	v_mfma_f32_32x32x16_bf16 v[48:63], v[98:101], v[110:113], v[48:63]
	s_waitcnt lgkmcnt(0)
	v_mfma_f32_32x32x16_bf16 v[0:15], v[114:117], v[102:105], v[0:15]
	s_waitcnt vmcnt(0)
	s_barrier
	v_lshl_add_u64 v[66:67], v[66:67], 0, s[96:97]
	s_add_u32 m0, s94, 0x0
	s_nop 1
	global_load_lds_dwordx4 v[66:67], off
	v_lshl_add_u64 v[68:69], v[68:69], 0, s[96:97]
	s_add_u32 m0, s94, 0x4000
	s_nop 1
	global_load_lds_dwordx4 v[68:69], off
	v_lshl_add_u64 v[70:71], v[70:71], 0, s[96:97]
	s_add_u32 m0, s94, 0x1000
	s_nop 1
	global_load_lds_dwordx4 v[70:71], off
	v_lshl_add_u64 v[72:73], v[72:73], 0, s[96:97]
	s_add_u32 m0, s94, 0x5000
	s_nop 1
	global_load_lds_dwordx4 v[72:73], off
	v_lshl_add_u64 v[74:75], v[74:75], 0, s[96:97]
	s_add_u32 m0, s94, 0x2000
	s_nop 1
	global_load_lds_dwordx4 v[74:75], off
	v_lshl_add_u64 v[76:77], v[76:77], 0, s[96:97]
	s_add_u32 m0, s94, 0x6000
	s_nop 1
	global_load_lds_dwordx4 v[76:77], off
	v_lshl_add_u64 v[80:81], v[80:81], 0, s[96:97]
	s_add_u32 m0, s94, 0x3000
	s_nop 1
	global_load_lds_dwordx4 v[80:81], off
	v_lshl_add_u64 v[78:79], v[78:79], 0, s[96:97]
	s_add_u32 m0, s94, 0x7000
	s_nop 1
	global_load_lds_dwordx4 v[78:79], off
	v_mfma_f32_32x32x16_bf16 v[16:31], v[114:117], v[110:113], v[16:31]
	ds_read_b128 v[88:91], v170 offset:32768
	ds_read_b128 v[92:95], v174 offset:49152
	ds_read_b128 v[98:101], v171 offset:32768
	ds_read_b128 v[102:105], v175 offset:49152
	ds_read_b128 v[106:109], v174 offset:53248
	ds_read_b128 v[110:113], v175 offset:53248
	s_waitcnt lgkmcnt(4)
	v_mfma_f32_32x32x16_bf16 v[32:47], v[88:91], v[92:95], v[32:47]
	s_waitcnt lgkmcnt(1)
	v_mfma_f32_32x32x16_bf16 v[48:63], v[88:91], v[106:109], v[48:63]
	ds_read_b128 v[88:91], v170 offset:36864
	ds_read_b128 v[114:117], v171 offset:36864
	s_waitcnt lgkmcnt(1)
	v_mfma_f32_32x32x16_bf16 v[0:15], v[88:91], v[92:95], v[0:15]
	v_mfma_f32_32x32x16_bf16 v[16:31], v[88:91], v[106:109], v[16:31]
	v_mfma_f32_32x32x16_bf16 v[32:47], v[98:101], v[102:105], v[32:47]
	v_mfma_f32_32x32x16_bf16 v[48:63], v[98:101], v[110:113], v[48:63]
	s_waitcnt lgkmcnt(0)
	v_mfma_f32_32x32x16_bf16 v[0:15], v[114:117], v[102:105], v[0:15]
	ds_read_b128 v[88:91], v172 offset:32768
	ds_read_b128 v[92:95], v176 offset:49152
	ds_read_b128 v[98:101], v173 offset:32768
	ds_read_b128 v[102:105], v177 offset:49152
	v_mfma_f32_32x32x16_bf16 v[16:31], v[114:117], v[110:113], v[16:31]
	ds_read_b128 v[106:109], v176 offset:53248
	ds_read_b128 v[110:113], v177 offset:53248
	s_waitcnt lgkmcnt(4)
	v_mfma_f32_32x32x16_bf16 v[32:47], v[88:91], v[92:95], v[32:47]
	s_waitcnt lgkmcnt(1)
	v_mfma_f32_32x32x16_bf16 v[48:63], v[88:91], v[106:109], v[48:63]
	ds_read_b128 v[88:91], v172 offset:36864
	ds_read_b128 v[114:117], v173 offset:36864
	s_waitcnt lgkmcnt(1)
	v_mfma_f32_32x32x16_bf16 v[0:15], v[88:91], v[92:95], v[0:15]
	v_mfma_f32_32x32x16_bf16 v[16:31], v[88:91], v[106:109], v[16:31]
	v_mfma_f32_32x32x16_bf16 v[32:47], v[98:101], v[102:105], v[32:47]
	v_mfma_f32_32x32x16_bf16 v[48:63], v[98:101], v[110:113], v[48:63]
	s_waitcnt lgkmcnt(0)
	v_mfma_f32_32x32x16_bf16 v[0:15], v[114:117], v[102:105], v[0:15]
	s_waitcnt vmcnt(0)
	s_barrier
;     ...
;   bf16* As1 = As + 2 * 128 * 72;
;   bf16* Bs1 = As1 + 128 * 72;
;   G_LOAD(ra0, rb0, 0);
;   if (nk > 1) G_LOAD(ra1, rb1, 1);
;   G_STORE(ra0, rb0, As, Bs);
;   __syncthreads();
;   for (int kt = 0; kt < nk; kt += 2) {
;     if (kt + 2 < nk) G_LOAD(ra0, rb0, kt + 2);
;     if (kt + 1 < nk) G_STORE(ra1, rb1, As1, Bs1);
;     G_COMPUTE(As, Bs);
;     __syncthreads();
;     if (kt + 1 < nk) {
;       if (kt + 3 < nk) G_LOAD(ra1, rb1, kt + 3);
;       if (kt + 2 < nk) G_STORE(ra0, rb0, As, Bs);
;       G_COMPUTE(As1, Bs1);
;       __syncthreads();
	v_lshl_add_u64 v[66:67], v[66:67], 0, s[96:97]
	s_add_u32 m0, s94, 0x8000
	s_nop 1
	global_load_lds_dwordx4 v[66:67], off
	v_lshl_add_u64 v[68:69], v[68:69], 0, s[96:97]
	s_add_u32 m0, s94, 0xc000
	s_nop 1
	global_load_lds_dwordx4 v[68:69], off
	v_lshl_add_u64 v[70:71], v[70:71], 0, s[96:97]
	s_add_u32 m0, s94, 0x9000
	s_nop 1
	global_load_lds_dwordx4 v[70:71], off
	v_lshl_add_u64 v[72:73], v[72:73], 0, s[96:97]
	s_add_u32 m0, s94, 0xd000
	s_nop 1
	global_load_lds_dwordx4 v[72:73], off
	v_lshl_add_u64 v[74:75], v[74:75], 0, s[96:97]
	s_add_u32 m0, s94, 0xa000
	s_nop 1
	global_load_lds_dwordx4 v[74:75], off
	v_lshl_add_u64 v[76:77], v[76:77], 0, s[96:97]
	s_add_u32 m0, s94, 0xe000
	s_nop 1
	global_load_lds_dwordx4 v[76:77], off
	v_lshl_add_u64 v[80:81], v[80:81], 0, s[96:97]
	s_add_u32 m0, s94, 0xb000
	s_nop 1
	global_load_lds_dwordx4 v[80:81], off
	v_lshl_add_u64 v[78:79], v[78:79], 0, s[96:97]
	s_add_u32 m0, s94, 0xf000
	s_nop 1
	global_load_lds_dwordx4 v[78:79], off
	v_mfma_f32_32x32x16_bf16 v[16:31], v[114:117], v[110:113], v[16:31]
	ds_read_b128 v[88:91], v170 offset:0
	ds_read_b128 v[92:95], v174 offset:16384
	ds_read_b128 v[98:101], v171 offset:0
	ds_read_b128 v[102:105], v175 offset:16384
	ds_read_b128 v[106:109], v174 offset:20480
	ds_read_b128 v[110:113], v175 offset:20480
	s_waitcnt lgkmcnt(4)
	v_mfma_f32_32x32x16_bf16 v[32:47], v[88:91], v[92:95], v[32:47]
	s_waitcnt lgkmcnt(1)
	v_mfma_f32_32x32x16_bf16 v[48:63], v[88:91], v[106:109], v[48:63]
	ds_read_b128 v[88:91], v170 offset:4096
	ds_read_b128 v[114:117], v171 offset:4096
	s_waitcnt lgkmcnt(1)
	v_mfma_f32_32x32x16_bf16 v[0:15], v[88:91], v[92:95], v[0:15]
	v_mfma_f32_32x32x16_bf16 v[16:31], v[88:91], v[106:109], v[16:31]
	v_mfma_f32_32x32x16_bf16 v[32:47], v[98:101], v[102:105], v[32:47]
	v_mfma_f32_32x32x16_bf16 v[48:63], v[98:101], v[110:113], v[48:63]
	s_waitcnt lgkmcnt(0)
	v_mfma_f32_32x32x16_bf16 v[0:15], v[114:117], v[102:105], v[0:15]
	ds_read_b128 v[88:91], v172 offset:0
	ds_read_b128 v[92:95], v176 offset:16384
	ds_read_b128 v[98:101], v173 offset:0
	ds_read_b128 v[102:105], v177 offset:16384
	v_mfma_f32_32x32x16_bf16 v[16:31], v[114:117], v[110:113], v[16:31]
	ds_read_b128 v[106:109], v176 offset:20480
	ds_read_b128 v[110:113], v177 offset:20480
	s_waitcnt lgkmcnt(4)
	v_mfma_f32_32x32x16_bf16 v[32:47], v[88:91], v[92:95], v[32:47]
	s_waitcnt lgkmcnt(1)
	v_mfma_f32_32x32x16_bf16 v[48:63], v[88:91], v[106:109], v[48:63]
	ds_read_b128 v[88:91], v172 offset:4096
	ds_read_b128 v[114:117], v173 offset:4096
	s_waitcnt lgkmcnt(1)
	v_mfma_f32_32x32x16_bf16 v[0:15], v[88:91], v[92:95], v[0:15]
	v_mfma_f32_32x32x16_bf16 v[16:31], v[88:91], v[106:109], v[16:31]
	v_mfma_f32_32x32x16_bf16 v[32:47], v[98:101], v[102:105], v[32:47]
	v_mfma_f32_32x32x16_bf16 v[48:63], v[98:101], v[110:113], v[48:63]
	s_waitcnt lgkmcnt(0)
	v_mfma_f32_32x32x16_bf16 v[0:15], v[114:117], v[102:105], v[0:15]
	s_waitcnt vmcnt(0)
	s_barrier
	v_lshl_add_u64 v[66:67], v[66:67], 0, s[96:97]
	s_add_u32 m0, s94, 0x0
	s_nop 1
	global_load_lds_dwordx4 v[66:67], off
	v_lshl_add_u64 v[68:69], v[68:69], 0, s[96:97]
	s_add_u32 m0, s94, 0x4000
	s_nop 1
	global_load_lds_dwordx4 v[68:69], off
	v_lshl_add_u64 v[70:71], v[70:71], 0, s[96:97]
	s_add_u32 m0, s94, 0x1000
	s_nop 1
	global_load_lds_dwordx4 v[70:71], off
	v_lshl_add_u64 v[72:73], v[72:73], 0, s[96:97]
	s_add_u32 m0, s94, 0x5000
	s_nop 1
	global_load_lds_dwordx4 v[72:73], off
	v_lshl_add_u64 v[74:75], v[74:75], 0, s[96:97]
	s_add_u32 m0, s94, 0x2000
	s_nop 1
	global_load_lds_dwordx4 v[74:75], off
	v_lshl_add_u64 v[76:77], v[76:77], 0, s[96:97]
	s_add_u32 m0, s94, 0x6000
	s_nop 1
	global_load_lds_dwordx4 v[76:77], off
	v_lshl_add_u64 v[80:81], v[80:81], 0, s[96:97]
	s_add_u32 m0, s94, 0x3000
	s_nop 1
	global_load_lds_dwordx4 v[80:81], off
	v_lshl_add_u64 v[78:79], v[78:79], 0, s[96:97]
	s_add_u32 m0, s94, 0x7000
	s_nop 1
	global_load_lds_dwordx4 v[78:79], off
	v_mfma_f32_32x32x16_bf16 v[16:31], v[114:117], v[110:113], v[16:31]
	ds_read_b128 v[88:91], v170 offset:32768
	ds_read_b128 v[92:95], v174 offset:49152
	ds_read_b128 v[98:101], v171 offset:32768
	ds_read_b128 v[102:105], v175 offset:49152
	ds_read_b128 v[106:109], v174 offset:53248
	ds_read_b128 v[110:113], v175 offset:53248
	s_waitcnt lgkmcnt(4)
	v_mfma_f32_32x32x16_bf16 v[32:47], v[88:91], v[92:95], v[32:47]
	s_waitcnt lgkmcnt(1)
	v_mfma_f32_32x32x16_bf16 v[48:63], v[88:91], v[106:109], v[48:63]
	ds_read_b128 v[88:91], v170 offset:36864
	ds_read_b128 v[114:117], v171 offset:36864
	s_waitcnt lgkmcnt(1)
	v_mfma_f32_32x32x16_bf16 v[0:15], v[88:91], v[92:95], v[0:15]
	v_mfma_f32_32x32x16_bf16 v[16:31], v[88:91], v[106:109], v[16:31]
	v_mfma_f32_32x32x16_bf16 v[32:47], v[98:101], v[102:105], v[32:47]
	v_mfma_f32_32x32x16_bf16 v[48:63], v[98:101], v[110:113], v[48:63]
	s_waitcnt lgkmcnt(0)
	v_mfma_f32_32x32x16_bf16 v[0:15], v[114:117], v[102:105], v[0:15]
	ds_read_b128 v[88:91], v172 offset:32768
	ds_read_b128 v[92:95], v176 offset:49152
	ds_read_b128 v[98:101], v173 offset:32768
	ds_read_b128 v[102:105], v177 offset:49152
	v_mfma_f32_32x32x16_bf16 v[16:31], v[114:117], v[110:113], v[16:31]
	ds_read_b128 v[106:109], v176 offset:53248
	ds_read_b128 v[110:113], v177 offset:53248
	s_waitcnt lgkmcnt(4)
	v_mfma_f32_32x32x16_bf16 v[32:47], v[88:91], v[92:95], v[32:47]
	s_waitcnt lgkmcnt(1)
	v_mfma_f32_32x32x16_bf16 v[48:63], v[88:91], v[106:109], v[48:63]
	ds_read_b128 v[88:91], v172 offset:36864
	ds_read_b128 v[114:117], v173 offset:36864
	s_waitcnt lgkmcnt(1)
	v_mfma_f32_32x32x16_bf16 v[0:15], v[88:91], v[92:95], v[0:15]
	v_mfma_f32_32x32x16_bf16 v[16:31], v[88:91], v[106:109], v[16:31]
	v_mfma_f32_32x32x16_bf16 v[32:47], v[98:101], v[102:105], v[32:47]
	v_mfma_f32_32x32x16_bf16 v[48:63], v[98:101], v[110:113], v[48:63]
	s_waitcnt lgkmcnt(0)
	v_mfma_f32_32x32x16_bf16 v[0:15], v[114:117], v[102:105], v[0:15]
	s_waitcnt vmcnt(0)
	s_barrier
;     ...
;   bf16* As1 = As + 2 * 128 * 72;
;   bf16* Bs1 = As1 + 128 * 72;
;   G_LOAD(ra0, rb0, 0);
;   if (nk > 1) G_LOAD(ra1, rb1, 1);
;   G_STORE(ra0, rb0, As, Bs);
;   __syncthreads();
;   for (int kt = 0; kt < nk; kt += 2) {
;     if (kt + 2 < nk) G_LOAD(ra0, rb0, kt + 2);
;     if (kt + 1 < nk) G_STORE(ra1, rb1, As1, Bs1);
;     G_COMPUTE(As, Bs);
;     __syncthreads();
;     if (kt + 1 < nk) {
;       if (kt + 3 < nk) G_LOAD(ra1, rb1, kt + 3);
;       if (kt + 2 < nk) G_STORE(ra0, rb0, As, Bs);
;       G_COMPUTE(As1, Bs1);
;       __syncthreads();
	v_lshl_add_u64 v[66:67], v[66:67], 0, s[96:97]
	s_add_u32 m0, s94, 0x8000
	s_nop 1
	global_load_lds_dwordx4 v[66:67], off
	v_lshl_add_u64 v[68:69], v[68:69], 0, s[96:97]
	s_add_u32 m0, s94, 0xc000
	s_nop 1
	global_load_lds_dwordx4 v[68:69], off
	v_lshl_add_u64 v[70:71], v[70:71], 0, s[96:97]
	s_add_u32 m0, s94, 0x9000
	s_nop 1
	global_load_lds_dwordx4 v[70:71], off
	v_lshl_add_u64 v[72:73], v[72:73], 0, s[96:97]
	s_add_u32 m0, s94, 0xd000
	s_nop 1
	global_load_lds_dwordx4 v[72:73], off
	v_lshl_add_u64 v[74:75], v[74:75], 0, s[96:97]
	s_add_u32 m0, s94, 0xa000
	s_nop 1
	global_load_lds_dwordx4 v[74:75], off
	v_lshl_add_u64 v[76:77], v[76:77], 0, s[96:97]
	s_add_u32 m0, s94, 0xe000
	s_nop 1
	global_load_lds_dwordx4 v[76:77], off
	v_lshl_add_u64 v[80:81], v[80:81], 0, s[96:97]
	s_add_u32 m0, s94, 0xb000
	s_nop 1
	global_load_lds_dwordx4 v[80:81], off
	v_lshl_add_u64 v[78:79], v[78:79], 0, s[96:97]
	s_add_u32 m0, s94, 0xf000
	s_nop 1
	global_load_lds_dwordx4 v[78:79], off
	v_mfma_f32_32x32x16_bf16 v[16:31], v[114:117], v[110:113], v[16:31]
	ds_read_b128 v[88:91], v170 offset:0
	ds_read_b128 v[92:95], v174 offset:16384
	ds_read_b128 v[98:101], v171 offset:0
	ds_read_b128 v[102:105], v175 offset:16384
	ds_read_b128 v[106:109], v174 offset:20480
	ds_read_b128 v[110:113], v175 offset:20480
	s_waitcnt lgkmcnt(4)
	v_mfma_f32_32x32x16_bf16 v[32:47], v[88:91], v[92:95], v[32:47]
	s_waitcnt lgkmcnt(1)
	v_mfma_f32_32x32x16_bf16 v[48:63], v[88:91], v[106:109], v[48:63]
	ds_read_b128 v[88:91], v170 offset:4096
	ds_read_b128 v[114:117], v171 offset:4096
	s_waitcnt lgkmcnt(1)
	v_mfma_f32_32x32x16_bf16 v[0:15], v[88:91], v[92:95], v[0:15]
	v_mfma_f32_32x32x16_bf16 v[16:31], v[88:91], v[106:109], v[16:31]
	v_mfma_f32_32x32x16_bf16 v[32:47], v[98:101], v[102:105], v[32:47]
	v_mfma_f32_32x32x16_bf16 v[48:63], v[98:101], v[110:113], v[48:63]
	s_waitcnt lgkmcnt(0)
	v_mfma_f32_32x32x16_bf16 v[0:15], v[114:117], v[102:105], v[0:15]
	ds_read_b128 v[88:91], v172 offset:0
	ds_read_b128 v[92:95], v176 offset:16384
	ds_read_b128 v[98:101], v173 offset:0
	ds_read_b128 v[102:105], v177 offset:16384
	v_mfma_f32_32x32x16_bf16 v[16:31], v[114:117], v[110:113], v[16:31]
	ds_read_b128 v[106:109], v176 offset:20480
	ds_read_b128 v[110:113], v177 offset:20480
	s_waitcnt lgkmcnt(4)
	v_mfma_f32_32x32x16_bf16 v[32:47], v[88:91], v[92:95], v[32:47]
	s_waitcnt lgkmcnt(1)
	v_mfma_f32_32x32x16_bf16 v[48:63], v[88:91], v[106:109], v[48:63]
	ds_read_b128 v[88:91], v172 offset:4096
	ds_read_b128 v[114:117], v173 offset:4096
	s_waitcnt lgkmcnt(1)
	v_mfma_f32_32x32x16_bf16 v[0:15], v[88:91], v[92:95], v[0:15]
	v_mfma_f32_32x32x16_bf16 v[16:31], v[88:91], v[106:109], v[16:31]
	v_mfma_f32_32x32x16_bf16 v[32:47], v[98:101], v[102:105], v[32:47]
	v_mfma_f32_32x32x16_bf16 v[48:63], v[98:101], v[110:113], v[48:63]
	s_waitcnt lgkmcnt(0)
	v_mfma_f32_32x32x16_bf16 v[0:15], v[114:117], v[102:105], v[0:15]
	s_waitcnt vmcnt(0)
	s_barrier
	v_lshl_add_u64 v[66:67], v[66:67], 0, s[96:97]
	s_add_u32 m0, s94, 0x0
	s_nop 1
	global_load_lds_dwordx4 v[66:67], off
	v_lshl_add_u64 v[68:69], v[68:69], 0, s[96:97]
	s_add_u32 m0, s94, 0x4000
	s_nop 1
	global_load_lds_dwordx4 v[68:69], off
	v_lshl_add_u64 v[70:71], v[70:71], 0, s[96:97]
	s_add_u32 m0, s94, 0x1000
	s_nop 1
	global_load_lds_dwordx4 v[70:71], off
	v_lshl_add_u64 v[72:73], v[72:73], 0, s[96:97]
	s_add_u32 m0, s94, 0x5000
	s_nop 1
	global_load_lds_dwordx4 v[72:73], off
	v_lshl_add_u64 v[74:75], v[74:75], 0, s[96:97]
	s_add_u32 m0, s94, 0x2000
	s_nop 1
	global_load_lds_dwordx4 v[74:75], off
	v_lshl_add_u64 v[76:77], v[76:77], 0, s[96:97]
	s_add_u32 m0, s94, 0x6000
	s_nop 1
	global_load_lds_dwordx4 v[76:77], off
	v_lshl_add_u64 v[80:81], v[80:81], 0, s[96:97]
	s_add_u32 m0, s94, 0x3000
	s_nop 1
	global_load_lds_dwordx4 v[80:81], off
	v_lshl_add_u64 v[78:79], v[78:79], 0, s[96:97]
	s_add_u32 m0, s94, 0x7000
	s_nop 1
	global_load_lds_dwordx4 v[78:79], off
	v_mfma_f32_32x32x16_bf16 v[16:31], v[114:117], v[110:113], v[16:31]
	ds_read_b128 v[88:91], v170 offset:32768
	ds_read_b128 v[92:95], v174 offset:49152
	ds_read_b128 v[98:101], v171 offset:32768
	ds_read_b128 v[102:105], v175 offset:49152
	ds_read_b128 v[106:109], v174 offset:53248
	ds_read_b128 v[110:113], v175 offset:53248
	s_waitcnt lgkmcnt(4)
	v_mfma_f32_32x32x16_bf16 v[32:47], v[88:91], v[92:95], v[32:47]
	s_waitcnt lgkmcnt(1)
	v_mfma_f32_32x32x16_bf16 v[48:63], v[88:91], v[106:109], v[48:63]
	ds_read_b128 v[88:91], v170 offset:36864
	ds_read_b128 v[114:117], v171 offset:36864
	s_waitcnt lgkmcnt(1)
	v_mfma_f32_32x32x16_bf16 v[0:15], v[88:91], v[92:95], v[0:15]
	v_mfma_f32_32x32x16_bf16 v[16:31], v[88:91], v[106:109], v[16:31]
	v_mfma_f32_32x32x16_bf16 v[32:47], v[98:101], v[102:105], v[32:47]
	v_mfma_f32_32x32x16_bf16 v[48:63], v[98:101], v[110:113], v[48:63]
	s_waitcnt lgkmcnt(0)
	v_mfma_f32_32x32x16_bf16 v[0:15], v[114:117], v[102:105], v[0:15]
	ds_read_b128 v[88:91], v172 offset:32768
	ds_read_b128 v[92:95], v176 offset:49152
	ds_read_b128 v[98:101], v173 offset:32768
	ds_read_b128 v[102:105], v177 offset:49152
	v_mfma_f32_32x32x16_bf16 v[16:31], v[114:117], v[110:113], v[16:31]
	ds_read_b128 v[106:109], v176 offset:53248
	ds_read_b128 v[110:113], v177 offset:53248
	s_waitcnt lgkmcnt(4)
	v_mfma_f32_32x32x16_bf16 v[32:47], v[88:91], v[92:95], v[32:47]
	s_waitcnt lgkmcnt(1)
	v_mfma_f32_32x32x16_bf16 v[48:63], v[88:91], v[106:109], v[48:63]
	ds_read_b128 v[88:91], v172 offset:36864
	ds_read_b128 v[114:117], v173 offset:36864
	s_waitcnt lgkmcnt(1)
	v_mfma_f32_32x32x16_bf16 v[0:15], v[88:91], v[92:95], v[0:15]
	v_mfma_f32_32x32x16_bf16 v[16:31], v[88:91], v[106:109], v[16:31]
	v_mfma_f32_32x32x16_bf16 v[32:47], v[98:101], v[102:105], v[32:47]
	v_mfma_f32_32x32x16_bf16 v[48:63], v[98:101], v[110:113], v[48:63]
	s_waitcnt lgkmcnt(0)
	v_mfma_f32_32x32x16_bf16 v[0:15], v[114:117], v[102:105], v[0:15]
	s_waitcnt vmcnt(0)
	s_barrier
;     ...
;   bf16* As1 = As + 2 * 128 * 72;
;   bf16* Bs1 = As1 + 128 * 72;
;   G_LOAD(ra0, rb0, 0);
;   if (nk > 1) G_LOAD(ra1, rb1, 1);
;   G_STORE(ra0, rb0, As, Bs);
;   __syncthreads();
;   for (int kt = 0; kt < nk; kt += 2) {
;     if (kt + 2 < nk) G_LOAD(ra0, rb0, kt + 2);
;     if (kt + 1 < nk) G_STORE(ra1, rb1, As1, Bs1);
;     G_COMPUTE(As, Bs);
;     __syncthreads();
;     if (kt + 1 < nk) {
;       if (kt + 3 < nk) G_LOAD(ra1, rb1, kt + 3);
;       if (kt + 2 < nk) G_STORE(ra0, rb0, As, Bs);
;       G_COMPUTE(As1, Bs1);
;       __syncthreads();
;     }
;   }
	v_lshl_add_u64 v[66:67], v[66:67], 0, s[96:97]
	s_add_u32 m0, s94, 0x8000
	s_nop 1
	global_load_lds_dwordx4 v[66:67], off
	v_lshl_add_u64 v[68:69], v[68:69], 0, s[96:97]
	s_add_u32 m0, s94, 0xc000
	s_nop 1
	global_load_lds_dwordx4 v[68:69], off
	v_lshl_add_u64 v[70:71], v[70:71], 0, s[96:97]
	s_add_u32 m0, s94, 0x9000
	s_nop 1
	global_load_lds_dwordx4 v[70:71], off
	v_lshl_add_u64 v[72:73], v[72:73], 0, s[96:97]
	s_add_u32 m0, s94, 0xd000
	s_nop 1
	global_load_lds_dwordx4 v[72:73], off
	v_lshl_add_u64 v[74:75], v[74:75], 0, s[96:97]
	s_add_u32 m0, s94, 0xa000
	s_nop 1
	global_load_lds_dwordx4 v[74:75], off
	v_lshl_add_u64 v[76:77], v[76:77], 0, s[96:97]
	s_add_u32 m0, s94, 0xe000
	s_nop 1
	global_load_lds_dwordx4 v[76:77], off
	v_lshl_add_u64 v[80:81], v[80:81], 0, s[96:97]
	s_add_u32 m0, s94, 0xb000
	s_nop 1
	global_load_lds_dwordx4 v[80:81], off
	v_lshl_add_u64 v[78:79], v[78:79], 0, s[96:97]
	s_add_u32 m0, s94, 0xf000
	s_nop 1
	global_load_lds_dwordx4 v[78:79], off
	v_mfma_f32_32x32x16_bf16 v[16:31], v[114:117], v[110:113], v[16:31]
	ds_read_b128 v[88:91], v170 offset:0
	ds_read_b128 v[92:95], v174 offset:16384
	ds_read_b128 v[98:101], v171 offset:0
	ds_read_b128 v[102:105], v175 offset:16384
	ds_read_b128 v[106:109], v174 offset:20480
	ds_read_b128 v[110:113], v175 offset:20480
	s_waitcnt lgkmcnt(4)
	v_mfma_f32_32x32x16_bf16 v[32:47], v[88:91], v[92:95], v[32:47]
	s_waitcnt lgkmcnt(1)
	v_mfma_f32_32x32x16_bf16 v[48:63], v[88:91], v[106:109], v[48:63]
	ds_read_b128 v[88:91], v170 offset:4096
	ds_read_b128 v[114:117], v171 offset:4096
	s_waitcnt lgkmcnt(1)
	v_mfma_f32_32x32x16_bf16 v[0:15], v[88:91], v[92:95], v[0:15]
	v_mfma_f32_32x32x16_bf16 v[16:31], v[88:91], v[106:109], v[16:31]
	v_mfma_f32_32x32x16_bf16 v[32:47], v[98:101], v[102:105], v[32:47]
	v_mfma_f32_32x32x16_bf16 v[48:63], v[98:101], v[110:113], v[48:63]
	s_waitcnt lgkmcnt(0)
	v_mfma_f32_32x32x16_bf16 v[0:15], v[114:117], v[102:105], v[0:15]
	ds_read_b128 v[88:91], v172 offset:0
	ds_read_b128 v[92:95], v176 offset:16384
	ds_read_b128 v[98:101], v173 offset:0
	ds_read_b128 v[102:105], v177 offset:16384
	v_mfma_f32_32x32x16_bf16 v[16:31], v[114:117], v[110:113], v[16:31]
	ds_read_b128 v[106:109], v176 offset:20480
	ds_read_b128 v[110:113], v177 offset:20480
	s_waitcnt lgkmcnt(4)
	v_mfma_f32_32x32x16_bf16 v[32:47], v[88:91], v[92:95], v[32:47]
	s_waitcnt lgkmcnt(1)
	v_mfma_f32_32x32x16_bf16 v[48:63], v[88:91], v[106:109], v[48:63]
	ds_read_b128 v[88:91], v172 offset:4096
	ds_read_b128 v[114:117], v173 offset:4096
	s_waitcnt lgkmcnt(1)
	v_mfma_f32_32x32x16_bf16 v[0:15], v[88:91], v[92:95], v[0:15]
	v_mfma_f32_32x32x16_bf16 v[16:31], v[88:91], v[106:109], v[16:31]
	v_mfma_f32_32x32x16_bf16 v[32:47], v[98:101], v[102:105], v[32:47]
	v_mfma_f32_32x32x16_bf16 v[48:63], v[98:101], v[110:113], v[48:63]
	s_waitcnt lgkmcnt(0)
	v_mfma_f32_32x32x16_bf16 v[0:15], v[114:117], v[102:105], v[0:15]
	s_waitcnt vmcnt(0)
	s_barrier
	v_lshl_add_u64 v[66:67], v[66:67], 0, s[96:97]
	s_add_u32 m0, s94, 0x0
	s_nop 1
	global_load_lds_dwordx4 v[66:67], off
	v_lshl_add_u64 v[68:69], v[68:69], 0, s[96:97]
	s_add_u32 m0, s94, 0x4000
	s_nop 1
	global_load_lds_dwordx4 v[68:69], off
	v_lshl_add_u64 v[70:71], v[70:71], 0, s[96:97]
	s_add_u32 m0, s94, 0x1000
	s_nop 1
	global_load_lds_dwordx4 v[70:71], off
	v_lshl_add_u64 v[72:73], v[72:73], 0, s[96:97]
	s_add_u32 m0, s94, 0x5000
	s_nop 1
	global_load_lds_dwordx4 v[72:73], off
	v_lshl_add_u64 v[74:75], v[74:75], 0, s[96:97]
	s_add_u32 m0, s94, 0x2000
	s_nop 1
	global_load_lds_dwordx4 v[74:75], off
	v_lshl_add_u64 v[76:77], v[76:77], 0, s[96:97]
	s_add_u32 m0, s94, 0x6000
	s_nop 1
	global_load_lds_dwordx4 v[76:77], off
	v_lshl_add_u64 v[80:81], v[80:81], 0, s[96:97]
	s_add_u32 m0, s94, 0x3000
	s_nop 1
	global_load_lds_dwordx4 v[80:81], off
	v_lshl_add_u64 v[78:79], v[78:79], 0, s[96:97]
	s_add_u32 m0, s94, 0x7000
	s_nop 1
	global_load_lds_dwordx4 v[78:79], off
	v_mfma_f32_32x32x16_bf16 v[16:31], v[114:117], v[110:113], v[16:31]
	ds_read_b128 v[88:91], v170 offset:32768
	ds_read_b128 v[92:95], v174 offset:49152
	ds_read_b128 v[98:101], v171 offset:32768
	ds_read_b128 v[102:105], v175 offset:49152
	ds_read_b128 v[106:109], v174 offset:53248
	ds_read_b128 v[110:113], v175 offset:53248
	s_waitcnt lgkmcnt(4)
	v_mfma_f32_32x32x16_bf16 v[32:47], v[88:91], v[92:95], v[32:47]
	s_waitcnt lgkmcnt(1)
	v_mfma_f32_32x32x16_bf16 v[48:63], v[88:91], v[106:109], v[48:63]
	ds_read_b128 v[88:91], v170 offset:36864
	ds_read_b128 v[114:117], v171 offset:36864
	s_waitcnt lgkmcnt(1)
	v_mfma_f32_32x32x16_bf16 v[0:15], v[88:91], v[92:95], v[0:15]
	v_mfma_f32_32x32x16_bf16 v[16:31], v[88:91], v[106:109], v[16:31]
	v_mfma_f32_32x32x16_bf16 v[32:47], v[98:101], v[102:105], v[32:47]
	v_mfma_f32_32x32x16_bf16 v[48:63], v[98:101], v[110:113], v[48:63]
	s_waitcnt lgkmcnt(0)
	v_mfma_f32_32x32x16_bf16 v[0:15], v[114:117], v[102:105], v[0:15]
	ds_read_b128 v[88:91], v172 offset:32768
	ds_read_b128 v[92:95], v176 offset:49152
	ds_read_b128 v[98:101], v173 offset:32768
	ds_read_b128 v[102:105], v177 offset:49152
	v_mfma_f32_32x32x16_bf16 v[16:31], v[114:117], v[110:113], v[16:31]
	ds_read_b128 v[106:109], v176 offset:53248
	ds_read_b128 v[110:113], v177 offset:53248
	s_waitcnt lgkmcnt(4)
	v_mfma_f32_32x32x16_bf16 v[32:47], v[88:91], v[92:95], v[32:47]
	s_waitcnt lgkmcnt(1)
	v_mfma_f32_32x32x16_bf16 v[48:63], v[88:91], v[106:109], v[48:63]
	ds_read_b128 v[88:91], v172 offset:36864
	ds_read_b128 v[114:117], v173 offset:36864
	s_waitcnt lgkmcnt(1)
	v_mfma_f32_32x32x16_bf16 v[0:15], v[88:91], v[92:95], v[0:15]
	v_mfma_f32_32x32x16_bf16 v[16:31], v[88:91], v[106:109], v[16:31]
	v_mfma_f32_32x32x16_bf16 v[32:47], v[98:101], v[102:105], v[32:47]
	v_mfma_f32_32x32x16_bf16 v[48:63], v[98:101], v[110:113], v[48:63]
	s_waitcnt lgkmcnt(0)
	v_mfma_f32_32x32x16_bf16 v[0:15], v[114:117], v[102:105], v[0:15]
	s_waitcnt vmcnt(0)
	s_barrier
;     ...
;   bf16* As1 = As + 2 * 128 * 72;
;   bf16* Bs1 = As1 + 128 * 72;
;   G_LOAD(ra0, rb0, 0);
;   if (nk > 1) G_LOAD(ra1, rb1, 1);
;   G_STORE(ra0, rb0, As, Bs);
;   __syncthreads();
;   for (int kt = 0; kt < nk; kt += 2) {
;     if (kt + 2 < nk) G_LOAD(ra0, rb0, kt + 2);
;     if (kt + 1 < nk) G_STORE(ra1, rb1, As1, Bs1);
;     G_COMPUTE(As, Bs);
;     __syncthreads();
;     if (kt + 1 < nk) {
;       if (kt + 3 < nk) G_LOAD(ra1, rb1, kt + 3);
;       if (kt + 2 < nk) G_STORE(ra0, rb0, As, Bs);
;       G_COMPUTE(As1, Bs1);
;       __syncthreads();
;     }
;   }
	v_lshl_add_u64 v[66:67], v[66:67], 0, s[96:97]
	s_add_u32 m0, s94, 0x8000
	s_nop 1
	global_load_lds_dwordx4 v[66:67], off
	v_lshl_add_u64 v[68:69], v[68:69], 0, s[96:97]
	s_add_u32 m0, s94, 0xc000
	s_nop 1
	global_load_lds_dwordx4 v[68:69], off
	v_lshl_add_u64 v[70:71], v[70:71], 0, s[96:97]
	s_add_u32 m0, s94, 0x9000
	s_nop 1
	global_load_lds_dwordx4 v[70:71], off
	v_lshl_add_u64 v[72:73], v[72:73], 0, s[96:97]
	s_add_u32 m0, s94, 0xd000
	s_nop 1
	global_load_lds_dwordx4 v[72:73], off
	v_lshl_add_u64 v[74:75], v[74:75], 0, s[96:97]
	s_add_u32 m0, s94, 0xa000
	s_nop 1
	global_load_lds_dwordx4 v[74:75], off
	v_lshl_add_u64 v[76:77], v[76:77], 0, s[96:97]
	s_add_u32 m0, s94, 0xe000
	s_nop 1
	global_load_lds_dwordx4 v[76:77], off
	v_lshl_add_u64 v[80:81], v[80:81], 0, s[96:97]
	s_add_u32 m0, s94, 0xb000
	s_nop 1
	global_load_lds_dwordx4 v[80:81], off
	v_lshl_add_u64 v[78:79], v[78:79], 0, s[96:97]
	s_add_u32 m0, s94, 0xf000
	s_nop 1
	global_load_lds_dwordx4 v[78:79], off
	v_mfma_f32_32x32x16_bf16 v[16:31], v[114:117], v[110:113], v[16:31]
	ds_read_b128 v[88:91], v170 offset:0
	ds_read_b128 v[92:95], v174 offset:16384
	ds_read_b128 v[98:101], v171 offset:0
	ds_read_b128 v[102:105], v175 offset:16384
	ds_read_b128 v[106:109], v174 offset:20480
	ds_read_b128 v[110:113], v175 offset:20480
	s_waitcnt lgkmcnt(4)
	v_mfma_f32_32x32x16_bf16 v[32:47], v[88:91], v[92:95], v[32:47]
	s_waitcnt lgkmcnt(1)
	v_mfma_f32_32x32x16_bf16 v[48:63], v[88:91], v[106:109], v[48:63]
	ds_read_b128 v[88:91], v170 offset:4096
	ds_read_b128 v[114:117], v171 offset:4096
	s_waitcnt lgkmcnt(1)
	v_mfma_f32_32x32x16_bf16 v[0:15], v[88:91], v[92:95], v[0:15]
	v_mfma_f32_32x32x16_bf16 v[16:31], v[88:91], v[106:109], v[16:31]
	v_mfma_f32_32x32x16_bf16 v[32:47], v[98:101], v[102:105], v[32:47]
	v_mfma_f32_32x32x16_bf16 v[48:63], v[98:101], v[110:113], v[48:63]
	s_waitcnt lgkmcnt(0)
	v_mfma_f32_32x32x16_bf16 v[0:15], v[114:117], v[102:105], v[0:15]
	ds_read_b128 v[88:91], v172 offset:0
	ds_read_b128 v[92:95], v176 offset:16384
	ds_read_b128 v[98:101], v173 offset:0
	ds_read_b128 v[102:105], v177 offset:16384
	v_mfma_f32_32x32x16_bf16 v[16:31], v[114:117], v[110:113], v[16:31]
	ds_read_b128 v[106:109], v176 offset:20480
	ds_read_b128 v[110:113], v177 offset:20480
	s_waitcnt lgkmcnt(4)
	v_mfma_f32_32x32x16_bf16 v[32:47], v[88:91], v[92:95], v[32:47]
	s_waitcnt lgkmcnt(1)
	v_mfma_f32_32x32x16_bf16 v[48:63], v[88:91], v[106:109], v[48:63]
	ds_read_b128 v[88:91], v172 offset:4096
	ds_read_b128 v[114:117], v173 offset:4096
	s_waitcnt lgkmcnt(1)
	v_mfma_f32_32x32x16_bf16 v[0:15], v[88:91], v[92:95], v[0:15]
	v_mfma_f32_32x32x16_bf16 v[16:31], v[88:91], v[106:109], v[16:31]
	v_mfma_f32_32x32x16_bf16 v[32:47], v[98:101], v[102:105], v[32:47]
	v_mfma_f32_32x32x16_bf16 v[48:63], v[98:101], v[110:113], v[48:63]
	s_waitcnt lgkmcnt(0)
	v_mfma_f32_32x32x16_bf16 v[0:15], v[114:117], v[102:105], v[0:15]
	s_waitcnt vmcnt(0)
	s_barrier
	v_lshl_add_u64 v[66:67], v[66:67], 0, s[96:97]
	s_add_u32 m0, s94, 0x0
	s_nop 1
	global_load_lds_dwordx4 v[66:67], off
	v_lshl_add_u64 v[68:69], v[68:69], 0, s[96:97]
	s_add_u32 m0, s94, 0x4000
	s_nop 1
	global_load_lds_dwordx4 v[68:69], off
	v_lshl_add_u64 v[70:71], v[70:71], 0, s[96:97]
	s_add_u32 m0, s94, 0x1000
	s_nop 1
	global_load_lds_dwordx4 v[70:71], off
	v_lshl_add_u64 v[72:73], v[72:73], 0, s[96:97]
	s_add_u32 m0, s94, 0x5000
	s_nop 1
	global_load_lds_dwordx4 v[72:73], off
	v_lshl_add_u64 v[74:75], v[74:75], 0, s[96:97]
	s_add_u32 m0, s94, 0x2000
	s_nop 1
	global_load_lds_dwordx4 v[74:75], off
	v_lshl_add_u64 v[76:77], v[76:77], 0, s[96:97]
	s_add_u32 m0, s94, 0x6000
	s_nop 1
	global_load_lds_dwordx4 v[76:77], off
	v_lshl_add_u64 v[80:81], v[80:81], 0, s[96:97]
	s_add_u32 m0, s94, 0x3000
	s_nop 1
	global_load_lds_dwordx4 v[80:81], off
	v_lshl_add_u64 v[78:79], v[78:79], 0, s[96:97]
	s_add_u32 m0, s94, 0x7000
	s_nop 1
	global_load_lds_dwordx4 v[78:79], off
	v_mfma_f32_32x32x16_bf16 v[16:31], v[114:117], v[110:113], v[16:31]
	ds_read_b128 v[88:91], v170 offset:32768
	ds_read_b128 v[92:95], v174 offset:49152
	ds_read_b128 v[98:101], v171 offset:32768
	ds_read_b128 v[102:105], v175 offset:49152
	ds_read_b128 v[106:109], v174 offset:53248
	ds_read_b128 v[110:113], v175 offset:53248
	s_waitcnt lgkmcnt(4)
	v_mfma_f32_32x32x16_bf16 v[32:47], v[88:91], v[92:95], v[32:47]
	s_waitcnt lgkmcnt(1)
	v_mfma_f32_32x32x16_bf16 v[48:63], v[88:91], v[106:109], v[48:63]
	ds_read_b128 v[88:91], v170 offset:36864
	ds_read_b128 v[114:117], v171 offset:36864
	s_waitcnt lgkmcnt(1)
	v_mfma_f32_32x32x16_bf16 v[0:15], v[88:91], v[92:95], v[0:15]
	v_mfma_f32_32x32x16_bf16 v[16:31], v[88:91], v[106:109], v[16:31]
	v_mfma_f32_32x32x16_bf16 v[32:47], v[98:101], v[102:105], v[32:47]
	v_mfma_f32_32x32x16_bf16 v[48:63], v[98:101], v[110:113], v[48:63]
	s_waitcnt lgkmcnt(0)
	v_mfma_f32_32x32x16_bf16 v[0:15], v[114:117], v[102:105], v[0:15]
	ds_read_b128 v[88:91], v172 offset:32768
	ds_read_b128 v[92:95], v176 offset:49152
	ds_read_b128 v[98:101], v173 offset:32768
	ds_read_b128 v[102:105], v177 offset:49152
	v_mfma_f32_32x32x16_bf16 v[16:31], v[114:117], v[110:113], v[16:31]
	ds_read_b128 v[106:109], v176 offset:53248
	ds_read_b128 v[110:113], v177 offset:53248
	s_waitcnt lgkmcnt(4)
	v_mfma_f32_32x32x16_bf16 v[32:47], v[88:91], v[92:95], v[32:47]
	s_waitcnt lgkmcnt(1)
	v_mfma_f32_32x32x16_bf16 v[48:63], v[88:91], v[106:109], v[48:63]
	ds_read_b128 v[88:91], v172 offset:36864
	ds_read_b128 v[114:117], v173 offset:36864
	s_waitcnt lgkmcnt(1)
	v_mfma_f32_32x32x16_bf16 v[0:15], v[88:91], v[92:95], v[0:15]
	v_mfma_f32_32x32x16_bf16 v[16:31], v[88:91], v[106:109], v[16:31]
	v_mfma_f32_32x32x16_bf16 v[32:47], v[98:101], v[102:105], v[32:47]
	v_mfma_f32_32x32x16_bf16 v[48:63], v[98:101], v[110:113], v[48:63]
	s_waitcnt lgkmcnt(0)
	v_mfma_f32_32x32x16_bf16 v[0:15], v[114:117], v[102:105], v[0:15]
	s_waitcnt vmcnt(0)
	s_barrier
;     ...
;   bf16* As1 = As + 2 * 128 * 72;
;   bf16* Bs1 = As1 + 128 * 72;
;   G_LOAD(ra0, rb0, 0);
;   if (nk > 1) G_LOAD(ra1, rb1, 1);
;   G_STORE(ra0, rb0, As, Bs);
;   __syncthreads();
;   for (int kt = 0; kt < nk; kt += 2) {
;     if (kt + 2 < nk) G_LOAD(ra0, rb0, kt + 2);
;     if (kt + 1 < nk) G_STORE(ra1, rb1, As1, Bs1);
;     G_COMPUTE(As, Bs);
;     __syncthreads();
;     if (kt + 1 < nk) {
;       if (kt + 3 < nk) G_LOAD(ra1, rb1, kt + 3);
;       if (kt + 2 < nk) G_STORE(ra0, rb0, As, Bs);
;       G_COMPUTE(As1, Bs1);
;       __syncthreads();
;     }
;   }
	v_lshl_add_u64 v[66:67], v[66:67], 0, s[96:97]
	s_add_u32 m0, s94, 0x8000
	s_nop 1
	global_load_lds_dwordx4 v[66:67], off
	v_lshl_add_u64 v[68:69], v[68:69], 0, s[96:97]
	s_add_u32 m0, s94, 0xc000
	s_nop 1
	global_load_lds_dwordx4 v[68:69], off
	v_lshl_add_u64 v[70:71], v[70:71], 0, s[96:97]
	s_add_u32 m0, s94, 0x9000
	s_nop 1
	global_load_lds_dwordx4 v[70:71], off
	v_lshl_add_u64 v[72:73], v[72:73], 0, s[96:97]
	s_add_u32 m0, s94, 0xd000
	s_nop 1
	global_load_lds_dwordx4 v[72:73], off
	v_lshl_add_u64 v[74:75], v[74:75], 0, s[96:97]
	s_add_u32 m0, s94, 0xa000
	s_nop 1
	global_load_lds_dwordx4 v[74:75], off
	v_lshl_add_u64 v[76:77], v[76:77], 0, s[96:97]
	s_add_u32 m0, s94, 0xe000
	s_nop 1
	global_load_lds_dwordx4 v[76:77], off
	v_lshl_add_u64 v[80:81], v[80:81], 0, s[96:97]
	s_add_u32 m0, s94, 0xb000
	s_nop 1
	global_load_lds_dwordx4 v[80:81], off
	v_lshl_add_u64 v[78:79], v[78:79], 0, s[96:97]
	s_add_u32 m0, s94, 0xf000
	s_nop 1
	global_load_lds_dwordx4 v[78:79], off
	v_mfma_f32_32x32x16_bf16 v[16:31], v[114:117], v[110:113], v[16:31]
	ds_read_b128 v[88:91], v170 offset:0
	ds_read_b128 v[92:95], v174 offset:16384
	ds_read_b128 v[98:101], v171 offset:0
	ds_read_b128 v[102:105], v175 offset:16384
	ds_read_b128 v[106:109], v174 offset:20480
	ds_read_b128 v[110:113], v175 offset:20480
	s_waitcnt lgkmcnt(4)
	v_mfma_f32_32x32x16_bf16 v[32:47], v[88:91], v[92:95], v[32:47]
	s_waitcnt lgkmcnt(1)
	v_mfma_f32_32x32x16_bf16 v[48:63], v[88:91], v[106:109], v[48:63]
	ds_read_b128 v[88:91], v170 offset:4096
	ds_read_b128 v[114:117], v171 offset:4096
	s_waitcnt lgkmcnt(1)
	v_mfma_f32_32x32x16_bf16 v[0:15], v[88:91], v[92:95], v[0:15]
	v_mfma_f32_32x32x16_bf16 v[16:31], v[88:91], v[106:109], v[16:31]
	v_mfma_f32_32x32x16_bf16 v[32:47], v[98:101], v[102:105], v[32:47]
	v_mfma_f32_32x32x16_bf16 v[48:63], v[98:101], v[110:113], v[48:63]
	s_waitcnt lgkmcnt(0)
	v_mfma_f32_32x32x16_bf16 v[0:15], v[114:117], v[102:105], v[0:15]
	ds_read_b128 v[88:91], v172 offset:0
	ds_read_b128 v[92:95], v176 offset:16384
	ds_read_b128 v[98:101], v173 offset:0
	ds_read_b128 v[102:105], v177 offset:16384
	v_mfma_f32_32x32x16_bf16 v[16:31], v[114:117], v[110:113], v[16:31]
	ds_read_b128 v[106:109], v176 offset:20480
	ds_read_b128 v[110:113], v177 offset:20480
	s_waitcnt lgkmcnt(4)
	v_mfma_f32_32x32x16_bf16 v[32:47], v[88:91], v[92:95], v[32:47]
	s_waitcnt lgkmcnt(1)
	v_mfma_f32_32x32x16_bf16 v[48:63], v[88:91], v[106:109], v[48:63]
	ds_read_b128 v[88:91], v172 offset:4096
	ds_read_b128 v[114:117], v173 offset:4096
	s_waitcnt lgkmcnt(1)
	v_mfma_f32_32x32x16_bf16 v[0:15], v[88:91], v[92:95], v[0:15]
	v_mfma_f32_32x32x16_bf16 v[16:31], v[88:91], v[106:109], v[16:31]
	v_mfma_f32_32x32x16_bf16 v[32:47], v[98:101], v[102:105], v[32:47]
	v_mfma_f32_32x32x16_bf16 v[48:63], v[98:101], v[110:113], v[48:63]
	s_waitcnt lgkmcnt(0)
	v_mfma_f32_32x32x16_bf16 v[0:15], v[114:117], v[102:105], v[0:15]
	s_waitcnt vmcnt(0)
	s_barrier
	v_lshl_add_u64 v[66:67], v[66:67], 0, s[96:97]
	s_add_u32 m0, s94, 0x0
	s_nop 1
	global_load_lds_dwordx4 v[66:67], off
	v_lshl_add_u64 v[68:69], v[68:69], 0, s[96:97]
	s_add_u32 m0, s94, 0x4000
	s_nop 1
	global_load_lds_dwordx4 v[68:69], off
	v_lshl_add_u64 v[70:71], v[70:71], 0, s[96:97]
	s_add_u32 m0, s94, 0x1000
	s_nop 1
	global_load_lds_dwordx4 v[70:71], off
	v_lshl_add_u64 v[72:73], v[72:73], 0, s[96:97]
	s_add_u32 m0, s94, 0x5000
	s_nop 1
	global_load_lds_dwordx4 v[72:73], off
	v_lshl_add_u64 v[74:75], v[74:75], 0, s[96:97]
	s_add_u32 m0, s94, 0x2000
	s_nop 1
	global_load_lds_dwordx4 v[74:75], off
	v_lshl_add_u64 v[76:77], v[76:77], 0, s[96:97]
	s_add_u32 m0, s94, 0x6000
	s_nop 1
	global_load_lds_dwordx4 v[76:77], off
	v_lshl_add_u64 v[80:81], v[80:81], 0, s[96:97]
	s_add_u32 m0, s94, 0x3000
	s_nop 1
	global_load_lds_dwordx4 v[80:81], off
	v_lshl_add_u64 v[78:79], v[78:79], 0, s[96:97]
	s_add_u32 m0, s94, 0x7000
	s_nop 1
	global_load_lds_dwordx4 v[78:79], off
	v_mfma_f32_32x32x16_bf16 v[16:31], v[114:117], v[110:113], v[16:31]
	ds_read_b128 v[88:91], v170 offset:32768
	ds_read_b128 v[92:95], v174 offset:49152
	ds_read_b128 v[98:101], v171 offset:32768
	ds_read_b128 v[102:105], v175 offset:49152
	ds_read_b128 v[106:109], v174 offset:53248
	ds_read_b128 v[110:113], v175 offset:53248
	s_waitcnt lgkmcnt(4)
	v_mfma_f32_32x32x16_bf16 v[32:47], v[88:91], v[92:95], v[32:47]
	s_waitcnt lgkmcnt(1)
	v_mfma_f32_32x32x16_bf16 v[48:63], v[88:91], v[106:109], v[48:63]
	ds_read_b128 v[88:91], v170 offset:36864
	ds_read_b128 v[114:117], v171 offset:36864
	s_waitcnt lgkmcnt(1)
	v_mfma_f32_32x32x16_bf16 v[0:15], v[88:91], v[92:95], v[0:15]
	v_mfma_f32_32x32x16_bf16 v[16:31], v[88:91], v[106:109], v[16:31]
	v_mfma_f32_32x32x16_bf16 v[32:47], v[98:101], v[102:105], v[32:47]
	v_mfma_f32_32x32x16_bf16 v[48:63], v[98:101], v[110:113], v[48:63]
	s_waitcnt lgkmcnt(0)
	v_mfma_f32_32x32x16_bf16 v[0:15], v[114:117], v[102:105], v[0:15]
	ds_read_b128 v[88:91], v172 offset:32768
	ds_read_b128 v[92:95], v176 offset:49152
	ds_read_b128 v[98:101], v173 offset:32768
	ds_read_b128 v[102:105], v177 offset:49152
	v_mfma_f32_32x32x16_bf16 v[16:31], v[114:117], v[110:113], v[16:31]
	ds_read_b128 v[106:109], v176 offset:53248
	ds_read_b128 v[110:113], v177 offset:53248
	s_waitcnt lgkmcnt(4)
	v_mfma_f32_32x32x16_bf16 v[32:47], v[88:91], v[92:95], v[32:47]
	s_waitcnt lgkmcnt(1)
	v_mfma_f32_32x32x16_bf16 v[48:63], v[88:91], v[106:109], v[48:63]
	ds_read_b128 v[88:91], v172 offset:36864
	ds_read_b128 v[114:117], v173 offset:36864
	s_waitcnt lgkmcnt(1)
	v_mfma_f32_32x32x16_bf16 v[0:15], v[88:91], v[92:95], v[0:15]
	v_mfma_f32_32x32x16_bf16 v[16:31], v[88:91], v[106:109], v[16:31]
	v_mfma_f32_32x32x16_bf16 v[32:47], v[98:101], v[102:105], v[32:47]
	v_mfma_f32_32x32x16_bf16 v[48:63], v[98:101], v[110:113], v[48:63]
	s_waitcnt lgkmcnt(0)
	v_mfma_f32_32x32x16_bf16 v[0:15], v[114:117], v[102:105], v[0:15]
	s_waitcnt vmcnt(0)
	s_barrier
;     ...
;   bf16* As1 = As + 2 * 128 * 72;
;   bf16* Bs1 = As1 + 128 * 72;
;   G_LOAD(ra0, rb0, 0);
;   if (nk > 1) G_LOAD(ra1, rb1, 1);
;   G_STORE(ra0, rb0, As, Bs);
;   __syncthreads();
;   for (int kt = 0; kt < nk; kt += 2) {
;     if (kt + 2 < nk) G_LOAD(ra0, rb0, kt + 2);
;     if (kt + 1 < nk) G_STORE(ra1, rb1, As1, Bs1);
;     G_COMPUTE(As, Bs);
;     __syncthreads();
;     if (kt + 1 < nk) {
;       if (kt + 3 < nk) G_LOAD(ra1, rb1, kt + 3);
;       if (kt + 2 < nk) G_STORE(ra0, rb0, As, Bs);
;       G_COMPUTE(As1, Bs1);
;       __syncthreads();
;     }
;   }
	v_lshl_add_u64 v[66:67], v[66:67], 0, s[96:97]
	s_add_u32 m0, s94, 0x8000
	s_nop 1
	global_load_lds_dwordx4 v[66:67], off
	v_lshl_add_u64 v[68:69], v[68:69], 0, s[96:97]
	s_add_u32 m0, s94, 0xc000
	s_nop 1
	global_load_lds_dwordx4 v[68:69], off
	v_lshl_add_u64 v[70:71], v[70:71], 0, s[96:97]
	s_add_u32 m0, s94, 0x9000
	s_nop 1
	global_load_lds_dwordx4 v[70:71], off
	v_lshl_add_u64 v[72:73], v[72:73], 0, s[96:97]
	s_add_u32 m0, s94, 0xd000
	s_nop 1
	global_load_lds_dwordx4 v[72:73], off
	v_lshl_add_u64 v[74:75], v[74:75], 0, s[96:97]
	s_add_u32 m0, s94, 0xa000
	s_nop 1
	global_load_lds_dwordx4 v[74:75], off
	v_lshl_add_u64 v[76:77], v[76:77], 0, s[96:97]
	s_add_u32 m0, s94, 0xe000
	s_nop 1
	global_load_lds_dwordx4 v[76:77], off
	v_lshl_add_u64 v[80:81], v[80:81], 0, s[96:97]
	s_add_u32 m0, s94, 0xb000
	s_nop 1
	global_load_lds_dwordx4 v[80:81], off
	v_lshl_add_u64 v[78:79], v[78:79], 0, s[96:97]
	s_add_u32 m0, s94, 0xf000
	s_nop 1
	global_load_lds_dwordx4 v[78:79], off
	v_mfma_f32_32x32x16_bf16 v[16:31], v[114:117], v[110:113], v[16:31]
	ds_read_b128 v[88:91], v170 offset:0
	ds_read_b128 v[92:95], v174 offset:16384
	ds_read_b128 v[98:101], v171 offset:0
	ds_read_b128 v[102:105], v175 offset:16384
	ds_read_b128 v[106:109], v174 offset:20480
	ds_read_b128 v[110:113], v175 offset:20480
	s_waitcnt lgkmcnt(4)
	v_mfma_f32_32x32x16_bf16 v[32:47], v[88:91], v[92:95], v[32:47]
	s_waitcnt lgkmcnt(1)
	v_mfma_f32_32x32x16_bf16 v[48:63], v[88:91], v[106:109], v[48:63]
	ds_read_b128 v[88:91], v170 offset:4096
	ds_read_b128 v[114:117], v171 offset:4096
	s_waitcnt lgkmcnt(1)
	v_mfma_f32_32x32x16_bf16 v[0:15], v[88:91], v[92:95], v[0:15]
	v_mfma_f32_32x32x16_bf16 v[16:31], v[88:91], v[106:109], v[16:31]
	v_mfma_f32_32x32x16_bf16 v[32:47], v[98:101], v[102:105], v[32:47]
	v_mfma_f32_32x32x16_bf16 v[48:63], v[98:101], v[110:113], v[48:63]
	s_waitcnt lgkmcnt(0)
	v_mfma_f32_32x32x16_bf16 v[0:15], v[114:117], v[102:105], v[0:15]
	ds_read_b128 v[88:91], v172 offset:0
	ds_read_b128 v[92:95], v176 offset:16384
	ds_read_b128 v[98:101], v173 offset:0
	ds_read_b128 v[102:105], v177 offset:16384
	v_mfma_f32_32x32x16_bf16 v[16:31], v[114:117], v[110:113], v[16:31]
	ds_read_b128 v[106:109], v176 offset:20480
	ds_read_b128 v[110:113], v177 offset:20480
	s_waitcnt lgkmcnt(4)
	v_mfma_f32_32x32x16_bf16 v[32:47], v[88:91], v[92:95], v[32:47]
	s_waitcnt lgkmcnt(1)
	v_mfma_f32_32x32x16_bf16 v[48:63], v[88:91], v[106:109], v[48:63]
	ds_read_b128 v[88:91], v172 offset:4096
	ds_read_b128 v[114:117], v173 offset:4096
	s_waitcnt lgkmcnt(1)
	v_mfma_f32_32x32x16_bf16 v[0:15], v[88:91], v[92:95], v[0:15]
	v_mfma_f32_32x32x16_bf16 v[16:31], v[88:91], v[106:109], v[16:31]
	v_mfma_f32_32x32x16_bf16 v[32:47], v[98:101], v[102:105], v[32:47]
	v_mfma_f32_32x32x16_bf16 v[48:63], v[98:101], v[110:113], v[48:63]
	s_waitcnt lgkmcnt(0)
	v_mfma_f32_32x32x16_bf16 v[0:15], v[114:117], v[102:105], v[0:15]
	s_waitcnt vmcnt(0)
	s_barrier
	v_lshl_add_u64 v[66:67], v[66:67], 0, s[96:97]
	s_add_u32 m0, s94, 0x0
	s_nop 1
	global_load_lds_dwordx4 v[66:67], off
	v_lshl_add_u64 v[68:69], v[68:69], 0, s[96:97]
	s_add_u32 m0, s94, 0x4000
	s_nop 1
	global_load_lds_dwordx4 v[68:69], off
	v_lshl_add_u64 v[70:71], v[70:71], 0, s[96:97]
	s_add_u32 m0, s94, 0x1000
	s_nop 1
	global_load_lds_dwordx4 v[70:71], off
	v_lshl_add_u64 v[72:73], v[72:73], 0, s[96:97]
	s_add_u32 m0, s94, 0x5000
	s_nop 1
	global_load_lds_dwordx4 v[72:73], off
	v_lshl_add_u64 v[74:75], v[74:75], 0, s[96:97]
	s_add_u32 m0, s94, 0x2000
	s_nop 1
	global_load_lds_dwordx4 v[74:75], off
	v_lshl_add_u64 v[76:77], v[76:77], 0, s[96:97]
	s_add_u32 m0, s94, 0x6000
	s_nop 1
	global_load_lds_dwordx4 v[76:77], off
	v_lshl_add_u64 v[80:81], v[80:81], 0, s[96:97]
	s_add_u32 m0, s94, 0x3000
	s_nop 1
	global_load_lds_dwordx4 v[80:81], off
	v_lshl_add_u64 v[78:79], v[78:79], 0, s[96:97]
	s_add_u32 m0, s94, 0x7000
	s_nop 1
	global_load_lds_dwordx4 v[78:79], off
	v_mfma_f32_32x32x16_bf16 v[16:31], v[114:117], v[110:113], v[16:31]
	ds_read_b128 v[88:91], v170 offset:32768
	ds_read_b128 v[92:95], v174 offset:49152
	ds_read_b128 v[98:101], v171 offset:32768
	ds_read_b128 v[102:105], v175 offset:49152
	ds_read_b128 v[106:109], v174 offset:53248
	ds_read_b128 v[110:113], v175 offset:53248
	s_waitcnt lgkmcnt(4)
	v_mfma_f32_32x32x16_bf16 v[32:47], v[88:91], v[92:95], v[32:47]
	s_waitcnt lgkmcnt(1)
	v_mfma_f32_32x32x16_bf16 v[48:63], v[88:91], v[106:109], v[48:63]
	ds_read_b128 v[88:91], v170 offset:36864
	ds_read_b128 v[114:117], v171 offset:36864
	s_waitcnt lgkmcnt(1)
	v_mfma_f32_32x32x16_bf16 v[0:15], v[88:91], v[92:95], v[0:15]
	v_mfma_f32_32x32x16_bf16 v[16:31], v[88:91], v[106:109], v[16:31]
	v_mfma_f32_32x32x16_bf16 v[32:47], v[98:101], v[102:105], v[32:47]
	v_mfma_f32_32x32x16_bf16 v[48:63], v[98:101], v[110:113], v[48:63]
	s_waitcnt lgkmcnt(0)
	v_mfma_f32_32x32x16_bf16 v[0:15], v[114:117], v[102:105], v[0:15]
	ds_read_b128 v[88:91], v172 offset:32768
	ds_read_b128 v[92:95], v176 offset:49152
	ds_read_b128 v[98:101], v173 offset:32768
	ds_read_b128 v[102:105], v177 offset:49152
	v_mfma_f32_32x32x16_bf16 v[16:31], v[114:117], v[110:113], v[16:31]
	ds_read_b128 v[106:109], v176 offset:53248
	ds_read_b128 v[110:113], v177 offset:53248
	s_waitcnt lgkmcnt(4)
	v_mfma_f32_32x32x16_bf16 v[32:47], v[88:91], v[92:95], v[32:47]
	s_waitcnt lgkmcnt(1)
	v_mfma_f32_32x32x16_bf16 v[48:63], v[88:91], v[106:109], v[48:63]
	ds_read_b128 v[88:91], v172 offset:36864
	ds_read_b128 v[114:117], v173 offset:36864
	s_waitcnt lgkmcnt(1)
	v_mfma_f32_32x32x16_bf16 v[0:15], v[88:91], v[92:95], v[0:15]
	v_mfma_f32_32x32x16_bf16 v[16:31], v[88:91], v[106:109], v[16:31]
	v_mfma_f32_32x32x16_bf16 v[32:47], v[98:101], v[102:105], v[32:47]
	v_mfma_f32_32x32x16_bf16 v[48:63], v[98:101], v[110:113], v[48:63]
	s_nop 0
	s_nop 0
	s_nop 0
	s_nop 0
	s_nop 0
	s_nop 0
	s_nop 0
	s_waitcnt lgkmcnt(0)
	s_waitcnt vmcnt(0)
	s_barrier
; #define PW(T, off) ((T*)(lndp(p.ws) + (off)))
; DEVI void gemm_epi_qkv(const Params& p, f32x16 (&acc)[2][2], int rbase, int cbase, int lane) {
;   char* ar = PW(char, W_arena);
;   const int which = cbase >> 10, cc = cbase & 1023, d = lane & 31, hl = lane >> 5;
; #pragma unroll
;   for (int i = 0; i < 2; ++i) {
; #pragma unroll
;     for (int rq = 0; rq < 4; ++rq) {
;       const int row0 = rbase + i * 32 + 8 * rq + 4 * hl;
;       if (row0 >= M) continue;
;       const bool pr = row0 < TP;
;       const int b = pr ? 0 : (row0 - TP) >> 4, t0 = pr ? row0 : (row0 - TP) & 15;
;       if (which < 2) {
;         const float* csp = PW(float, W_cs) + (size_t)row0 * 64 + d;
;         bf16* dst;
;         float* fo = nullptr;
;         if (which == 0) dst = (bf16*)(ar + A_QB) + (size_t)row0 * 1024 + cc + d;
;         else {
;           const size_t ur = pr ? (size_t)(48 + row0) : (size_t)(LDVP + b * LDVS + 48 + 4096 + t0);
;           dst = (bf16*)(ar + A_KALL) + ur * 1024 + cc + d;
;     ...
;   bf16* As1 = As + 2 * 128 * 72;
;   bf16* Bs1 = As1 + 128 * 72;
;   G_LOAD(ra0, rb0, 0);
;   if (nk > 1) G_LOAD(ra1, rb1, 1);
;   G_STORE(ra0, rb0, As, Bs);
;   __syncthreads();
;   for (int kt = 0; kt < nk; kt += 2) {
;     if (kt + 2 < nk) G_LOAD(ra0, rb0, kt + 2);
;     if (kt + 1 < nk) G_STORE(ra1, rb1, As1, Bs1);
;     G_COMPUTE(As, Bs);
;     __syncthreads();
;     if (kt + 1 < nk) {
;       if (kt + 3 < nk) G_LOAD(ra1, rb1, kt + 3);
;       if (kt + 2 < nk) G_STORE(ra0, rb0, As, Bs);
;       G_COMPUTE(As1, Bs1);
;       __syncthreads();
;     }
;   }
	v_lshl_add_u64 v[66:67], v[66:67], 0, s[96:97]
	s_add_u32 m0, s94, 0x8000
	s_nop 1
	global_load_lds_dwordx4 v[66:67], off
	v_lshl_add_u64 v[68:69], v[68:69], 0, s[96:97]
	s_add_u32 m0, s94, 0xc000
	s_nop 1
	global_load_lds_dwordx4 v[68:69], off
	v_lshl_add_u64 v[70:71], v[70:71], 0, s[96:97]
	s_add_u32 m0, s94, 0x9000
	s_nop 1
	global_load_lds_dwordx4 v[70:71], off
	v_lshl_add_u64 v[72:73], v[72:73], 0, s[96:97]
	s_add_u32 m0, s94, 0xd000
	s_nop 1
	global_load_lds_dwordx4 v[72:73], off
	v_lshl_add_u64 v[74:75], v[74:75], 0, s[96:97]
	s_add_u32 m0, s94, 0xa000
	s_nop 1
	global_load_lds_dwordx4 v[74:75], off
	v_lshl_add_u64 v[76:77], v[76:77], 0, s[96:97]
	s_add_u32 m0, s94, 0xe000
	s_nop 1
	global_load_lds_dwordx4 v[76:77], off
	v_lshl_add_u64 v[80:81], v[80:81], 0, s[96:97]
	s_add_u32 m0, s94, 0xb000
	s_nop 1
	global_load_lds_dwordx4 v[80:81], off
	v_lshl_add_u64 v[78:79], v[78:79], 0, s[96:97]
	s_add_u32 m0, s94, 0xf000
	s_nop 1
	global_load_lds_dwordx4 v[78:79], off
	v_mfma_f32_32x32x16_bf16 v[0:15], v[114:117], v[102:105], v[0:15]
	ds_read_b128 v[66:69], v170 offset:0
	ds_read_b128 v[70:73], v174 offset:16384
	ds_read_b128 v[74:77], v171 offset:0
	ds_read_b128 v[78:81], v175 offset:16384
	ds_read_b128 v[88:91], v174 offset:20480
	ds_read_b128 v[92:95], v175 offset:20480
	v_mfma_f32_32x32x16_bf16 v[16:31], v[114:117], v[110:113], v[16:31]
	s_waitcnt lgkmcnt(4)
	v_mfma_f32_32x32x16_bf16 v[32:47], v[66:69], v[70:73], v[32:47]
	s_waitcnt lgkmcnt(1)
	v_mfma_f32_32x32x16_bf16 v[48:63], v[66:69], v[88:91], v[48:63]
	ds_read_b128 v[66:69], v170 offset:4096
	ds_read_b128 v[98:101], v171 offset:4096
	s_waitcnt lgkmcnt(1)
	v_mfma_f32_32x32x16_bf16 v[0:15], v[66:69], v[70:73], v[0:15]
	v_mfma_f32_32x32x16_bf16 v[16:31], v[66:69], v[88:91], v[16:31]
	v_mfma_f32_32x32x16_bf16 v[32:47], v[74:77], v[78:81], v[32:47]
	v_mfma_f32_32x32x16_bf16 v[48:63], v[74:77], v[92:95], v[48:63]
	s_waitcnt lgkmcnt(0)
	v_mfma_f32_32x32x16_bf16 v[0:15], v[98:101], v[78:81], v[0:15]
	ds_read_b128 v[66:69], v172 offset:0
	ds_read_b128 v[70:73], v176 offset:16384
	ds_read_b128 v[74:77], v173 offset:0
	ds_read_b128 v[78:81], v177 offset:16384
	v_mfma_f32_32x32x16_bf16 v[16:31], v[98:101], v[92:95], v[16:31]
	ds_read_b128 v[88:91], v176 offset:20480
	ds_read_b128 v[92:95], v177 offset:20480
	s_waitcnt lgkmcnt(4)
	v_mfma_f32_32x32x16_bf16 v[32:47], v[66:69], v[70:73], v[32:47]
	s_waitcnt lgkmcnt(1)
	v_mfma_f32_32x32x16_bf16 v[48:63], v[66:69], v[88:91], v[48:63]
	ds_read_b128 v[66:69], v172 offset:4096
	ds_read_b128 v[98:101], v173 offset:4096
	s_waitcnt lgkmcnt(0)
	s_waitcnt vmcnt(0)
	s_barrier
	v_mfma_f32_32x32x16_bf16 v[0:15], v[66:69], v[70:73], v[0:15]
	v_mfma_f32_32x32x16_bf16 v[32:47], v[74:77], v[78:81], v[32:47]
	v_mfma_f32_32x32x16_bf16 v[48:63], v[74:77], v[92:95], v[48:63]
	v_mfma_f32_32x32x16_bf16 v[16:31], v[66:69], v[88:91], v[16:31]
	v_mfma_f32_32x32x16_bf16 v[0:15], v[98:101], v[78:81], v[0:15]
	ds_read_b128 v[66:69], v170 offset:32768
	ds_read_b128 v[70:73], v174 offset:49152
	ds_read_b128 v[74:77], v175 offset:49152
	ds_read_b128 v[78:81], v171 offset:32768
	ds_read_b128 v[88:91], v174 offset:53248
	s_waitcnt lgkmcnt(3)
	v_mfma_f32_32x32x16_bf16 v[32:47], v[66:69], v[70:73], v[32:47]
	s_waitcnt lgkmcnt(0)
	v_mfma_f32_32x32x16_bf16 v[48:63], v[66:69], v[88:91], v[48:63]
	ds_read_b128 v[66:69], v170 offset:36864
	v_mfma_f32_32x32x16_bf16 v[16:31], v[98:101], v[92:95], v[16:31]
	s_waitcnt lgkmcnt(0)
	v_mfma_f32_32x32x16_bf16 v[0:15], v[66:69], v[70:73], v[0:15]
	ds_read_b128 v[70:73], v171 offset:36864
	v_mfma_f32_32x32x16_bf16 v[16:31], v[66:69], v[88:91], v[16:31]
	ds_read_b128 v[66:69], v175 offset:53248
	v_mfma_f32_32x32x16_bf16 v[32:47], v[78:81], v[74:77], v[32:47]
	s_waitcnt lgkmcnt(0)
	v_mfma_f32_32x32x16_bf16 v[48:63], v[78:81], v[66:69], v[48:63]
	v_and_or_b32 v80, v85, 64, s2
	v_or_b32_e32 v81, v80, v84
	v_mfma_f32_32x32x16_bf16 v[0:15], v[70:73], v[74:77], v[0:15]
	v_mfma_f32_32x32x16_bf16 v[16:31], v[70:73], v[66:69], v[16:31]
	ds_read_b128 v[66:69], v172 offset:32768
	ds_read_b128 v[70:73], v176 offset:49152
	ds_read_b128 v[74:77], v176 offset:53248
	s_waitcnt lgkmcnt(1)
	v_mfma_f32_32x32x16_bf16 v[32:47], v[66:69], v[70:73], v[32:47]
	s_waitcnt lgkmcnt(0)
	v_mfma_f32_32x32x16_bf16 v[48:63], v[66:69], v[74:77], v[48:63]
	ds_read_b128 v[66:69], v172 offset:36864
	s_waitcnt lgkmcnt(0)
	v_mfma_f32_32x32x16_bf16 v[0:15], v[66:69], v[70:73], v[0:15]
	ds_read_b128 v[88:91], v177 offset:53248
	ds_read_b128 v[92:95], v177 offset:49152
	ds_read_b128 v[70:73], v173 offset:32768
	v_lshrrev_b32_e32 v65, 3, v85
	v_and_b32_e32 v82, 4, v65
	v_mfma_f32_32x32x16_bf16 v[16:31], v[66:69], v[74:77], v[16:31]
	ds_read_b128 v[74:77], v173 offset:36864
	v_add_u32_e32 v64, s3, v86
	v_or_b32_e32 v68, v64, v82
	v_mul_u32_u24_e32 v64, 0x4040, v81
	v_lshlrev_b32_e32 v96, 1, v64
	s_waitcnt lgkmcnt(0)
	s_barrier
	v_mfma_f32_32x32x16_bf16 v[32:47], v[70:73], v[92:95], v[32:47]
	s_cmp_gt_i32 s5, 1
	s_cselect_b64 s[2:3], -1, 0
	v_lshl_add_u64 v[64:65], s[22:23], 0, v[96:97]
	v_lshlrev_b32_e32 v96, 1, v80
	s_cmpk_gt_u32 s4, 0x3ff
	s_cselect_b64 s[20:21], -1, 0
	v_mfma_f32_32x32x16_bf16 v[48:63], v[70:73], v[88:91], v[48:63]
	v_lshl_add_u64 v[70:71], v[64:65], 0, s[6:7]
	v_lshl_add_u64 v[64:65], s[22:23], 0, v[96:97]
	s_mov_b64 s[6:7], 0x13e3c000
	v_lshl_add_u64 v[66:67], v[64:65], 0, s[6:7]
	s_mov_b64 s[6:7], 0x11d7c000
	s_cmp_eq_u32 s5, 1
	v_lshl_add_u64 v[64:65], v[64:65], 0, s[6:7]
	v_mfma_f32_32x32x16_bf16 v[0:15], v[74:77], v[92:95], v[0:15]
	s_cselect_b64 s[18:19], -1, 0
	v_cmp_gt_i32_e32 vcc, s90, v68
	v_mfma_f32_32x32x16_bf16 v[16:31], v[74:77], v[88:91], v[16:31]
	s_and_saveexec_b64 s[4:5], vcc
	s_cbranch_execz .LBB0_2113
	s_movk_i32 s6, 0x400f
	v_add_u32_e32 v72, 0xffffbff0, v68
	v_cmp_lt_i32_e64 s[6:7], s6, v68
	v_ashrrev_i32_e32 v78, 4, v72
	s_mov_b64 s[8:9], -1
	s_and_b64 vcc, exec, s[2:3]
	s_cbranch_vccz .LBB0_2092
	s_and_saveexec_b64 s[8:9], s[6:7]
	s_xor_b64 s[8:9], exec, s[8:9]
	s_cbranch_execz .LBB0_2085
	s_mov_b64 s[10:11], s[72:73]
	s_add_u32 s10, s10, 0xc48f000
	v_mov_b32_e32 v73, v97
	s_addc_u32 s11, s11, 0
	v_mov_b64_e32 v[74:75], v[72:73]

; DEVI int TID() { int t = threadIdx.x; asm volatile("" : "+v"(t)); return t; }
;   bf16* As = (bf16*)smem;
;   bf16* Bs = As + 128 * 72;
;   const int tid = TID(), lane = tid & 63, wave = tid >> 6, wm = wave >> 1, wn = wave & 1;
;   f32x16 acc[2][2];
; #pragma unroll
;   for (int i = 0; i < 2; ++i)
; #pragma unroll
;     for (int j = 0; j < 2; ++j) acc[i][j] = zero16();
;   const int lrow = tid >> 3, lkc = (tid & 7) * 8;
;   const bf16* Ag = jb.A + (size_t)max(m0 + lrow, 0) * jb.lda + lkc;
;   const bf16* Ag1 = jb.A + (ptrdiff_t)(m0 + lrow) * jb.lda + lkc;
;   const bf16* Bg = jb.Bt + (size_t)(n0 + lrow) * jb.K + lkc;
;   const size_t astep = (size_t)32 * jb.lda, bstep = (size_t)32 * jb.K;
;   if (kt1 < 0) kt1 = jb.K >> 6;
;   const int nk = kt1 - kt0;
;   Ag += (size_t)kt0 * 64; Ag1 += (size_t)kt0 * 64; Bg += (size_t)kt0 * 64;
;   u32x4 ra0[4], rb0[4], ra1[4], rb1[4];
;     ...
;   bf16* As1 = As + 2 * 128 * 72;
;   bf16* Bs1 = As1 + 128 * 72;
;   G_LOAD(ra0, rb0, 0);
;   if (nk > 1) G_LOAD(ra1, rb1, 1);
;   G_STORE(ra0, rb0, As, Bs);
;   __syncthreads();
.LBB0_2341:
	s_abs_i32 s3, s17
	s_mul_hi_u32 s4, s3, s30
	s_mul_i32 s5, s4, s27
	s_ashr_i32 s2, s17, 31
	s_sub_i32 s3, s3, s5
	s_xor_b32 s2, s2, s29
	s_add_i32 s5, s4, 1
	s_sub_i32 s6, s3, s27
	s_cmp_ge_u32 s3, s27
	s_cselect_b32 s4, s5, s4
	s_cselect_b32 s3, s6, s3
	s_add_i32 s5, s4, 1
	s_cmp_ge_u32 s3, s27
	s_cselect_b32 s3, s5, s4
	s_xor_b32 s3, s3, s2
	s_sub_i32 s4, s3, s2
	s_mul_i32 s2, s2, 6
	s_mul_i32 s3, s3, 6
	s_add_i32 s4, s4, s25
	s_sub_i32 s2, s2, s3
	s_add_i32 s3, s24, s17
	s_waitcnt vmcnt(2)
	v_mov_b32_e32 v85, v208
	s_add_i32 s2, s3, s2
	s_lshl_b32 s3, s4, 7
	s_lshl_b32 s4, s2, 7
	v_ashrrev_i32_e32 v64, 3, v85
	v_add_u32_e32 v0, s3, v64
	v_max_i32_e32 v96, 0, v0
	v_lshlrev_b32_e32 v1, 4, v85
	v_lshlrev_b64 v[2:3], 11, v[96:97]
	v_and_b32_e32 v96, 0x70, v1
	s_mov_b64 s[96:97], 0x80
	v_lshrrev_b32_e32 v178, 4, v208
	v_and_b32_e32 v178, 7, v178
	v_lshlrev_b32_e32 v178, 4, v178
	v_xor_b32_e32 v96, v96, v178
	v_lshrrev_b32_e32 v179, 6, v208
	v_lshlrev_b32_e32 v179, 10, v179
	v_lshrrev_b32_e32 v180, 5, v208
	v_lshrrev_b32_e32 v181, 1, v208
	v_xor_b32_e32 v180, v180, v181
	v_readfirstlane_b32 s94, v179
	v_and_b32_e32 v180, 1, v180
	v_lshlrev_b32_e32 v180, 4, v180
	v_and_b32_e32 v181, 31, v208
	v_lshlrev_b32_e32 v181, 7, v181
	v_or_b32_e32 v180, v180, v181
	v_lshrrev_b32_e32 v181, 7, v208
	v_lshlrev_b32_e32 v181, 13, v181
	v_or_b32_e32 v194, v180, v181
	v_bfe_u32 v181, v208, 6, 1
	v_lshlrev_b32_e32 v181, 13, v181
	v_or_b32_e32 v195, v180, v181
	v_bfe_u32 v178, v208, 2, 2
	v_xor_b32_e32 v179, 0, v178
	v_lshlrev_b32_e32 v179, 5, v179
	v_or_b32_e32 v170, v194, v179
	v_or_b32_e32 v174, v195, v179
	v_xor_b32_e32 v179, 1, v178
	v_lshlrev_b32_e32 v179, 5, v179
	v_or_b32_e32 v171, v194, v179
	v_or_b32_e32 v175, v195, v179
	v_xor_b32_e32 v179, 2, v178
	v_lshlrev_b32_e32 v179, 5, v179
	v_or_b32_e32 v172, v194, v179
	v_or_b32_e32 v176, v195, v179
	v_xor_b32_e32 v179, 3, v178
	v_lshlrev_b32_e32 v179, 5, v179
	v_or_b32_e32 v173, v194, v179
	v_or_b32_e32 v177, v195, v179
	v_ashrrev_i32_e32 v1, 31, v0
	v_lshlrev_b64 v[0:1], 11, v[0:1]
	v_lshl_add_u64 v[0:1], s[12:13], 0, v[0:1]
	v_lshl_add_u64 v[24:25], v[0:1], 0, v[96:97]
	v_add_u32_e32 v0, s4, v64
	v_ashrrev_i32_e32 v1, 31, v0
	v_lshlrev_b64 v[0:1], 11, v[0:1]
	v_lshl_add_u64 v[0:1], s[14:15], 0, v[0:1]
	v_add_co_u32_e32 v70, vcc, s63, v24
	v_lshl_add_u64 v[68:69], v[0:1], 0, v[96:97]
	s_nop 0
	v_addc_co_u32_e32 v71, vcc, 0, v25, vcc
	v_add_co_u32_e32 v72, vcc, s63, v68
	v_lshl_add_u64 v[2:3], s[12:13], 0, v[2:3]
	s_nop 0
	v_addc_co_u32_e32 v73, vcc, 0, v69, vcc
	v_add_co_u32_e32 v74, vcc, s64, v24
	v_lshl_add_u64 v[66:67], v[2:3], 0, v[96:97]
	s_nop 0
	v_addc_co_u32_e32 v75, vcc, 0, v25, vcc
	v_add_co_u32_e32 v76, vcc, s64, v68
	v_addc_co_u32_e32 v77, vcc, 0, v69, vcc
	v_add_co_u32_e32 v78, vcc, s65, v24
	s_nop 0
	v_addc_co_u32_e32 v79, vcc, 0, v25, vcc
	v_add_co_u32_e32 v80, vcc, s65, v68
	s_nop 0
	v_addc_co_u32_e32 v81, vcc, 0, v69, vcc
	v_ashrrev_i32_e32 v65, 1, v85
	v_and_b32_e32 v84, 31, v85
	v_lshrrev_b32_e32 v82, 1, v85
	v_and_b32_e32 v86, 0xffffffc0, v65
	s_waitcnt vmcnt(0)
	v_and_b32_e32 v88, 16, v82
	v_or_b32_e32 v65, v86, v84
	v_mad_u64_u32 v[82:83], s[6:7], v64, s91, v[96:97]
	v_add_u32_e32 v87, 0xd800, v82
	v_mad_u64_u32 v[64:65], s[6:7], v65, s91, v[88:89]
	v_and_b32_e32 v65, 0x5f, v85
	v_mad_u32_u24 v83, v65, s91, v88
	s_and_b32 s6, s4, 0x380
	s_mov_b64 s[22:23], s[74:75]
	s_ashr_i32 s5, s2, 3
	s_add_u32 m0, s94, 0x0
	s_nop 1
	global_load_lds_dwordx4 v[66:67], off
	s_add_u32 m0, s94, 0x4000
	s_nop 1
	global_load_lds_dwordx4 v[68:69], off
	s_add_u32 m0, s94, 0x1000
	s_nop 1
	global_load_lds_dwordx4 v[70:71], off
	s_add_u32 m0, s94, 0x2000
	s_nop 1
	global_load_lds_dwordx4 v[74:75], off
	s_add_u32 m0, s94, 0x3000
	s_nop 1
	global_load_lds_dwordx4 v[78:79], off
	s_add_u32 m0, s94, 0x5000
	s_nop 1
	global_load_lds_dwordx4 v[72:73], off
	s_add_u32 m0, s94, 0x6000
	s_nop 1
	global_load_lds_dwordx4 v[76:77], off
	s_add_u32 m0, s94, 0x7000
	s_nop 1
	global_load_lds_dwordx4 v[80:81], off
	s_waitcnt lgkmcnt(0)
	s_waitcnt vmcnt(0)
	s_barrier
	v_lshl_add_u64 v[66:67], v[66:67], 0, s[96:97]
	s_add_u32 m0, s94, 0x8000
	s_nop 1
	global_load_lds_dwordx4 v[66:67], off
	v_lshl_add_u64 v[68:69], v[68:69], 0, s[96:97]
	s_add_u32 m0, s94, 0xc000
	s_nop 1
	global_load_lds_dwordx4 v[68:69], off
	v_lshl_add_u64 v[70:71], v[70:71], 0, s[96:97]
	s_add_u32 m0, s94, 0x9000
	s_nop 1
	global_load_lds_dwordx4 v[70:71], off
	v_lshl_add_u64 v[72:73], v[72:73], 0, s[96:97]
	s_add_u32 m0, s94, 0xd000
	s_nop 1
	global_load_lds_dwordx4 v[72:73], off
	v_lshl_add_u64 v[74:75], v[74:75], 0, s[96:97]
	s_add_u32 m0, s94, 0xa000
	s_nop 1
	global_load_lds_dwordx4 v[74:75], off
	v_lshl_add_u64 v[76:77], v[76:77], 0, s[96:97]
	s_add_u32 m0, s94, 0xe000
	s_nop 1
	global_load_lds_dwordx4 v[76:77], off
	v_lshl_add_u64 v[78:79], v[78:79], 0, s[96:97]
	s_add_u32 m0, s94, 0xb000
	s_nop 1
	global_load_lds_dwordx4 v[78:79], off
	v_lshl_add_u64 v[80:81], v[80:81], 0, s[96:97]
	s_add_u32 m0, s94, 0xf000
	s_nop 1
	global_load_lds_dwordx4 v[80:81], off
	ds_read_b128 v[0:3], v170 offset:0
	ds_read_b128 v[4:7], v174 offset:16384
	ds_read_b128 v[88:91], v171 offset:0
	ds_read_b128 v[92:95], v175 offset:16384
	ds_read_b128 v[16:19], v174 offset:20480
	ds_read_b128 v[98:101], v175 offset:20480
	s_waitcnt lgkmcnt(4)
	v_mfma_f32_32x32x16_bf16 v[32:47], v[0:3], v[4:7], 0
	ds_read_b128 v[20:23], v170 offset:4096
	ds_read_b128 v[102:105], v171 offset:4096
	s_waitcnt lgkmcnt(3)
	v_mfma_f32_32x32x16_bf16 v[48:63], v[0:3], v[16:19], 0
	s_waitcnt lgkmcnt(1)
	v_mfma_f32_32x32x16_bf16 v[0:15], v[20:23], v[4:7], 0
	v_mfma_f32_32x32x16_bf16 v[16:31], v[20:23], v[16:19], 0
	v_mfma_f32_32x32x16_bf16 v[32:47], v[88:91], v[92:95], v[32:47]
	v_mfma_f32_32x32x16_bf16 v[48:63], v[88:91], v[98:101], v[48:63]
	s_waitcnt lgkmcnt(0)
	v_mfma_f32_32x32x16_bf16 v[0:15], v[102:105], v[92:95], v[0:15]
	v_mfma_f32_32x32x16_bf16 v[16:31], v[102:105], v[98:101], v[16:31]
	ds_read_b128 v[88:91], v172 offset:0
	ds_read_b128 v[92:95], v176 offset:16384
	ds_read_b128 v[98:101], v173 offset:0
	ds_read_b128 v[102:105], v177 offset:16384
	ds_read_b128 v[106:109], v176 offset:20480
	ds_read_b128 v[110:113], v177 offset:20480
	s_waitcnt lgkmcnt(4)
	v_mfma_f32_32x32x16_bf16 v[32:47], v[88:91], v[92:95], v[32:47]
	s_waitcnt lgkmcnt(1)
	v_mfma_f32_32x32x16_bf16 v[48:63], v[88:91], v[106:109], v[48:63]
	ds_read_b128 v[88:91], v172 offset:4096
	ds_read_b128 v[114:117], v173 offset:4096
	s_waitcnt lgkmcnt(1)
	v_mfma_f32_32x32x16_bf16 v[0:15], v[88:91], v[92:95], v[0:15]
	v_mfma_f32_32x32x16_bf16 v[16:31], v[88:91], v[106:109], v[16:31]
	v_mfma_f32_32x32x16_bf16 v[32:47], v[98:101], v[102:105], v[32:47]
	v_mfma_f32_32x32x16_bf16 v[48:63], v[98:101], v[110:113], v[48:63]
	s_waitcnt lgkmcnt(0)
	v_mfma_f32_32x32x16_bf16 v[0:15], v[114:117], v[102:105], v[0:15]
	s_waitcnt vmcnt(0)
	s_barrier
;     ...
;   bf16* As1 = As + 2 * 128 * 72;
;   bf16* Bs1 = As1 + 128 * 72;
;   G_LOAD(ra0, rb0, 0);
;   if (nk > 1) G_LOAD(ra1, rb1, 1);
;   G_STORE(ra0, rb0, As, Bs);
;   __syncthreads();
;   for (int kt = 0; kt < nk; kt += 2) {
;     if (kt + 2 < nk) G_LOAD(ra0, rb0, kt + 2);
;     if (kt + 1 < nk) G_STORE(ra1, rb1, As1, Bs1);
;     G_COMPUTE(As, Bs);
;     __syncthreads();
;     if (kt + 1 < nk) {
;       if (kt + 3 < nk) G_LOAD(ra1, rb1, kt + 3);
;       if (kt + 2 < nk) G_STORE(ra0, rb0, As, Bs);
;       G_COMPUTE(As1, Bs1);
;       __syncthreads();
;     }
;   }
	v_lshl_add_u64 v[66:67], v[66:67], 0, s[96:97]
	s_add_u32 m0, s94, 0x0
	s_nop 1
	global_load_lds_dwordx4 v[66:67], off
	v_lshl_add_u64 v[68:69], v[68:69], 0, s[96:97]
	s_add_u32 m0, s94, 0x4000
	s_nop 1
	global_load_lds_dwordx4 v[68:69], off
	v_lshl_add_u64 v[70:71], v[70:71], 0, s[96:97]
	s_add_u32 m0, s94, 0x1000
	s_nop 1
	global_load_lds_dwordx4 v[70:71], off
	v_lshl_add_u64 v[72:73], v[72:73], 0, s[96:97]
	s_add_u32 m0, s94, 0x5000
	s_nop 1
	global_load_lds_dwordx4 v[72:73], off
	v_lshl_add_u64 v[74:75], v[74:75], 0, s[96:97]
	s_add_u32 m0, s94, 0x2000
	s_nop 1
	global_load_lds_dwordx4 v[74:75], off
	v_lshl_add_u64 v[76:77], v[76:77], 0, s[96:97]
	s_add_u32 m0, s94, 0x6000
	s_nop 1
	global_load_lds_dwordx4 v[76:77], off
	v_lshl_add_u64 v[78:79], v[78:79], 0, s[96:97]
	s_add_u32 m0, s94, 0x3000
	s_nop 1
	global_load_lds_dwordx4 v[78:79], off
	v_lshl_add_u64 v[80:81], v[80:81], 0, s[96:97]
	s_add_u32 m0, s94, 0x7000
	s_nop 1
	global_load_lds_dwordx4 v[80:81], off
	v_mfma_f32_32x32x16_bf16 v[16:31], v[114:117], v[110:113], v[16:31]
	ds_read_b128 v[88:91], v170 offset:32768
	ds_read_b128 v[92:95], v174 offset:49152
	ds_read_b128 v[98:101], v171 offset:32768
	ds_read_b128 v[102:105], v175 offset:49152
	ds_read_b128 v[106:109], v174 offset:53248
	ds_read_b128 v[110:113], v175 offset:53248
	s_waitcnt lgkmcnt(4)
	v_mfma_f32_32x32x16_bf16 v[32:47], v[88:91], v[92:95], v[32:47]
	s_waitcnt lgkmcnt(1)
	v_mfma_f32_32x32x16_bf16 v[48:63], v[88:91], v[106:109], v[48:63]
	ds_read_b128 v[88:91], v170 offset:36864
	ds_read_b128 v[114:117], v171 offset:36864
	s_waitcnt lgkmcnt(1)
	v_mfma_f32_32x32x16_bf16 v[0:15], v[88:91], v[92:95], v[0:15]
	v_mfma_f32_32x32x16_bf16 v[16:31], v[88:91], v[106:109], v[16:31]
	v_mfma_f32_32x32x16_bf16 v[32:47], v[98:101], v[102:105], v[32:47]
	v_mfma_f32_32x32x16_bf16 v[48:63], v[98:101], v[110:113], v[48:63]
	s_waitcnt lgkmcnt(0)
	v_mfma_f32_32x32x16_bf16 v[0:15], v[114:117], v[102:105], v[0:15]
	ds_read_b128 v[88:91], v172 offset:32768
	ds_read_b128 v[92:95], v176 offset:49152
	ds_read_b128 v[98:101], v173 offset:32768
	ds_read_b128 v[102:105], v177 offset:49152
	v_mfma_f32_32x32x16_bf16 v[16:31], v[114:117], v[110:113], v[16:31]
	ds_read_b128 v[106:109], v176 offset:53248
	ds_read_b128 v[110:113], v177 offset:53248
	s_waitcnt lgkmcnt(4)
	v_mfma_f32_32x32x16_bf16 v[32:47], v[88:91], v[92:95], v[32:47]
	s_waitcnt lgkmcnt(1)
	v_mfma_f32_32x32x16_bf16 v[48:63], v[88:91], v[106:109], v[48:63]
	ds_read_b128 v[88:91], v172 offset:36864
	ds_read_b128 v[114:117], v173 offset:36864
	s_waitcnt lgkmcnt(1)
	v_mfma_f32_32x32x16_bf16 v[0:15], v[88:91], v[92:95], v[0:15]
	v_mfma_f32_32x32x16_bf16 v[16:31], v[88:91], v[106:109], v[16:31]
	v_mfma_f32_32x32x16_bf16 v[32:47], v[98:101], v[102:105], v[32:47]
	v_mfma_f32_32x32x16_bf16 v[48:63], v[98:101], v[110:113], v[48:63]
	s_waitcnt lgkmcnt(0)
	v_mfma_f32_32x32x16_bf16 v[0:15], v[114:117], v[102:105], v[0:15]
	s_waitcnt vmcnt(0)
	s_barrier
	v_lshl_add_u64 v[66:67], v[66:67], 0, s[96:97]
	s_add_u32 m0, s94, 0x8000
	s_nop 1
	global_load_lds_dwordx4 v[66:67], off
	v_lshl_add_u64 v[68:69], v[68:69], 0, s[96:97]
	s_add_u32 m0, s94, 0xc000
	s_nop 1
	global_load_lds_dwordx4 v[68:69], off
	v_lshl_add_u64 v[70:71], v[70:71], 0, s[96:97]
	s_add_u32 m0, s94, 0x9000
	s_nop 1
	global_load_lds_dwordx4 v[70:71], off
	v_lshl_add_u64 v[72:73], v[72:73], 0, s[96:97]
	s_add_u32 m0, s94, 0xd000
	s_nop 1
	global_load_lds_dwordx4 v[72:73], off
	v_lshl_add_u64 v[74:75], v[74:75], 0, s[96:97]
	s_add_u32 m0, s94, 0xa000
	s_nop 1
	global_load_lds_dwordx4 v[74:75], off
	v_lshl_add_u64 v[76:77], v[76:77], 0, s[96:97]
	s_add_u32 m0, s94, 0xe000
	s_nop 1
	global_load_lds_dwordx4 v[76:77], off
	v_lshl_add_u64 v[78:79], v[78:79], 0, s[96:97]
	s_add_u32 m0, s94, 0xb000
	s_nop 1
	global_load_lds_dwordx4 v[78:79], off
	v_lshl_add_u64 v[80:81], v[80:81], 0, s[96:97]
	s_add_u32 m0, s94, 0xf000
	s_nop 1
	global_load_lds_dwordx4 v[80:81], off
	v_mfma_f32_32x32x16_bf16 v[16:31], v[114:117], v[110:113], v[16:31]
	ds_read_b128 v[88:91], v170 offset:0
	ds_read_b128 v[92:95], v174 offset:16384
	ds_read_b128 v[98:101], v171 offset:0
	ds_read_b128 v[102:105], v175 offset:16384
	ds_read_b128 v[106:109], v174 offset:20480
	ds_read_b128 v[110:113], v175 offset:20480
	s_waitcnt lgkmcnt(4)
	v_mfma_f32_32x32x16_bf16 v[32:47], v[88:91], v[92:95], v[32:47]
	s_waitcnt lgkmcnt(1)
	v_mfma_f32_32x32x16_bf16 v[48:63], v[88:91], v[106:109], v[48:63]
	ds_read_b128 v[88:91], v170 offset:4096
	ds_read_b128 v[114:117], v171 offset:4096
	s_waitcnt lgkmcnt(1)
	v_mfma_f32_32x32x16_bf16 v[0:15], v[88:91], v[92:95], v[0:15]
	v_mfma_f32_32x32x16_bf16 v[16:31], v[88:91], v[106:109], v[16:31]
	v_mfma_f32_32x32x16_bf16 v[32:47], v[98:101], v[102:105], v[32:47]
	v_mfma_f32_32x32x16_bf16 v[48:63], v[98:101], v[110:113], v[48:63]
	s_waitcnt lgkmcnt(0)
	v_mfma_f32_32x32x16_bf16 v[0:15], v[114:117], v[102:105], v[0:15]
	ds_read_b128 v[88:91], v172 offset:0
	ds_read_b128 v[92:95], v176 offset:16384
	ds_read_b128 v[98:101], v173 offset:0
	ds_read_b128 v[102:105], v177 offset:16384
	v_mfma_f32_32x32x16_bf16 v[16:31], v[114:117], v[110:113], v[16:31]
	ds_read_b128 v[106:109], v176 offset:20480
	ds_read_b128 v[110:113], v177 offset:20480
	s_waitcnt lgkmcnt(4)
	v_mfma_f32_32x32x16_bf16 v[32:47], v[88:91], v[92:95], v[32:47]
	s_waitcnt lgkmcnt(1)
	v_mfma_f32_32x32x16_bf16 v[48:63], v[88:91], v[106:109], v[48:63]
	ds_read_b128 v[88:91], v172 offset:4096
	ds_read_b128 v[114:117], v173 offset:4096
	s_waitcnt lgkmcnt(1)
	v_mfma_f32_32x32x16_bf16 v[0:15], v[88:91], v[92:95], v[0:15]
	v_mfma_f32_32x32x16_bf16 v[16:31], v[88:91], v[106:109], v[16:31]
	v_mfma_f32_32x32x16_bf16 v[32:47], v[98:101], v[102:105], v[32:47]
	v_mfma_f32_32x32x16_bf16 v[48:63], v[98:101], v[110:113], v[48:63]
	s_waitcnt lgkmcnt(0)
	v_mfma_f32_32x32x16_bf16 v[0:15], v[114:117], v[102:105], v[0:15]
	s_waitcnt vmcnt(0)
	s_barrier
;     ...
;   bf16* As1 = As + 2 * 128 * 72;
;   bf16* Bs1 = As1 + 128 * 72;
;   G_LOAD(ra0, rb0, 0);
;   if (nk > 1) G_LOAD(ra1, rb1, 1);
;   G_STORE(ra0, rb0, As, Bs);
;   __syncthreads();
;   for (int kt = 0; kt < nk; kt += 2) {
;     if (kt + 2 < nk) G_LOAD(ra0, rb0, kt + 2);
;     if (kt + 1 < nk) G_STORE(ra1, rb1, As1, Bs1);
;     G_COMPUTE(As, Bs);
;     __syncthreads();
;     if (kt + 1 < nk) {
;       if (kt + 3 < nk) G_LOAD(ra1, rb1, kt + 3);
;       if (kt + 2 < nk) G_STORE(ra0, rb0, As, Bs);
;       G_COMPUTE(As1, Bs1);
;       __syncthreads();
;     }
;   }
	v_lshl_add_u64 v[66:67], v[66:67], 0, s[96:97]
	s_add_u32 m0, s94, 0x0
	s_nop 1
	global_load_lds_dwordx4 v[66:67], off
	v_lshl_add_u64 v[68:69], v[68:69], 0, s[96:97]
	s_add_u32 m0, s94, 0x4000
	s_nop 1
	global_load_lds_dwordx4 v[68:69], off
	v_lshl_add_u64 v[70:71], v[70:71], 0, s[96:97]
	s_add_u32 m0, s94, 0x1000
	s_nop 1
	global_load_lds_dwordx4 v[70:71], off
	v_lshl_add_u64 v[72:73], v[72:73], 0, s[96:97]
	s_add_u32 m0, s94, 0x5000
	s_nop 1
	global_load_lds_dwordx4 v[72:73], off
	v_lshl_add_u64 v[74:75], v[74:75], 0, s[96:97]
	s_add_u32 m0, s94, 0x2000
	s_nop 1
	global_load_lds_dwordx4 v[74:75], off
	v_lshl_add_u64 v[76:77], v[76:77], 0, s[96:97]
	s_add_u32 m0, s94, 0x6000
	s_nop 1
	global_load_lds_dwordx4 v[76:77], off
	v_lshl_add_u64 v[78:79], v[78:79], 0, s[96:97]
	s_add_u32 m0, s94, 0x3000
	s_nop 1
	global_load_lds_dwordx4 v[78:79], off
	v_lshl_add_u64 v[80:81], v[80:81], 0, s[96:97]
	s_add_u32 m0, s94, 0x7000
	s_nop 1
	global_load_lds_dwordx4 v[80:81], off
	v_mfma_f32_32x32x16_bf16 v[16:31], v[114:117], v[110:113], v[16:31]
	ds_read_b128 v[88:91], v170 offset:32768
	ds_read_b128 v[92:95], v174 offset:49152
	ds_read_b128 v[98:101], v171 offset:32768
	ds_read_b128 v[102:105], v175 offset:49152
	ds_read_b128 v[106:109], v174 offset:53248
	ds_read_b128 v[110:113], v175 offset:53248
	s_waitcnt lgkmcnt(4)
	v_mfma_f32_32x32x16_bf16 v[32:47], v[88:91], v[92:95], v[32:47]
	s_waitcnt lgkmcnt(1)
	v_mfma_f32_32x32x16_bf16 v[48:63], v[88:91], v[106:109], v[48:63]
	ds_read_b128 v[88:91], v170 offset:36864
	ds_read_b128 v[114:117], v171 offset:36864
	s_waitcnt lgkmcnt(1)
	v_mfma_f32_32x32x16_bf16 v[0:15], v[88:91], v[92:95], v[0:15]
	v_mfma_f32_32x32x16_bf16 v[16:31], v[88:91], v[106:109], v[16:31]
	v_mfma_f32_32x32x16_bf16 v[32:47], v[98:101], v[102:105], v[32:47]
	v_mfma_f32_32x32x16_bf16 v[48:63], v[98:101], v[110:113], v[48:63]
	s_waitcnt lgkmcnt(0)
	v_mfma_f32_32x32x16_bf16 v[0:15], v[114:117], v[102:105], v[0:15]
	ds_read_b128 v[88:91], v172 offset:32768
	ds_read_b128 v[92:95], v176 offset:49152
	ds_read_b128 v[98:101], v173 offset:32768
	ds_read_b128 v[102:105], v177 offset:49152
	v_mfma_f32_32x32x16_bf16 v[16:31], v[114:117], v[110:113], v[16:31]
	ds_read_b128 v[106:109], v176 offset:53248
	ds_read_b128 v[110:113], v177 offset:53248
	s_waitcnt lgkmcnt(4)
	v_mfma_f32_32x32x16_bf16 v[32:47], v[88:91], v[92:95], v[32:47]
	s_waitcnt lgkmcnt(1)
	v_mfma_f32_32x32x16_bf16 v[48:63], v[88:91], v[106:109], v[48:63]
	ds_read_b128 v[88:91], v172 offset:36864
	ds_read_b128 v[114:117], v173 offset:36864
	s_waitcnt lgkmcnt(1)
	v_mfma_f32_32x32x16_bf16 v[0:15], v[88:91], v[92:95], v[0:15]
	v_mfma_f32_32x32x16_bf16 v[16:31], v[88:91], v[106:109], v[16:31]
	v_mfma_f32_32x32x16_bf16 v[32:47], v[98:101], v[102:105], v[32:47]
	v_mfma_f32_32x32x16_bf16 v[48:63], v[98:101], v[110:113], v[48:63]
	s_waitcnt lgkmcnt(0)
	v_mfma_f32_32x32x16_bf16 v[0:15], v[114:117], v[102:105], v[0:15]
	s_waitcnt vmcnt(0)
	s_barrier
	v_lshl_add_u64 v[66:67], v[66:67], 0, s[96:97]
	s_add_u32 m0, s94, 0x8000
	s_nop 1
	global_load_lds_dwordx4 v[66:67], off
	v_lshl_add_u64 v[68:69], v[68:69], 0, s[96:97]
	s_add_u32 m0, s94, 0xc000
	s_nop 1
	global_load_lds_dwordx4 v[68:69], off
	v_lshl_add_u64 v[70:71], v[70:71], 0, s[96:97]
	s_add_u32 m0, s94, 0x9000
	s_nop 1
	global_load_lds_dwordx4 v[70:71], off
	v_lshl_add_u64 v[72:73], v[72:73], 0, s[96:97]
	s_add_u32 m0, s94, 0xd000
	s_nop 1
	global_load_lds_dwordx4 v[72:73], off
	v_lshl_add_u64 v[74:75], v[74:75], 0, s[96:97]
	s_add_u32 m0, s94, 0xa000
	s_nop 1
	global_load_lds_dwordx4 v[74:75], off
	v_lshl_add_u64 v[76:77], v[76:77], 0, s[96:97]
	s_add_u32 m0, s94, 0xe000
	s_nop 1
	global_load_lds_dwordx4 v[76:77], off
	v_lshl_add_u64 v[78:79], v[78:79], 0, s[96:97]
	s_add_u32 m0, s94, 0xb000
	s_nop 1
	global_load_lds_dwordx4 v[78:79], off
	v_lshl_add_u64 v[80:81], v[80:81], 0, s[96:97]
	s_add_u32 m0, s94, 0xf000
	s_nop 1
	global_load_lds_dwordx4 v[80:81], off
	v_mfma_f32_32x32x16_bf16 v[16:31], v[114:117], v[110:113], v[16:31]
	ds_read_b128 v[88:91], v170 offset:0
	ds_read_b128 v[92:95], v174 offset:16384
	ds_read_b128 v[98:101], v171 offset:0
	ds_read_b128 v[102:105], v175 offset:16384
	ds_read_b128 v[106:109], v174 offset:20480
	ds_read_b128 v[110:113], v175 offset:20480
	s_waitcnt lgkmcnt(4)
	v_mfma_f32_32x32x16_bf16 v[32:47], v[88:91], v[92:95], v[32:47]
	s_waitcnt lgkmcnt(1)
	v_mfma_f32_32x32x16_bf16 v[48:63], v[88:91], v[106:109], v[48:63]
	ds_read_b128 v[88:91], v170 offset:4096
	ds_read_b128 v[114:117], v171 offset:4096
	s_waitcnt lgkmcnt(1)
	v_mfma_f32_32x32x16_bf16 v[0:15], v[88:91], v[92:95], v[0:15]
	v_mfma_f32_32x32x16_bf16 v[16:31], v[88:91], v[106:109], v[16:31]
	v_mfma_f32_32x32x16_bf16 v[32:47], v[98:101], v[102:105], v[32:47]
	v_mfma_f32_32x32x16_bf16 v[48:63], v[98:101], v[110:113], v[48:63]
	s_waitcnt lgkmcnt(0)
	v_mfma_f32_32x32x16_bf16 v[0:15], v[114:117], v[102:105], v[0:15]
	ds_read_b128 v[88:91], v172 offset:0
	ds_read_b128 v[92:95], v176 offset:16384
	ds_read_b128 v[98:101], v173 offset:0
	ds_read_b128 v[102:105], v177 offset:16384
	v_mfma_f32_32x32x16_bf16 v[16:31], v[114:117], v[110:113], v[16:31]
	ds_read_b128 v[106:109], v176 offset:20480
	ds_read_b128 v[110:113], v177 offset:20480
	s_waitcnt lgkmcnt(4)
	v_mfma_f32_32x32x16_bf16 v[32:47], v[88:91], v[92:95], v[32:47]
	s_waitcnt lgkmcnt(1)
	v_mfma_f32_32x32x16_bf16 v[48:63], v[88:91], v[106:109], v[48:63]
	ds_read_b128 v[88:91], v172 offset:4096
	ds_read_b128 v[114:117], v173 offset:4096
	s_waitcnt lgkmcnt(1)
	v_mfma_f32_32x32x16_bf16 v[0:15], v[88:91], v[92:95], v[0:15]
	v_mfma_f32_32x32x16_bf16 v[16:31], v[88:91], v[106:109], v[16:31]
	v_mfma_f32_32x32x16_bf16 v[32:47], v[98:101], v[102:105], v[32:47]
	v_mfma_f32_32x32x16_bf16 v[48:63], v[98:101], v[110:113], v[48:63]
	s_waitcnt lgkmcnt(0)
	v_mfma_f32_32x32x16_bf16 v[0:15], v[114:117], v[102:105], v[0:15]
	s_waitcnt vmcnt(0)
	s_barrier
;     ...
;   bf16* As1 = As + 2 * 128 * 72;
;   bf16* Bs1 = As1 + 128 * 72;
;   G_LOAD(ra0, rb0, 0);
;   if (nk > 1) G_LOAD(ra1, rb1, 1);
;   G_STORE(ra0, rb0, As, Bs);
;   __syncthreads();
;   for (int kt = 0; kt < nk; kt += 2) {
;     if (kt + 2 < nk) G_LOAD(ra0, rb0, kt + 2);
;     if (kt + 1 < nk) G_STORE(ra1, rb1, As1, Bs1);
;     G_COMPUTE(As, Bs);
;     __syncthreads();
;     if (kt + 1 < nk) {
;       if (kt + 3 < nk) G_LOAD(ra1, rb1, kt + 3);
;       if (kt + 2 < nk) G_STORE(ra0, rb0, As, Bs);
;       G_COMPUTE(As1, Bs1);
;       __syncthreads();
;     }
;   }
	v_lshl_add_u64 v[66:67], v[66:67], 0, s[96:97]
	s_add_u32 m0, s94, 0x0
	s_nop 1
	global_load_lds_dwordx4 v[66:67], off
	v_lshl_add_u64 v[68:69], v[68:69], 0, s[96:97]
	s_add_u32 m0, s94, 0x4000
	s_nop 1
	global_load_lds_dwordx4 v[68:69], off
	v_lshl_add_u64 v[70:71], v[70:71], 0, s[96:97]
	s_add_u32 m0, s94, 0x1000
	s_nop 1
	global_load_lds_dwordx4 v[70:71], off
	v_lshl_add_u64 v[72:73], v[72:73], 0, s[96:97]
	s_add_u32 m0, s94, 0x5000
	s_nop 1
	global_load_lds_dwordx4 v[72:73], off
	v_lshl_add_u64 v[74:75], v[74:75], 0, s[96:97]
	s_add_u32 m0, s94, 0x2000
	s_nop 1
	global_load_lds_dwordx4 v[74:75], off
	v_lshl_add_u64 v[76:77], v[76:77], 0, s[96:97]
	s_add_u32 m0, s94, 0x6000
	s_nop 1
	global_load_lds_dwordx4 v[76:77], off
	v_lshl_add_u64 v[78:79], v[78:79], 0, s[96:97]
	s_add_u32 m0, s94, 0x3000
	s_nop 1
	global_load_lds_dwordx4 v[78:79], off
	v_lshl_add_u64 v[80:81], v[80:81], 0, s[96:97]
	s_add_u32 m0, s94, 0x7000
	s_nop 1
	global_load_lds_dwordx4 v[80:81], off
	v_mfma_f32_32x32x16_bf16 v[16:31], v[114:117], v[110:113], v[16:31]
	ds_read_b128 v[88:91], v170 offset:32768
	ds_read_b128 v[92:95], v174 offset:49152
	ds_read_b128 v[98:101], v171 offset:32768
	ds_read_b128 v[102:105], v175 offset:49152
	ds_read_b128 v[106:109], v174 offset:53248
	ds_read_b128 v[110:113], v175 offset:53248
	s_waitcnt lgkmcnt(4)
	v_mfma_f32_32x32x16_bf16 v[32:47], v[88:91], v[92:95], v[32:47]
	s_waitcnt lgkmcnt(1)
	v_mfma_f32_32x32x16_bf16 v[48:63], v[88:91], v[106:109], v[48:63]
	ds_read_b128 v[88:91], v170 offset:36864
	ds_read_b128 v[114:117], v171 offset:36864
	s_waitcnt lgkmcnt(1)
	v_mfma_f32_32x32x16_bf16 v[0:15], v[88:91], v[92:95], v[0:15]
	v_mfma_f32_32x32x16_bf16 v[16:31], v[88:91], v[106:109], v[16:31]
	v_mfma_f32_32x32x16_bf16 v[32:47], v[98:101], v[102:105], v[32:47]
	v_mfma_f32_32x32x16_bf16 v[48:63], v[98:101], v[110:113], v[48:63]
	s_waitcnt lgkmcnt(0)
	v_mfma_f32_32x32x16_bf16 v[0:15], v[114:117], v[102:105], v[0:15]
	ds_read_b128 v[88:91], v172 offset:32768
	ds_read_b128 v[92:95], v176 offset:49152
	ds_read_b128 v[98:101], v173 offset:32768
	ds_read_b128 v[102:105], v177 offset:49152
	v_mfma_f32_32x32x16_bf16 v[16:31], v[114:117], v[110:113], v[16:31]
	ds_read_b128 v[106:109], v176 offset:53248
	ds_read_b128 v[110:113], v177 offset:53248
	s_waitcnt lgkmcnt(4)
	v_mfma_f32_32x32x16_bf16 v[32:47], v[88:91], v[92:95], v[32:47]
	s_waitcnt lgkmcnt(1)
	v_mfma_f32_32x32x16_bf16 v[48:63], v[88:91], v[106:109], v[48:63]
	ds_read_b128 v[88:91], v172 offset:36864
	ds_read_b128 v[114:117], v173 offset:36864
	s_waitcnt lgkmcnt(1)
	v_mfma_f32_32x32x16_bf16 v[0:15], v[88:91], v[92:95], v[0:15]
	v_mfma_f32_32x32x16_bf16 v[16:31], v[88:91], v[106:109], v[16:31]
	v_mfma_f32_32x32x16_bf16 v[32:47], v[98:101], v[102:105], v[32:47]
	v_mfma_f32_32x32x16_bf16 v[48:63], v[98:101], v[110:113], v[48:63]
	s_waitcnt lgkmcnt(0)
	v_mfma_f32_32x32x16_bf16 v[0:15], v[114:117], v[102:105], v[0:15]
	s_waitcnt vmcnt(0)
	s_barrier
	v_lshl_add_u64 v[66:67], v[66:67], 0, s[96:97]
	s_add_u32 m0, s94, 0x8000
	s_nop 1
	global_load_lds_dwordx4 v[66:67], off
	v_lshl_add_u64 v[68:69], v[68:69], 0, s[96:97]
	s_add_u32 m0, s94, 0xc000
	s_nop 1
	global_load_lds_dwordx4 v[68:69], off
	v_lshl_add_u64 v[70:71], v[70:71], 0, s[96:97]
	s_add_u32 m0, s94, 0x9000
	s_nop 1
	global_load_lds_dwordx4 v[70:71], off
	v_lshl_add_u64 v[72:73], v[72:73], 0, s[96:97]
	s_add_u32 m0, s94, 0xd000
	s_nop 1
	global_load_lds_dwordx4 v[72:73], off
	v_lshl_add_u64 v[74:75], v[74:75], 0, s[96:97]
	s_add_u32 m0, s94, 0xa000
	s_nop 1
	global_load_lds_dwordx4 v[74:75], off
	v_lshl_add_u64 v[76:77], v[76:77], 0, s[96:97]
	s_add_u32 m0, s94, 0xe000
	s_nop 1
	global_load_lds_dwordx4 v[76:77], off
	v_lshl_add_u64 v[78:79], v[78:79], 0, s[96:97]
	s_add_u32 m0, s94, 0xb000
	s_nop 1
	global_load_lds_dwordx4 v[78:79], off
	v_lshl_add_u64 v[80:81], v[80:81], 0, s[96:97]
	s_add_u32 m0, s94, 0xf000
	s_nop 1
	global_load_lds_dwordx4 v[80:81], off
	v_mfma_f32_32x32x16_bf16 v[16:31], v[114:117], v[110:113], v[16:31]
	ds_read_b128 v[88:91], v170 offset:0
	ds_read_b128 v[92:95], v174 offset:16384
	ds_read_b128 v[98:101], v171 offset:0
	ds_read_b128 v[102:105], v175 offset:16384
	ds_read_b128 v[106:109], v174 offset:20480
	ds_read_b128 v[110:113], v175 offset:20480
	s_waitcnt lgkmcnt(4)
	v_mfma_f32_32x32x16_bf16 v[32:47], v[88:91], v[92:95], v[32:47]
	s_waitcnt lgkmcnt(1)
	v_mfma_f32_32x32x16_bf16 v[48:63], v[88:91], v[106:109], v[48:63]
	ds_read_b128 v[88:91], v170 offset:4096
	ds_read_b128 v[114:117], v171 offset:4096
	s_waitcnt lgkmcnt(1)
	v_mfma_f32_32x32x16_bf16 v[0:15], v[88:91], v[92:95], v[0:15]
	v_mfma_f32_32x32x16_bf16 v[16:31], v[88:91], v[106:109], v[16:31]
	v_mfma_f32_32x32x16_bf16 v[32:47], v[98:101], v[102:105], v[32:47]
	v_mfma_f32_32x32x16_bf16 v[48:63], v[98:101], v[110:113], v[48:63]
	s_waitcnt lgkmcnt(0)
	v_mfma_f32_32x32x16_bf16 v[0:15], v[114:117], v[102:105], v[0:15]
	ds_read_b128 v[88:91], v172 offset:0
	ds_read_b128 v[92:95], v176 offset:16384
	ds_read_b128 v[98:101], v173 offset:0
	ds_read_b128 v[102:105], v177 offset:16384
	v_mfma_f32_32x32x16_bf16 v[16:31], v[114:117], v[110:113], v[16:31]
	ds_read_b128 v[106:109], v176 offset:20480
	ds_read_b128 v[110:113], v177 offset:20480
	s_waitcnt lgkmcnt(4)
	v_mfma_f32_32x32x16_bf16 v[32:47], v[88:91], v[92:95], v[32:47]
	s_waitcnt lgkmcnt(1)
	v_mfma_f32_32x32x16_bf16 v[48:63], v[88:91], v[106:109], v[48:63]
	ds_read_b128 v[88:91], v172 offset:4096
	ds_read_b128 v[114:117], v173 offset:4096
	s_waitcnt lgkmcnt(1)
	v_mfma_f32_32x32x16_bf16 v[0:15], v[88:91], v[92:95], v[0:15]
	v_mfma_f32_32x32x16_bf16 v[16:31], v[88:91], v[106:109], v[16:31]
	v_mfma_f32_32x32x16_bf16 v[32:47], v[98:101], v[102:105], v[32:47]
	v_mfma_f32_32x32x16_bf16 v[48:63], v[98:101], v[110:113], v[48:63]
	s_waitcnt lgkmcnt(0)
	v_mfma_f32_32x32x16_bf16 v[0:15], v[114:117], v[102:105], v[0:15]
	s_waitcnt vmcnt(0)
	s_barrier
;     ...
;   bf16* As1 = As + 2 * 128 * 72;
;   bf16* Bs1 = As1 + 128 * 72;
;   G_LOAD(ra0, rb0, 0);
;   if (nk > 1) G_LOAD(ra1, rb1, 1);
;   G_STORE(ra0, rb0, As, Bs);
;   __syncthreads();
;   for (int kt = 0; kt < nk; kt += 2) {
;     if (kt + 2 < nk) G_LOAD(ra0, rb0, kt + 2);
;     if (kt + 1 < nk) G_STORE(ra1, rb1, As1, Bs1);
;     G_COMPUTE(As, Bs);
;     __syncthreads();
;     if (kt + 1 < nk) {
;       if (kt + 3 < nk) G_LOAD(ra1, rb1, kt + 3);
;       if (kt + 2 < nk) G_STORE(ra0, rb0, As, Bs);
;       G_COMPUTE(As1, Bs1);
;       __syncthreads();
;     }
;   }
	v_lshl_add_u64 v[66:67], v[66:67], 0, s[96:97]
	s_add_u32 m0, s94, 0x0
	s_nop 1
	global_load_lds_dwordx4 v[66:67], off
	v_lshl_add_u64 v[68:69], v[68:69], 0, s[96:97]
	s_add_u32 m0, s94, 0x4000
	s_nop 1
	global_load_lds_dwordx4 v[68:69], off
	v_lshl_add_u64 v[70:71], v[70:71], 0, s[96:97]
	s_add_u32 m0, s94, 0x1000
	s_nop 1
	global_load_lds_dwordx4 v[70:71], off
	v_lshl_add_u64 v[72:73], v[72:73], 0, s[96:97]
	s_add_u32 m0, s94, 0x5000
	s_nop 1
	global_load_lds_dwordx4 v[72:73], off
	v_lshl_add_u64 v[74:75], v[74:75], 0, s[96:97]
	s_add_u32 m0, s94, 0x2000
	s_nop 1
	global_load_lds_dwordx4 v[74:75], off
	v_lshl_add_u64 v[76:77], v[76:77], 0, s[96:97]
	s_add_u32 m0, s94, 0x6000
	s_nop 1
	global_load_lds_dwordx4 v[76:77], off
	v_lshl_add_u64 v[78:79], v[78:79], 0, s[96:97]
	s_add_u32 m0, s94, 0x3000
	s_nop 1
	global_load_lds_dwordx4 v[78:79], off
	v_lshl_add_u64 v[80:81], v[80:81], 0, s[96:97]
	s_add_u32 m0, s94, 0x7000
	s_nop 1
	global_load_lds_dwordx4 v[80:81], off
	v_mfma_f32_32x32x16_bf16 v[16:31], v[114:117], v[110:113], v[16:31]
	ds_read_b128 v[88:91], v170 offset:32768
	ds_read_b128 v[92:95], v174 offset:49152
	ds_read_b128 v[98:101], v171 offset:32768
	ds_read_b128 v[102:105], v175 offset:49152
	ds_read_b128 v[106:109], v174 offset:53248
	ds_read_b128 v[110:113], v175 offset:53248
	s_waitcnt lgkmcnt(4)
	v_mfma_f32_32x32x16_bf16 v[32:47], v[88:91], v[92:95], v[32:47]
	s_waitcnt lgkmcnt(1)
	v_mfma_f32_32x32x16_bf16 v[48:63], v[88:91], v[106:109], v[48:63]
	ds_read_b128 v[88:91], v170 offset:36864
	ds_read_b128 v[114:117], v171 offset:36864
	s_waitcnt lgkmcnt(1)
	v_mfma_f32_32x32x16_bf16 v[0:15], v[88:91], v[92:95], v[0:15]
	v_mfma_f32_32x32x16_bf16 v[16:31], v[88:91], v[106:109], v[16:31]
	v_mfma_f32_32x32x16_bf16 v[32:47], v[98:101], v[102:105], v[32:47]
	v_mfma_f32_32x32x16_bf16 v[48:63], v[98:101], v[110:113], v[48:63]
	s_waitcnt lgkmcnt(0)
	v_mfma_f32_32x32x16_bf16 v[0:15], v[114:117], v[102:105], v[0:15]
	ds_read_b128 v[88:91], v172 offset:32768
	ds_read_b128 v[92:95], v176 offset:49152
	ds_read_b128 v[98:101], v173 offset:32768
	ds_read_b128 v[102:105], v177 offset:49152
	v_mfma_f32_32x32x16_bf16 v[16:31], v[114:117], v[110:113], v[16:31]
	ds_read_b128 v[106:109], v176 offset:53248
	ds_read_b128 v[110:113], v177 offset:53248
	s_waitcnt lgkmcnt(4)
	v_mfma_f32_32x32x16_bf16 v[32:47], v[88:91], v[92:95], v[32:47]
	s_waitcnt lgkmcnt(1)
	v_mfma_f32_32x32x16_bf16 v[48:63], v[88:91], v[106:109], v[48:63]
	ds_read_b128 v[88:91], v172 offset:36864
	ds_read_b128 v[114:117], v173 offset:36864
	s_waitcnt lgkmcnt(1)
	v_mfma_f32_32x32x16_bf16 v[0:15], v[88:91], v[92:95], v[0:15]
	v_mfma_f32_32x32x16_bf16 v[16:31], v[88:91], v[106:109], v[16:31]
	v_mfma_f32_32x32x16_bf16 v[32:47], v[98:101], v[102:105], v[32:47]
	v_mfma_f32_32x32x16_bf16 v[48:63], v[98:101], v[110:113], v[48:63]
	s_waitcnt lgkmcnt(0)
	v_mfma_f32_32x32x16_bf16 v[0:15], v[114:117], v[102:105], v[0:15]
	s_waitcnt vmcnt(0)
	s_barrier
	v_lshl_add_u64 v[66:67], v[66:67], 0, s[96:97]
	s_add_u32 m0, s94, 0x8000
	s_nop 1
	global_load_lds_dwordx4 v[66:67], off
	v_lshl_add_u64 v[68:69], v[68:69], 0, s[96:97]
	s_add_u32 m0, s94, 0xc000
	s_nop 1
	global_load_lds_dwordx4 v[68:69], off
	v_lshl_add_u64 v[70:71], v[70:71], 0, s[96:97]
	s_add_u32 m0, s94, 0x9000
	s_nop 1
	global_load_lds_dwordx4 v[70:71], off
	v_lshl_add_u64 v[72:73], v[72:73], 0, s[96:97]
	s_add_u32 m0, s94, 0xd000
	s_nop 1
	global_load_lds_dwordx4 v[72:73], off
	v_lshl_add_u64 v[74:75], v[74:75], 0, s[96:97]
	s_add_u32 m0, s94, 0xa000
	s_nop 1
	global_load_lds_dwordx4 v[74:75], off
	v_lshl_add_u64 v[76:77], v[76:77], 0, s[96:97]
	s_add_u32 m0, s94, 0xe000
	s_nop 1
	global_load_lds_dwordx4 v[76:77], off
	v_lshl_add_u64 v[78:79], v[78:79], 0, s[96:97]
	s_add_u32 m0, s94, 0xb000
	s_nop 1
	global_load_lds_dwordx4 v[78:79], off
	v_lshl_add_u64 v[80:81], v[80:81], 0, s[96:97]
	s_add_u32 m0, s94, 0xf000
	s_nop 1
	global_load_lds_dwordx4 v[80:81], off
	v_mfma_f32_32x32x16_bf16 v[16:31], v[114:117], v[110:113], v[16:31]
	ds_read_b128 v[88:91], v170 offset:0
	ds_read_b128 v[92:95], v174 offset:16384
	ds_read_b128 v[98:101], v171 offset:0
	ds_read_b128 v[102:105], v175 offset:16384
	ds_read_b128 v[106:109], v174 offset:20480
	ds_read_b128 v[110:113], v175 offset:20480
	s_waitcnt lgkmcnt(4)
	v_mfma_f32_32x32x16_bf16 v[32:47], v[88:91], v[92:95], v[32:47]
	s_waitcnt lgkmcnt(1)
	v_mfma_f32_32x32x16_bf16 v[48:63], v[88:91], v[106:109], v[48:63]
	ds_read_b128 v[88:91], v170 offset:4096
	ds_read_b128 v[114:117], v171 offset:4096
	s_waitcnt lgkmcnt(1)
	v_mfma_f32_32x32x16_bf16 v[0:15], v[88:91], v[92:95], v[0:15]
	v_mfma_f32_32x32x16_bf16 v[16:31], v[88:91], v[106:109], v[16:31]
	v_mfma_f32_32x32x16_bf16 v[32:47], v[98:101], v[102:105], v[32:47]
	v_mfma_f32_32x32x16_bf16 v[48:63], v[98:101], v[110:113], v[48:63]
	s_waitcnt lgkmcnt(0)
	v_mfma_f32_32x32x16_bf16 v[0:15], v[114:117], v[102:105], v[0:15]
	ds_read_b128 v[88:91], v172 offset:0
	ds_read_b128 v[92:95], v176 offset:16384
	ds_read_b128 v[98:101], v173 offset:0
	ds_read_b128 v[102:105], v177 offset:16384
	v_mfma_f32_32x32x16_bf16 v[16:31], v[114:117], v[110:113], v[16:31]
	ds_read_b128 v[106:109], v176 offset:20480
	ds_read_b128 v[110:113], v177 offset:20480
	s_waitcnt lgkmcnt(4)
	v_mfma_f32_32x32x16_bf16 v[32:47], v[88:91], v[92:95], v[32:47]
	s_waitcnt lgkmcnt(1)
	v_mfma_f32_32x32x16_bf16 v[48:63], v[88:91], v[106:109], v[48:63]
	ds_read_b128 v[88:91], v172 offset:4096
	ds_read_b128 v[114:117], v173 offset:4096
	s_waitcnt lgkmcnt(1)
	v_mfma_f32_32x32x16_bf16 v[0:15], v[88:91], v[92:95], v[0:15]
	v_mfma_f32_32x32x16_bf16 v[16:31], v[88:91], v[106:109], v[16:31]
	v_mfma_f32_32x32x16_bf16 v[32:47], v[98:101], v[102:105], v[32:47]
	v_mfma_f32_32x32x16_bf16 v[48:63], v[98:101], v[110:113], v[48:63]
	s_waitcnt lgkmcnt(0)
	v_mfma_f32_32x32x16_bf16 v[0:15], v[114:117], v[102:105], v[0:15]
	s_waitcnt vmcnt(0)
	s_barrier
;     ...
;   bf16* As1 = As + 2 * 128 * 72;
;   bf16* Bs1 = As1 + 128 * 72;
;   G_LOAD(ra0, rb0, 0);
;   if (nk > 1) G_LOAD(ra1, rb1, 1);
;   G_STORE(ra0, rb0, As, Bs);
;   __syncthreads();
;   for (int kt = 0; kt < nk; kt += 2) {
;     if (kt + 2 < nk) G_LOAD(ra0, rb0, kt + 2);
;     if (kt + 1 < nk) G_STORE(ra1, rb1, As1, Bs1);
;     G_COMPUTE(As, Bs);
;     __syncthreads();
;     if (kt + 1 < nk) {
;       if (kt + 3 < nk) G_LOAD(ra1, rb1, kt + 3);
;       if (kt + 2 < nk) G_STORE(ra0, rb0, As, Bs);
;       G_COMPUTE(As1, Bs1);
;       __syncthreads();
;     }
;   }
	v_lshl_add_u64 v[66:67], v[66:67], 0, s[96:97]
	s_add_u32 m0, s94, 0x0
	s_nop 1
	global_load_lds_dwordx4 v[66:67], off
	v_lshl_add_u64 v[68:69], v[68:69], 0, s[96:97]
	s_add_u32 m0, s94, 0x4000
	s_nop 1
	global_load_lds_dwordx4 v[68:69], off
	v_lshl_add_u64 v[70:71], v[70:71], 0, s[96:97]
	s_add_u32 m0, s94, 0x1000
	s_nop 1
	global_load_lds_dwordx4 v[70:71], off
	v_lshl_add_u64 v[72:73], v[72:73], 0, s[96:97]
	s_add_u32 m0, s94, 0x5000
	s_nop 1
	global_load_lds_dwordx4 v[72:73], off
	v_lshl_add_u64 v[74:75], v[74:75], 0, s[96:97]
	s_add_u32 m0, s94, 0x2000
	s_nop 1
	global_load_lds_dwordx4 v[74:75], off
	v_lshl_add_u64 v[76:77], v[76:77], 0, s[96:97]
	s_add_u32 m0, s94, 0x6000
	s_nop 1
	global_load_lds_dwordx4 v[76:77], off
	v_lshl_add_u64 v[78:79], v[78:79], 0, s[96:97]
	s_add_u32 m0, s94, 0x3000
	s_nop 1
	global_load_lds_dwordx4 v[78:79], off
	v_lshl_add_u64 v[80:81], v[80:81], 0, s[96:97]
	s_add_u32 m0, s94, 0x7000
	s_nop 1
	global_load_lds_dwordx4 v[80:81], off
	v_mfma_f32_32x32x16_bf16 v[16:31], v[114:117], v[110:113], v[16:31]
	ds_read_b128 v[88:91], v170 offset:32768
	ds_read_b128 v[92:95], v174 offset:49152
	ds_read_b128 v[98:101], v171 offset:32768
	ds_read_b128 v[102:105], v175 offset:49152
	ds_read_b128 v[106:109], v174 offset:53248
	ds_read_b128 v[110:113], v175 offset:53248
	s_waitcnt lgkmcnt(4)
	v_mfma_f32_32x32x16_bf16 v[32:47], v[88:91], v[92:95], v[32:47]
	s_waitcnt lgkmcnt(1)
	v_mfma_f32_32x32x16_bf16 v[48:63], v[88:91], v[106:109], v[48:63]
	ds_read_b128 v[88:91], v170 offset:36864
	ds_read_b128 v[114:117], v171 offset:36864
	s_waitcnt lgkmcnt(1)
	v_mfma_f32_32x32x16_bf16 v[0:15], v[88:91], v[92:95], v[0:15]
	v_mfma_f32_32x32x16_bf16 v[16:31], v[88:91], v[106:109], v[16:31]
	v_mfma_f32_32x32x16_bf16 v[32:47], v[98:101], v[102:105], v[32:47]
	v_mfma_f32_32x32x16_bf16 v[48:63], v[98:101], v[110:113], v[48:63]
	s_waitcnt lgkmcnt(0)
	v_mfma_f32_32x32x16_bf16 v[0:15], v[114:117], v[102:105], v[0:15]
	ds_read_b128 v[88:91], v172 offset:32768
	ds_read_b128 v[92:95], v176 offset:49152
	ds_read_b128 v[98:101], v173 offset:32768
	ds_read_b128 v[102:105], v177 offset:49152
	v_mfma_f32_32x32x16_bf16 v[16:31], v[114:117], v[110:113], v[16:31]
	ds_read_b128 v[106:109], v176 offset:53248
	ds_read_b128 v[110:113], v177 offset:53248
	s_waitcnt lgkmcnt(4)
	v_mfma_f32_32x32x16_bf16 v[32:47], v[88:91], v[92:95], v[32:47]
	s_waitcnt lgkmcnt(1)
	v_mfma_f32_32x32x16_bf16 v[48:63], v[88:91], v[106:109], v[48:63]
	ds_read_b128 v[88:91], v172 offset:36864
	ds_read_b128 v[114:117], v173 offset:36864
	s_waitcnt lgkmcnt(1)
	v_mfma_f32_32x32x16_bf16 v[0:15], v[88:91], v[92:95], v[0:15]
	v_mfma_f32_32x32x16_bf16 v[16:31], v[88:91], v[106:109], v[16:31]
	v_mfma_f32_32x32x16_bf16 v[32:47], v[98:101], v[102:105], v[32:47]
	v_mfma_f32_32x32x16_bf16 v[48:63], v[98:101], v[110:113], v[48:63]
	s_waitcnt lgkmcnt(0)
	v_mfma_f32_32x32x16_bf16 v[0:15], v[114:117], v[102:105], v[0:15]
	s_waitcnt vmcnt(0)
	s_barrier
	v_lshl_add_u64 v[66:67], v[66:67], 0, s[96:97]
	s_add_u32 m0, s94, 0x8000
	s_nop 1
	global_load_lds_dwordx4 v[66:67], off
	v_lshl_add_u64 v[68:69], v[68:69], 0, s[96:97]
	s_add_u32 m0, s94, 0xc000
	s_nop 1
	global_load_lds_dwordx4 v[68:69], off
	v_lshl_add_u64 v[70:71], v[70:71], 0, s[96:97]
	s_add_u32 m0, s94, 0x9000
	s_nop 1
	global_load_lds_dwordx4 v[70:71], off
	v_lshl_add_u64 v[72:73], v[72:73], 0, s[96:97]
	s_add_u32 m0, s94, 0xd000
	s_nop 1
	global_load_lds_dwordx4 v[72:73], off
	v_lshl_add_u64 v[74:75], v[74:75], 0, s[96:97]
	s_add_u32 m0, s94, 0xa000
	s_nop 1
	global_load_lds_dwordx4 v[74:75], off
	v_lshl_add_u64 v[76:77], v[76:77], 0, s[96:97]
	s_add_u32 m0, s94, 0xe000
	s_nop 1
	global_load_lds_dwordx4 v[76:77], off
	v_lshl_add_u64 v[78:79], v[78:79], 0, s[96:97]
	s_add_u32 m0, s94, 0xb000
	s_nop 1
	global_load_lds_dwordx4 v[78:79], off
	v_lshl_add_u64 v[80:81], v[80:81], 0, s[96:97]
	s_add_u32 m0, s94, 0xf000
	s_nop 1
	global_load_lds_dwordx4 v[80:81], off
	v_mfma_f32_32x32x16_bf16 v[16:31], v[114:117], v[110:113], v[16:31]
	ds_read_b128 v[88:91], v170 offset:0
	ds_read_b128 v[92:95], v174 offset:16384
	ds_read_b128 v[98:101], v171 offset:0
	ds_read_b128 v[102:105], v175 offset:16384
	ds_read_b128 v[106:109], v174 offset:20480
	ds_read_b128 v[110:113], v175 offset:20480
	s_waitcnt lgkmcnt(4)
	v_mfma_f32_32x32x16_bf16 v[32:47], v[88:91], v[92:95], v[32:47]
	s_waitcnt lgkmcnt(1)
	v_mfma_f32_32x32x16_bf16 v[48:63], v[88:91], v[106:109], v[48:63]
	ds_read_b128 v[88:91], v170 offset:4096
	ds_read_b128 v[114:117], v171 offset:4096
	s_waitcnt lgkmcnt(1)
	v_mfma_f32_32x32x16_bf16 v[0:15], v[88:91], v[92:95], v[0:15]
	v_mfma_f32_32x32x16_bf16 v[16:31], v[88:91], v[106:109], v[16:31]
	v_mfma_f32_32x32x16_bf16 v[32:47], v[98:101], v[102:105], v[32:47]
	v_mfma_f32_32x32x16_bf16 v[48:63], v[98:101], v[110:113], v[48:63]
	s_waitcnt lgkmcnt(0)
	v_mfma_f32_32x32x16_bf16 v[0:15], v[114:117], v[102:105], v[0:15]
	ds_read_b128 v[88:91], v172 offset:0
	ds_read_b128 v[92:95], v176 offset:16384
	ds_read_b128 v[98:101], v173 offset:0
	ds_read_b128 v[102:105], v177 offset:16384
	v_mfma_f32_32x32x16_bf16 v[16:31], v[114:117], v[110:113], v[16:31]
	ds_read_b128 v[106:109], v176 offset:20480
	ds_read_b128 v[110:113], v177 offset:20480
	s_waitcnt lgkmcnt(4)
	v_mfma_f32_32x32x16_bf16 v[32:47], v[88:91], v[92:95], v[32:47]
	s_waitcnt lgkmcnt(1)
	v_mfma_f32_32x32x16_bf16 v[48:63], v[88:91], v[106:109], v[48:63]
	ds_read_b128 v[88:91], v172 offset:4096
	ds_read_b128 v[114:117], v173 offset:4096
	s_waitcnt lgkmcnt(1)
	v_mfma_f32_32x32x16_bf16 v[0:15], v[88:91], v[92:95], v[0:15]
	v_mfma_f32_32x32x16_bf16 v[16:31], v[88:91], v[106:109], v[16:31]
	v_mfma_f32_32x32x16_bf16 v[32:47], v[98:101], v[102:105], v[32:47]
	v_mfma_f32_32x32x16_bf16 v[48:63], v[98:101], v[110:113], v[48:63]
	s_waitcnt lgkmcnt(0)
	v_mfma_f32_32x32x16_bf16 v[0:15], v[114:117], v[102:105], v[0:15]
	s_waitcnt vmcnt(0)
	s_barrier
;     ...
;   bf16* As1 = As + 2 * 128 * 72;
;   bf16* Bs1 = As1 + 128 * 72;
;   G_LOAD(ra0, rb0, 0);
;   if (nk > 1) G_LOAD(ra1, rb1, 1);
;   G_STORE(ra0, rb0, As, Bs);
;   __syncthreads();
;   for (int kt = 0; kt < nk; kt += 2) {
;     if (kt + 2 < nk) G_LOAD(ra0, rb0, kt + 2);
;     if (kt + 1 < nk) G_STORE(ra1, rb1, As1, Bs1);
;     G_COMPUTE(As, Bs);
;     __syncthreads();
;     if (kt + 1 < nk) {
;       if (kt + 3 < nk) G_LOAD(ra1, rb1, kt + 3);
;       if (kt + 2 < nk) G_STORE(ra0, rb0, As, Bs);
;       G_COMPUTE(As1, Bs1);
;       __syncthreads();
;     }
;   }
	v_lshl_add_u64 v[66:67], v[66:67], 0, s[96:97]
	s_add_u32 m0, s94, 0x0
	s_nop 1
	global_load_lds_dwordx4 v[66:67], off
	v_lshl_add_u64 v[68:69], v[68:69], 0, s[96:97]
	s_add_u32 m0, s94, 0x4000
	s_nop 1
	global_load_lds_dwordx4 v[68:69], off
	v_lshl_add_u64 v[70:71], v[70:71], 0, s[96:97]
	s_add_u32 m0, s94, 0x1000
	s_nop 1
	global_load_lds_dwordx4 v[70:71], off
	v_lshl_add_u64 v[72:73], v[72:73], 0, s[96:97]
	s_add_u32 m0, s94, 0x5000
	s_nop 1
	global_load_lds_dwordx4 v[72:73], off
	v_lshl_add_u64 v[74:75], v[74:75], 0, s[96:97]
	s_add_u32 m0, s94, 0x2000
	s_nop 1
	global_load_lds_dwordx4 v[74:75], off
	v_lshl_add_u64 v[76:77], v[76:77], 0, s[96:97]
	s_add_u32 m0, s94, 0x6000
	s_nop 1
	global_load_lds_dwordx4 v[76:77], off
	v_lshl_add_u64 v[78:79], v[78:79], 0, s[96:97]
	s_add_u32 m0, s94, 0x3000
	s_nop 1
	global_load_lds_dwordx4 v[78:79], off
	v_lshl_add_u64 v[80:81], v[80:81], 0, s[96:97]
	s_add_u32 m0, s94, 0x7000
	s_nop 1
	global_load_lds_dwordx4 v[80:81], off
	v_mfma_f32_32x32x16_bf16 v[16:31], v[114:117], v[110:113], v[16:31]
	ds_read_b128 v[88:91], v170 offset:32768
	ds_read_b128 v[92:95], v174 offset:49152
	ds_read_b128 v[98:101], v171 offset:32768
	ds_read_b128 v[102:105], v175 offset:49152
	ds_read_b128 v[106:109], v174 offset:53248
	ds_read_b128 v[110:113], v175 offset:53248
	s_waitcnt lgkmcnt(4)
	v_mfma_f32_32x32x16_bf16 v[32:47], v[88:91], v[92:95], v[32:47]
	s_waitcnt lgkmcnt(1)
	v_mfma_f32_32x32x16_bf16 v[48:63], v[88:91], v[106:109], v[48:63]
	ds_read_b128 v[88:91], v170 offset:36864
	ds_read_b128 v[114:117], v171 offset:36864
	s_waitcnt lgkmcnt(1)
	v_mfma_f32_32x32x16_bf16 v[0:15], v[88:91], v[92:95], v[0:15]
	v_mfma_f32_32x32x16_bf16 v[16:31], v[88:91], v[106:109], v[16:31]
	v_mfma_f32_32x32x16_bf16 v[32:47], v[98:101], v[102:105], v[32:47]
	v_mfma_f32_32x32x16_bf16 v[48:63], v[98:101], v[110:113], v[48:63]
	s_waitcnt lgkmcnt(0)
	v_mfma_f32_32x32x16_bf16 v[0:15], v[114:117], v[102:105], v[0:15]
	ds_read_b128 v[88:91], v172 offset:32768
	ds_read_b128 v[92:95], v176 offset:49152
	ds_read_b128 v[98:101], v173 offset:32768
	ds_read_b128 v[102:105], v177 offset:49152
	v_mfma_f32_32x32x16_bf16 v[16:31], v[114:117], v[110:113], v[16:31]
	ds_read_b128 v[106:109], v176 offset:53248
	ds_read_b128 v[110:113], v177 offset:53248
	s_waitcnt lgkmcnt(4)
	v_mfma_f32_32x32x16_bf16 v[32:47], v[88:91], v[92:95], v[32:47]
	s_waitcnt lgkmcnt(1)
	v_mfma_f32_32x32x16_bf16 v[48:63], v[88:91], v[106:109], v[48:63]
	ds_read_b128 v[88:91], v172 offset:36864
	ds_read_b128 v[114:117], v173 offset:36864
	s_waitcnt lgkmcnt(1)
	v_mfma_f32_32x32x16_bf16 v[0:15], v[88:91], v[92:95], v[0:15]
	v_mfma_f32_32x32x16_bf16 v[16:31], v[88:91], v[106:109], v[16:31]
	v_mfma_f32_32x32x16_bf16 v[32:47], v[98:101], v[102:105], v[32:47]
	v_mfma_f32_32x32x16_bf16 v[48:63], v[98:101], v[110:113], v[48:63]
	s_waitcnt lgkmcnt(0)
	v_mfma_f32_32x32x16_bf16 v[0:15], v[114:117], v[102:105], v[0:15]
	s_waitcnt vmcnt(0)
	s_barrier
	v_lshl_add_u64 v[66:67], v[66:67], 0, s[96:97]
	s_add_u32 m0, s94, 0x8000
	s_nop 1
	global_load_lds_dwordx4 v[66:67], off
	v_lshl_add_u64 v[68:69], v[68:69], 0, s[96:97]
	s_add_u32 m0, s94, 0xc000
	s_nop 1
	global_load_lds_dwordx4 v[68:69], off
	v_lshl_add_u64 v[70:71], v[70:71], 0, s[96:97]
	s_add_u32 m0, s94, 0x9000
	s_nop 1
	global_load_lds_dwordx4 v[70:71], off
	v_lshl_add_u64 v[72:73], v[72:73], 0, s[96:97]
	s_add_u32 m0, s94, 0xd000
	s_nop 1
	global_load_lds_dwordx4 v[72:73], off
	v_lshl_add_u64 v[74:75], v[74:75], 0, s[96:97]
	s_add_u32 m0, s94, 0xa000
	s_nop 1
	global_load_lds_dwordx4 v[74:75], off
	v_lshl_add_u64 v[76:77], v[76:77], 0, s[96:97]
	s_add_u32 m0, s94, 0xe000
	s_nop 1
	global_load_lds_dwordx4 v[76:77], off
	v_lshl_add_u64 v[78:79], v[78:79], 0, s[96:97]
	s_add_u32 m0, s94, 0xb000
	s_nop 1
	global_load_lds_dwordx4 v[78:79], off
	v_lshl_add_u64 v[80:81], v[80:81], 0, s[96:97]
	s_add_u32 m0, s94, 0xf000
	s_nop 1
	global_load_lds_dwordx4 v[80:81], off
	v_mfma_f32_32x32x16_bf16 v[16:31], v[114:117], v[110:113], v[16:31]
	ds_read_b128 v[88:91], v170 offset:0
	ds_read_b128 v[92:95], v174 offset:16384
	ds_read_b128 v[98:101], v171 offset:0
	ds_read_b128 v[102:105], v175 offset:16384
	ds_read_b128 v[106:109], v174 offset:20480
	ds_read_b128 v[110:113], v175 offset:20480
	s_waitcnt lgkmcnt(4)
	v_mfma_f32_32x32x16_bf16 v[32:47], v[88:91], v[92:95], v[32:47]
	s_waitcnt lgkmcnt(1)
	v_mfma_f32_32x32x16_bf16 v[48:63], v[88:91], v[106:109], v[48:63]
	ds_read_b128 v[88:91], v170 offset:4096
	ds_read_b128 v[114:117], v171 offset:4096
	s_waitcnt lgkmcnt(1)
	v_mfma_f32_32x32x16_bf16 v[0:15], v[88:91], v[92:95], v[0:15]
	v_mfma_f32_32x32x16_bf16 v[16:31], v[88:91], v[106:109], v[16:31]
	v_mfma_f32_32x32x16_bf16 v[32:47], v[98:101], v[102:105], v[32:47]
	v_mfma_f32_32x32x16_bf16 v[48:63], v[98:101], v[110:113], v[48:63]
	s_waitcnt lgkmcnt(0)
	v_mfma_f32_32x32x16_bf16 v[0:15], v[114:117], v[102:105], v[0:15]
	ds_read_b128 v[88:91], v172 offset:0
	ds_read_b128 v[92:95], v176 offset:16384
	ds_read_b128 v[98:101], v173 offset:0
	ds_read_b128 v[102:105], v177 offset:16384
	v_mfma_f32_32x32x16_bf16 v[16:31], v[114:117], v[110:113], v[16:31]
	ds_read_b128 v[106:109], v176 offset:20480
	ds_read_b128 v[110:113], v177 offset:20480
	s_waitcnt lgkmcnt(4)
	v_mfma_f32_32x32x16_bf16 v[32:47], v[88:91], v[92:95], v[32:47]
	s_waitcnt lgkmcnt(1)
	v_mfma_f32_32x32x16_bf16 v[48:63], v[88:91], v[106:109], v[48:63]
	ds_read_b128 v[88:91], v172 offset:4096
	ds_read_b128 v[114:117], v173 offset:4096
	s_waitcnt lgkmcnt(1)
	v_mfma_f32_32x32x16_bf16 v[0:15], v[88:91], v[92:95], v[0:15]
	v_mfma_f32_32x32x16_bf16 v[16:31], v[88:91], v[106:109], v[16:31]
	v_mfma_f32_32x32x16_bf16 v[32:47], v[98:101], v[102:105], v[32:47]
	v_mfma_f32_32x32x16_bf16 v[48:63], v[98:101], v[110:113], v[48:63]
	s_waitcnt lgkmcnt(0)
	v_mfma_f32_32x32x16_bf16 v[0:15], v[114:117], v[102:105], v[0:15]
	s_waitcnt vmcnt(0)
	s_barrier
;     ...
;   bf16* As1 = As + 2 * 128 * 72;
;   bf16* Bs1 = As1 + 128 * 72;
;   G_LOAD(ra0, rb0, 0);
;   if (nk > 1) G_LOAD(ra1, rb1, 1);
;   G_STORE(ra0, rb0, As, Bs);
;   __syncthreads();
;   for (int kt = 0; kt < nk; kt += 2) {
;     if (kt + 2 < nk) G_LOAD(ra0, rb0, kt + 2);
;     if (kt + 1 < nk) G_STORE(ra1, rb1, As1, Bs1);
;     G_COMPUTE(As, Bs);
;     __syncthreads();
;     if (kt + 1 < nk) {
;       if (kt + 3 < nk) G_LOAD(ra1, rb1, kt + 3);
;       if (kt + 2 < nk) G_STORE(ra0, rb0, As, Bs);
;       G_COMPUTE(As1, Bs1);
;       __syncthreads();
;     }
;   }
	v_lshl_add_u64 v[66:67], v[66:67], 0, s[96:97]
	s_add_u32 m0, s94, 0x0
	s_nop 1
	global_load_lds_dwordx4 v[66:67], off
	v_lshl_add_u64 v[68:69], v[68:69], 0, s[96:97]
	s_add_u32 m0, s94, 0x4000
	s_nop 1
	global_load_lds_dwordx4 v[68:69], off
	v_lshl_add_u64 v[70:71], v[70:71], 0, s[96:97]
	s_add_u32 m0, s94, 0x1000
	s_nop 1
	global_load_lds_dwordx4 v[70:71], off
	v_lshl_add_u64 v[72:73], v[72:73], 0, s[96:97]
	s_add_u32 m0, s94, 0x5000
	s_nop 1
	global_load_lds_dwordx4 v[72:73], off
	v_lshl_add_u64 v[74:75], v[74:75], 0, s[96:97]
	s_add_u32 m0, s94, 0x2000
	s_nop 1
	global_load_lds_dwordx4 v[74:75], off
	v_lshl_add_u64 v[76:77], v[76:77], 0, s[96:97]
	s_add_u32 m0, s94, 0x6000
	s_nop 1
	global_load_lds_dwordx4 v[76:77], off
	v_lshl_add_u64 v[78:79], v[78:79], 0, s[96:97]
	s_add_u32 m0, s94, 0x3000
	s_nop 1
	global_load_lds_dwordx4 v[78:79], off
	v_lshl_add_u64 v[80:81], v[80:81], 0, s[96:97]
	s_add_u32 m0, s94, 0x7000
	s_nop 1
	global_load_lds_dwordx4 v[80:81], off
	v_mfma_f32_32x32x16_bf16 v[16:31], v[114:117], v[110:113], v[16:31]
	ds_read_b128 v[88:91], v170 offset:32768
	ds_read_b128 v[92:95], v174 offset:49152
	ds_read_b128 v[98:101], v171 offset:32768
	ds_read_b128 v[102:105], v175 offset:49152
	ds_read_b128 v[106:109], v174 offset:53248
	ds_read_b128 v[110:113], v175 offset:53248
	s_waitcnt lgkmcnt(4)
	v_mfma_f32_32x32x16_bf16 v[32:47], v[88:91], v[92:95], v[32:47]
	s_waitcnt lgkmcnt(1)
	v_mfma_f32_32x32x16_bf16 v[48:63], v[88:91], v[106:109], v[48:63]
	ds_read_b128 v[88:91], v170 offset:36864
	ds_read_b128 v[114:117], v171 offset:36864
	s_waitcnt lgkmcnt(1)
	v_mfma_f32_32x32x16_bf16 v[0:15], v[88:91], v[92:95], v[0:15]
	v_mfma_f32_32x32x16_bf16 v[16:31], v[88:91], v[106:109], v[16:31]
	v_mfma_f32_32x32x16_bf16 v[32:47], v[98:101], v[102:105], v[32:47]
	v_mfma_f32_32x32x16_bf16 v[48:63], v[98:101], v[110:113], v[48:63]
	s_waitcnt lgkmcnt(0)
	v_mfma_f32_32x32x16_bf16 v[0:15], v[114:117], v[102:105], v[0:15]
	ds_read_b128 v[88:91], v172 offset:32768
	ds_read_b128 v[92:95], v176 offset:49152
	ds_read_b128 v[98:101], v173 offset:32768
	ds_read_b128 v[102:105], v177 offset:49152
	v_mfma_f32_32x32x16_bf16 v[16:31], v[114:117], v[110:113], v[16:31]
	ds_read_b128 v[106:109], v176 offset:53248
	ds_read_b128 v[110:113], v177 offset:53248
	s_waitcnt lgkmcnt(4)
	v_mfma_f32_32x32x16_bf16 v[32:47], v[88:91], v[92:95], v[32:47]
	s_waitcnt lgkmcnt(1)
	v_mfma_f32_32x32x16_bf16 v[48:63], v[88:91], v[106:109], v[48:63]
	ds_read_b128 v[88:91], v172 offset:36864
	ds_read_b128 v[114:117], v173 offset:36864
	s_waitcnt lgkmcnt(1)
	v_mfma_f32_32x32x16_bf16 v[0:15], v[88:91], v[92:95], v[0:15]
	v_mfma_f32_32x32x16_bf16 v[16:31], v[88:91], v[106:109], v[16:31]
	v_mfma_f32_32x32x16_bf16 v[32:47], v[98:101], v[102:105], v[32:47]
	v_mfma_f32_32x32x16_bf16 v[48:63], v[98:101], v[110:113], v[48:63]
	s_nop 0
	s_nop 0
	s_nop 0
	s_nop 0
	s_nop 0
	s_nop 0
	s_nop 0
	s_waitcnt lgkmcnt(0)
	s_waitcnt vmcnt(0)
	s_barrier
	v_lshl_add_u64 v[66:67], v[66:67], 0, s[96:97]
	s_add_u32 m0, s94, 0x8000
	s_nop 1
	global_load_lds_dwordx4 v[66:67], off
	v_lshl_add_u64 v[68:69], v[68:69], 0, s[96:97]
	s_add_u32 m0, s94, 0xc000
	s_nop 1
	global_load_lds_dwordx4 v[68:69], off
	v_lshl_add_u64 v[70:71], v[70:71], 0, s[96:97]
	s_add_u32 m0, s94, 0x9000
	s_nop 1
	global_load_lds_dwordx4 v[70:71], off
	v_lshl_add_u64 v[72:73], v[72:73], 0, s[96:97]
	s_add_u32 m0, s94, 0xd000
	s_nop 1
	global_load_lds_dwordx4 v[72:73], off
	v_lshl_add_u64 v[74:75], v[74:75], 0, s[96:97]
	s_add_u32 m0, s94, 0xa000
	s_nop 1
	global_load_lds_dwordx4 v[74:75], off
	v_lshl_add_u64 v[76:77], v[76:77], 0, s[96:97]
	s_add_u32 m0, s94, 0xe000
	s_nop 1
	global_load_lds_dwordx4 v[76:77], off
	v_lshl_add_u64 v[78:79], v[78:79], 0, s[96:97]
	s_add_u32 m0, s94, 0xb000
	s_nop 1
	global_load_lds_dwordx4 v[78:79], off
	v_lshl_add_u64 v[80:81], v[80:81], 0, s[96:97]
	s_add_u32 m0, s94, 0xf000
	s_nop 1
	global_load_lds_dwordx4 v[80:81], off
	v_mfma_f32_32x32x16_bf16 v[0:15], v[114:117], v[102:105], v[0:15]
	ds_read_b128 v[66:69], v170 offset:0
	ds_read_b128 v[70:73], v174 offset:16384
	ds_read_b128 v[74:77], v171 offset:0
	ds_read_b128 v[78:81], v175 offset:16384
	ds_read_b128 v[88:91], v174 offset:20480
	ds_read_b128 v[92:95], v175 offset:20480
	v_mfma_f32_32x32x16_bf16 v[16:31], v[114:117], v[110:113], v[16:31]
	s_waitcnt lgkmcnt(4)
	v_mfma_f32_32x32x16_bf16 v[32:47], v[66:69], v[70:73], v[32:47]
	s_waitcnt lgkmcnt(1)
	v_mfma_f32_32x32x16_bf16 v[48:63], v[66:69], v[88:91], v[48:63]
	ds_read_b128 v[66:69], v170 offset:4096
	ds_read_b128 v[98:101], v171 offset:4096
	s_waitcnt lgkmcnt(1)
	v_mfma_f32_32x32x16_bf16 v[0:15], v[66:69], v[70:73], v[0:15]
	v_mfma_f32_32x32x16_bf16 v[16:31], v[66:69], v[88:91], v[16:31]
	v_mfma_f32_32x32x16_bf16 v[32:47], v[74:77], v[78:81], v[32:47]
	v_mfma_f32_32x32x16_bf16 v[48:63], v[74:77], v[92:95], v[48:63]
	s_waitcnt lgkmcnt(0)
	v_mfma_f32_32x32x16_bf16 v[0:15], v[98:101], v[78:81], v[0:15]
	ds_read_b128 v[66:69], v172 offset:0
	ds_read_b128 v[70:73], v176 offset:16384
	ds_read_b128 v[74:77], v173 offset:0
	ds_read_b128 v[78:81], v177 offset:16384
	v_mfma_f32_32x32x16_bf16 v[16:31], v[98:101], v[92:95], v[16:31]
	ds_read_b128 v[88:91], v176 offset:20480
	ds_read_b128 v[92:95], v177 offset:20480
	s_waitcnt lgkmcnt(4)
	v_mfma_f32_32x32x16_bf16 v[32:47], v[66:69], v[70:73], v[32:47]
	s_waitcnt lgkmcnt(1)
	v_mfma_f32_32x32x16_bf16 v[48:63], v[66:69], v[88:91], v[48:63]
	ds_read_b128 v[66:69], v172 offset:4096
	ds_read_b128 v[98:101], v173 offset:4096
	s_waitcnt lgkmcnt(0)
	s_waitcnt vmcnt(0)
	s_barrier
; #define PW(T, off) ((T*)(lndp(p.ws) + (off)))
; DEVI void gemm_epi_qkv(const Params& p, f32x16 (&acc)[2][2], int rbase, int cbase, int lane) {
;   char* ar = PW(char, W_arena);
;   const int which = cbase >> 10, cc = cbase & 1023, d = lane & 31, hl = lane >> 5;
; #pragma unroll
;   for (int i = 0; i < 2; ++i) {
; #pragma unroll
;     for (int rq = 0; rq < 4; ++rq) {
;       const int row0 = rbase + i * 32 + 8 * rq + 4 * hl;
;       if (row0 >= M) continue;
;       const bool pr = row0 < TP;
;       const int b = pr ? 0 : (row0 - TP) >> 4, t0 = pr ? row0 : (row0 - TP) & 15;
;       if (which < 2) {
;         const float* csp = PW(float, W_cs) + (size_t)row0 * 64 + d;
;         bf16* dst;
;         float* fo = nullptr;
;         if (which == 0) dst = (bf16*)(ar + A_QB) + (size_t)row0 * 1024 + cc + d;
;         else {
;           const size_t ur = pr ? (size_t)(48 + row0) : (size_t)(LDVP + b * LDVS + 48 + 4096 + t0);
;           dst = (bf16*)(ar + A_KALL) + ur * 1024 + cc + d;
;     ...
;   bf16* As1 = As + 2 * 128 * 72;
;   bf16* Bs1 = As1 + 128 * 72;
;   G_LOAD(ra0, rb0, 0);
;   if (nk > 1) G_LOAD(ra1, rb1, 1);
;   G_STORE(ra0, rb0, As, Bs);
;   __syncthreads();
;   for (int kt = 0; kt < nk; kt += 2) {
;     if (kt + 2 < nk) G_LOAD(ra0, rb0, kt + 2);
;     if (kt + 1 < nk) G_STORE(ra1, rb1, As1, Bs1);
;     G_COMPUTE(As, Bs);
;     __syncthreads();
;     if (kt + 1 < nk) {
;       if (kt + 3 < nk) G_LOAD(ra1, rb1, kt + 3);
;       if (kt + 2 < nk) G_STORE(ra0, rb0, As, Bs);
;       G_COMPUTE(As1, Bs1);
;       __syncthreads();
;     }
;   }
	v_mfma_f32_32x32x16_bf16 v[0:15], v[66:69], v[70:73], v[0:15]
	v_mfma_f32_32x32x16_bf16 v[32:47], v[74:77], v[78:81], v[32:47]
	v_mfma_f32_32x32x16_bf16 v[48:63], v[74:77], v[92:95], v[48:63]
	v_mfma_f32_32x32x16_bf16 v[16:31], v[66:69], v[88:91], v[16:31]
	v_mfma_f32_32x32x16_bf16 v[0:15], v[98:101], v[78:81], v[0:15]
	ds_read_b128 v[66:69], v170 offset:32768
	ds_read_b128 v[70:73], v174 offset:49152
	ds_read_b128 v[74:77], v175 offset:49152
	ds_read_b128 v[78:81], v171 offset:32768
	ds_read_b128 v[88:91], v174 offset:53248
	s_waitcnt lgkmcnt(3)
	v_mfma_f32_32x32x16_bf16 v[32:47], v[66:69], v[70:73], v[32:47]
	s_waitcnt lgkmcnt(0)
	v_mfma_f32_32x32x16_bf16 v[48:63], v[66:69], v[88:91], v[48:63]
	ds_read_b128 v[66:69], v170 offset:36864
	v_mfma_f32_32x32x16_bf16 v[16:31], v[98:101], v[92:95], v[16:31]
	s_waitcnt lgkmcnt(0)
	v_mfma_f32_32x32x16_bf16 v[0:15], v[66:69], v[70:73], v[0:15]
	ds_read_b128 v[70:73], v171 offset:36864
	v_mfma_f32_32x32x16_bf16 v[16:31], v[66:69], v[88:91], v[16:31]
	ds_read_b128 v[66:69], v175 offset:53248
	v_mfma_f32_32x32x16_bf16 v[32:47], v[78:81], v[74:77], v[32:47]
	s_waitcnt lgkmcnt(0)
	v_mfma_f32_32x32x16_bf16 v[48:63], v[78:81], v[66:69], v[48:63]
	v_or_b32_e32 v81, s6, v65
	v_and_or_b32 v80, v85, 64, s6
	s_mov_b64 s[6:7], 0x1e05c060
	v_mfma_f32_32x32x16_bf16 v[0:15], v[70:73], v[74:77], v[0:15]
	v_mfma_f32_32x32x16_bf16 v[16:31], v[70:73], v[66:69], v[16:31]
	ds_read_b128 v[66:69], v172 offset:32768
	ds_read_b128 v[70:73], v176 offset:49152
	ds_read_b128 v[74:77], v176 offset:53248
	s_waitcnt lgkmcnt(1)
	v_mfma_f32_32x32x16_bf16 v[32:47], v[66:69], v[70:73], v[32:47]
	s_waitcnt lgkmcnt(0)
	v_mfma_f32_32x32x16_bf16 v[48:63], v[66:69], v[74:77], v[48:63]
	ds_read_b128 v[66:69], v172 offset:36864
	s_waitcnt lgkmcnt(0)
	v_mfma_f32_32x32x16_bf16 v[0:15], v[66:69], v[70:73], v[0:15]
	ds_read_b128 v[88:91], v177 offset:53248
	ds_read_b128 v[92:95], v177 offset:49152
	ds_read_b128 v[70:73], v173 offset:32768
	v_mfma_f32_32x32x16_bf16 v[16:31], v[66:69], v[74:77], v[16:31]
	ds_read_b128 v[74:77], v173 offset:36864
	v_lshrrev_b32_e32 v66, 3, v85
	v_add_u32_e32 v64, s3, v86
	v_and_b32_e32 v82, 4, v66
	v_or_b32_e32 v68, v64, v82
	v_mul_u32_u24_e32 v64, 0x4040, v81
	v_lshlrev_b32_e32 v96, 1, v64
	s_waitcnt lgkmcnt(1)
	v_mfma_f32_32x32x16_bf16 v[32:47], v[70:73], v[92:95], v[32:47]
	s_waitcnt lgkmcnt(0)
	s_barrier
	s_cmp_gt_i32 s5, 1
	s_cselect_b64 s[2:3], -1, 0
	v_lshl_add_u64 v[64:65], s[22:23], 0, v[96:97]
	v_lshlrev_b32_e32 v96, 1, v80
	v_mfma_f32_32x32x16_bf16 v[48:63], v[70:73], v[88:91], v[48:63]
	v_lshl_add_u64 v[70:71], v[64:65], 0, s[6:7]
	s_cmpk_gt_u32 s4, 0x3ff
	v_lshl_add_u64 v[64:65], s[22:23], 0, v[96:97]
	s_mov_b64 s[6:7], 0x13e3c000
	s_cselect_b64 s[20:21], -1, 0
	v_lshl_add_u64 v[66:67], v[64:65], 0, s[6:7]
	s_mov_b64 s[6:7], 0x11d7c000
	v_mfma_f32_32x32x16_bf16 v[0:15], v[74:77], v[92:95], v[0:15]
	s_cmp_eq_u32 s5, 1
	v_lshl_add_u64 v[64:65], v[64:65], 0, s[6:7]
	s_cselect_b64 s[18:19], -1, 0
	v_cmp_gt_i32_e32 vcc, s90, v68
	v_mfma_f32_32x32x16_bf16 v[16:31], v[74:77], v[88:91], v[16:31]
	s_and_saveexec_b64 s[4:5], vcc
	s_cbranch_execz .LBB0_2373
	s_movk_i32 s6, 0x400f
	v_add_u32_e32 v72, 0xffffbff0, v68
	v_cmp_lt_i32_e64 s[6:7], s6, v68
	v_ashrrev_i32_e32 v78, 4, v72
	s_mov_b64 s[8:9], -1
	s_and_b64 vcc, exec, s[2:3]
	s_cbranch_vccz .LBB0_2352
	s_and_saveexec_b64 s[8:9], s[6:7]
	s_xor_b64 s[8:9], exec, s[8:9]
	s_cbranch_execz .LBB0_2345
	s_mov_b64 s[10:11], s[72:73]
	s_add_u32 s10, s10, 0xc48f000
	v_mov_b32_e32 v73, v97
	s_addc_u32 s11, s11, 0
	v_mov_b64_e32 v[74:75], v[72:73]

;     ...
;   const int lrow = tid >> 3, lkc = (tid & 7) * 8;
;   const bf16* Ag = jb.A + (size_t)max(m0 + lrow, 0) * jb.lda + lkc;
;   const bf16* Ag1 = jb.A + (ptrdiff_t)(m0 + lrow) * jb.lda + lkc;
;   const bf16* Bg = jb.Bt + (size_t)(n0 + lrow) * jb.K + lkc;
;   const size_t astep = (size_t)32 * jb.lda, bstep = (size_t)32 * jb.K;
;   if (kt1 < 0) kt1 = jb.K >> 6;
;   const int nk = kt1 - kt0;
;   Ag += (size_t)kt0 * 64; Ag1 += (size_t)kt0 * 64; Bg += (size_t)kt0 * 64;
;   u32x4 ra0[4], rb0[4], ra1[4], rb1[4];
;     ...
;   bf16* As1 = As + 2 * 128 * 72;
;   bf16* Bs1 = As1 + 128 * 72;
;   G_LOAD(ra0, rb0, 0);
;   if (nk > 1) G_LOAD(ra1, rb1, 1);
;   G_STORE(ra0, rb0, As, Bs);
;   __syncthreads();
;   for (int kt = 0; kt < nk; kt += 2) {
;     if (kt + 2 < nk) G_LOAD(ra0, rb0, kt + 2);
;     if (kt + 1 < nk) G_STORE(ra1, rb1, As1, Bs1);
;     G_COMPUTE(As, Bs);
; DEVI void gemm_single(const Params& p, const GJob& jb, int nt, char* smem) {
;     ...
;     for (int t = lb; t < nmt * nnt; t += nlb) {
;       const int mt = m_lo + t / nnt, ntg = n_lo + t % nnt;
;       gemm_tile(p, jb, fused ? mt * 126 - 2 : mt * 128, ntg * 128, smem);
.LBB0_3493:
	s_abs_i32 s3, s23
	s_mul_hi_u32 s4, s3, s29
	s_mul_i32 s5, s4, s27
	s_ashr_i32 s2, s23, 31
	s_sub_i32 s3, s3, s5
	s_xor_b32 s2, s2, s28
	s_add_i32 s5, s4, 1
	s_sub_i32 s6, s3, s27
	s_cmp_ge_u32 s3, s27
	s_cselect_b32 s4, s5, s4
	s_cselect_b32 s3, s6, s3
	s_add_i32 s5, s4, 1
	s_cmp_ge_u32 s3, s27
	s_cselect_b32 s3, s5, s4
	s_xor_b32 s3, s3, s2
	s_sub_i32 s4, s3, s2
	s_add_i32 s4, s4, s25
	s_mul_i32 s30, s4, 0x7e
	s_waitcnt vmcnt(0)
	v_mov_b32_e32 v93, v208
	s_add_i32 s30, s30, -2
	s_mul_i32 s2, s2, 11
	v_ashrrev_i32_e32 v70, 3, v93
	v_add_u32_e32 v0, s30, v70
	s_mul_i32 s3, s3, 11
	v_max_i32_e32 v96, 0, v0
	v_lshlrev_b32_e32 v1, 4, v93
	s_sub_i32 s2, s2, s3
	s_add_i32 s3, s24, s23
	v_lshlrev_b64 v[2:3], 11, v[96:97]
	v_and_b32_e32 v96, 0x70, v1
	s_mov_b64 s[96:97], 0x80
	v_lshrrev_b32_e32 v178, 4, v93
	v_and_b32_e32 v178, 7, v178
	v_lshlrev_b32_e32 v178, 4, v178
	v_xor_b32_e32 v96, v96, v178
	v_lshrrev_b32_e32 v179, 6, v93
	v_lshlrev_b32_e32 v179, 10, v179
	v_lshrrev_b32_e32 v180, 5, v93
	v_lshrrev_b32_e32 v181, 1, v93
	v_xor_b32_e32 v180, v180, v181
	v_readfirstlane_b32 s94, v179
	v_and_b32_e32 v180, 1, v180
	v_lshlrev_b32_e32 v180, 4, v180
	v_and_b32_e32 v181, 31, v93
	v_lshlrev_b32_e32 v181, 7, v181
	v_or_b32_e32 v180, v180, v181
	v_lshrrev_b32_e32 v181, 7, v93
	v_lshlrev_b32_e32 v181, 13, v181
	v_or_b32_e32 v194, v180, v181
	v_bfe_u32 v181, v93, 6, 1
	v_lshlrev_b32_e32 v181, 13, v181
	v_or_b32_e32 v195, v180, v181
	v_bfe_u32 v178, v93, 2, 2
	v_xor_b32_e32 v179, 0, v178
	v_lshlrev_b32_e32 v179, 5, v179
	v_or_b32_e32 v170, v194, v179
	v_or_b32_e32 v174, v195, v179
	v_xor_b32_e32 v179, 1, v178
	v_lshlrev_b32_e32 v179, 5, v179
	v_or_b32_e32 v171, v194, v179
	v_or_b32_e32 v175, v195, v179
	v_xor_b32_e32 v179, 2, v178
	v_lshlrev_b32_e32 v179, 5, v179
	v_or_b32_e32 v172, v194, v179
	v_or_b32_e32 v176, v195, v179
	v_xor_b32_e32 v179, 3, v178
	v_lshlrev_b32_e32 v179, 5, v179
	v_or_b32_e32 v173, v194, v179
	v_or_b32_e32 v177, v195, v179
	v_ashrrev_i32_e32 v1, 31, v0
	s_add_i32 s3, s3, s2
	v_lshlrev_b64 v[0:1], 11, v[0:1]
	s_lshl_b32 s2, s3, 7
	v_lshl_add_u64 v[0:1], s[12:13], 0, v[0:1]
	v_lshl_add_u64 v[24:25], v[0:1], 0, v[96:97]
	v_add_u32_e32 v0, s2, v70
	v_ashrrev_i32_e32 v1, 31, v0
	v_lshlrev_b64 v[0:1], 11, v[0:1]
	v_lshl_add_u64 v[0:1], v[64:65], 0, v[0:1]
	v_add_co_u32_e32 v76, vcc, s63, v24
	v_lshl_add_u64 v[74:75], v[0:1], 0, v[96:97]
	s_nop 0
	v_addc_co_u32_e32 v77, vcc, 0, v25, vcc
	v_add_co_u32_e32 v78, vcc, s63, v74
	v_lshl_add_u64 v[2:3], s[12:13], 0, v[2:3]
	s_nop 0
	v_addc_co_u32_e32 v79, vcc, 0, v75, vcc
	v_add_co_u32_e32 v80, vcc, s64, v24
	v_lshl_add_u64 v[72:73], v[2:3], 0, v[96:97]
	s_nop 0
	v_addc_co_u32_e32 v81, vcc, 0, v25, vcc
	v_add_co_u32_e32 v82, vcc, s64, v74
	v_addc_co_u32_e32 v83, vcc, 0, v75, vcc
	v_add_co_u32_e32 v84, vcc, s65, v24
	s_nop 0
	v_addc_co_u32_e32 v85, vcc, 0, v25, vcc
	v_add_co_u32_e32 v86, vcc, s65, v74
	s_nop 0
	v_addc_co_u32_e32 v87, vcc, 0, v75, vcc
	v_ashrrev_i32_e32 v71, 1, v93
	v_mad_u64_u32 v[88:89], s[4:5], v70, s91, v[96:97]
	v_and_b32_e32 v94, 31, v93
	v_and_b32_e32 v92, 0xffffffc0, v71
	v_or_b32_e32 v71, v92, v94
	v_add_u32_e32 v96, 0xd800, v88
	v_bfe_u32 v95, v93, 6, 1
	s_mov_b32 s6, 43
	s_mov_b64 s[16:17], s[72:73]
	s_add_u32 m0, s94, 0x0
	s_nop 1
	global_load_lds_dwordx4 v[72:73], off
	s_add_u32 m0, s94, 0x4000
	s_nop 1
	global_load_lds_dwordx4 v[74:75], off
	s_add_u32 m0, s94, 0x1000
	s_nop 1
	global_load_lds_dwordx4 v[76:77], off
	s_add_u32 m0, s94, 0x5000
	s_nop 1
	global_load_lds_dwordx4 v[78:79], off
	s_add_u32 m0, s94, 0x2000
	s_nop 1
	global_load_lds_dwordx4 v[80:81], off
	s_add_u32 m0, s94, 0x6000
	s_nop 1
	global_load_lds_dwordx4 v[82:83], off
	s_add_u32 m0, s94, 0x3000
	s_nop 1
	global_load_lds_dwordx4 v[84:85], off
	s_add_u32 m0, s94, 0x7000
	s_nop 1
	global_load_lds_dwordx4 v[86:87], off
	v_lshrrev_b32_e32 v0, 1, v93
	v_and_b32_e32 v4, 16, v0
	s_waitcnt lgkmcnt(0)
	s_waitcnt vmcnt(0)
	s_barrier
	v_mad_u64_u32 v[70:71], s[4:5], v71, s91, v[4:5]
	v_lshl_add_u64 v[72:73], v[72:73], 0, s[96:97]
	s_add_u32 m0, s94, 0x8000
	s_nop 1
	global_load_lds_dwordx4 v[72:73], off
	v_lshl_add_u64 v[74:75], v[74:75], 0, s[96:97]
	s_add_u32 m0, s94, 0xc000
	s_nop 1
	global_load_lds_dwordx4 v[74:75], off
	v_lshl_add_u64 v[76:77], v[76:77], 0, s[96:97]
	s_add_u32 m0, s94, 0x9000
	s_nop 1
	global_load_lds_dwordx4 v[76:77], off
	v_lshl_add_u64 v[78:79], v[78:79], 0, s[96:97]
	s_add_u32 m0, s94, 0xd000
	s_nop 1
	global_load_lds_dwordx4 v[78:79], off
	v_lshl_add_u64 v[80:81], v[80:81], 0, s[96:97]
	s_add_u32 m0, s94, 0xa000
	s_nop 1
	global_load_lds_dwordx4 v[80:81], off
	v_lshl_add_u64 v[82:83], v[82:83], 0, s[96:97]
	s_add_u32 m0, s94, 0xe000
	s_nop 1
	global_load_lds_dwordx4 v[82:83], off
	v_lshl_add_u64 v[84:85], v[84:85], 0, s[96:97]
	s_add_u32 m0, s94, 0xb000
	s_nop 1
	global_load_lds_dwordx4 v[84:85], off
	v_lshl_add_u64 v[86:87], v[86:87], 0, s[96:97]
	s_add_u32 m0, s94, 0xf000
	s_nop 1
	global_load_lds_dwordx4 v[86:87], off
	ds_read_b128 v[0:3], v170 offset:0
	v_lshlrev_b32_e32 v71, 6, v95
	v_or_b32_e32 v5, v71, v94
	v_mad_u32_u24 v89, v5, s91, v4
	ds_read_b128 v[4:7], v174 offset:16384
	ds_read_b128 v[98:101], v171 offset:0
	ds_read_b128 v[102:105], v175 offset:16384
	ds_read_b128 v[8:11], v174 offset:20480
	ds_read_b128 v[106:109], v175 offset:20480
	s_waitcnt lgkmcnt(4)
	v_mfma_f32_32x32x16_bf16 v[48:63], v[0:3], v[4:7], 0
	s_mov_b32 s4, 8
	s_waitcnt lgkmcnt(1)
	v_mfma_f32_32x32x16_bf16 v[32:47], v[0:3], v[8:11], 0
	ds_read_b128 v[0:3], v170 offset:4096
	ds_read_b128 v[110:113], v171 offset:4096
	s_waitcnt lgkmcnt(1)
	v_mfma_f32_32x32x16_bf16 v[16:31], v[0:3], v[4:7], 0
	v_mfma_f32_32x32x16_bf16 v[0:15], v[0:3], v[8:11], 0
	v_mfma_f32_32x32x16_bf16 v[48:63], v[98:101], v[102:105], v[48:63]
	v_mfma_f32_32x32x16_bf16 v[32:47], v[98:101], v[106:109], v[32:47]
	s_waitcnt lgkmcnt(0)
	v_mfma_f32_32x32x16_bf16 v[16:31], v[110:113], v[102:105], v[16:31]
	v_mfma_f32_32x32x16_bf16 v[0:15], v[110:113], v[106:109], v[0:15]
	ds_read_b128 v[98:101], v172 offset:0
	ds_read_b128 v[102:105], v176 offset:16384
	ds_read_b128 v[106:109], v173 offset:0
	ds_read_b128 v[110:113], v177 offset:16384
	ds_read_b128 v[114:117], v176 offset:20480
	ds_read_b128 v[118:121], v177 offset:20480
	s_waitcnt lgkmcnt(4)
	v_mfma_f32_32x32x16_bf16 v[48:63], v[98:101], v[102:105], v[48:63]
	s_waitcnt lgkmcnt(1)
	v_mfma_f32_32x32x16_bf16 v[32:47], v[98:101], v[114:117], v[32:47]
	ds_read_b128 v[98:101], v172 offset:4096
	ds_read_b128 v[122:125], v173 offset:4096
	s_waitcnt lgkmcnt(1)
	v_mfma_f32_32x32x16_bf16 v[16:31], v[98:101], v[102:105], v[16:31]
	v_mfma_f32_32x32x16_bf16 v[0:15], v[98:101], v[114:117], v[0:15]
	v_mfma_f32_32x32x16_bf16 v[48:63], v[106:109], v[110:113], v[48:63]
	v_mfma_f32_32x32x16_bf16 v[32:47], v[106:109], v[118:121], v[32:47]
	s_waitcnt lgkmcnt(0)
	v_mfma_f32_32x32x16_bf16 v[16:31], v[122:125], v[110:113], v[16:31]
	s_waitcnt vmcnt(0)
	s_barrier
;     ...
;   bf16* As1 = As + 2 * 128 * 72;
;   bf16* Bs1 = As1 + 128 * 72;
;   G_LOAD(ra0, rb0, 0);
;   if (nk > 1) G_LOAD(ra1, rb1, 1);
;   G_STORE(ra0, rb0, As, Bs);
;   __syncthreads();
;   for (int kt = 0; kt < nk; kt += 2) {
;     if (kt + 2 < nk) G_LOAD(ra0, rb0, kt + 2);
;     if (kt + 1 < nk) G_STORE(ra1, rb1, As1, Bs1);
;     G_COMPUTE(As, Bs);
;     __syncthreads();
;     if (kt + 1 < nk) {
;       if (kt + 3 < nk) G_LOAD(ra1, rb1, kt + 3);
;       if (kt + 2 < nk) G_STORE(ra0, rb0, As, Bs);
;       G_COMPUTE(As1, Bs1);
;       __syncthreads();
	v_lshl_add_u64 v[72:73], v[72:73], 0, s[96:97]
	s_add_u32 m0, s94, 0x0
	s_nop 1
	global_load_lds_dwordx4 v[72:73], off
	v_lshl_add_u64 v[74:75], v[74:75], 0, s[96:97]
	s_add_u32 m0, s94, 0x4000
	s_nop 1
	global_load_lds_dwordx4 v[74:75], off
	v_lshl_add_u64 v[76:77], v[76:77], 0, s[96:97]
	s_add_u32 m0, s94, 0x1000
	s_nop 1
	global_load_lds_dwordx4 v[76:77], off
	v_lshl_add_u64 v[78:79], v[78:79], 0, s[96:97]
	s_add_u32 m0, s94, 0x5000
	s_nop 1
	global_load_lds_dwordx4 v[78:79], off
	v_lshl_add_u64 v[80:81], v[80:81], 0, s[96:97]
	s_add_u32 m0, s94, 0x2000
	s_nop 1
	global_load_lds_dwordx4 v[80:81], off
	v_lshl_add_u64 v[82:83], v[82:83], 0, s[96:97]
	s_add_u32 m0, s94, 0x6000
	s_nop 1
	global_load_lds_dwordx4 v[82:83], off
	v_lshl_add_u64 v[84:85], v[84:85], 0, s[96:97]
	s_add_u32 m0, s94, 0x3000
	s_nop 1
	global_load_lds_dwordx4 v[84:85], off
	v_lshl_add_u64 v[86:87], v[86:87], 0, s[96:97]
	s_add_u32 m0, s94, 0x7000
	s_nop 1
	global_load_lds_dwordx4 v[86:87], off
	v_mfma_f32_32x32x16_bf16 v[0:15], v[122:125], v[118:121], v[0:15]
	ds_read_b128 v[98:101], v170 offset:32768
	ds_read_b128 v[102:105], v174 offset:49152
	ds_read_b128 v[106:109], v171 offset:32768
	ds_read_b128 v[110:113], v175 offset:49152
	ds_read_b128 v[114:117], v174 offset:53248
	ds_read_b128 v[118:121], v175 offset:53248
	s_waitcnt lgkmcnt(4)
	v_mfma_f32_32x32x16_bf16 v[48:63], v[98:101], v[102:105], v[48:63]
	s_waitcnt lgkmcnt(1)
	v_mfma_f32_32x32x16_bf16 v[32:47], v[98:101], v[114:117], v[32:47]
	ds_read_b128 v[98:101], v170 offset:36864
	ds_read_b128 v[122:125], v171 offset:36864
	s_waitcnt lgkmcnt(1)
	v_mfma_f32_32x32x16_bf16 v[16:31], v[98:101], v[102:105], v[16:31]
	v_mfma_f32_32x32x16_bf16 v[0:15], v[98:101], v[114:117], v[0:15]
	v_mfma_f32_32x32x16_bf16 v[48:63], v[106:109], v[110:113], v[48:63]
	v_mfma_f32_32x32x16_bf16 v[32:47], v[106:109], v[118:121], v[32:47]
	s_waitcnt lgkmcnt(0)
	v_mfma_f32_32x32x16_bf16 v[16:31], v[122:125], v[110:113], v[16:31]
	ds_read_b128 v[98:101], v172 offset:32768
	ds_read_b128 v[102:105], v176 offset:49152
	ds_read_b128 v[106:109], v173 offset:32768
	ds_read_b128 v[110:113], v177 offset:49152
	v_mfma_f32_32x32x16_bf16 v[0:15], v[122:125], v[118:121], v[0:15]
	ds_read_b128 v[114:117], v176 offset:53248
	ds_read_b128 v[118:121], v177 offset:53248
	s_waitcnt lgkmcnt(4)
	v_mfma_f32_32x32x16_bf16 v[48:63], v[98:101], v[102:105], v[48:63]
	s_waitcnt lgkmcnt(1)
	v_mfma_f32_32x32x16_bf16 v[32:47], v[98:101], v[114:117], v[32:47]
	ds_read_b128 v[98:101], v172 offset:36864
	ds_read_b128 v[122:125], v173 offset:36864
	s_waitcnt lgkmcnt(1)
	v_mfma_f32_32x32x16_bf16 v[16:31], v[98:101], v[102:105], v[16:31]
	v_mfma_f32_32x32x16_bf16 v[0:15], v[98:101], v[114:117], v[0:15]
	v_mfma_f32_32x32x16_bf16 v[48:63], v[106:109], v[110:113], v[48:63]
	v_mfma_f32_32x32x16_bf16 v[32:47], v[106:109], v[118:121], v[32:47]
	s_waitcnt lgkmcnt(0)
	v_mfma_f32_32x32x16_bf16 v[16:31], v[122:125], v[110:113], v[16:31]
	s_waitcnt vmcnt(0)
	s_barrier
	v_lshl_add_u64 v[72:73], v[72:73], 0, s[96:97]
	s_add_u32 m0, s94, 0x8000
	s_nop 1
	global_load_lds_dwordx4 v[72:73], off
	v_lshl_add_u64 v[74:75], v[74:75], 0, s[96:97]
	s_add_u32 m0, s94, 0xc000
	s_nop 1
	global_load_lds_dwordx4 v[74:75], off
	v_lshl_add_u64 v[76:77], v[76:77], 0, s[96:97]
	s_add_u32 m0, s94, 0x9000
	s_nop 1
	global_load_lds_dwordx4 v[76:77], off
	v_lshl_add_u64 v[78:79], v[78:79], 0, s[96:97]
	s_add_u32 m0, s94, 0xd000
	s_nop 1
	global_load_lds_dwordx4 v[78:79], off
	v_lshl_add_u64 v[80:81], v[80:81], 0, s[96:97]
	s_add_u32 m0, s94, 0xa000
	s_nop 1
	global_load_lds_dwordx4 v[80:81], off
	v_lshl_add_u64 v[82:83], v[82:83], 0, s[96:97]
	s_add_u32 m0, s94, 0xe000
	s_nop 1
	global_load_lds_dwordx4 v[82:83], off
	v_lshl_add_u64 v[84:85], v[84:85], 0, s[96:97]
	s_add_u32 m0, s94, 0xb000
	s_nop 1
	global_load_lds_dwordx4 v[84:85], off
	v_lshl_add_u64 v[86:87], v[86:87], 0, s[96:97]
	s_add_u32 m0, s94, 0xf000
	s_nop 1
	global_load_lds_dwordx4 v[86:87], off
	v_mfma_f32_32x32x16_bf16 v[0:15], v[122:125], v[118:121], v[0:15]
	ds_read_b128 v[98:101], v170 offset:0
	ds_read_b128 v[102:105], v174 offset:16384
	ds_read_b128 v[106:109], v171 offset:0
	ds_read_b128 v[110:113], v175 offset:16384
	ds_read_b128 v[114:117], v174 offset:20480
	ds_read_b128 v[118:121], v175 offset:20480
	s_waitcnt lgkmcnt(4)
	v_mfma_f32_32x32x16_bf16 v[48:63], v[98:101], v[102:105], v[48:63]
	s_waitcnt lgkmcnt(1)
	v_mfma_f32_32x32x16_bf16 v[32:47], v[98:101], v[114:117], v[32:47]
	ds_read_b128 v[98:101], v170 offset:4096
	ds_read_b128 v[122:125], v171 offset:4096
	s_waitcnt lgkmcnt(1)
	v_mfma_f32_32x32x16_bf16 v[16:31], v[98:101], v[102:105], v[16:31]
	v_mfma_f32_32x32x16_bf16 v[0:15], v[98:101], v[114:117], v[0:15]
	v_mfma_f32_32x32x16_bf16 v[48:63], v[106:109], v[110:113], v[48:63]
	v_mfma_f32_32x32x16_bf16 v[32:47], v[106:109], v[118:121], v[32:47]
	s_waitcnt lgkmcnt(0)
	v_mfma_f32_32x32x16_bf16 v[16:31], v[122:125], v[110:113], v[16:31]
	ds_read_b128 v[98:101], v172 offset:0
	ds_read_b128 v[102:105], v176 offset:16384
	ds_read_b128 v[106:109], v173 offset:0
	ds_read_b128 v[110:113], v177 offset:16384
	v_mfma_f32_32x32x16_bf16 v[0:15], v[122:125], v[118:121], v[0:15]
	ds_read_b128 v[114:117], v176 offset:20480
	ds_read_b128 v[118:121], v177 offset:20480
	s_waitcnt lgkmcnt(4)
	v_mfma_f32_32x32x16_bf16 v[48:63], v[98:101], v[102:105], v[48:63]
	s_waitcnt lgkmcnt(1)
	v_mfma_f32_32x32x16_bf16 v[32:47], v[98:101], v[114:117], v[32:47]
	ds_read_b128 v[98:101], v172 offset:4096
	ds_read_b128 v[122:125], v173 offset:4096
	s_waitcnt lgkmcnt(1)
	v_mfma_f32_32x32x16_bf16 v[16:31], v[98:101], v[102:105], v[16:31]
	v_mfma_f32_32x32x16_bf16 v[0:15], v[98:101], v[114:117], v[0:15]
	v_mfma_f32_32x32x16_bf16 v[48:63], v[106:109], v[110:113], v[48:63]
	v_mfma_f32_32x32x16_bf16 v[32:47], v[106:109], v[118:121], v[32:47]
	s_waitcnt lgkmcnt(0)
	v_mfma_f32_32x32x16_bf16 v[16:31], v[122:125], v[110:113], v[16:31]
	s_waitcnt vmcnt(0)
	s_barrier
;     ...
;   bf16* As1 = As + 2 * 128 * 72;
;   bf16* Bs1 = As1 + 128 * 72;
;   G_LOAD(ra0, rb0, 0);
;   if (nk > 1) G_LOAD(ra1, rb1, 1);
;   G_STORE(ra0, rb0, As, Bs);
;   __syncthreads();
;   for (int kt = 0; kt < nk; kt += 2) {
;     if (kt + 2 < nk) G_LOAD(ra0, rb0, kt + 2);
;     if (kt + 1 < nk) G_STORE(ra1, rb1, As1, Bs1);
;     G_COMPUTE(As, Bs);
;     __syncthreads();
;     if (kt + 1 < nk) {
;       if (kt + 3 < nk) G_LOAD(ra1, rb1, kt + 3);
;       if (kt + 2 < nk) G_STORE(ra0, rb0, As, Bs);
;       G_COMPUTE(As1, Bs1);
;       __syncthreads();
	v_lshl_add_u64 v[72:73], v[72:73], 0, s[96:97]
	s_add_u32 m0, s94, 0x0
	s_nop 1
	global_load_lds_dwordx4 v[72:73], off
	v_lshl_add_u64 v[74:75], v[74:75], 0, s[96:97]
	s_add_u32 m0, s94, 0x4000
	s_nop 1
	global_load_lds_dwordx4 v[74:75], off
	v_lshl_add_u64 v[76:77], v[76:77], 0, s[96:97]
	s_add_u32 m0, s94, 0x1000
	s_nop 1
	global_load_lds_dwordx4 v[76:77], off
	v_lshl_add_u64 v[78:79], v[78:79], 0, s[96:97]
	s_add_u32 m0, s94, 0x5000
	s_nop 1
	global_load_lds_dwordx4 v[78:79], off
	v_lshl_add_u64 v[80:81], v[80:81], 0, s[96:97]
	s_add_u32 m0, s94, 0x2000
	s_nop 1
	global_load_lds_dwordx4 v[80:81], off
	v_lshl_add_u64 v[82:83], v[82:83], 0, s[96:97]
	s_add_u32 m0, s94, 0x6000
	s_nop 1
	global_load_lds_dwordx4 v[82:83], off
	v_lshl_add_u64 v[84:85], v[84:85], 0, s[96:97]
	s_add_u32 m0, s94, 0x3000
	s_nop 1
	global_load_lds_dwordx4 v[84:85], off
	v_lshl_add_u64 v[86:87], v[86:87], 0, s[96:97]
	s_add_u32 m0, s94, 0x7000
	s_nop 1
	global_load_lds_dwordx4 v[86:87], off
	v_mfma_f32_32x32x16_bf16 v[0:15], v[122:125], v[118:121], v[0:15]
	ds_read_b128 v[98:101], v170 offset:32768
	ds_read_b128 v[102:105], v174 offset:49152
	ds_read_b128 v[106:109], v171 offset:32768
	ds_read_b128 v[110:113], v175 offset:49152
	ds_read_b128 v[114:117], v174 offset:53248
	ds_read_b128 v[118:121], v175 offset:53248
	s_waitcnt lgkmcnt(4)
	v_mfma_f32_32x32x16_bf16 v[48:63], v[98:101], v[102:105], v[48:63]
	s_waitcnt lgkmcnt(1)
	v_mfma_f32_32x32x16_bf16 v[32:47], v[98:101], v[114:117], v[32:47]
	ds_read_b128 v[98:101], v170 offset:36864
	ds_read_b128 v[122:125], v171 offset:36864
	s_waitcnt lgkmcnt(1)
	v_mfma_f32_32x32x16_bf16 v[16:31], v[98:101], v[102:105], v[16:31]
	v_mfma_f32_32x32x16_bf16 v[0:15], v[98:101], v[114:117], v[0:15]
	v_mfma_f32_32x32x16_bf16 v[48:63], v[106:109], v[110:113], v[48:63]
	v_mfma_f32_32x32x16_bf16 v[32:47], v[106:109], v[118:121], v[32:47]
	s_waitcnt lgkmcnt(0)
	v_mfma_f32_32x32x16_bf16 v[16:31], v[122:125], v[110:113], v[16:31]
	ds_read_b128 v[98:101], v172 offset:32768
	ds_read_b128 v[102:105], v176 offset:49152
	ds_read_b128 v[106:109], v173 offset:32768
	ds_read_b128 v[110:113], v177 offset:49152
	v_mfma_f32_32x32x16_bf16 v[0:15], v[122:125], v[118:121], v[0:15]
	ds_read_b128 v[114:117], v176 offset:53248
	ds_read_b128 v[118:121], v177 offset:53248
	s_waitcnt lgkmcnt(4)
	v_mfma_f32_32x32x16_bf16 v[48:63], v[98:101], v[102:105], v[48:63]
	s_waitcnt lgkmcnt(1)
	v_mfma_f32_32x32x16_bf16 v[32:47], v[98:101], v[114:117], v[32:47]
	ds_read_b128 v[98:101], v172 offset:36864
	ds_read_b128 v[122:125], v173 offset:36864
	s_waitcnt lgkmcnt(1)
	v_mfma_f32_32x32x16_bf16 v[16:31], v[98:101], v[102:105], v[16:31]
	v_mfma_f32_32x32x16_bf16 v[0:15], v[98:101], v[114:117], v[0:15]
	v_mfma_f32_32x32x16_bf16 v[48:63], v[106:109], v[110:113], v[48:63]
	v_mfma_f32_32x32x16_bf16 v[32:47], v[106:109], v[118:121], v[32:47]
	s_waitcnt lgkmcnt(0)
	v_mfma_f32_32x32x16_bf16 v[16:31], v[122:125], v[110:113], v[16:31]
	s_waitcnt vmcnt(0)
	s_barrier
	v_lshl_add_u64 v[72:73], v[72:73], 0, s[96:97]
	s_add_u32 m0, s94, 0x8000
	s_nop 1
	global_load_lds_dwordx4 v[72:73], off
	v_lshl_add_u64 v[74:75], v[74:75], 0, s[96:97]
	s_add_u32 m0, s94, 0xc000
	s_nop 1
	global_load_lds_dwordx4 v[74:75], off
	v_lshl_add_u64 v[76:77], v[76:77], 0, s[96:97]
	s_add_u32 m0, s94, 0x9000
	s_nop 1
	global_load_lds_dwordx4 v[76:77], off
	v_lshl_add_u64 v[78:79], v[78:79], 0, s[96:97]
	s_add_u32 m0, s94, 0xd000
	s_nop 1
	global_load_lds_dwordx4 v[78:79], off
	v_lshl_add_u64 v[80:81], v[80:81], 0, s[96:97]
	s_add_u32 m0, s94, 0xa000
	s_nop 1
	global_load_lds_dwordx4 v[80:81], off
	v_lshl_add_u64 v[82:83], v[82:83], 0, s[96:97]
	s_add_u32 m0, s94, 0xe000
	s_nop 1
	global_load_lds_dwordx4 v[82:83], off
	v_lshl_add_u64 v[84:85], v[84:85], 0, s[96:97]
	s_add_u32 m0, s94, 0xb000
	s_nop 1
	global_load_lds_dwordx4 v[84:85], off
	v_lshl_add_u64 v[86:87], v[86:87], 0, s[96:97]
	s_add_u32 m0, s94, 0xf000
	s_nop 1
	global_load_lds_dwordx4 v[86:87], off
	v_mfma_f32_32x32x16_bf16 v[0:15], v[122:125], v[118:121], v[0:15]
	ds_read_b128 v[98:101], v170 offset:0
	ds_read_b128 v[102:105], v174 offset:16384
	ds_read_b128 v[106:109], v171 offset:0
	ds_read_b128 v[110:113], v175 offset:16384
	ds_read_b128 v[114:117], v174 offset:20480
	ds_read_b128 v[118:121], v175 offset:20480
	s_waitcnt lgkmcnt(4)
	v_mfma_f32_32x32x16_bf16 v[48:63], v[98:101], v[102:105], v[48:63]
	s_waitcnt lgkmcnt(1)
	v_mfma_f32_32x32x16_bf16 v[32:47], v[98:101], v[114:117], v[32:47]
	ds_read_b128 v[98:101], v170 offset:4096
	ds_read_b128 v[122:125], v171 offset:4096
	s_waitcnt lgkmcnt(1)
	v_mfma_f32_32x32x16_bf16 v[16:31], v[98:101], v[102:105], v[16:31]
	v_mfma_f32_32x32x16_bf16 v[0:15], v[98:101], v[114:117], v[0:15]
	v_mfma_f32_32x32x16_bf16 v[48:63], v[106:109], v[110:113], v[48:63]
	v_mfma_f32_32x32x16_bf16 v[32:47], v[106:109], v[118:121], v[32:47]
	s_waitcnt lgkmcnt(0)
	v_mfma_f32_32x32x16_bf16 v[16:31], v[122:125], v[110:113], v[16:31]
	ds_read_b128 v[98:101], v172 offset:0
	ds_read_b128 v[102:105], v176 offset:16384
	ds_read_b128 v[106:109], v173 offset:0
	ds_read_b128 v[110:113], v177 offset:16384
	v_mfma_f32_32x32x16_bf16 v[0:15], v[122:125], v[118:121], v[0:15]
	ds_read_b128 v[114:117], v176 offset:20480
	ds_read_b128 v[118:121], v177 offset:20480
	s_waitcnt lgkmcnt(4)
	v_mfma_f32_32x32x16_bf16 v[48:63], v[98:101], v[102:105], v[48:63]
	s_waitcnt lgkmcnt(1)
	v_mfma_f32_32x32x16_bf16 v[32:47], v[98:101], v[114:117], v[32:47]
	ds_read_b128 v[98:101], v172 offset:4096
	ds_read_b128 v[122:125], v173 offset:4096
	s_waitcnt lgkmcnt(1)
	v_mfma_f32_32x32x16_bf16 v[16:31], v[98:101], v[102:105], v[16:31]
	v_mfma_f32_32x32x16_bf16 v[0:15], v[98:101], v[114:117], v[0:15]
	v_mfma_f32_32x32x16_bf16 v[48:63], v[106:109], v[110:113], v[48:63]
	v_mfma_f32_32x32x16_bf16 v[32:47], v[106:109], v[118:121], v[32:47]
	s_waitcnt lgkmcnt(0)
	v_mfma_f32_32x32x16_bf16 v[16:31], v[122:125], v[110:113], v[16:31]
	s_waitcnt vmcnt(0)
	s_barrier
;     ...
;   bf16* As1 = As + 2 * 128 * 72;
;   bf16* Bs1 = As1 + 128 * 72;
;   G_LOAD(ra0, rb0, 0);
;   if (nk > 1) G_LOAD(ra1, rb1, 1);
;   G_STORE(ra0, rb0, As, Bs);
;   __syncthreads();
;   for (int kt = 0; kt < nk; kt += 2) {
;     if (kt + 2 < nk) G_LOAD(ra0, rb0, kt + 2);
;     if (kt + 1 < nk) G_STORE(ra1, rb1, As1, Bs1);
;     G_COMPUTE(As, Bs);
;     __syncthreads();
;     if (kt + 1 < nk) {
;       if (kt + 3 < nk) G_LOAD(ra1, rb1, kt + 3);
;       if (kt + 2 < nk) G_STORE(ra0, rb0, As, Bs);
;       G_COMPUTE(As1, Bs1);
;       __syncthreads();
	v_lshl_add_u64 v[72:73], v[72:73], 0, s[96:97]
	s_add_u32 m0, s94, 0x0
	s_nop 1
	global_load_lds_dwordx4 v[72:73], off
	v_lshl_add_u64 v[74:75], v[74:75], 0, s[96:97]
	s_add_u32 m0, s94, 0x4000
	s_nop 1
	global_load_lds_dwordx4 v[74:75], off
	v_lshl_add_u64 v[76:77], v[76:77], 0, s[96:97]
	s_add_u32 m0, s94, 0x1000
	s_nop 1
	global_load_lds_dwordx4 v[76:77], off
	v_lshl_add_u64 v[78:79], v[78:79], 0, s[96:97]
	s_add_u32 m0, s94, 0x5000
	s_nop 1
	global_load_lds_dwordx4 v[78:79], off
	v_lshl_add_u64 v[80:81], v[80:81], 0, s[96:97]
	s_add_u32 m0, s94, 0x2000
	s_nop 1
	global_load_lds_dwordx4 v[80:81], off
	v_lshl_add_u64 v[82:83], v[82:83], 0, s[96:97]
	s_add_u32 m0, s94, 0x6000
	s_nop 1
	global_load_lds_dwordx4 v[82:83], off
	v_lshl_add_u64 v[84:85], v[84:85], 0, s[96:97]
	s_add_u32 m0, s94, 0x3000
	s_nop 1
	global_load_lds_dwordx4 v[84:85], off
	v_lshl_add_u64 v[86:87], v[86:87], 0, s[96:97]
	s_add_u32 m0, s94, 0x7000
	s_nop 1
	global_load_lds_dwordx4 v[86:87], off
	v_mfma_f32_32x32x16_bf16 v[0:15], v[122:125], v[118:121], v[0:15]
	ds_read_b128 v[98:101], v170 offset:32768
	ds_read_b128 v[102:105], v174 offset:49152
	ds_read_b128 v[106:109], v171 offset:32768
	ds_read_b128 v[110:113], v175 offset:49152
	ds_read_b128 v[114:117], v174 offset:53248
	ds_read_b128 v[118:121], v175 offset:53248
	s_waitcnt lgkmcnt(4)
	v_mfma_f32_32x32x16_bf16 v[48:63], v[98:101], v[102:105], v[48:63]
	s_waitcnt lgkmcnt(1)
	v_mfma_f32_32x32x16_bf16 v[32:47], v[98:101], v[114:117], v[32:47]
	ds_read_b128 v[98:101], v170 offset:36864
	ds_read_b128 v[122:125], v171 offset:36864
	s_waitcnt lgkmcnt(1)
	v_mfma_f32_32x32x16_bf16 v[16:31], v[98:101], v[102:105], v[16:31]
	v_mfma_f32_32x32x16_bf16 v[0:15], v[98:101], v[114:117], v[0:15]
	v_mfma_f32_32x32x16_bf16 v[48:63], v[106:109], v[110:113], v[48:63]
	v_mfma_f32_32x32x16_bf16 v[32:47], v[106:109], v[118:121], v[32:47]
	s_waitcnt lgkmcnt(0)
	v_mfma_f32_32x32x16_bf16 v[16:31], v[122:125], v[110:113], v[16:31]
	ds_read_b128 v[98:101], v172 offset:32768
	ds_read_b128 v[102:105], v176 offset:49152
	ds_read_b128 v[106:109], v173 offset:32768
	ds_read_b128 v[110:113], v177 offset:49152
	v_mfma_f32_32x32x16_bf16 v[0:15], v[122:125], v[118:121], v[0:15]
	ds_read_b128 v[114:117], v176 offset:53248
	ds_read_b128 v[118:121], v177 offset:53248
	s_waitcnt lgkmcnt(4)
	v_mfma_f32_32x32x16_bf16 v[48:63], v[98:101], v[102:105], v[48:63]
	s_waitcnt lgkmcnt(1)
	v_mfma_f32_32x32x16_bf16 v[32:47], v[98:101], v[114:117], v[32:47]
	ds_read_b128 v[98:101], v172 offset:36864
	ds_read_b128 v[122:125], v173 offset:36864
	s_waitcnt lgkmcnt(1)
	v_mfma_f32_32x32x16_bf16 v[16:31], v[98:101], v[102:105], v[16:31]
	v_mfma_f32_32x32x16_bf16 v[0:15], v[98:101], v[114:117], v[0:15]
	v_mfma_f32_32x32x16_bf16 v[48:63], v[106:109], v[110:113], v[48:63]
	v_mfma_f32_32x32x16_bf16 v[32:47], v[106:109], v[118:121], v[32:47]
	s_waitcnt lgkmcnt(0)
	v_mfma_f32_32x32x16_bf16 v[16:31], v[122:125], v[110:113], v[16:31]
	s_waitcnt vmcnt(0)
	s_barrier
	v_lshl_add_u64 v[72:73], v[72:73], 0, s[96:97]
	s_add_u32 m0, s94, 0x8000
	s_nop 1
	global_load_lds_dwordx4 v[72:73], off
	v_lshl_add_u64 v[74:75], v[74:75], 0, s[96:97]
	s_add_u32 m0, s94, 0xc000
	s_nop 1
	global_load_lds_dwordx4 v[74:75], off
	v_lshl_add_u64 v[76:77], v[76:77], 0, s[96:97]
	s_add_u32 m0, s94, 0x9000
	s_nop 1
	global_load_lds_dwordx4 v[76:77], off
	v_lshl_add_u64 v[78:79], v[78:79], 0, s[96:97]
	s_add_u32 m0, s94, 0xd000
	s_nop 1
	global_load_lds_dwordx4 v[78:79], off
	v_lshl_add_u64 v[80:81], v[80:81], 0, s[96:97]
	s_add_u32 m0, s94, 0xa000
	s_nop 1
	global_load_lds_dwordx4 v[80:81], off
	v_lshl_add_u64 v[82:83], v[82:83], 0, s[96:97]
	s_add_u32 m0, s94, 0xe000
	s_nop 1
	global_load_lds_dwordx4 v[82:83], off
	v_lshl_add_u64 v[84:85], v[84:85], 0, s[96:97]
	s_add_u32 m0, s94, 0xb000
	s_nop 1
	global_load_lds_dwordx4 v[84:85], off
	v_lshl_add_u64 v[86:87], v[86:87], 0, s[96:97]
	s_add_u32 m0, s94, 0xf000
	s_nop 1
	global_load_lds_dwordx4 v[86:87], off
	v_mfma_f32_32x32x16_bf16 v[0:15], v[122:125], v[118:121], v[0:15]
	ds_read_b128 v[98:101], v170 offset:0
	ds_read_b128 v[102:105], v174 offset:16384
	ds_read_b128 v[106:109], v171 offset:0
	ds_read_b128 v[110:113], v175 offset:16384
	ds_read_b128 v[114:117], v174 offset:20480
	ds_read_b128 v[118:121], v175 offset:20480
	s_waitcnt lgkmcnt(4)
	v_mfma_f32_32x32x16_bf16 v[48:63], v[98:101], v[102:105], v[48:63]
	s_waitcnt lgkmcnt(1)
	v_mfma_f32_32x32x16_bf16 v[32:47], v[98:101], v[114:117], v[32:47]
	ds_read_b128 v[98:101], v170 offset:4096
	ds_read_b128 v[122:125], v171 offset:4096
	s_waitcnt lgkmcnt(1)
	v_mfma_f32_32x32x16_bf16 v[16:31], v[98:101], v[102:105], v[16:31]
	v_mfma_f32_32x32x16_bf16 v[0:15], v[98:101], v[114:117], v[0:15]
	v_mfma_f32_32x32x16_bf16 v[48:63], v[106:109], v[110:113], v[48:63]
	v_mfma_f32_32x32x16_bf16 v[32:47], v[106:109], v[118:121], v[32:47]
	s_waitcnt lgkmcnt(0)
	v_mfma_f32_32x32x16_bf16 v[16:31], v[122:125], v[110:113], v[16:31]
	ds_read_b128 v[98:101], v172 offset:0
	ds_read_b128 v[102:105], v176 offset:16384
	ds_read_b128 v[106:109], v173 offset:0
	ds_read_b128 v[110:113], v177 offset:16384
	v_mfma_f32_32x32x16_bf16 v[0:15], v[122:125], v[118:121], v[0:15]
	ds_read_b128 v[114:117], v176 offset:20480
	ds_read_b128 v[118:121], v177 offset:20480
	s_waitcnt lgkmcnt(4)
	v_mfma_f32_32x32x16_bf16 v[48:63], v[98:101], v[102:105], v[48:63]
	s_waitcnt lgkmcnt(1)
	v_mfma_f32_32x32x16_bf16 v[32:47], v[98:101], v[114:117], v[32:47]
	ds_read_b128 v[98:101], v172 offset:4096
	ds_read_b128 v[122:125], v173 offset:4096
	s_waitcnt lgkmcnt(1)
	v_mfma_f32_32x32x16_bf16 v[16:31], v[98:101], v[102:105], v[16:31]
	v_mfma_f32_32x32x16_bf16 v[0:15], v[98:101], v[114:117], v[0:15]
	v_mfma_f32_32x32x16_bf16 v[48:63], v[106:109], v[110:113], v[48:63]
	v_mfma_f32_32x32x16_bf16 v[32:47], v[106:109], v[118:121], v[32:47]
	s_waitcnt lgkmcnt(0)
	v_mfma_f32_32x32x16_bf16 v[16:31], v[122:125], v[110:113], v[16:31]
	s_waitcnt vmcnt(0)
	s_barrier
;     ...
;   bf16* As1 = As + 2 * 128 * 72;
;   bf16* Bs1 = As1 + 128 * 72;
;   G_LOAD(ra0, rb0, 0);
;   if (nk > 1) G_LOAD(ra1, rb1, 1);
;   G_STORE(ra0, rb0, As, Bs);
;   __syncthreads();
;   for (int kt = 0; kt < nk; kt += 2) {
;     if (kt + 2 < nk) G_LOAD(ra0, rb0, kt + 2);
;     if (kt + 1 < nk) G_STORE(ra1, rb1, As1, Bs1);
;     G_COMPUTE(As, Bs);
;     __syncthreads();
;     if (kt + 1 < nk) {
;       if (kt + 3 < nk) G_LOAD(ra1, rb1, kt + 3);
;       if (kt + 2 < nk) G_STORE(ra0, rb0, As, Bs);
;       G_COMPUTE(As1, Bs1);
;       __syncthreads();
	v_lshl_add_u64 v[72:73], v[72:73], 0, s[96:97]
	s_add_u32 m0, s94, 0x0
	s_nop 1
	global_load_lds_dwordx4 v[72:73], off
	v_lshl_add_u64 v[74:75], v[74:75], 0, s[96:97]
	s_add_u32 m0, s94, 0x4000
	s_nop 1
	global_load_lds_dwordx4 v[74:75], off
	v_lshl_add_u64 v[76:77], v[76:77], 0, s[96:97]
	s_add_u32 m0, s94, 0x1000
	s_nop 1
	global_load_lds_dwordx4 v[76:77], off
	v_lshl_add_u64 v[78:79], v[78:79], 0, s[96:97]
	s_add_u32 m0, s94, 0x5000
	s_nop 1
	global_load_lds_dwordx4 v[78:79], off
	v_lshl_add_u64 v[80:81], v[80:81], 0, s[96:97]
	s_add_u32 m0, s94, 0x2000
	s_nop 1
	global_load_lds_dwordx4 v[80:81], off
	v_lshl_add_u64 v[82:83], v[82:83], 0, s[96:97]
	s_add_u32 m0, s94, 0x6000
	s_nop 1
	global_load_lds_dwordx4 v[82:83], off
	v_lshl_add_u64 v[84:85], v[84:85], 0, s[96:97]
	s_add_u32 m0, s94, 0x3000
	s_nop 1
	global_load_lds_dwordx4 v[84:85], off
	v_lshl_add_u64 v[86:87], v[86:87], 0, s[96:97]
	s_add_u32 m0, s94, 0x7000
	s_nop 1
	global_load_lds_dwordx4 v[86:87], off
	v_mfma_f32_32x32x16_bf16 v[0:15], v[122:125], v[118:121], v[0:15]
	ds_read_b128 v[98:101], v170 offset:32768
	ds_read_b128 v[102:105], v174 offset:49152
	ds_read_b128 v[106:109], v171 offset:32768
	ds_read_b128 v[110:113], v175 offset:49152
	ds_read_b128 v[114:117], v174 offset:53248
	ds_read_b128 v[118:121], v175 offset:53248
	s_waitcnt lgkmcnt(4)
	v_mfma_f32_32x32x16_bf16 v[48:63], v[98:101], v[102:105], v[48:63]
	s_waitcnt lgkmcnt(1)
	v_mfma_f32_32x32x16_bf16 v[32:47], v[98:101], v[114:117], v[32:47]
	ds_read_b128 v[98:101], v170 offset:36864
	ds_read_b128 v[122:125], v171 offset:36864
	s_waitcnt lgkmcnt(1)
	v_mfma_f32_32x32x16_bf16 v[16:31], v[98:101], v[102:105], v[16:31]
	v_mfma_f32_32x32x16_bf16 v[0:15], v[98:101], v[114:117], v[0:15]
	v_mfma_f32_32x32x16_bf16 v[48:63], v[106:109], v[110:113], v[48:63]
	v_mfma_f32_32x32x16_bf16 v[32:47], v[106:109], v[118:121], v[32:47]
	s_waitcnt lgkmcnt(0)
	v_mfma_f32_32x32x16_bf16 v[16:31], v[122:125], v[110:113], v[16:31]
	ds_read_b128 v[98:101], v172 offset:32768
	ds_read_b128 v[102:105], v176 offset:49152
	ds_read_b128 v[106:109], v173 offset:32768
	ds_read_b128 v[110:113], v177 offset:49152
	v_mfma_f32_32x32x16_bf16 v[0:15], v[122:125], v[118:121], v[0:15]
	ds_read_b128 v[114:117], v176 offset:53248
	ds_read_b128 v[118:121], v177 offset:53248
	s_waitcnt lgkmcnt(4)
	v_mfma_f32_32x32x16_bf16 v[48:63], v[98:101], v[102:105], v[48:63]
	s_waitcnt lgkmcnt(1)
	v_mfma_f32_32x32x16_bf16 v[32:47], v[98:101], v[114:117], v[32:47]
	ds_read_b128 v[98:101], v172 offset:36864
	ds_read_b128 v[122:125], v173 offset:36864
	s_waitcnt lgkmcnt(1)
	v_mfma_f32_32x32x16_bf16 v[16:31], v[98:101], v[102:105], v[16:31]
	v_mfma_f32_32x32x16_bf16 v[0:15], v[98:101], v[114:117], v[0:15]
	v_mfma_f32_32x32x16_bf16 v[48:63], v[106:109], v[110:113], v[48:63]
	v_mfma_f32_32x32x16_bf16 v[32:47], v[106:109], v[118:121], v[32:47]
	s_waitcnt lgkmcnt(0)
	v_mfma_f32_32x32x16_bf16 v[16:31], v[122:125], v[110:113], v[16:31]
	s_waitcnt vmcnt(0)
	s_barrier
	v_lshl_add_u64 v[72:73], v[72:73], 0, s[96:97]
	s_add_u32 m0, s94, 0x8000
	s_nop 1
	global_load_lds_dwordx4 v[72:73], off
	v_lshl_add_u64 v[74:75], v[74:75], 0, s[96:97]
	s_add_u32 m0, s94, 0xc000
	s_nop 1
	global_load_lds_dwordx4 v[74:75], off
	v_lshl_add_u64 v[76:77], v[76:77], 0, s[96:97]
	s_add_u32 m0, s94, 0x9000
	s_nop 1
	global_load_lds_dwordx4 v[76:77], off
	v_lshl_add_u64 v[78:79], v[78:79], 0, s[96:97]
	s_add_u32 m0, s94, 0xd000
	s_nop 1
	global_load_lds_dwordx4 v[78:79], off
	v_lshl_add_u64 v[80:81], v[80:81], 0, s[96:97]
	s_add_u32 m0, s94, 0xa000
	s_nop 1
	global_load_lds_dwordx4 v[80:81], off
	v_lshl_add_u64 v[82:83], v[82:83], 0, s[96:97]
	s_add_u32 m0, s94, 0xe000
	s_nop 1
	global_load_lds_dwordx4 v[82:83], off
	v_lshl_add_u64 v[84:85], v[84:85], 0, s[96:97]
	s_add_u32 m0, s94, 0xb000
	s_nop 1
	global_load_lds_dwordx4 v[84:85], off
	v_lshl_add_u64 v[86:87], v[86:87], 0, s[96:97]
	s_add_u32 m0, s94, 0xf000
	s_nop 1
	global_load_lds_dwordx4 v[86:87], off
	v_mfma_f32_32x32x16_bf16 v[0:15], v[122:125], v[118:121], v[0:15]
	ds_read_b128 v[98:101], v170 offset:0
	ds_read_b128 v[102:105], v174 offset:16384
	ds_read_b128 v[106:109], v171 offset:0
	ds_read_b128 v[110:113], v175 offset:16384
	ds_read_b128 v[114:117], v174 offset:20480
	ds_read_b128 v[118:121], v175 offset:20480
	s_waitcnt lgkmcnt(4)
	v_mfma_f32_32x32x16_bf16 v[48:63], v[98:101], v[102:105], v[48:63]
	s_waitcnt lgkmcnt(1)
	v_mfma_f32_32x32x16_bf16 v[32:47], v[98:101], v[114:117], v[32:47]
	ds_read_b128 v[98:101], v170 offset:4096
	ds_read_b128 v[122:125], v171 offset:4096
	s_waitcnt lgkmcnt(1)
	v_mfma_f32_32x32x16_bf16 v[16:31], v[98:101], v[102:105], v[16:31]
	v_mfma_f32_32x32x16_bf16 v[0:15], v[98:101], v[114:117], v[0:15]
	v_mfma_f32_32x32x16_bf16 v[48:63], v[106:109], v[110:113], v[48:63]
	v_mfma_f32_32x32x16_bf16 v[32:47], v[106:109], v[118:121], v[32:47]
	s_waitcnt lgkmcnt(0)
	v_mfma_f32_32x32x16_bf16 v[16:31], v[122:125], v[110:113], v[16:31]
	ds_read_b128 v[98:101], v172 offset:0
	ds_read_b128 v[102:105], v176 offset:16384
	ds_read_b128 v[106:109], v173 offset:0
	ds_read_b128 v[110:113], v177 offset:16384
	v_mfma_f32_32x32x16_bf16 v[0:15], v[122:125], v[118:121], v[0:15]
	ds_read_b128 v[114:117], v176 offset:20480
	ds_read_b128 v[118:121], v177 offset:20480
	s_waitcnt lgkmcnt(4)
	v_mfma_f32_32x32x16_bf16 v[48:63], v[98:101], v[102:105], v[48:63]
	s_waitcnt lgkmcnt(1)
	v_mfma_f32_32x32x16_bf16 v[32:47], v[98:101], v[114:117], v[32:47]
	ds_read_b128 v[98:101], v172 offset:4096
	ds_read_b128 v[122:125], v173 offset:4096
	s_waitcnt lgkmcnt(1)
	v_mfma_f32_32x32x16_bf16 v[16:31], v[98:101], v[102:105], v[16:31]
	v_mfma_f32_32x32x16_bf16 v[0:15], v[98:101], v[114:117], v[0:15]
	v_mfma_f32_32x32x16_bf16 v[48:63], v[106:109], v[110:113], v[48:63]
	v_mfma_f32_32x32x16_bf16 v[32:47], v[106:109], v[118:121], v[32:47]
	s_waitcnt lgkmcnt(0)
	v_mfma_f32_32x32x16_bf16 v[16:31], v[122:125], v[110:113], v[16:31]
	s_waitcnt vmcnt(0)
	s_barrier
;     ...
;   bf16* As1 = As + 2 * 128 * 72;
;   bf16* Bs1 = As1 + 128 * 72;
;   G_LOAD(ra0, rb0, 0);
;   if (nk > 1) G_LOAD(ra1, rb1, 1);
;   G_STORE(ra0, rb0, As, Bs);
;   __syncthreads();
;   for (int kt = 0; kt < nk; kt += 2) {
;     if (kt + 2 < nk) G_LOAD(ra0, rb0, kt + 2);
;     if (kt + 1 < nk) G_STORE(ra1, rb1, As1, Bs1);
;     G_COMPUTE(As, Bs);
;     __syncthreads();
;     if (kt + 1 < nk) {
;       if (kt + 3 < nk) G_LOAD(ra1, rb1, kt + 3);
;       if (kt + 2 < nk) G_STORE(ra0, rb0, As, Bs);
;       G_COMPUTE(As1, Bs1);
;       __syncthreads();
	v_lshl_add_u64 v[72:73], v[72:73], 0, s[96:97]
	s_add_u32 m0, s94, 0x0
	s_nop 1
	global_load_lds_dwordx4 v[72:73], off
	v_lshl_add_u64 v[74:75], v[74:75], 0, s[96:97]
	s_add_u32 m0, s94, 0x4000
	s_nop 1
	global_load_lds_dwordx4 v[74:75], off
	v_lshl_add_u64 v[76:77], v[76:77], 0, s[96:97]
	s_add_u32 m0, s94, 0x1000
	s_nop 1
	global_load_lds_dwordx4 v[76:77], off
	v_lshl_add_u64 v[78:79], v[78:79], 0, s[96:97]
	s_add_u32 m0, s94, 0x5000
	s_nop 1
	global_load_lds_dwordx4 v[78:79], off
	v_lshl_add_u64 v[80:81], v[80:81], 0, s[96:97]
	s_add_u32 m0, s94, 0x2000
	s_nop 1
	global_load_lds_dwordx4 v[80:81], off
	v_lshl_add_u64 v[82:83], v[82:83], 0, s[96:97]
	s_add_u32 m0, s94, 0x6000
	s_nop 1
	global_load_lds_dwordx4 v[82:83], off
	v_lshl_add_u64 v[84:85], v[84:85], 0, s[96:97]
	s_add_u32 m0, s94, 0x3000
	s_nop 1
	global_load_lds_dwordx4 v[84:85], off
	v_lshl_add_u64 v[86:87], v[86:87], 0, s[96:97]
	s_add_u32 m0, s94, 0x7000
	s_nop 1
	global_load_lds_dwordx4 v[86:87], off
	v_mfma_f32_32x32x16_bf16 v[0:15], v[122:125], v[118:121], v[0:15]
	ds_read_b128 v[98:101], v170 offset:32768
	ds_read_b128 v[102:105], v174 offset:49152
	ds_read_b128 v[106:109], v171 offset:32768
	ds_read_b128 v[110:113], v175 offset:49152
	ds_read_b128 v[114:117], v174 offset:53248
	ds_read_b128 v[118:121], v175 offset:53248
	s_waitcnt lgkmcnt(4)
	v_mfma_f32_32x32x16_bf16 v[48:63], v[98:101], v[102:105], v[48:63]
	s_waitcnt lgkmcnt(1)
	v_mfma_f32_32x32x16_bf16 v[32:47], v[98:101], v[114:117], v[32:47]
	ds_read_b128 v[98:101], v170 offset:36864
	ds_read_b128 v[122:125], v171 offset:36864
	s_waitcnt lgkmcnt(1)
	v_mfma_f32_32x32x16_bf16 v[16:31], v[98:101], v[102:105], v[16:31]
	v_mfma_f32_32x32x16_bf16 v[0:15], v[98:101], v[114:117], v[0:15]
	v_mfma_f32_32x32x16_bf16 v[48:63], v[106:109], v[110:113], v[48:63]
	v_mfma_f32_32x32x16_bf16 v[32:47], v[106:109], v[118:121], v[32:47]
	s_waitcnt lgkmcnt(0)
	v_mfma_f32_32x32x16_bf16 v[16:31], v[122:125], v[110:113], v[16:31]
	ds_read_b128 v[98:101], v172 offset:32768
	ds_read_b128 v[102:105], v176 offset:49152
	ds_read_b128 v[106:109], v173 offset:32768
	ds_read_b128 v[110:113], v177 offset:49152
	v_mfma_f32_32x32x16_bf16 v[0:15], v[122:125], v[118:121], v[0:15]
	ds_read_b128 v[114:117], v176 offset:53248
	ds_read_b128 v[118:121], v177 offset:53248
	s_waitcnt lgkmcnt(4)
	v_mfma_f32_32x32x16_bf16 v[48:63], v[98:101], v[102:105], v[48:63]
	s_waitcnt lgkmcnt(1)
	v_mfma_f32_32x32x16_bf16 v[32:47], v[98:101], v[114:117], v[32:47]
	ds_read_b128 v[98:101], v172 offset:36864
	ds_read_b128 v[122:125], v173 offset:36864
	s_waitcnt lgkmcnt(1)
	v_mfma_f32_32x32x16_bf16 v[16:31], v[98:101], v[102:105], v[16:31]
	v_mfma_f32_32x32x16_bf16 v[0:15], v[98:101], v[114:117], v[0:15]
	v_mfma_f32_32x32x16_bf16 v[48:63], v[106:109], v[110:113], v[48:63]
	v_mfma_f32_32x32x16_bf16 v[32:47], v[106:109], v[118:121], v[32:47]
	s_waitcnt lgkmcnt(0)
	v_mfma_f32_32x32x16_bf16 v[16:31], v[122:125], v[110:113], v[16:31]
	s_waitcnt vmcnt(0)
	s_barrier
	v_lshl_add_u64 v[72:73], v[72:73], 0, s[96:97]
	s_add_u32 m0, s94, 0x8000
	s_nop 1
	global_load_lds_dwordx4 v[72:73], off
	v_lshl_add_u64 v[74:75], v[74:75], 0, s[96:97]
	s_add_u32 m0, s94, 0xc000
	s_nop 1
	global_load_lds_dwordx4 v[74:75], off
	v_lshl_add_u64 v[76:77], v[76:77], 0, s[96:97]
	s_add_u32 m0, s94, 0x9000
	s_nop 1
	global_load_lds_dwordx4 v[76:77], off
	v_lshl_add_u64 v[78:79], v[78:79], 0, s[96:97]
	s_add_u32 m0, s94, 0xd000
	s_nop 1
	global_load_lds_dwordx4 v[78:79], off
	v_lshl_add_u64 v[80:81], v[80:81], 0, s[96:97]
	s_add_u32 m0, s94, 0xa000
	s_nop 1
	global_load_lds_dwordx4 v[80:81], off
	v_lshl_add_u64 v[82:83], v[82:83], 0, s[96:97]
	s_add_u32 m0, s94, 0xe000
	s_nop 1
	global_load_lds_dwordx4 v[82:83], off
	v_lshl_add_u64 v[84:85], v[84:85], 0, s[96:97]
	s_add_u32 m0, s94, 0xb000
	s_nop 1
	global_load_lds_dwordx4 v[84:85], off
	v_lshl_add_u64 v[86:87], v[86:87], 0, s[96:97]
	s_add_u32 m0, s94, 0xf000
	s_nop 1
	global_load_lds_dwordx4 v[86:87], off
	v_mfma_f32_32x32x16_bf16 v[0:15], v[122:125], v[118:121], v[0:15]
	ds_read_b128 v[98:101], v170 offset:0
	ds_read_b128 v[102:105], v174 offset:16384
	ds_read_b128 v[106:109], v171 offset:0
	ds_read_b128 v[110:113], v175 offset:16384
	ds_read_b128 v[114:117], v174 offset:20480
	ds_read_b128 v[118:121], v175 offset:20480
	s_waitcnt lgkmcnt(4)
	v_mfma_f32_32x32x16_bf16 v[48:63], v[98:101], v[102:105], v[48:63]
	s_waitcnt lgkmcnt(1)
	v_mfma_f32_32x32x16_bf16 v[32:47], v[98:101], v[114:117], v[32:47]
	ds_read_b128 v[98:101], v170 offset:4096
	ds_read_b128 v[122:125], v171 offset:4096
	s_waitcnt lgkmcnt(1)
	v_mfma_f32_32x32x16_bf16 v[16:31], v[98:101], v[102:105], v[16:31]
	v_mfma_f32_32x32x16_bf16 v[0:15], v[98:101], v[114:117], v[0:15]
	v_mfma_f32_32x32x16_bf16 v[48:63], v[106:109], v[110:113], v[48:63]
	v_mfma_f32_32x32x16_bf16 v[32:47], v[106:109], v[118:121], v[32:47]
	s_waitcnt lgkmcnt(0)
	v_mfma_f32_32x32x16_bf16 v[16:31], v[122:125], v[110:113], v[16:31]
	ds_read_b128 v[98:101], v172 offset:0
	ds_read_b128 v[102:105], v176 offset:16384
	ds_read_b128 v[106:109], v173 offset:0
	ds_read_b128 v[110:113], v177 offset:16384
	v_mfma_f32_32x32x16_bf16 v[0:15], v[122:125], v[118:121], v[0:15]
	ds_read_b128 v[114:117], v176 offset:20480
	ds_read_b128 v[118:121], v177 offset:20480
	s_waitcnt lgkmcnt(4)
	v_mfma_f32_32x32x16_bf16 v[48:63], v[98:101], v[102:105], v[48:63]
	s_waitcnt lgkmcnt(1)
	v_mfma_f32_32x32x16_bf16 v[32:47], v[98:101], v[114:117], v[32:47]
	ds_read_b128 v[98:101], v172 offset:4096
	ds_read_b128 v[122:125], v173 offset:4096
	s_waitcnt lgkmcnt(1)
	v_mfma_f32_32x32x16_bf16 v[16:31], v[98:101], v[102:105], v[16:31]
	v_mfma_f32_32x32x16_bf16 v[0:15], v[98:101], v[114:117], v[0:15]
	v_mfma_f32_32x32x16_bf16 v[48:63], v[106:109], v[110:113], v[48:63]
	v_mfma_f32_32x32x16_bf16 v[32:47], v[106:109], v[118:121], v[32:47]
	s_waitcnt lgkmcnt(0)
	v_mfma_f32_32x32x16_bf16 v[16:31], v[122:125], v[110:113], v[16:31]
	s_waitcnt vmcnt(0)
	s_barrier
;     ...
;   bf16* As1 = As + 2 * 128 * 72;
;   bf16* Bs1 = As1 + 128 * 72;
;   G_LOAD(ra0, rb0, 0);
;   if (nk > 1) G_LOAD(ra1, rb1, 1);
;   G_STORE(ra0, rb0, As, Bs);
;   __syncthreads();
;   for (int kt = 0; kt < nk; kt += 2) {
;     if (kt + 2 < nk) G_LOAD(ra0, rb0, kt + 2);
;     if (kt + 1 < nk) G_STORE(ra1, rb1, As1, Bs1);
;     G_COMPUTE(As, Bs);
;     __syncthreads();
;     if (kt + 1 < nk) {
;       if (kt + 3 < nk) G_LOAD(ra1, rb1, kt + 3);
;       if (kt + 2 < nk) G_STORE(ra0, rb0, As, Bs);
;       G_COMPUTE(As1, Bs1);
;       __syncthreads();
	v_lshl_add_u64 v[72:73], v[72:73], 0, s[96:97]
	s_add_u32 m0, s94, 0x0
	s_nop 1
	global_load_lds_dwordx4 v[72:73], off
	v_lshl_add_u64 v[74:75], v[74:75], 0, s[96:97]
	s_add_u32 m0, s94, 0x4000
	s_nop 1
	global_load_lds_dwordx4 v[74:75], off
	v_lshl_add_u64 v[76:77], v[76:77], 0, s[96:97]
	s_add_u32 m0, s94, 0x1000
	s_nop 1
	global_load_lds_dwordx4 v[76:77], off
	v_lshl_add_u64 v[78:79], v[78:79], 0, s[96:97]
	s_add_u32 m0, s94, 0x5000
	s_nop 1
	global_load_lds_dwordx4 v[78:79], off
	v_lshl_add_u64 v[80:81], v[80:81], 0, s[96:97]
	s_add_u32 m0, s94, 0x2000
	s_nop 1
	global_load_lds_dwordx4 v[80:81], off
	v_lshl_add_u64 v[82:83], v[82:83], 0, s[96:97]
	s_add_u32 m0, s94, 0x6000
	s_nop 1
	global_load_lds_dwordx4 v[82:83], off
	v_lshl_add_u64 v[84:85], v[84:85], 0, s[96:97]
	s_add_u32 m0, s94, 0x3000
	s_nop 1
	global_load_lds_dwordx4 v[84:85], off
	v_lshl_add_u64 v[86:87], v[86:87], 0, s[96:97]
	s_add_u32 m0, s94, 0x7000
	s_nop 1
	global_load_lds_dwordx4 v[86:87], off
	v_mfma_f32_32x32x16_bf16 v[0:15], v[122:125], v[118:121], v[0:15]
	ds_read_b128 v[98:101], v170 offset:32768
	ds_read_b128 v[102:105], v174 offset:49152
	ds_read_b128 v[106:109], v171 offset:32768
	ds_read_b128 v[110:113], v175 offset:49152
	ds_read_b128 v[114:117], v174 offset:53248
	ds_read_b128 v[118:121], v175 offset:53248
	s_waitcnt lgkmcnt(4)
	v_mfma_f32_32x32x16_bf16 v[48:63], v[98:101], v[102:105], v[48:63]
	s_waitcnt lgkmcnt(1)
	v_mfma_f32_32x32x16_bf16 v[32:47], v[98:101], v[114:117], v[32:47]
	ds_read_b128 v[98:101], v170 offset:36864
	ds_read_b128 v[122:125], v171 offset:36864
	s_waitcnt lgkmcnt(1)
	v_mfma_f32_32x32x16_bf16 v[16:31], v[98:101], v[102:105], v[16:31]
	v_mfma_f32_32x32x16_bf16 v[0:15], v[98:101], v[114:117], v[0:15]
	v_mfma_f32_32x32x16_bf16 v[48:63], v[106:109], v[110:113], v[48:63]
	v_mfma_f32_32x32x16_bf16 v[32:47], v[106:109], v[118:121], v[32:47]
	s_waitcnt lgkmcnt(0)
	v_mfma_f32_32x32x16_bf16 v[16:31], v[122:125], v[110:113], v[16:31]
	ds_read_b128 v[98:101], v172 offset:32768
	ds_read_b128 v[102:105], v176 offset:49152
	ds_read_b128 v[106:109], v173 offset:32768
	ds_read_b128 v[110:113], v177 offset:49152
	v_mfma_f32_32x32x16_bf16 v[0:15], v[122:125], v[118:121], v[0:15]
	ds_read_b128 v[114:117], v176 offset:53248
	ds_read_b128 v[118:121], v177 offset:53248
	s_waitcnt lgkmcnt(4)
	v_mfma_f32_32x32x16_bf16 v[48:63], v[98:101], v[102:105], v[48:63]
	s_waitcnt lgkmcnt(1)
	v_mfma_f32_32x32x16_bf16 v[32:47], v[98:101], v[114:117], v[32:47]
	ds_read_b128 v[98:101], v172 offset:36864
	ds_read_b128 v[122:125], v173 offset:36864
	s_waitcnt lgkmcnt(1)
	v_mfma_f32_32x32x16_bf16 v[16:31], v[98:101], v[102:105], v[16:31]
	v_mfma_f32_32x32x16_bf16 v[0:15], v[98:101], v[114:117], v[0:15]
	v_mfma_f32_32x32x16_bf16 v[48:63], v[106:109], v[110:113], v[48:63]
	v_mfma_f32_32x32x16_bf16 v[32:47], v[106:109], v[118:121], v[32:47]
	s_waitcnt lgkmcnt(0)
	v_mfma_f32_32x32x16_bf16 v[16:31], v[122:125], v[110:113], v[16:31]
	s_waitcnt vmcnt(0)
	s_barrier
	v_lshl_add_u64 v[72:73], v[72:73], 0, s[96:97]
	s_add_u32 m0, s94, 0x8000
	s_nop 1
	global_load_lds_dwordx4 v[72:73], off
	v_lshl_add_u64 v[74:75], v[74:75], 0, s[96:97]
	s_add_u32 m0, s94, 0xc000
	s_nop 1
	global_load_lds_dwordx4 v[74:75], off
	v_lshl_add_u64 v[76:77], v[76:77], 0, s[96:97]
	s_add_u32 m0, s94, 0x9000
	s_nop 1
	global_load_lds_dwordx4 v[76:77], off
	v_lshl_add_u64 v[78:79], v[78:79], 0, s[96:97]
	s_add_u32 m0, s94, 0xd000
	s_nop 1
	global_load_lds_dwordx4 v[78:79], off
	v_lshl_add_u64 v[80:81], v[80:81], 0, s[96:97]
	s_add_u32 m0, s94, 0xa000
	s_nop 1
	global_load_lds_dwordx4 v[80:81], off
	v_lshl_add_u64 v[82:83], v[82:83], 0, s[96:97]
	s_add_u32 m0, s94, 0xe000
	s_nop 1
	global_load_lds_dwordx4 v[82:83], off
	v_lshl_add_u64 v[84:85], v[84:85], 0, s[96:97]
	s_add_u32 m0, s94, 0xb000
	s_nop 1
	global_load_lds_dwordx4 v[84:85], off
	v_lshl_add_u64 v[86:87], v[86:87], 0, s[96:97]
	s_add_u32 m0, s94, 0xf000
	s_nop 1
	global_load_lds_dwordx4 v[86:87], off
	v_mfma_f32_32x32x16_bf16 v[0:15], v[122:125], v[118:121], v[0:15]
	ds_read_b128 v[98:101], v170 offset:0
	ds_read_b128 v[102:105], v174 offset:16384
	ds_read_b128 v[106:109], v171 offset:0
	ds_read_b128 v[110:113], v175 offset:16384
	ds_read_b128 v[114:117], v174 offset:20480
	ds_read_b128 v[118:121], v175 offset:20480
	s_waitcnt lgkmcnt(4)
	v_mfma_f32_32x32x16_bf16 v[48:63], v[98:101], v[102:105], v[48:63]
	s_waitcnt lgkmcnt(1)
	v_mfma_f32_32x32x16_bf16 v[32:47], v[98:101], v[114:117], v[32:47]
	ds_read_b128 v[98:101], v170 offset:4096
	ds_read_b128 v[122:125], v171 offset:4096
	s_waitcnt lgkmcnt(1)
	v_mfma_f32_32x32x16_bf16 v[16:31], v[98:101], v[102:105], v[16:31]
	v_mfma_f32_32x32x16_bf16 v[0:15], v[98:101], v[114:117], v[0:15]
	v_mfma_f32_32x32x16_bf16 v[48:63], v[106:109], v[110:113], v[48:63]
	v_mfma_f32_32x32x16_bf16 v[32:47], v[106:109], v[118:121], v[32:47]
	s_waitcnt lgkmcnt(0)
	v_mfma_f32_32x32x16_bf16 v[16:31], v[122:125], v[110:113], v[16:31]
	ds_read_b128 v[98:101], v172 offset:0
	ds_read_b128 v[102:105], v176 offset:16384
	ds_read_b128 v[106:109], v173 offset:0
	ds_read_b128 v[110:113], v177 offset:16384
	v_mfma_f32_32x32x16_bf16 v[0:15], v[122:125], v[118:121], v[0:15]
	ds_read_b128 v[114:117], v176 offset:20480
	ds_read_b128 v[118:121], v177 offset:20480
	s_waitcnt lgkmcnt(4)
	v_mfma_f32_32x32x16_bf16 v[48:63], v[98:101], v[102:105], v[48:63]
	s_waitcnt lgkmcnt(1)
	v_mfma_f32_32x32x16_bf16 v[32:47], v[98:101], v[114:117], v[32:47]
	ds_read_b128 v[98:101], v172 offset:4096
	ds_read_b128 v[122:125], v173 offset:4096
	s_waitcnt lgkmcnt(1)
	v_mfma_f32_32x32x16_bf16 v[16:31], v[98:101], v[102:105], v[16:31]
	v_mfma_f32_32x32x16_bf16 v[0:15], v[98:101], v[114:117], v[0:15]
	v_mfma_f32_32x32x16_bf16 v[48:63], v[106:109], v[110:113], v[48:63]
	v_mfma_f32_32x32x16_bf16 v[32:47], v[106:109], v[118:121], v[32:47]
	s_waitcnt lgkmcnt(0)
	v_mfma_f32_32x32x16_bf16 v[16:31], v[122:125], v[110:113], v[16:31]
	s_waitcnt vmcnt(0)
	s_barrier
;     ...
;   bf16* As1 = As + 2 * 128 * 72;
;   bf16* Bs1 = As1 + 128 * 72;
;   G_LOAD(ra0, rb0, 0);
;   if (nk > 1) G_LOAD(ra1, rb1, 1);
;   G_STORE(ra0, rb0, As, Bs);
;   __syncthreads();
;   for (int kt = 0; kt < nk; kt += 2) {
;     if (kt + 2 < nk) G_LOAD(ra0, rb0, kt + 2);
;     if (kt + 1 < nk) G_STORE(ra1, rb1, As1, Bs1);
;     G_COMPUTE(As, Bs);
;     __syncthreads();
;     if (kt + 1 < nk) {
;       if (kt + 3 < nk) G_LOAD(ra1, rb1, kt + 3);
;       if (kt + 2 < nk) G_STORE(ra0, rb0, As, Bs);
;       G_COMPUTE(As1, Bs1);
;       __syncthreads();
	v_lshl_add_u64 v[72:73], v[72:73], 0, s[96:97]
	s_add_u32 m0, s94, 0x0
	s_nop 1
	global_load_lds_dwordx4 v[72:73], off
	v_lshl_add_u64 v[74:75], v[74:75], 0, s[96:97]
	s_add_u32 m0, s94, 0x4000
	s_nop 1
	global_load_lds_dwordx4 v[74:75], off
	v_lshl_add_u64 v[76:77], v[76:77], 0, s[96:97]
	s_add_u32 m0, s94, 0x1000
	s_nop 1
	global_load_lds_dwordx4 v[76:77], off
	v_lshl_add_u64 v[78:79], v[78:79], 0, s[96:97]
	s_add_u32 m0, s94, 0x5000
	s_nop 1
	global_load_lds_dwordx4 v[78:79], off
	v_lshl_add_u64 v[80:81], v[80:81], 0, s[96:97]
	s_add_u32 m0, s94, 0x2000
	s_nop 1
	global_load_lds_dwordx4 v[80:81], off
	v_lshl_add_u64 v[82:83], v[82:83], 0, s[96:97]
	s_add_u32 m0, s94, 0x6000
	s_nop 1
	global_load_lds_dwordx4 v[82:83], off
	v_lshl_add_u64 v[84:85], v[84:85], 0, s[96:97]
	s_add_u32 m0, s94, 0x3000
	s_nop 1
	global_load_lds_dwordx4 v[84:85], off
	v_lshl_add_u64 v[86:87], v[86:87], 0, s[96:97]
	s_add_u32 m0, s94, 0x7000
	s_nop 1
	global_load_lds_dwordx4 v[86:87], off
	v_mfma_f32_32x32x16_bf16 v[0:15], v[122:125], v[118:121], v[0:15]
	ds_read_b128 v[98:101], v170 offset:32768
	ds_read_b128 v[102:105], v174 offset:49152
	ds_read_b128 v[106:109], v171 offset:32768
	ds_read_b128 v[110:113], v175 offset:49152
	ds_read_b128 v[114:117], v174 offset:53248
	ds_read_b128 v[118:121], v175 offset:53248
	s_waitcnt lgkmcnt(4)
	v_mfma_f32_32x32x16_bf16 v[48:63], v[98:101], v[102:105], v[48:63]
	s_waitcnt lgkmcnt(1)
	v_mfma_f32_32x32x16_bf16 v[32:47], v[98:101], v[114:117], v[32:47]
	ds_read_b128 v[98:101], v170 offset:36864
	ds_read_b128 v[122:125], v171 offset:36864
	s_waitcnt lgkmcnt(1)
	v_mfma_f32_32x32x16_bf16 v[16:31], v[98:101], v[102:105], v[16:31]
	v_mfma_f32_32x32x16_bf16 v[0:15], v[98:101], v[114:117], v[0:15]
	v_mfma_f32_32x32x16_bf16 v[48:63], v[106:109], v[110:113], v[48:63]
	v_mfma_f32_32x32x16_bf16 v[32:47], v[106:109], v[118:121], v[32:47]
	s_waitcnt lgkmcnt(0)
	v_mfma_f32_32x32x16_bf16 v[16:31], v[122:125], v[110:113], v[16:31]
	ds_read_b128 v[98:101], v172 offset:32768
	ds_read_b128 v[102:105], v176 offset:49152
	ds_read_b128 v[106:109], v173 offset:32768
	ds_read_b128 v[110:113], v177 offset:49152
	v_mfma_f32_32x32x16_bf16 v[0:15], v[122:125], v[118:121], v[0:15]
	ds_read_b128 v[114:117], v176 offset:53248
	ds_read_b128 v[118:121], v177 offset:53248
	s_waitcnt lgkmcnt(4)
	v_mfma_f32_32x32x16_bf16 v[48:63], v[98:101], v[102:105], v[48:63]
	s_waitcnt lgkmcnt(1)
	v_mfma_f32_32x32x16_bf16 v[32:47], v[98:101], v[114:117], v[32:47]
	ds_read_b128 v[98:101], v172 offset:36864
	ds_read_b128 v[122:125], v173 offset:36864
	s_waitcnt lgkmcnt(1)
	v_mfma_f32_32x32x16_bf16 v[16:31], v[98:101], v[102:105], v[16:31]
	v_mfma_f32_32x32x16_bf16 v[0:15], v[98:101], v[114:117], v[0:15]
	v_mfma_f32_32x32x16_bf16 v[48:63], v[106:109], v[110:113], v[48:63]
	v_mfma_f32_32x32x16_bf16 v[32:47], v[106:109], v[118:121], v[32:47]
	s_nop 0
	s_nop 0
	s_nop 0
	s_nop 0
	s_nop 0
	s_nop 0
	s_nop 0
	s_waitcnt lgkmcnt(0)
	s_waitcnt vmcnt(0)
	s_barrier
	v_lshl_add_u64 v[72:73], v[72:73], 0, s[96:97]
	s_add_u32 m0, s94, 0x8000
	s_nop 1
	global_load_lds_dwordx4 v[72:73], off
	v_lshl_add_u64 v[74:75], v[74:75], 0, s[96:97]
	s_add_u32 m0, s94, 0xc000
	s_nop 1
	global_load_lds_dwordx4 v[74:75], off
	v_lshl_add_u64 v[76:77], v[76:77], 0, s[96:97]
	s_add_u32 m0, s94, 0x9000
	s_nop 1
	global_load_lds_dwordx4 v[76:77], off
	v_lshl_add_u64 v[78:79], v[78:79], 0, s[96:97]
	s_add_u32 m0, s94, 0xd000
	s_nop 1
	global_load_lds_dwordx4 v[78:79], off
	v_lshl_add_u64 v[80:81], v[80:81], 0, s[96:97]
	s_add_u32 m0, s94, 0xa000
	s_nop 1
	global_load_lds_dwordx4 v[80:81], off
	v_lshl_add_u64 v[82:83], v[82:83], 0, s[96:97]
	s_add_u32 m0, s94, 0xe000
	s_nop 1
	global_load_lds_dwordx4 v[82:83], off
	v_lshl_add_u64 v[84:85], v[84:85], 0, s[96:97]
	s_add_u32 m0, s94, 0xb000
	s_nop 1
	global_load_lds_dwordx4 v[84:85], off
	v_lshl_add_u64 v[86:87], v[86:87], 0, s[96:97]
	s_add_u32 m0, s94, 0xf000
	s_nop 1
	global_load_lds_dwordx4 v[86:87], off
	v_mfma_f32_32x32x16_bf16 v[16:31], v[122:125], v[110:113], v[16:31]
	ds_read_b128 v[72:75], v170 offset:0
	ds_read_b128 v[76:79], v174 offset:16384
	ds_read_b128 v[80:83], v171 offset:0
	ds_read_b128 v[84:87], v175 offset:16384
	ds_read_b128 v[98:101], v174 offset:20480
	ds_read_b128 v[102:105], v175 offset:20480
	v_mfma_f32_32x32x16_bf16 v[0:15], v[122:125], v[118:121], v[0:15]
	s_waitcnt lgkmcnt(4)
	v_mfma_f32_32x32x16_bf16 v[48:63], v[72:75], v[76:79], v[48:63]
	s_waitcnt lgkmcnt(1)
	v_mfma_f32_32x32x16_bf16 v[32:47], v[72:75], v[98:101], v[32:47]
	ds_read_b128 v[72:75], v170 offset:4096
	ds_read_b128 v[106:109], v171 offset:4096
	s_waitcnt lgkmcnt(1)
	v_mfma_f32_32x32x16_bf16 v[16:31], v[72:75], v[76:79], v[16:31]
	v_mfma_f32_32x32x16_bf16 v[0:15], v[72:75], v[98:101], v[0:15]
	v_mfma_f32_32x32x16_bf16 v[48:63], v[80:83], v[84:87], v[48:63]
	v_mfma_f32_32x32x16_bf16 v[32:47], v[80:83], v[102:105], v[32:47]
	s_waitcnt lgkmcnt(0)
	v_mfma_f32_32x32x16_bf16 v[16:31], v[106:109], v[84:87], v[16:31]
	ds_read_b128 v[72:75], v172 offset:0
	ds_read_b128 v[76:79], v176 offset:16384
	ds_read_b128 v[80:83], v173 offset:0
	ds_read_b128 v[84:87], v177 offset:16384
	v_mfma_f32_32x32x16_bf16 v[0:15], v[106:109], v[102:105], v[0:15]
	ds_read_b128 v[98:101], v176 offset:20480
	ds_read_b128 v[102:105], v177 offset:20480
	s_waitcnt lgkmcnt(4)
	v_mfma_f32_32x32x16_bf16 v[48:63], v[72:75], v[76:79], v[48:63]
	s_waitcnt lgkmcnt(1)
	v_mfma_f32_32x32x16_bf16 v[32:47], v[72:75], v[98:101], v[32:47]
	ds_read_b128 v[72:75], v172 offset:4096
	ds_read_b128 v[106:109], v173 offset:4096
	s_waitcnt lgkmcnt(0)
	s_waitcnt vmcnt(0)
	s_barrier
; #define PW(T, off) ((T*)(lndp(p.ws) + (off)))
; #define POUT (lndf(p.out))
; DEVI int accrow(int r, int lane) { return (r & 3) + 8 * (r >> 2) + 4 * (lane >> 5); }
; DEVI void gemm_epi_gu(const Params& p, const GJob& jb, f32x16 (&acc)[2][2], int m0, int cbase, int wm, int wn, int lane, char* smem) {
;     ...
;   float* Gs = (float*)smem;
;   const int col = wn * 32 + (lane & 31);
; #pragma unroll
;   for (int i = 0; i < 2; ++i)
; #pragma unroll
;     for (int r = 0; r < 16; ++r) Gs[(wm * 64 + i * 32 + accrow(r, lane)) * 64 + col] = acc[i][0][r];
;   __syncthreads();
;   const int c = (cbase >> 6) * 32 + (lane & 31);
;   const float w0 = i_ffn_conv_w[(size_t)layer * 3 * 2816 + c], w1 = i_ffn_conv_w[(size_t)layer * 3 * 2816 + 2816 + c];
;   const float w2 = i_ffn_conv_w[(size_t)layer * 3 * 2816 + 2 * 2816 + c], cb = i_ffn_conv_b[(size_t)layer * 2816 + c];
;   bf16* Hb = (bf16*)(PW(char, W_arena) + F_HB);
;   float* outp = POUT;
;   if (m0 >= 0 && m0 + 128 <= TP - 2) {
;     ...
;     G_COMPUTE(As, Bs);
;     __syncthreads();
;     if (kt + 1 < nk) {
;       if (kt + 3 < nk) G_LOAD(ra1, rb1, kt + 3);
;       if (kt + 2 < nk) G_STORE(ra0, rb0, As, Bs);
;       G_COMPUTE(As1, Bs1);
;       __syncthreads();
	v_mfma_f32_32x32x16_bf16 v[16:31], v[72:75], v[76:79], v[16:31]
	v_mfma_f32_32x32x16_bf16 v[0:15], v[72:75], v[98:101], v[0:15]
	v_mfma_f32_32x32x16_bf16 v[48:63], v[80:83], v[84:87], v[48:63]
	v_mfma_f32_32x32x16_bf16 v[32:47], v[80:83], v[102:105], v[32:47]
	ds_read_b128 v[72:75], v170 offset:32768
	ds_read_b128 v[76:79], v174 offset:49152
	ds_read_b128 v[80:83], v175 offset:49152
	ds_read_b128 v[98:101], v171 offset:32768
	v_mfma_f32_32x32x16_bf16 v[16:31], v[106:109], v[84:87], v[16:31]
	ds_read_b128 v[84:87], v174 offset:53248
	v_mfma_f32_32x32x16_bf16 v[0:15], v[106:109], v[102:105], v[0:15]
	s_waitcnt lgkmcnt(3)
	v_mfma_f32_32x32x16_bf16 v[48:63], v[72:75], v[76:79], v[48:63]
	s_waitcnt lgkmcnt(0)
	v_mfma_f32_32x32x16_bf16 v[32:47], v[72:75], v[84:87], v[32:47]
	ds_read_b128 v[72:75], v170 offset:36864
	ds_read_b128 v[102:105], v175 offset:53248
	s_waitcnt lgkmcnt(1)
	v_mfma_f32_32x32x16_bf16 v[16:31], v[72:75], v[76:79], v[16:31]
	ds_read_b128 v[76:79], v171 offset:36864
	ds_read_b128 v[106:109], v177 offset:53248
	ds_read_b128 v[110:113], v176 offset:53248
	ds_read_b128 v[114:117], v177 offset:49152
	ds_read_b128 v[118:121], v176 offset:49152
	ds_read_b128 v[122:125], v173 offset:36864
	ds_read_b128 v[126:129], v172 offset:36864
	ds_read_b128 v[130:133], v173 offset:32768
	ds_read_b128 v[134:137], v172 offset:32768
	s_waitcnt lgkmcnt(0)
	s_barrier
	s_ashr_i32 s5, s4, 31
	v_mfma_f32_32x32x16_bf16 v[48:63], v[98:101], v[80:83], v[48:63]
	s_lshl_b64 s[4:5], s[4:5], 3
	s_add_u32 s4, s0, s4
	s_addc_u32 s5, s1, s5
	s_load_dwordx2 s[18:19], s[4:5], 0x0
	s_mov_b32 s4, 42
	s_waitcnt lgkmcnt(0)
	v_mfma_f32_32x32x16_bf16 v[16:31], v[76:79], v[80:83], v[16:31]
	s_ashr_i32 s5, s4, 31
	s_lshl_b64 s[4:5], s[4:5], 3
	s_add_u32 s4, s0, s4
	s_addc_u32 s5, s1, s5
	s_load_dwordx2 s[4:5], s[4:5], 0x0
	s_waitcnt lgkmcnt(0)
	v_mfma_f32_32x32x16_bf16 v[48:63], v[134:137], v[118:121], v[48:63]
	s_ashr_i32 s7, s6, 31
	v_or_b32_e32 v70, s2, v71
	v_lshrrev_b32_e32 v71, 3, v93
	s_lshl_b64 s[6:7], s[6:7], 3
	v_and_b32_e32 v82, 4, v71
	s_add_u32 s6, s0, s6
	v_ashrrev_i32_e32 v70, 1, v70
	v_mfma_f32_32x32x16_bf16 v[16:31], v[126:129], v[118:121], v[16:31]
	s_addc_u32 s7, s1, s7
	s_load_dwordx2 s[6:7], s[6:7], 0x0
	s_waitcnt lgkmcnt(0)
	s_movk_i32 s2, 0x2000
	v_bfe_u32 v83, v93, 3, 3
	v_mfma_f32_32x32x16_bf16 v[48:63], v[130:133], v[114:117], v[48:63]
	v_mfma_f32_32x32x16_bf16 v[16:31], v[122:125], v[114:117], v[16:31]
	v_mfma_f32_32x32x16_bf16 v[0:15], v[72:75], v[84:87], v[0:15]
	v_or_b32_e32 v85, v92, v82
	v_lshl_or_b32 v84, v95, 5, v94
	v_lshlrev_b32_e32 v86, 8, v85
	v_or_b32_e32 v72, v70, v94
	v_lshl_or_b32 v71, v84, 2, v86
	v_ashrrev_i32_e32 v73, 31, v72
	s_nop 3
	ds_write2st64_b32 v71, v48, v49 offset1:1
	ds_write2st64_b32 v71, v50, v51 offset0:2 offset1:3
	ds_write2st64_b32 v71, v52, v53 offset0:8 offset1:9
	ds_write2st64_b32 v71, v54, v55 offset0:10 offset1:11
	ds_write2st64_b32 v71, v56, v57 offset0:16 offset1:17
	ds_write2st64_b32 v71, v58, v59 offset0:18 offset1:19
	ds_write2st64_b32 v71, v60, v61 offset0:24 offset1:25
	ds_write2st64_b32 v71, v62, v63 offset0:26 offset1:27
	ds_write2st64_b32 v71, v16, v17 offset0:32 offset1:33
	ds_write2st64_b32 v71, v18, v19 offset0:34 offset1:35
	ds_write2st64_b32 v71, v20, v21 offset0:40 offset1:41
	ds_write2st64_b32 v71, v22, v23 offset0:42 offset1:43
	ds_write2st64_b32 v71, v24, v25 offset0:48 offset1:49
	ds_write2st64_b32 v71, v26, v27 offset0:50 offset1:51
	ds_write2st64_b32 v71, v28, v29 offset0:56 offset1:57
	ds_write2st64_b32 v71, v30, v31 offset0:58 offset1:59
	v_lshl_add_u64 v[70:71], s[4:5], 0, v[66:67]
	v_lshlrev_b64 v[74:75], 2, v[72:73]
	v_lshl_add_u64 v[70:71], v[70:71], 0, v[74:75]
	v_mfma_f32_32x32x16_bf16 v[0:15], v[76:79], v[102:105], v[0:15]
	v_add_co_u32_e32 v76, vcc, s2, v70
	s_movk_i32 s2, 0x5000
	s_nop 0
	v_addc_co_u32_e32 v77, vcc, 0, v71, vcc
	v_add_co_u32_e32 v78, vcc, s2, v70
	s_waitcnt lgkmcnt(0)
	s_barrier
	v_addc_co_u32_e32 v79, vcc, 0, v71, vcc
	global_load_dword v80, v[70:71], off
	s_nop 0
	global_load_dword v71, v[76:77], off offset:3072
	global_load_dword v70, v[78:79], off offset:2048
	v_lshl_add_u64 v[76:77], s[6:7], 0, v[68:69]
	v_lshl_add_u64 v[74:75], v[76:77], 0, v[74:75]
	global_load_dword v81, v[74:75], off
	v_mfma_f32_32x32x16_bf16 v[32:47], v[98:101], v[102:105], v[32:47]
	s_mov_b64 s[2:3], s[74:75]
	s_add_u32 s14, s2, 0x1d19c000
	s_addc_u32 s15, s3, 0
	s_cmpk_lt_u32 s30, 0x3f8f
	v_cmp_lt_i32_e64 s[6:7], 1, v85
	s_mov_b64 s[2:3], -1
	v_mfma_f32_32x32x16_bf16 v[32:47], v[134:137], v[110:113], v[32:47]
	v_mfma_f32_32x32x16_bf16 v[0:15], v[126:129], v[110:113], v[0:15]
	v_mfma_f32_32x32x16_bf16 v[32:47], v[130:133], v[106:109], v[32:47]
	v_mfma_f32_32x32x16_bf16 v[0:15], v[122:125], v[106:109], v[0:15]
	s_cbranch_scc1 .LBB0_3975
	v_add_u32_e32 v87, s30, v85
	v_cmp_gt_i32_e32 vcc, s90, v87
	v_lshl_add_u64 v[76:77], v[72:73], 2, s[18:19]
	v_lshl_add_u64 v[74:75], v[72:73], 1, s[14:15]
	s_and_b64 s[4:5], s[6:7], vcc
	s_and_saveexec_b64 s[2:3], s[4:5]
	s_cbranch_execz .LBB0_3509
	v_and_b32_e32 v89, 14, v87
	v_cmp_gt_i32_e64 s[8:9], s92, v87
	s_movk_i32 s4, 0x400f
	v_add_u32_e32 v78, 0xffffbff0, v87
	v_cndmask_b32_e64 v93, v89, v87, s[8:9]
	v_cmp_lt_i32_e64 s[10:11], s4, v87
	v_lshrrev_b32_e32 v88, 4, v78
	v_cmp_gt_i32_e32 vcc, 1, v93
	s_and_saveexec_b64 s[4:5], vcc
	s_xor_b64 s[4:5], exec, s[4:5]
	s_cbranch_execz .LBB0_3499
	v_mov_b32_e32 v79, 0
	s_and_saveexec_b64 s[20:21], s[10:11]
	s_cbranch_execz .LBB0_3498
	v_add_u32_e32 v94, v88, v90
	v_mov_b64_e32 v[78:79], s[18:19]
	s_movk_i32 s31, 0x5800
	v_mad_u64_u32 v[78:79], s[34:35], v94, s31, v[78:79]
	v_lshl_add_u64 v[78:79], v[72:73], 2, v[78:79]
	v_add_co_u32_e32 v78, vcc, 0x2000, v78
	s_nop 1
	v_addc_co_u32_e32 v79, vcc, 0, v79, vcc
	global_load_dword v79, v[78:79], off offset:3072

;     ...
;   const int lrow = tid >> 3, lkc = (tid & 7) * 8;
;   const bf16* Ag = jb.A + (size_t)max(m0 + lrow, 0) * jb.lda + lkc;
;   const bf16* Ag1 = jb.A + (ptrdiff_t)(m0 + lrow) * jb.lda + lkc;
;   const bf16* Bg = jb.Bt + (size_t)(n0 + lrow) * jb.K + lkc;
;   const size_t astep = (size_t)32 * jb.lda, bstep = (size_t)32 * jb.K;
;   if (kt1 < 0) kt1 = jb.K >> 6;
;   const int nk = kt1 - kt0;
;   Ag += (size_t)kt0 * 64; Ag1 += (size_t)kt0 * 64; Bg += (size_t)kt0 * 64;
;   u32x4 ra0[4], rb0[4], ra1[4], rb1[4];
;     ...
;   bf16* As1 = As + 2 * 128 * 72;
;   bf16* Bs1 = As1 + 128 * 72;
;   G_LOAD(ra0, rb0, 0);
;   if (nk > 1) G_LOAD(ra1, rb1, 1);
;   G_STORE(ra0, rb0, As, Bs);
;   __syncthreads();
.LBB0_4695:
	s_cmpk_gt_i32 s11, 0x1912
	s_cbranch_scc1 .LBB0_4827
	s_mul_hi_i32 s2, s11, 0x5397829d
	s_lshr_b32 s3, s2, 31
	s_ashr_i32 s2, s2, 8
	s_add_i32 s2, s2, s3
	s_lshl_b32 s3, s2, 4
	s_sub_i32 s4, 0x83, s3
	s_min_u32 s4, s4, 16
	v_cvt_f32_ubyte0_e32 v0, s4
	v_rcp_iflag_f32_e32 v0, v0
	s_sub_i32 s7, 0, s4
	s_mulk_i32 s2, 0xfcf0
	s_add_i32 s2, s11, s2
	v_mul_f32_e32 v0, 0x4f7ffffe, v0
	v_cvt_u32_f32_e32 v0, v0
	s_abs_i32 s6, s2
	s_ashr_i32 s5, s2, 31
	v_mov_b32_e32 v86, v208
	v_readfirstlane_b32 s12, v0
	s_mul_i32 s7, s7, s12
	s_mul_hi_u32 s7, s12, s7
	s_add_i32 s12, s12, s7
	s_mul_hi_u32 s7, s6, s12
	s_mul_i32 s12, s7, s4
	s_sub_i32 s6, s6, s12
	s_add_i32 s12, s7, 1
	s_sub_i32 s13, s6, s4
	s_cmp_ge_u32 s6, s4
	s_cselect_b32 s7, s12, s7
	s_cselect_b32 s6, s13, s6
	s_add_i32 s12, s7, 1
	s_cmp_ge_u32 s6, s4
	s_cselect_b32 s6, s12, s7
	s_xor_b32 s6, s6, s5
	s_sub_i32 s5, s6, s5
	s_mul_i32 s4, s5, s4
	s_sub_i32 s2, s2, s4
	s_add_i32 s3, s3, s2
	s_lshl_b32 s2, s3, 7
	s_lshl_b32 s3, s5, 7
	v_ashrrev_i32_e32 v84, 3, v86
	v_add_u32_e32 v0, s2, v84
	v_max_i32_e32 v96, 0, v0
	v_lshlrev_b32_e32 v1, 4, v86
	v_lshlrev_b64 v[2:3], 11, v[96:97]
	v_and_b32_e32 v96, 0x70, v1
	s_mov_b64 s[96:97], 0x80
	v_lshrrev_b32_e32 v178, 4, v208
	v_and_b32_e32 v178, 7, v178
	v_lshlrev_b32_e32 v178, 4, v178
	v_xor_b32_e32 v96, v96, v178
	v_lshrrev_b32_e32 v179, 6, v208
	v_lshlrev_b32_e32 v179, 10, v179
	v_lshrrev_b32_e32 v180, 5, v208
	v_lshrrev_b32_e32 v181, 1, v208
	v_xor_b32_e32 v180, v180, v181
	v_readfirstlane_b32 s94, v179
	v_and_b32_e32 v180, 1, v180
	v_lshlrev_b32_e32 v180, 4, v180
	v_and_b32_e32 v181, 31, v208
	v_lshlrev_b32_e32 v181, 7, v181
	v_or_b32_e32 v180, v180, v181
	v_lshrrev_b32_e32 v181, 7, v208
	v_lshlrev_b32_e32 v181, 13, v181
	v_or_b32_e32 v194, v180, v181
	v_bfe_u32 v181, v208, 6, 1
	v_lshlrev_b32_e32 v181, 13, v181
	v_or_b32_e32 v195, v180, v181
	v_bfe_u32 v178, v208, 2, 2
	v_xor_b32_e32 v179, 0, v178
	v_lshlrev_b32_e32 v179, 5, v179
	v_or_b32_e32 v170, v194, v179
	v_or_b32_e32 v174, v195, v179
	v_xor_b32_e32 v179, 1, v178
	v_lshlrev_b32_e32 v179, 5, v179
	v_or_b32_e32 v171, v194, v179
	v_or_b32_e32 v175, v195, v179
	v_xor_b32_e32 v179, 2, v178
	v_lshlrev_b32_e32 v179, 5, v179
	v_or_b32_e32 v172, v194, v179
	v_or_b32_e32 v176, v195, v179
	v_xor_b32_e32 v179, 3, v178
	v_lshlrev_b32_e32 v179, 5, v179
	v_or_b32_e32 v173, v194, v179
	v_or_b32_e32 v177, v195, v179
	v_ashrrev_i32_e32 v1, 31, v0
	v_lshlrev_b64 v[0:1], 11, v[0:1]
	v_lshl_add_u64 v[0:1], s[8:9], 0, v[0:1]
	v_lshl_add_u64 v[28:29], v[0:1], 0, v[96:97]
	v_add_u32_e32 v0, s3, v84
	v_ashrrev_i32_e32 v1, 31, v0
	v_lshlrev_b64 v[0:1], 11, v[0:1]
	v_lshl_add_u64 v[0:1], v[64:65], 0, v[0:1]
	v_add_co_u32_e32 v72, vcc, s63, v28
	v_lshl_add_u64 v[70:71], v[0:1], 0, v[96:97]
	s_nop 0
	v_addc_co_u32_e32 v73, vcc, 0, v29, vcc
	v_add_co_u32_e32 v74, vcc, s63, v70
	v_lshl_add_u64 v[2:3], s[8:9], 0, v[2:3]
	s_nop 0
	v_addc_co_u32_e32 v75, vcc, 0, v71, vcc
	v_add_co_u32_e32 v76, vcc, s64, v28
	v_lshl_add_u64 v[68:69], v[2:3], 0, v[96:97]
	s_nop 0
	v_addc_co_u32_e32 v77, vcc, 0, v29, vcc
	v_add_co_u32_e32 v78, vcc, s64, v70
	v_addc_co_u32_e32 v79, vcc, 0, v71, vcc
	v_add_co_u32_e32 v80, vcc, s65, v70
	s_nop 0
	v_addc_co_u32_e32 v81, vcc, 0, v71, vcc
	v_add_co_u32_e32 v82, vcc, s65, v28
	s_nop 0
	v_addc_co_u32_e32 v83, vcc, 0, v29, vcc
	v_ashrrev_i32_e32 v66, 1, v86
	v_and_b32_e32 v87, 31, v86
	v_lshrrev_b32_e32 v67, 1, v86
	v_and_b32_e32 v88, 0xffffffc0, v66
	v_and_b32_e32 v90, 16, v67
	v_or_b32_e32 v66, v88, v87
	v_mad_u64_u32 v[84:85], s[4:5], v84, s91, v[96:97]
	v_mad_u64_u32 v[66:67], s[4:5], v66, s91, v[90:91]
	v_add_u32_e32 v85, 0xd800, v84
	s_mov_b64 s[4:5], s[74:75]
	s_add_u32 m0, s94, 0x4000
	s_nop 1
	global_load_lds_dwordx4 v[70:71], off
	s_add_u32 m0, s94, 0x0
	s_nop 1
	global_load_lds_dwordx4 v[68:69], off
	s_add_u32 m0, s94, 0x5000
	s_nop 1
	global_load_lds_dwordx4 v[74:75], off
	s_add_u32 m0, s94, 0x6000
	s_nop 1
	global_load_lds_dwordx4 v[78:79], off
	s_add_u32 m0, s94, 0x7000
	s_nop 1
	global_load_lds_dwordx4 v[80:81], off
	s_add_u32 m0, s94, 0x1000
	s_nop 1
	global_load_lds_dwordx4 v[72:73], off
	s_add_u32 m0, s94, 0x2000
	s_nop 1
	global_load_lds_dwordx4 v[76:77], off
	s_add_u32 m0, s94, 0x3000
	s_nop 1
	global_load_lds_dwordx4 v[82:83], off
	s_waitcnt lgkmcnt(0)
	s_waitcnt vmcnt(0)
	s_barrier
;     ...
;   bf16* As1 = As + 2 * 128 * 72;
;   bf16* Bs1 = As1 + 128 * 72;
;   G_LOAD(ra0, rb0, 0);
;   if (nk > 1) G_LOAD(ra1, rb1, 1);
;   G_STORE(ra0, rb0, As, Bs);
;   __syncthreads();
;   for (int kt = 0; kt < nk; kt += 2) {
;     if (kt + 2 < nk) G_LOAD(ra0, rb0, kt + 2);
;     if (kt + 1 < nk) G_STORE(ra1, rb1, As1, Bs1);
;     G_COMPUTE(As, Bs);
;     __syncthreads();
;     if (kt + 1 < nk) {
;       if (kt + 3 < nk) G_LOAD(ra1, rb1, kt + 3);
;       if (kt + 2 < nk) G_STORE(ra0, rb0, As, Bs);
;       G_COMPUTE(As1, Bs1);
;       __syncthreads();
	v_lshl_add_u64 v[68:69], v[68:69], 0, s[96:97]
	s_add_u32 m0, s94, 0x8000
	s_nop 1
	global_load_lds_dwordx4 v[68:69], off
	v_lshl_add_u64 v[70:71], v[70:71], 0, s[96:97]
	s_add_u32 m0, s94, 0xc000
	s_nop 1
	global_load_lds_dwordx4 v[70:71], off
	v_lshl_add_u64 v[72:73], v[72:73], 0, s[96:97]
	s_add_u32 m0, s94, 0x9000
	s_nop 1
	global_load_lds_dwordx4 v[72:73], off
	v_lshl_add_u64 v[74:75], v[74:75], 0, s[96:97]
	s_add_u32 m0, s94, 0xd000
	s_nop 1
	global_load_lds_dwordx4 v[74:75], off
	v_lshl_add_u64 v[76:77], v[76:77], 0, s[96:97]
	s_add_u32 m0, s94, 0xa000
	s_nop 1
	global_load_lds_dwordx4 v[76:77], off
	v_lshl_add_u64 v[78:79], v[78:79], 0, s[96:97]
	s_add_u32 m0, s94, 0xe000
	s_nop 1
	global_load_lds_dwordx4 v[78:79], off
	v_lshl_add_u64 v[82:83], v[82:83], 0, s[96:97]
	s_add_u32 m0, s94, 0xb000
	s_nop 1
	global_load_lds_dwordx4 v[82:83], off
	v_lshl_add_u64 v[80:81], v[80:81], 0, s[96:97]
	s_add_u32 m0, s94, 0xf000
	s_nop 1
	global_load_lds_dwordx4 v[80:81], off
	ds_read_b128 v[0:3], v170 offset:0
	v_and_b32_e32 v4, 0x5f, v86
	v_mad_u32_u24 v67, v4, s91, v90
	ds_read_b128 v[4:7], v174 offset:16384
	ds_read_b128 v[90:93], v171 offset:0
	ds_read_b128 v[98:101], v175 offset:16384
	ds_read_b128 v[32:35], v174 offset:20480
	ds_read_b128 v[102:105], v175 offset:20480
	s_waitcnt lgkmcnt(4)
	v_mfma_f32_32x32x16_bf16 v[16:31], v[0:3], v[4:7], 0
	ds_read_b128 v[36:39], v170 offset:4096
	ds_read_b128 v[106:109], v171 offset:4096
	s_waitcnt lgkmcnt(3)
	v_mfma_f32_32x32x16_bf16 v[48:63], v[0:3], v[32:35], 0
	s_waitcnt lgkmcnt(1)
	v_mfma_f32_32x32x16_bf16 v[0:15], v[36:39], v[4:7], 0
	v_mfma_f32_32x32x16_bf16 v[32:47], v[36:39], v[32:35], 0
	v_mfma_f32_32x32x16_bf16 v[16:31], v[90:93], v[98:101], v[16:31]
	v_mfma_f32_32x32x16_bf16 v[48:63], v[90:93], v[102:105], v[48:63]
	s_waitcnt lgkmcnt(0)
	v_mfma_f32_32x32x16_bf16 v[0:15], v[106:109], v[98:101], v[0:15]
	v_mfma_f32_32x32x16_bf16 v[32:47], v[106:109], v[102:105], v[32:47]
	ds_read_b128 v[90:93], v172 offset:0
	ds_read_b128 v[98:101], v176 offset:16384
	ds_read_b128 v[102:105], v173 offset:0
	ds_read_b128 v[106:109], v177 offset:16384
	ds_read_b128 v[110:113], v176 offset:20480
	ds_read_b128 v[114:117], v177 offset:20480
	s_waitcnt lgkmcnt(4)
	v_mfma_f32_32x32x16_bf16 v[16:31], v[90:93], v[98:101], v[16:31]
	s_waitcnt lgkmcnt(1)
	v_mfma_f32_32x32x16_bf16 v[48:63], v[90:93], v[110:113], v[48:63]
	ds_read_b128 v[90:93], v172 offset:4096
	ds_read_b128 v[118:121], v173 offset:4096
	s_waitcnt lgkmcnt(1)
	v_mfma_f32_32x32x16_bf16 v[0:15], v[90:93], v[98:101], v[0:15]
	v_mfma_f32_32x32x16_bf16 v[32:47], v[90:93], v[110:113], v[32:47]
	v_mfma_f32_32x32x16_bf16 v[16:31], v[102:105], v[106:109], v[16:31]
	v_mfma_f32_32x32x16_bf16 v[48:63], v[102:105], v[114:117], v[48:63]
	s_waitcnt lgkmcnt(0)
	v_mfma_f32_32x32x16_bf16 v[0:15], v[118:121], v[106:109], v[0:15]
	s_waitcnt vmcnt(0)
	s_barrier
	v_lshl_add_u64 v[68:69], v[68:69], 0, s[96:97]
	s_add_u32 m0, s94, 0x0
	s_nop 1
	global_load_lds_dwordx4 v[68:69], off
	v_lshl_add_u64 v[70:71], v[70:71], 0, s[96:97]
	s_add_u32 m0, s94, 0x4000
	s_nop 1
	global_load_lds_dwordx4 v[70:71], off
	v_lshl_add_u64 v[72:73], v[72:73], 0, s[96:97]
	s_add_u32 m0, s94, 0x1000
	s_nop 1
	global_load_lds_dwordx4 v[72:73], off
	v_lshl_add_u64 v[74:75], v[74:75], 0, s[96:97]
	s_add_u32 m0, s94, 0x5000
	s_nop 1
	global_load_lds_dwordx4 v[74:75], off
	v_lshl_add_u64 v[76:77], v[76:77], 0, s[96:97]
	s_add_u32 m0, s94, 0x2000
	s_nop 1
	global_load_lds_dwordx4 v[76:77], off
	v_lshl_add_u64 v[78:79], v[78:79], 0, s[96:97]
	s_add_u32 m0, s94, 0x6000
	s_nop 1
	global_load_lds_dwordx4 v[78:79], off
	v_lshl_add_u64 v[82:83], v[82:83], 0, s[96:97]
	s_add_u32 m0, s94, 0x3000
	s_nop 1
	global_load_lds_dwordx4 v[82:83], off
	v_lshl_add_u64 v[80:81], v[80:81], 0, s[96:97]
	s_add_u32 m0, s94, 0x7000
	s_nop 1
	global_load_lds_dwordx4 v[80:81], off
	v_mfma_f32_32x32x16_bf16 v[32:47], v[118:121], v[114:117], v[32:47]
	ds_read_b128 v[90:93], v170 offset:32768
	ds_read_b128 v[98:101], v174 offset:49152
	ds_read_b128 v[102:105], v171 offset:32768
	ds_read_b128 v[106:109], v175 offset:49152
	ds_read_b128 v[110:113], v174 offset:53248
	ds_read_b128 v[114:117], v175 offset:53248
	s_waitcnt lgkmcnt(4)
	v_mfma_f32_32x32x16_bf16 v[16:31], v[90:93], v[98:101], v[16:31]
	s_waitcnt lgkmcnt(1)
	v_mfma_f32_32x32x16_bf16 v[48:63], v[90:93], v[110:113], v[48:63]
	ds_read_b128 v[90:93], v170 offset:36864
	ds_read_b128 v[118:121], v171 offset:36864
	s_waitcnt lgkmcnt(1)
	v_mfma_f32_32x32x16_bf16 v[0:15], v[90:93], v[98:101], v[0:15]
	v_mfma_f32_32x32x16_bf16 v[32:47], v[90:93], v[110:113], v[32:47]
	v_mfma_f32_32x32x16_bf16 v[16:31], v[102:105], v[106:109], v[16:31]
	v_mfma_f32_32x32x16_bf16 v[48:63], v[102:105], v[114:117], v[48:63]
	s_waitcnt lgkmcnt(0)
	v_mfma_f32_32x32x16_bf16 v[0:15], v[118:121], v[106:109], v[0:15]
	ds_read_b128 v[90:93], v172 offset:32768
	ds_read_b128 v[98:101], v176 offset:49152
	ds_read_b128 v[102:105], v173 offset:32768
	ds_read_b128 v[106:109], v177 offset:49152
	v_mfma_f32_32x32x16_bf16 v[32:47], v[118:121], v[114:117], v[32:47]
	ds_read_b128 v[110:113], v176 offset:53248
	ds_read_b128 v[114:117], v177 offset:53248
	s_waitcnt lgkmcnt(4)
	v_mfma_f32_32x32x16_bf16 v[16:31], v[90:93], v[98:101], v[16:31]
	s_waitcnt lgkmcnt(1)
	v_mfma_f32_32x32x16_bf16 v[48:63], v[90:93], v[110:113], v[48:63]
	ds_read_b128 v[90:93], v172 offset:36864
	ds_read_b128 v[118:121], v173 offset:36864
	s_waitcnt lgkmcnt(1)
	v_mfma_f32_32x32x16_bf16 v[0:15], v[90:93], v[98:101], v[0:15]
	v_mfma_f32_32x32x16_bf16 v[32:47], v[90:93], v[110:113], v[32:47]
	v_mfma_f32_32x32x16_bf16 v[16:31], v[102:105], v[106:109], v[16:31]
	v_mfma_f32_32x32x16_bf16 v[48:63], v[102:105], v[114:117], v[48:63]
	s_waitcnt lgkmcnt(0)
	v_mfma_f32_32x32x16_bf16 v[0:15], v[118:121], v[106:109], v[0:15]
	s_waitcnt vmcnt(0)
	s_barrier
;     ...
;   bf16* As1 = As + 2 * 128 * 72;
;   bf16* Bs1 = As1 + 128 * 72;
;   G_LOAD(ra0, rb0, 0);
;   if (nk > 1) G_LOAD(ra1, rb1, 1);
;   G_STORE(ra0, rb0, As, Bs);
;   __syncthreads();
;   for (int kt = 0; kt < nk; kt += 2) {
;     if (kt + 2 < nk) G_LOAD(ra0, rb0, kt + 2);
;     if (kt + 1 < nk) G_STORE(ra1, rb1, As1, Bs1);
;     G_COMPUTE(As, Bs);
;     __syncthreads();
;     if (kt + 1 < nk) {
;       if (kt + 3 < nk) G_LOAD(ra1, rb1, kt + 3);
;       if (kt + 2 < nk) G_STORE(ra0, rb0, As, Bs);
;       G_COMPUTE(As1, Bs1);
;       __syncthreads();
	v_lshl_add_u64 v[68:69], v[68:69], 0, s[96:97]
	s_add_u32 m0, s94, 0x8000
	s_nop 1
	global_load_lds_dwordx4 v[68:69], off
	v_lshl_add_u64 v[70:71], v[70:71], 0, s[96:97]
	s_add_u32 m0, s94, 0xc000
	s_nop 1
	global_load_lds_dwordx4 v[70:71], off
	v_lshl_add_u64 v[72:73], v[72:73], 0, s[96:97]
	s_add_u32 m0, s94, 0x9000
	s_nop 1
	global_load_lds_dwordx4 v[72:73], off
	v_lshl_add_u64 v[74:75], v[74:75], 0, s[96:97]
	s_add_u32 m0, s94, 0xd000
	s_nop 1
	global_load_lds_dwordx4 v[74:75], off
	v_lshl_add_u64 v[76:77], v[76:77], 0, s[96:97]
	s_add_u32 m0, s94, 0xa000
	s_nop 1
	global_load_lds_dwordx4 v[76:77], off
	v_lshl_add_u64 v[78:79], v[78:79], 0, s[96:97]
	s_add_u32 m0, s94, 0xe000
	s_nop 1
	global_load_lds_dwordx4 v[78:79], off
	v_lshl_add_u64 v[82:83], v[82:83], 0, s[96:97]
	s_add_u32 m0, s94, 0xb000
	s_nop 1
	global_load_lds_dwordx4 v[82:83], off
	v_lshl_add_u64 v[80:81], v[80:81], 0, s[96:97]
	s_add_u32 m0, s94, 0xf000
	s_nop 1
	global_load_lds_dwordx4 v[80:81], off
	v_mfma_f32_32x32x16_bf16 v[32:47], v[118:121], v[114:117], v[32:47]
	ds_read_b128 v[90:93], v170 offset:0
	ds_read_b128 v[98:101], v174 offset:16384
	ds_read_b128 v[102:105], v171 offset:0
	ds_read_b128 v[106:109], v175 offset:16384
	ds_read_b128 v[110:113], v174 offset:20480
	ds_read_b128 v[114:117], v175 offset:20480
	s_waitcnt lgkmcnt(4)
	v_mfma_f32_32x32x16_bf16 v[16:31], v[90:93], v[98:101], v[16:31]
	s_waitcnt lgkmcnt(1)
	v_mfma_f32_32x32x16_bf16 v[48:63], v[90:93], v[110:113], v[48:63]
	ds_read_b128 v[90:93], v170 offset:4096
	ds_read_b128 v[118:121], v171 offset:4096
	s_waitcnt lgkmcnt(1)
	v_mfma_f32_32x32x16_bf16 v[0:15], v[90:93], v[98:101], v[0:15]
	v_mfma_f32_32x32x16_bf16 v[32:47], v[90:93], v[110:113], v[32:47]
	v_mfma_f32_32x32x16_bf16 v[16:31], v[102:105], v[106:109], v[16:31]
	v_mfma_f32_32x32x16_bf16 v[48:63], v[102:105], v[114:117], v[48:63]
	s_waitcnt lgkmcnt(0)
	v_mfma_f32_32x32x16_bf16 v[0:15], v[118:121], v[106:109], v[0:15]
	ds_read_b128 v[90:93], v172 offset:0
	ds_read_b128 v[98:101], v176 offset:16384
	ds_read_b128 v[102:105], v173 offset:0
	ds_read_b128 v[106:109], v177 offset:16384
	v_mfma_f32_32x32x16_bf16 v[32:47], v[118:121], v[114:117], v[32:47]
	ds_read_b128 v[110:113], v176 offset:20480
	ds_read_b128 v[114:117], v177 offset:20480
	s_waitcnt lgkmcnt(4)
	v_mfma_f32_32x32x16_bf16 v[16:31], v[90:93], v[98:101], v[16:31]
	s_waitcnt lgkmcnt(1)
	v_mfma_f32_32x32x16_bf16 v[48:63], v[90:93], v[110:113], v[48:63]
	ds_read_b128 v[90:93], v172 offset:4096
	ds_read_b128 v[118:121], v173 offset:4096
	s_waitcnt lgkmcnt(1)
	v_mfma_f32_32x32x16_bf16 v[0:15], v[90:93], v[98:101], v[0:15]
	v_mfma_f32_32x32x16_bf16 v[32:47], v[90:93], v[110:113], v[32:47]
	v_mfma_f32_32x32x16_bf16 v[16:31], v[102:105], v[106:109], v[16:31]
	v_mfma_f32_32x32x16_bf16 v[48:63], v[102:105], v[114:117], v[48:63]
	s_waitcnt lgkmcnt(0)
	v_mfma_f32_32x32x16_bf16 v[0:15], v[118:121], v[106:109], v[0:15]
	s_waitcnt vmcnt(0)
	s_barrier
	v_lshl_add_u64 v[68:69], v[68:69], 0, s[96:97]
	s_add_u32 m0, s94, 0x0
	s_nop 1
	global_load_lds_dwordx4 v[68:69], off
	v_lshl_add_u64 v[70:71], v[70:71], 0, s[96:97]
	s_add_u32 m0, s94, 0x4000
	s_nop 1
	global_load_lds_dwordx4 v[70:71], off
	v_lshl_add_u64 v[72:73], v[72:73], 0, s[96:97]
	s_add_u32 m0, s94, 0x1000
	s_nop 1
	global_load_lds_dwordx4 v[72:73], off
	v_lshl_add_u64 v[74:75], v[74:75], 0, s[96:97]
	s_add_u32 m0, s94, 0x5000
	s_nop 1
	global_load_lds_dwordx4 v[74:75], off
	v_lshl_add_u64 v[76:77], v[76:77], 0, s[96:97]
	s_add_u32 m0, s94, 0x2000
	s_nop 1
	global_load_lds_dwordx4 v[76:77], off
	v_lshl_add_u64 v[78:79], v[78:79], 0, s[96:97]
	s_add_u32 m0, s94, 0x6000
	s_nop 1
	global_load_lds_dwordx4 v[78:79], off
	v_lshl_add_u64 v[82:83], v[82:83], 0, s[96:97]
	s_add_u32 m0, s94, 0x3000
	s_nop 1
	global_load_lds_dwordx4 v[82:83], off
	v_lshl_add_u64 v[80:81], v[80:81], 0, s[96:97]
	s_add_u32 m0, s94, 0x7000
	s_nop 1
	global_load_lds_dwordx4 v[80:81], off
	v_mfma_f32_32x32x16_bf16 v[32:47], v[118:121], v[114:117], v[32:47]
	ds_read_b128 v[90:93], v170 offset:32768
	ds_read_b128 v[98:101], v174 offset:49152
	ds_read_b128 v[102:105], v171 offset:32768
	ds_read_b128 v[106:109], v175 offset:49152
	ds_read_b128 v[110:113], v174 offset:53248
	ds_read_b128 v[114:117], v175 offset:53248
	s_waitcnt lgkmcnt(4)
	v_mfma_f32_32x32x16_bf16 v[16:31], v[90:93], v[98:101], v[16:31]
	s_waitcnt lgkmcnt(1)
	v_mfma_f32_32x32x16_bf16 v[48:63], v[90:93], v[110:113], v[48:63]
	ds_read_b128 v[90:93], v170 offset:36864
	ds_read_b128 v[118:121], v171 offset:36864
	s_waitcnt lgkmcnt(1)
	v_mfma_f32_32x32x16_bf16 v[0:15], v[90:93], v[98:101], v[0:15]
	v_mfma_f32_32x32x16_bf16 v[32:47], v[90:93], v[110:113], v[32:47]
	v_mfma_f32_32x32x16_bf16 v[16:31], v[102:105], v[106:109], v[16:31]
	v_mfma_f32_32x32x16_bf16 v[48:63], v[102:105], v[114:117], v[48:63]
	s_waitcnt lgkmcnt(0)
	v_mfma_f32_32x32x16_bf16 v[0:15], v[118:121], v[106:109], v[0:15]
	ds_read_b128 v[90:93], v172 offset:32768
	ds_read_b128 v[98:101], v176 offset:49152
	ds_read_b128 v[102:105], v173 offset:32768
	ds_read_b128 v[106:109], v177 offset:49152
	v_mfma_f32_32x32x16_bf16 v[32:47], v[118:121], v[114:117], v[32:47]
	ds_read_b128 v[110:113], v176 offset:53248
	ds_read_b128 v[114:117], v177 offset:53248
	s_waitcnt lgkmcnt(4)
	v_mfma_f32_32x32x16_bf16 v[16:31], v[90:93], v[98:101], v[16:31]
	s_waitcnt lgkmcnt(1)
	v_mfma_f32_32x32x16_bf16 v[48:63], v[90:93], v[110:113], v[48:63]
	ds_read_b128 v[90:93], v172 offset:36864
	ds_read_b128 v[118:121], v173 offset:36864
	s_waitcnt lgkmcnt(1)
	v_mfma_f32_32x32x16_bf16 v[0:15], v[90:93], v[98:101], v[0:15]
	v_mfma_f32_32x32x16_bf16 v[32:47], v[90:93], v[110:113], v[32:47]
	v_mfma_f32_32x32x16_bf16 v[16:31], v[102:105], v[106:109], v[16:31]
	v_mfma_f32_32x32x16_bf16 v[48:63], v[102:105], v[114:117], v[48:63]
	s_waitcnt lgkmcnt(0)
	v_mfma_f32_32x32x16_bf16 v[0:15], v[118:121], v[106:109], v[0:15]
	s_waitcnt vmcnt(0)
	s_barrier
;     ...
;   bf16* As1 = As + 2 * 128 * 72;
;   bf16* Bs1 = As1 + 128 * 72;
;   G_LOAD(ra0, rb0, 0);
;   if (nk > 1) G_LOAD(ra1, rb1, 1);
;   G_STORE(ra0, rb0, As, Bs);
;   __syncthreads();
;   for (int kt = 0; kt < nk; kt += 2) {
;     if (kt + 2 < nk) G_LOAD(ra0, rb0, kt + 2);
;     if (kt + 1 < nk) G_STORE(ra1, rb1, As1, Bs1);
;     G_COMPUTE(As, Bs);
;     __syncthreads();
;     if (kt + 1 < nk) {
;       if (kt + 3 < nk) G_LOAD(ra1, rb1, kt + 3);
;       if (kt + 2 < nk) G_STORE(ra0, rb0, As, Bs);
;       G_COMPUTE(As1, Bs1);
;       __syncthreads();
	v_lshl_add_u64 v[68:69], v[68:69], 0, s[96:97]
	s_add_u32 m0, s94, 0x8000
	s_nop 1
	global_load_lds_dwordx4 v[68:69], off
	v_lshl_add_u64 v[70:71], v[70:71], 0, s[96:97]
	s_add_u32 m0, s94, 0xc000
	s_nop 1
	global_load_lds_dwordx4 v[70:71], off
	v_lshl_add_u64 v[72:73], v[72:73], 0, s[96:97]
	s_add_u32 m0, s94, 0x9000
	s_nop 1
	global_load_lds_dwordx4 v[72:73], off
	v_lshl_add_u64 v[74:75], v[74:75], 0, s[96:97]
	s_add_u32 m0, s94, 0xd000
	s_nop 1
	global_load_lds_dwordx4 v[74:75], off
	v_lshl_add_u64 v[76:77], v[76:77], 0, s[96:97]
	s_add_u32 m0, s94, 0xa000
	s_nop 1
	global_load_lds_dwordx4 v[76:77], off
	v_lshl_add_u64 v[78:79], v[78:79], 0, s[96:97]
	s_add_u32 m0, s94, 0xe000
	s_nop 1
	global_load_lds_dwordx4 v[78:79], off
	v_lshl_add_u64 v[82:83], v[82:83], 0, s[96:97]
	s_add_u32 m0, s94, 0xb000
	s_nop 1
	global_load_lds_dwordx4 v[82:83], off
	v_lshl_add_u64 v[80:81], v[80:81], 0, s[96:97]
	s_add_u32 m0, s94, 0xf000
	s_nop 1
	global_load_lds_dwordx4 v[80:81], off
	v_mfma_f32_32x32x16_bf16 v[32:47], v[118:121], v[114:117], v[32:47]
	ds_read_b128 v[90:93], v170 offset:0
	ds_read_b128 v[98:101], v174 offset:16384
	ds_read_b128 v[102:105], v171 offset:0
	ds_read_b128 v[106:109], v175 offset:16384
	ds_read_b128 v[110:113], v174 offset:20480
	ds_read_b128 v[114:117], v175 offset:20480
	s_waitcnt lgkmcnt(4)
	v_mfma_f32_32x32x16_bf16 v[16:31], v[90:93], v[98:101], v[16:31]
	s_waitcnt lgkmcnt(1)
	v_mfma_f32_32x32x16_bf16 v[48:63], v[90:93], v[110:113], v[48:63]
	ds_read_b128 v[90:93], v170 offset:4096
	ds_read_b128 v[118:121], v171 offset:4096
	s_waitcnt lgkmcnt(1)
	v_mfma_f32_32x32x16_bf16 v[0:15], v[90:93], v[98:101], v[0:15]
	v_mfma_f32_32x32x16_bf16 v[32:47], v[90:93], v[110:113], v[32:47]
	v_mfma_f32_32x32x16_bf16 v[16:31], v[102:105], v[106:109], v[16:31]
	v_mfma_f32_32x32x16_bf16 v[48:63], v[102:105], v[114:117], v[48:63]
	s_waitcnt lgkmcnt(0)
	v_mfma_f32_32x32x16_bf16 v[0:15], v[118:121], v[106:109], v[0:15]
	ds_read_b128 v[90:93], v172 offset:0
	ds_read_b128 v[98:101], v176 offset:16384
	ds_read_b128 v[102:105], v173 offset:0
	ds_read_b128 v[106:109], v177 offset:16384
	v_mfma_f32_32x32x16_bf16 v[32:47], v[118:121], v[114:117], v[32:47]
	ds_read_b128 v[110:113], v176 offset:20480
	ds_read_b128 v[114:117], v177 offset:20480
	s_waitcnt lgkmcnt(4)
	v_mfma_f32_32x32x16_bf16 v[16:31], v[90:93], v[98:101], v[16:31]
	s_waitcnt lgkmcnt(1)
	v_mfma_f32_32x32x16_bf16 v[48:63], v[90:93], v[110:113], v[48:63]
	ds_read_b128 v[90:93], v172 offset:4096
	ds_read_b128 v[118:121], v173 offset:4096
	s_waitcnt lgkmcnt(1)
	v_mfma_f32_32x32x16_bf16 v[0:15], v[90:93], v[98:101], v[0:15]
	v_mfma_f32_32x32x16_bf16 v[32:47], v[90:93], v[110:113], v[32:47]
	v_mfma_f32_32x32x16_bf16 v[16:31], v[102:105], v[106:109], v[16:31]
	v_mfma_f32_32x32x16_bf16 v[48:63], v[102:105], v[114:117], v[48:63]
	s_waitcnt lgkmcnt(0)
	v_mfma_f32_32x32x16_bf16 v[0:15], v[118:121], v[106:109], v[0:15]
	s_waitcnt vmcnt(0)
	s_barrier
	v_lshl_add_u64 v[68:69], v[68:69], 0, s[96:97]
	s_add_u32 m0, s94, 0x0
	s_nop 1
	global_load_lds_dwordx4 v[68:69], off
	v_lshl_add_u64 v[70:71], v[70:71], 0, s[96:97]
	s_add_u32 m0, s94, 0x4000
	s_nop 1
	global_load_lds_dwordx4 v[70:71], off
	v_lshl_add_u64 v[72:73], v[72:73], 0, s[96:97]
	s_add_u32 m0, s94, 0x1000
	s_nop 1
	global_load_lds_dwordx4 v[72:73], off
	v_lshl_add_u64 v[74:75], v[74:75], 0, s[96:97]
	s_add_u32 m0, s94, 0x5000
	s_nop 1
	global_load_lds_dwordx4 v[74:75], off
	v_lshl_add_u64 v[76:77], v[76:77], 0, s[96:97]
	s_add_u32 m0, s94, 0x2000
	s_nop 1
	global_load_lds_dwordx4 v[76:77], off
	v_lshl_add_u64 v[78:79], v[78:79], 0, s[96:97]
	s_add_u32 m0, s94, 0x6000
	s_nop 1
	global_load_lds_dwordx4 v[78:79], off
	v_lshl_add_u64 v[82:83], v[82:83], 0, s[96:97]
	s_add_u32 m0, s94, 0x3000
	s_nop 1
	global_load_lds_dwordx4 v[82:83], off
	v_lshl_add_u64 v[80:81], v[80:81], 0, s[96:97]
	s_add_u32 m0, s94, 0x7000
	s_nop 1
	global_load_lds_dwordx4 v[80:81], off
	v_mfma_f32_32x32x16_bf16 v[32:47], v[118:121], v[114:117], v[32:47]
	ds_read_b128 v[90:93], v170 offset:32768
	ds_read_b128 v[98:101], v174 offset:49152
	ds_read_b128 v[102:105], v171 offset:32768
	ds_read_b128 v[106:109], v175 offset:49152
	ds_read_b128 v[110:113], v174 offset:53248
	ds_read_b128 v[114:117], v175 offset:53248
	s_waitcnt lgkmcnt(4)
	v_mfma_f32_32x32x16_bf16 v[16:31], v[90:93], v[98:101], v[16:31]
	s_waitcnt lgkmcnt(1)
	v_mfma_f32_32x32x16_bf16 v[48:63], v[90:93], v[110:113], v[48:63]
	ds_read_b128 v[90:93], v170 offset:36864
	ds_read_b128 v[118:121], v171 offset:36864
	s_waitcnt lgkmcnt(1)
	v_mfma_f32_32x32x16_bf16 v[0:15], v[90:93], v[98:101], v[0:15]
	v_mfma_f32_32x32x16_bf16 v[32:47], v[90:93], v[110:113], v[32:47]
	v_mfma_f32_32x32x16_bf16 v[16:31], v[102:105], v[106:109], v[16:31]
	v_mfma_f32_32x32x16_bf16 v[48:63], v[102:105], v[114:117], v[48:63]
	s_waitcnt lgkmcnt(0)
	v_mfma_f32_32x32x16_bf16 v[0:15], v[118:121], v[106:109], v[0:15]
	ds_read_b128 v[90:93], v172 offset:32768
	ds_read_b128 v[98:101], v176 offset:49152
	ds_read_b128 v[102:105], v173 offset:32768
	ds_read_b128 v[106:109], v177 offset:49152
	v_mfma_f32_32x32x16_bf16 v[32:47], v[118:121], v[114:117], v[32:47]
	ds_read_b128 v[110:113], v176 offset:53248
	ds_read_b128 v[114:117], v177 offset:53248
	s_waitcnt lgkmcnt(4)
	v_mfma_f32_32x32x16_bf16 v[16:31], v[90:93], v[98:101], v[16:31]
	s_waitcnt lgkmcnt(1)
	v_mfma_f32_32x32x16_bf16 v[48:63], v[90:93], v[110:113], v[48:63]
	ds_read_b128 v[90:93], v172 offset:36864
	ds_read_b128 v[118:121], v173 offset:36864
	s_waitcnt lgkmcnt(1)
	v_mfma_f32_32x32x16_bf16 v[0:15], v[90:93], v[98:101], v[0:15]
	v_mfma_f32_32x32x16_bf16 v[32:47], v[90:93], v[110:113], v[32:47]
	v_mfma_f32_32x32x16_bf16 v[16:31], v[102:105], v[106:109], v[16:31]
	v_mfma_f32_32x32x16_bf16 v[48:63], v[102:105], v[114:117], v[48:63]
	s_waitcnt lgkmcnt(0)
	v_mfma_f32_32x32x16_bf16 v[0:15], v[118:121], v[106:109], v[0:15]
	s_waitcnt vmcnt(0)
	s_barrier
;     ...
;   bf16* As1 = As + 2 * 128 * 72;
;   bf16* Bs1 = As1 + 128 * 72;
;   G_LOAD(ra0, rb0, 0);
;   if (nk > 1) G_LOAD(ra1, rb1, 1);
;   G_STORE(ra0, rb0, As, Bs);
;   __syncthreads();
;   for (int kt = 0; kt < nk; kt += 2) {
;     if (kt + 2 < nk) G_LOAD(ra0, rb0, kt + 2);
;     if (kt + 1 < nk) G_STORE(ra1, rb1, As1, Bs1);
;     G_COMPUTE(As, Bs);
;     __syncthreads();
;     if (kt + 1 < nk) {
;       if (kt + 3 < nk) G_LOAD(ra1, rb1, kt + 3);
;       if (kt + 2 < nk) G_STORE(ra0, rb0, As, Bs);
;       G_COMPUTE(As1, Bs1);
;       __syncthreads();
	v_lshl_add_u64 v[68:69], v[68:69], 0, s[96:97]
	s_add_u32 m0, s94, 0x8000
	s_nop 1
	global_load_lds_dwordx4 v[68:69], off
	v_lshl_add_u64 v[70:71], v[70:71], 0, s[96:97]
	s_add_u32 m0, s94, 0xc000
	s_nop 1
	global_load_lds_dwordx4 v[70:71], off
	v_lshl_add_u64 v[72:73], v[72:73], 0, s[96:97]
	s_add_u32 m0, s94, 0x9000
	s_nop 1
	global_load_lds_dwordx4 v[72:73], off
	v_lshl_add_u64 v[74:75], v[74:75], 0, s[96:97]
	s_add_u32 m0, s94, 0xd000
	s_nop 1
	global_load_lds_dwordx4 v[74:75], off
	v_lshl_add_u64 v[76:77], v[76:77], 0, s[96:97]
	s_add_u32 m0, s94, 0xa000
	s_nop 1
	global_load_lds_dwordx4 v[76:77], off
	v_lshl_add_u64 v[78:79], v[78:79], 0, s[96:97]
	s_add_u32 m0, s94, 0xe000
	s_nop 1
	global_load_lds_dwordx4 v[78:79], off
	v_lshl_add_u64 v[82:83], v[82:83], 0, s[96:97]
	s_add_u32 m0, s94, 0xb000
	s_nop 1
	global_load_lds_dwordx4 v[82:83], off
	v_lshl_add_u64 v[80:81], v[80:81], 0, s[96:97]
	s_add_u32 m0, s94, 0xf000
	s_nop 1
	global_load_lds_dwordx4 v[80:81], off
	v_mfma_f32_32x32x16_bf16 v[32:47], v[118:121], v[114:117], v[32:47]
	ds_read_b128 v[90:93], v170 offset:0
	ds_read_b128 v[98:101], v174 offset:16384
	ds_read_b128 v[102:105], v171 offset:0
	ds_read_b128 v[106:109], v175 offset:16384
	ds_read_b128 v[110:113], v174 offset:20480
	ds_read_b128 v[114:117], v175 offset:20480
	s_waitcnt lgkmcnt(4)
	v_mfma_f32_32x32x16_bf16 v[16:31], v[90:93], v[98:101], v[16:31]
	s_waitcnt lgkmcnt(1)
	v_mfma_f32_32x32x16_bf16 v[48:63], v[90:93], v[110:113], v[48:63]
	ds_read_b128 v[90:93], v170 offset:4096
	ds_read_b128 v[118:121], v171 offset:4096
	s_waitcnt lgkmcnt(1)
	v_mfma_f32_32x32x16_bf16 v[0:15], v[90:93], v[98:101], v[0:15]
	v_mfma_f32_32x32x16_bf16 v[32:47], v[90:93], v[110:113], v[32:47]
	v_mfma_f32_32x32x16_bf16 v[16:31], v[102:105], v[106:109], v[16:31]
	v_mfma_f32_32x32x16_bf16 v[48:63], v[102:105], v[114:117], v[48:63]
	s_waitcnt lgkmcnt(0)
	v_mfma_f32_32x32x16_bf16 v[0:15], v[118:121], v[106:109], v[0:15]
	ds_read_b128 v[90:93], v172 offset:0
	ds_read_b128 v[98:101], v176 offset:16384
	ds_read_b128 v[102:105], v173 offset:0
	ds_read_b128 v[106:109], v177 offset:16384
	v_mfma_f32_32x32x16_bf16 v[32:47], v[118:121], v[114:117], v[32:47]
	ds_read_b128 v[110:113], v176 offset:20480
	ds_read_b128 v[114:117], v177 offset:20480
	s_waitcnt lgkmcnt(4)
	v_mfma_f32_32x32x16_bf16 v[16:31], v[90:93], v[98:101], v[16:31]
	s_waitcnt lgkmcnt(1)
	v_mfma_f32_32x32x16_bf16 v[48:63], v[90:93], v[110:113], v[48:63]
	ds_read_b128 v[90:93], v172 offset:4096
	ds_read_b128 v[118:121], v173 offset:4096
	s_waitcnt lgkmcnt(1)
	v_mfma_f32_32x32x16_bf16 v[0:15], v[90:93], v[98:101], v[0:15]
	v_mfma_f32_32x32x16_bf16 v[32:47], v[90:93], v[110:113], v[32:47]
	v_mfma_f32_32x32x16_bf16 v[16:31], v[102:105], v[106:109], v[16:31]
	v_mfma_f32_32x32x16_bf16 v[48:63], v[102:105], v[114:117], v[48:63]
	s_waitcnt lgkmcnt(0)
	v_mfma_f32_32x32x16_bf16 v[0:15], v[118:121], v[106:109], v[0:15]
	s_waitcnt vmcnt(0)
	s_barrier
	v_lshl_add_u64 v[68:69], v[68:69], 0, s[96:97]
	s_add_u32 m0, s94, 0x0
	s_nop 1
	global_load_lds_dwordx4 v[68:69], off
	v_lshl_add_u64 v[70:71], v[70:71], 0, s[96:97]
	s_add_u32 m0, s94, 0x4000
	s_nop 1
	global_load_lds_dwordx4 v[70:71], off
	v_lshl_add_u64 v[72:73], v[72:73], 0, s[96:97]
	s_add_u32 m0, s94, 0x1000
	s_nop 1
	global_load_lds_dwordx4 v[72:73], off
	v_lshl_add_u64 v[74:75], v[74:75], 0, s[96:97]
	s_add_u32 m0, s94, 0x5000
	s_nop 1
	global_load_lds_dwordx4 v[74:75], off
	v_lshl_add_u64 v[76:77], v[76:77], 0, s[96:97]
	s_add_u32 m0, s94, 0x2000
	s_nop 1
	global_load_lds_dwordx4 v[76:77], off
	v_lshl_add_u64 v[78:79], v[78:79], 0, s[96:97]
	s_add_u32 m0, s94, 0x6000
	s_nop 1
	global_load_lds_dwordx4 v[78:79], off
	v_lshl_add_u64 v[82:83], v[82:83], 0, s[96:97]
	s_add_u32 m0, s94, 0x3000
	s_nop 1
	global_load_lds_dwordx4 v[82:83], off
	v_lshl_add_u64 v[80:81], v[80:81], 0, s[96:97]
	s_add_u32 m0, s94, 0x7000
	s_nop 1
	global_load_lds_dwordx4 v[80:81], off
	v_mfma_f32_32x32x16_bf16 v[32:47], v[118:121], v[114:117], v[32:47]
	ds_read_b128 v[90:93], v170 offset:32768
	ds_read_b128 v[98:101], v174 offset:49152
	ds_read_b128 v[102:105], v171 offset:32768
	ds_read_b128 v[106:109], v175 offset:49152
	ds_read_b128 v[110:113], v174 offset:53248
	ds_read_b128 v[114:117], v175 offset:53248
	s_waitcnt lgkmcnt(4)
	v_mfma_f32_32x32x16_bf16 v[16:31], v[90:93], v[98:101], v[16:31]
	s_waitcnt lgkmcnt(1)
	v_mfma_f32_32x32x16_bf16 v[48:63], v[90:93], v[110:113], v[48:63]
	ds_read_b128 v[90:93], v170 offset:36864
	ds_read_b128 v[118:121], v171 offset:36864
	s_waitcnt lgkmcnt(1)
	v_mfma_f32_32x32x16_bf16 v[0:15], v[90:93], v[98:101], v[0:15]
	v_mfma_f32_32x32x16_bf16 v[32:47], v[90:93], v[110:113], v[32:47]
	v_mfma_f32_32x32x16_bf16 v[16:31], v[102:105], v[106:109], v[16:31]
	v_mfma_f32_32x32x16_bf16 v[48:63], v[102:105], v[114:117], v[48:63]
	s_waitcnt lgkmcnt(0)
	v_mfma_f32_32x32x16_bf16 v[0:15], v[118:121], v[106:109], v[0:15]
	ds_read_b128 v[90:93], v172 offset:32768
	ds_read_b128 v[98:101], v176 offset:49152
	ds_read_b128 v[102:105], v173 offset:32768
	ds_read_b128 v[106:109], v177 offset:49152
	v_mfma_f32_32x32x16_bf16 v[32:47], v[118:121], v[114:117], v[32:47]
	ds_read_b128 v[110:113], v176 offset:53248
	ds_read_b128 v[114:117], v177 offset:53248
	s_waitcnt lgkmcnt(4)
	v_mfma_f32_32x32x16_bf16 v[16:31], v[90:93], v[98:101], v[16:31]
	s_waitcnt lgkmcnt(1)
	v_mfma_f32_32x32x16_bf16 v[48:63], v[90:93], v[110:113], v[48:63]
	ds_read_b128 v[90:93], v172 offset:36864
	ds_read_b128 v[118:121], v173 offset:36864
	s_waitcnt lgkmcnt(1)
	v_mfma_f32_32x32x16_bf16 v[0:15], v[90:93], v[98:101], v[0:15]
	v_mfma_f32_32x32x16_bf16 v[32:47], v[90:93], v[110:113], v[32:47]
	v_mfma_f32_32x32x16_bf16 v[16:31], v[102:105], v[106:109], v[16:31]
	v_mfma_f32_32x32x16_bf16 v[48:63], v[102:105], v[114:117], v[48:63]
	s_waitcnt lgkmcnt(0)
	v_mfma_f32_32x32x16_bf16 v[0:15], v[118:121], v[106:109], v[0:15]
	s_waitcnt vmcnt(0)
	s_barrier
;     ...
;   bf16* As1 = As + 2 * 128 * 72;
;   bf16* Bs1 = As1 + 128 * 72;
;   G_LOAD(ra0, rb0, 0);
;   if (nk > 1) G_LOAD(ra1, rb1, 1);
;   G_STORE(ra0, rb0, As, Bs);
;   __syncthreads();
;   for (int kt = 0; kt < nk; kt += 2) {
;     if (kt + 2 < nk) G_LOAD(ra0, rb0, kt + 2);
;     if (kt + 1 < nk) G_STORE(ra1, rb1, As1, Bs1);
;     G_COMPUTE(As, Bs);
;     __syncthreads();
;     if (kt + 1 < nk) {
;       if (kt + 3 < nk) G_LOAD(ra1, rb1, kt + 3);
;       if (kt + 2 < nk) G_STORE(ra0, rb0, As, Bs);
;       G_COMPUTE(As1, Bs1);
;       __syncthreads();
;     }
;   }
	v_lshl_add_u64 v[68:69], v[68:69], 0, s[96:97]
	s_add_u32 m0, s94, 0x8000
	s_nop 1
	global_load_lds_dwordx4 v[68:69], off
	v_lshl_add_u64 v[70:71], v[70:71], 0, s[96:97]
	s_add_u32 m0, s94, 0xc000
	s_nop 1
	global_load_lds_dwordx4 v[70:71], off
	v_lshl_add_u64 v[72:73], v[72:73], 0, s[96:97]
	s_add_u32 m0, s94, 0x9000
	s_nop 1
	global_load_lds_dwordx4 v[72:73], off
	v_lshl_add_u64 v[74:75], v[74:75], 0, s[96:97]
	s_add_u32 m0, s94, 0xd000
	s_nop 1
	global_load_lds_dwordx4 v[74:75], off
	v_lshl_add_u64 v[76:77], v[76:77], 0, s[96:97]
	s_add_u32 m0, s94, 0xa000
	s_nop 1
	global_load_lds_dwordx4 v[76:77], off
	v_lshl_add_u64 v[78:79], v[78:79], 0, s[96:97]
	s_add_u32 m0, s94, 0xe000
	s_nop 1
	global_load_lds_dwordx4 v[78:79], off
	v_lshl_add_u64 v[82:83], v[82:83], 0, s[96:97]
	s_add_u32 m0, s94, 0xb000
	s_nop 1
	global_load_lds_dwordx4 v[82:83], off
	v_lshl_add_u64 v[80:81], v[80:81], 0, s[96:97]
	s_add_u32 m0, s94, 0xf000
	s_nop 1
	global_load_lds_dwordx4 v[80:81], off
	v_mfma_f32_32x32x16_bf16 v[32:47], v[118:121], v[114:117], v[32:47]
	ds_read_b128 v[90:93], v170 offset:0
	ds_read_b128 v[98:101], v174 offset:16384
	ds_read_b128 v[102:105], v171 offset:0
	ds_read_b128 v[106:109], v175 offset:16384
	ds_read_b128 v[110:113], v174 offset:20480
	ds_read_b128 v[114:117], v175 offset:20480
	s_waitcnt lgkmcnt(4)
	v_mfma_f32_32x32x16_bf16 v[16:31], v[90:93], v[98:101], v[16:31]
	s_waitcnt lgkmcnt(1)
	v_mfma_f32_32x32x16_bf16 v[48:63], v[90:93], v[110:113], v[48:63]
	ds_read_b128 v[90:93], v170 offset:4096
	ds_read_b128 v[118:121], v171 offset:4096
	s_waitcnt lgkmcnt(1)
	v_mfma_f32_32x32x16_bf16 v[0:15], v[90:93], v[98:101], v[0:15]
	v_mfma_f32_32x32x16_bf16 v[32:47], v[90:93], v[110:113], v[32:47]
	v_mfma_f32_32x32x16_bf16 v[16:31], v[102:105], v[106:109], v[16:31]
	v_mfma_f32_32x32x16_bf16 v[48:63], v[102:105], v[114:117], v[48:63]
	s_waitcnt lgkmcnt(0)
	v_mfma_f32_32x32x16_bf16 v[0:15], v[118:121], v[106:109], v[0:15]
	ds_read_b128 v[90:93], v172 offset:0
	ds_read_b128 v[98:101], v176 offset:16384
	ds_read_b128 v[102:105], v173 offset:0
	ds_read_b128 v[106:109], v177 offset:16384
	v_mfma_f32_32x32x16_bf16 v[32:47], v[118:121], v[114:117], v[32:47]
	ds_read_b128 v[110:113], v176 offset:20480
	ds_read_b128 v[114:117], v177 offset:20480
	s_waitcnt lgkmcnt(4)
	v_mfma_f32_32x32x16_bf16 v[16:31], v[90:93], v[98:101], v[16:31]
	s_waitcnt lgkmcnt(1)
	v_mfma_f32_32x32x16_bf16 v[48:63], v[90:93], v[110:113], v[48:63]
	ds_read_b128 v[90:93], v172 offset:4096
	ds_read_b128 v[118:121], v173 offset:4096
	s_waitcnt lgkmcnt(1)
	v_mfma_f32_32x32x16_bf16 v[0:15], v[90:93], v[98:101], v[0:15]
	v_mfma_f32_32x32x16_bf16 v[32:47], v[90:93], v[110:113], v[32:47]
	v_mfma_f32_32x32x16_bf16 v[16:31], v[102:105], v[106:109], v[16:31]
	v_mfma_f32_32x32x16_bf16 v[48:63], v[102:105], v[114:117], v[48:63]
	s_waitcnt lgkmcnt(0)
	v_mfma_f32_32x32x16_bf16 v[0:15], v[118:121], v[106:109], v[0:15]
	s_waitcnt vmcnt(0)
	s_barrier
	v_lshl_add_u64 v[68:69], v[68:69], 0, s[96:97]
	s_add_u32 m0, s94, 0x0
	s_nop 1
	global_load_lds_dwordx4 v[68:69], off
	v_lshl_add_u64 v[70:71], v[70:71], 0, s[96:97]
	s_add_u32 m0, s94, 0x4000
	s_nop 1
	global_load_lds_dwordx4 v[70:71], off
	v_lshl_add_u64 v[72:73], v[72:73], 0, s[96:97]
	s_add_u32 m0, s94, 0x1000
	s_nop 1
	global_load_lds_dwordx4 v[72:73], off
	v_lshl_add_u64 v[74:75], v[74:75], 0, s[96:97]
	s_add_u32 m0, s94, 0x5000
	s_nop 1
	global_load_lds_dwordx4 v[74:75], off
	v_lshl_add_u64 v[76:77], v[76:77], 0, s[96:97]
	s_add_u32 m0, s94, 0x2000
	s_nop 1
	global_load_lds_dwordx4 v[76:77], off
	v_lshl_add_u64 v[78:79], v[78:79], 0, s[96:97]
	s_add_u32 m0, s94, 0x6000
	s_nop 1
	global_load_lds_dwordx4 v[78:79], off
	v_lshl_add_u64 v[82:83], v[82:83], 0, s[96:97]
	s_add_u32 m0, s94, 0x3000
	s_nop 1
	global_load_lds_dwordx4 v[82:83], off
	v_lshl_add_u64 v[80:81], v[80:81], 0, s[96:97]
	s_add_u32 m0, s94, 0x7000
	s_nop 1
	global_load_lds_dwordx4 v[80:81], off
	v_mfma_f32_32x32x16_bf16 v[32:47], v[118:121], v[114:117], v[32:47]
	ds_read_b128 v[90:93], v170 offset:32768
	ds_read_b128 v[98:101], v174 offset:49152
	ds_read_b128 v[102:105], v171 offset:32768
	ds_read_b128 v[106:109], v175 offset:49152
	ds_read_b128 v[110:113], v174 offset:53248
	ds_read_b128 v[114:117], v175 offset:53248
	s_waitcnt lgkmcnt(4)
	v_mfma_f32_32x32x16_bf16 v[16:31], v[90:93], v[98:101], v[16:31]
	s_waitcnt lgkmcnt(1)
	v_mfma_f32_32x32x16_bf16 v[48:63], v[90:93], v[110:113], v[48:63]
	ds_read_b128 v[90:93], v170 offset:36864
	ds_read_b128 v[118:121], v171 offset:36864
	s_waitcnt lgkmcnt(1)
	v_mfma_f32_32x32x16_bf16 v[0:15], v[90:93], v[98:101], v[0:15]
	v_mfma_f32_32x32x16_bf16 v[32:47], v[90:93], v[110:113], v[32:47]
	v_mfma_f32_32x32x16_bf16 v[16:31], v[102:105], v[106:109], v[16:31]
	v_mfma_f32_32x32x16_bf16 v[48:63], v[102:105], v[114:117], v[48:63]
	s_waitcnt lgkmcnt(0)
	v_mfma_f32_32x32x16_bf16 v[0:15], v[118:121], v[106:109], v[0:15]
	ds_read_b128 v[90:93], v172 offset:32768
	ds_read_b128 v[98:101], v176 offset:49152
	ds_read_b128 v[102:105], v173 offset:32768
	ds_read_b128 v[106:109], v177 offset:49152
	v_mfma_f32_32x32x16_bf16 v[32:47], v[118:121], v[114:117], v[32:47]
	ds_read_b128 v[110:113], v176 offset:53248
	ds_read_b128 v[114:117], v177 offset:53248
	s_waitcnt lgkmcnt(4)
	v_mfma_f32_32x32x16_bf16 v[16:31], v[90:93], v[98:101], v[16:31]
	s_waitcnt lgkmcnt(1)
	v_mfma_f32_32x32x16_bf16 v[48:63], v[90:93], v[110:113], v[48:63]
	ds_read_b128 v[90:93], v172 offset:36864
	ds_read_b128 v[118:121], v173 offset:36864
	s_waitcnt lgkmcnt(1)
	v_mfma_f32_32x32x16_bf16 v[0:15], v[90:93], v[98:101], v[0:15]
	v_mfma_f32_32x32x16_bf16 v[32:47], v[90:93], v[110:113], v[32:47]
	v_mfma_f32_32x32x16_bf16 v[16:31], v[102:105], v[106:109], v[16:31]
	v_mfma_f32_32x32x16_bf16 v[48:63], v[102:105], v[114:117], v[48:63]
	s_waitcnt lgkmcnt(0)
	v_mfma_f32_32x32x16_bf16 v[0:15], v[118:121], v[106:109], v[0:15]
	s_waitcnt vmcnt(0)
	s_barrier
;     ...
;   bf16* As1 = As + 2 * 128 * 72;
;   bf16* Bs1 = As1 + 128 * 72;
;   G_LOAD(ra0, rb0, 0);
;   if (nk > 1) G_LOAD(ra1, rb1, 1);
;   G_STORE(ra0, rb0, As, Bs);
;   __syncthreads();
;   for (int kt = 0; kt < nk; kt += 2) {
;     if (kt + 2 < nk) G_LOAD(ra0, rb0, kt + 2);
;     if (kt + 1 < nk) G_STORE(ra1, rb1, As1, Bs1);
;     G_COMPUTE(As, Bs);
;     __syncthreads();
;     if (kt + 1 < nk) {
;       if (kt + 3 < nk) G_LOAD(ra1, rb1, kt + 3);
;       if (kt + 2 < nk) G_STORE(ra0, rb0, As, Bs);
;       G_COMPUTE(As1, Bs1);
;       __syncthreads();
;     }
;   }
	v_lshl_add_u64 v[68:69], v[68:69], 0, s[96:97]
	s_add_u32 m0, s94, 0x8000
	s_nop 1
	global_load_lds_dwordx4 v[68:69], off
	v_lshl_add_u64 v[70:71], v[70:71], 0, s[96:97]
	s_add_u32 m0, s94, 0xc000
	s_nop 1
	global_load_lds_dwordx4 v[70:71], off
	v_lshl_add_u64 v[72:73], v[72:73], 0, s[96:97]
	s_add_u32 m0, s94, 0x9000
	s_nop 1
	global_load_lds_dwordx4 v[72:73], off
	v_lshl_add_u64 v[74:75], v[74:75], 0, s[96:97]
	s_add_u32 m0, s94, 0xd000
	s_nop 1
	global_load_lds_dwordx4 v[74:75], off
	v_lshl_add_u64 v[76:77], v[76:77], 0, s[96:97]
	s_add_u32 m0, s94, 0xa000
	s_nop 1
	global_load_lds_dwordx4 v[76:77], off
	v_lshl_add_u64 v[78:79], v[78:79], 0, s[96:97]
	s_add_u32 m0, s94, 0xe000
	s_nop 1
	global_load_lds_dwordx4 v[78:79], off
	v_lshl_add_u64 v[82:83], v[82:83], 0, s[96:97]
	s_add_u32 m0, s94, 0xb000
	s_nop 1
	global_load_lds_dwordx4 v[82:83], off
	v_lshl_add_u64 v[80:81], v[80:81], 0, s[96:97]
	s_add_u32 m0, s94, 0xf000
	s_nop 1
	global_load_lds_dwordx4 v[80:81], off
	v_mfma_f32_32x32x16_bf16 v[32:47], v[118:121], v[114:117], v[32:47]
	ds_read_b128 v[90:93], v170 offset:0
	ds_read_b128 v[98:101], v174 offset:16384
	ds_read_b128 v[102:105], v171 offset:0
	ds_read_b128 v[106:109], v175 offset:16384
	ds_read_b128 v[110:113], v174 offset:20480
	ds_read_b128 v[114:117], v175 offset:20480
	s_waitcnt lgkmcnt(4)
	v_mfma_f32_32x32x16_bf16 v[16:31], v[90:93], v[98:101], v[16:31]
	s_waitcnt lgkmcnt(1)
	v_mfma_f32_32x32x16_bf16 v[48:63], v[90:93], v[110:113], v[48:63]
	ds_read_b128 v[90:93], v170 offset:4096
	ds_read_b128 v[118:121], v171 offset:4096
	s_waitcnt lgkmcnt(1)
	v_mfma_f32_32x32x16_bf16 v[0:15], v[90:93], v[98:101], v[0:15]
	v_mfma_f32_32x32x16_bf16 v[32:47], v[90:93], v[110:113], v[32:47]
	v_mfma_f32_32x32x16_bf16 v[16:31], v[102:105], v[106:109], v[16:31]
	v_mfma_f32_32x32x16_bf16 v[48:63], v[102:105], v[114:117], v[48:63]
	s_waitcnt lgkmcnt(0)
	v_mfma_f32_32x32x16_bf16 v[0:15], v[118:121], v[106:109], v[0:15]
	ds_read_b128 v[90:93], v172 offset:0
	ds_read_b128 v[98:101], v176 offset:16384
	ds_read_b128 v[102:105], v173 offset:0
	ds_read_b128 v[106:109], v177 offset:16384
	v_mfma_f32_32x32x16_bf16 v[32:47], v[118:121], v[114:117], v[32:47]
	ds_read_b128 v[110:113], v176 offset:20480
	ds_read_b128 v[114:117], v177 offset:20480
	s_waitcnt lgkmcnt(4)
	v_mfma_f32_32x32x16_bf16 v[16:31], v[90:93], v[98:101], v[16:31]
	s_waitcnt lgkmcnt(1)
	v_mfma_f32_32x32x16_bf16 v[48:63], v[90:93], v[110:113], v[48:63]
	ds_read_b128 v[90:93], v172 offset:4096
	ds_read_b128 v[118:121], v173 offset:4096
	s_waitcnt lgkmcnt(1)
	v_mfma_f32_32x32x16_bf16 v[0:15], v[90:93], v[98:101], v[0:15]
	v_mfma_f32_32x32x16_bf16 v[32:47], v[90:93], v[110:113], v[32:47]
	v_mfma_f32_32x32x16_bf16 v[16:31], v[102:105], v[106:109], v[16:31]
	v_mfma_f32_32x32x16_bf16 v[48:63], v[102:105], v[114:117], v[48:63]
	s_waitcnt lgkmcnt(0)
	v_mfma_f32_32x32x16_bf16 v[0:15], v[118:121], v[106:109], v[0:15]
	s_waitcnt vmcnt(0)
	s_barrier
	v_lshl_add_u64 v[68:69], v[68:69], 0, s[96:97]
	s_add_u32 m0, s94, 0x0
	s_nop 1
	global_load_lds_dwordx4 v[68:69], off
	v_lshl_add_u64 v[70:71], v[70:71], 0, s[96:97]
	s_add_u32 m0, s94, 0x4000
	s_nop 1
	global_load_lds_dwordx4 v[70:71], off
	v_lshl_add_u64 v[72:73], v[72:73], 0, s[96:97]
	s_add_u32 m0, s94, 0x1000
	s_nop 1
	global_load_lds_dwordx4 v[72:73], off
	v_lshl_add_u64 v[74:75], v[74:75], 0, s[96:97]
	s_add_u32 m0, s94, 0x5000
	s_nop 1
	global_load_lds_dwordx4 v[74:75], off
	v_lshl_add_u64 v[76:77], v[76:77], 0, s[96:97]
	s_add_u32 m0, s94, 0x2000
	s_nop 1
	global_load_lds_dwordx4 v[76:77], off
	v_lshl_add_u64 v[78:79], v[78:79], 0, s[96:97]
	s_add_u32 m0, s94, 0x6000
	s_nop 1
	global_load_lds_dwordx4 v[78:79], off
	v_lshl_add_u64 v[82:83], v[82:83], 0, s[96:97]
	s_add_u32 m0, s94, 0x3000
	s_nop 1
	global_load_lds_dwordx4 v[82:83], off
	v_lshl_add_u64 v[80:81], v[80:81], 0, s[96:97]
	s_add_u32 m0, s94, 0x7000
	s_nop 1
	global_load_lds_dwordx4 v[80:81], off
	v_mfma_f32_32x32x16_bf16 v[32:47], v[118:121], v[114:117], v[32:47]
	ds_read_b128 v[90:93], v170 offset:32768
	ds_read_b128 v[98:101], v174 offset:49152
	ds_read_b128 v[102:105], v171 offset:32768
	ds_read_b128 v[106:109], v175 offset:49152
	ds_read_b128 v[110:113], v174 offset:53248
	ds_read_b128 v[114:117], v175 offset:53248
	s_waitcnt lgkmcnt(4)
	v_mfma_f32_32x32x16_bf16 v[16:31], v[90:93], v[98:101], v[16:31]
	s_waitcnt lgkmcnt(1)
	v_mfma_f32_32x32x16_bf16 v[48:63], v[90:93], v[110:113], v[48:63]
	ds_read_b128 v[90:93], v170 offset:36864
	ds_read_b128 v[118:121], v171 offset:36864
	s_waitcnt lgkmcnt(1)
	v_mfma_f32_32x32x16_bf16 v[0:15], v[90:93], v[98:101], v[0:15]
	v_mfma_f32_32x32x16_bf16 v[32:47], v[90:93], v[110:113], v[32:47]
	v_mfma_f32_32x32x16_bf16 v[16:31], v[102:105], v[106:109], v[16:31]
	v_mfma_f32_32x32x16_bf16 v[48:63], v[102:105], v[114:117], v[48:63]
	s_waitcnt lgkmcnt(0)
	v_mfma_f32_32x32x16_bf16 v[0:15], v[118:121], v[106:109], v[0:15]
	ds_read_b128 v[90:93], v172 offset:32768
	ds_read_b128 v[98:101], v176 offset:49152
	ds_read_b128 v[102:105], v173 offset:32768
	ds_read_b128 v[106:109], v177 offset:49152
	v_mfma_f32_32x32x16_bf16 v[32:47], v[118:121], v[114:117], v[32:47]
	ds_read_b128 v[110:113], v176 offset:53248
	ds_read_b128 v[114:117], v177 offset:53248
	s_waitcnt lgkmcnt(4)
	v_mfma_f32_32x32x16_bf16 v[16:31], v[90:93], v[98:101], v[16:31]
	s_waitcnt lgkmcnt(1)
	v_mfma_f32_32x32x16_bf16 v[48:63], v[90:93], v[110:113], v[48:63]
	ds_read_b128 v[90:93], v172 offset:36864
	ds_read_b128 v[118:121], v173 offset:36864
	s_waitcnt lgkmcnt(1)
	v_mfma_f32_32x32x16_bf16 v[0:15], v[90:93], v[98:101], v[0:15]
	v_mfma_f32_32x32x16_bf16 v[32:47], v[90:93], v[110:113], v[32:47]
	v_mfma_f32_32x32x16_bf16 v[16:31], v[102:105], v[106:109], v[16:31]
	v_mfma_f32_32x32x16_bf16 v[48:63], v[102:105], v[114:117], v[48:63]
	s_waitcnt lgkmcnt(0)
	v_mfma_f32_32x32x16_bf16 v[0:15], v[118:121], v[106:109], v[0:15]
	s_waitcnt vmcnt(0)
	s_barrier
;     ...
;   bf16* As1 = As + 2 * 128 * 72;
;   bf16* Bs1 = As1 + 128 * 72;
;   G_LOAD(ra0, rb0, 0);
;   if (nk > 1) G_LOAD(ra1, rb1, 1);
;   G_STORE(ra0, rb0, As, Bs);
;   __syncthreads();
;   for (int kt = 0; kt < nk; kt += 2) {
;     if (kt + 2 < nk) G_LOAD(ra0, rb0, kt + 2);
;     if (kt + 1 < nk) G_STORE(ra1, rb1, As1, Bs1);
;     G_COMPUTE(As, Bs);
;     __syncthreads();
;     if (kt + 1 < nk) {
;       if (kt + 3 < nk) G_LOAD(ra1, rb1, kt + 3);
;       if (kt + 2 < nk) G_STORE(ra0, rb0, As, Bs);
;       G_COMPUTE(As1, Bs1);
;       __syncthreads();
;     }
;   }
	v_lshl_add_u64 v[68:69], v[68:69], 0, s[96:97]
	s_add_u32 m0, s94, 0x8000
	s_nop 1
	global_load_lds_dwordx4 v[68:69], off
	v_lshl_add_u64 v[70:71], v[70:71], 0, s[96:97]
	s_add_u32 m0, s94, 0xc000
	s_nop 1
	global_load_lds_dwordx4 v[70:71], off
	v_lshl_add_u64 v[72:73], v[72:73], 0, s[96:97]
	s_add_u32 m0, s94, 0x9000
	s_nop 1
	global_load_lds_dwordx4 v[72:73], off
	v_lshl_add_u64 v[74:75], v[74:75], 0, s[96:97]
	s_add_u32 m0, s94, 0xd000
	s_nop 1
	global_load_lds_dwordx4 v[74:75], off
	v_lshl_add_u64 v[76:77], v[76:77], 0, s[96:97]
	s_add_u32 m0, s94, 0xa000
	s_nop 1
	global_load_lds_dwordx4 v[76:77], off
	v_lshl_add_u64 v[78:79], v[78:79], 0, s[96:97]
	s_add_u32 m0, s94, 0xe000
	s_nop 1
	global_load_lds_dwordx4 v[78:79], off
	v_lshl_add_u64 v[82:83], v[82:83], 0, s[96:97]
	s_add_u32 m0, s94, 0xb000
	s_nop 1
	global_load_lds_dwordx4 v[82:83], off
	v_lshl_add_u64 v[80:81], v[80:81], 0, s[96:97]
	s_add_u32 m0, s94, 0xf000
	s_nop 1
	global_load_lds_dwordx4 v[80:81], off
	v_mfma_f32_32x32x16_bf16 v[32:47], v[118:121], v[114:117], v[32:47]
	ds_read_b128 v[90:93], v170 offset:0
	ds_read_b128 v[98:101], v174 offset:16384
	ds_read_b128 v[102:105], v171 offset:0
	ds_read_b128 v[106:109], v175 offset:16384
	ds_read_b128 v[110:113], v174 offset:20480
	ds_read_b128 v[114:117], v175 offset:20480
	s_waitcnt lgkmcnt(4)
	v_mfma_f32_32x32x16_bf16 v[16:31], v[90:93], v[98:101], v[16:31]
	s_waitcnt lgkmcnt(1)
	v_mfma_f32_32x32x16_bf16 v[48:63], v[90:93], v[110:113], v[48:63]
	ds_read_b128 v[90:93], v170 offset:4096
	ds_read_b128 v[118:121], v171 offset:4096
	s_waitcnt lgkmcnt(1)
	v_mfma_f32_32x32x16_bf16 v[0:15], v[90:93], v[98:101], v[0:15]
	v_mfma_f32_32x32x16_bf16 v[32:47], v[90:93], v[110:113], v[32:47]
	v_mfma_f32_32x32x16_bf16 v[16:31], v[102:105], v[106:109], v[16:31]
	v_mfma_f32_32x32x16_bf16 v[48:63], v[102:105], v[114:117], v[48:63]
	s_waitcnt lgkmcnt(0)
	v_mfma_f32_32x32x16_bf16 v[0:15], v[118:121], v[106:109], v[0:15]
	ds_read_b128 v[90:93], v172 offset:0
	ds_read_b128 v[98:101], v176 offset:16384
	ds_read_b128 v[102:105], v173 offset:0
	ds_read_b128 v[106:109], v177 offset:16384
	v_mfma_f32_32x32x16_bf16 v[32:47], v[118:121], v[114:117], v[32:47]
	ds_read_b128 v[110:113], v176 offset:20480
	ds_read_b128 v[114:117], v177 offset:20480
	s_waitcnt lgkmcnt(4)
	v_mfma_f32_32x32x16_bf16 v[16:31], v[90:93], v[98:101], v[16:31]
	s_waitcnt lgkmcnt(1)
	v_mfma_f32_32x32x16_bf16 v[48:63], v[90:93], v[110:113], v[48:63]
	ds_read_b128 v[90:93], v172 offset:4096
	ds_read_b128 v[118:121], v173 offset:4096
	s_waitcnt lgkmcnt(1)
	v_mfma_f32_32x32x16_bf16 v[0:15], v[90:93], v[98:101], v[0:15]
	v_mfma_f32_32x32x16_bf16 v[32:47], v[90:93], v[110:113], v[32:47]
	v_mfma_f32_32x32x16_bf16 v[16:31], v[102:105], v[106:109], v[16:31]
	v_mfma_f32_32x32x16_bf16 v[48:63], v[102:105], v[114:117], v[48:63]
	s_waitcnt lgkmcnt(0)
	v_mfma_f32_32x32x16_bf16 v[0:15], v[118:121], v[106:109], v[0:15]
	s_waitcnt vmcnt(0)
	s_barrier
	v_lshl_add_u64 v[68:69], v[68:69], 0, s[96:97]
	s_add_u32 m0, s94, 0x0
	s_nop 1
	global_load_lds_dwordx4 v[68:69], off
	v_lshl_add_u64 v[70:71], v[70:71], 0, s[96:97]
	s_add_u32 m0, s94, 0x4000
	s_nop 1
	global_load_lds_dwordx4 v[70:71], off
	v_lshl_add_u64 v[72:73], v[72:73], 0, s[96:97]
	s_add_u32 m0, s94, 0x1000
	s_nop 1
	global_load_lds_dwordx4 v[72:73], off
	v_lshl_add_u64 v[74:75], v[74:75], 0, s[96:97]
	s_add_u32 m0, s94, 0x5000
	s_nop 1
	global_load_lds_dwordx4 v[74:75], off
	v_lshl_add_u64 v[76:77], v[76:77], 0, s[96:97]
	s_add_u32 m0, s94, 0x2000
	s_nop 1
	global_load_lds_dwordx4 v[76:77], off
	v_lshl_add_u64 v[78:79], v[78:79], 0, s[96:97]
	s_add_u32 m0, s94, 0x6000
	s_nop 1
	global_load_lds_dwordx4 v[78:79], off
	v_lshl_add_u64 v[82:83], v[82:83], 0, s[96:97]
	s_add_u32 m0, s94, 0x3000
	s_nop 1
	global_load_lds_dwordx4 v[82:83], off
	v_lshl_add_u64 v[80:81], v[80:81], 0, s[96:97]
	s_add_u32 m0, s94, 0x7000
	s_nop 1
	global_load_lds_dwordx4 v[80:81], off
	v_mfma_f32_32x32x16_bf16 v[32:47], v[118:121], v[114:117], v[32:47]
	ds_read_b128 v[90:93], v170 offset:32768
	ds_read_b128 v[98:101], v174 offset:49152
	ds_read_b128 v[102:105], v171 offset:32768
	ds_read_b128 v[106:109], v175 offset:49152
	ds_read_b128 v[110:113], v174 offset:53248
	ds_read_b128 v[114:117], v175 offset:53248
	s_waitcnt lgkmcnt(4)
	v_mfma_f32_32x32x16_bf16 v[16:31], v[90:93], v[98:101], v[16:31]
	s_waitcnt lgkmcnt(1)
	v_mfma_f32_32x32x16_bf16 v[48:63], v[90:93], v[110:113], v[48:63]
	ds_read_b128 v[90:93], v170 offset:36864
	ds_read_b128 v[118:121], v171 offset:36864
	s_waitcnt lgkmcnt(1)
	v_mfma_f32_32x32x16_bf16 v[0:15], v[90:93], v[98:101], v[0:15]
	v_mfma_f32_32x32x16_bf16 v[32:47], v[90:93], v[110:113], v[32:47]
	v_mfma_f32_32x32x16_bf16 v[16:31], v[102:105], v[106:109], v[16:31]
	v_mfma_f32_32x32x16_bf16 v[48:63], v[102:105], v[114:117], v[48:63]
	s_waitcnt lgkmcnt(0)
	v_mfma_f32_32x32x16_bf16 v[0:15], v[118:121], v[106:109], v[0:15]
	ds_read_b128 v[90:93], v172 offset:32768
	ds_read_b128 v[98:101], v176 offset:49152
	ds_read_b128 v[102:105], v173 offset:32768
	ds_read_b128 v[106:109], v177 offset:49152
	v_mfma_f32_32x32x16_bf16 v[32:47], v[118:121], v[114:117], v[32:47]
	ds_read_b128 v[110:113], v176 offset:53248
	ds_read_b128 v[114:117], v177 offset:53248
	s_waitcnt lgkmcnt(4)
	v_mfma_f32_32x32x16_bf16 v[16:31], v[90:93], v[98:101], v[16:31]
	s_waitcnt lgkmcnt(1)
	v_mfma_f32_32x32x16_bf16 v[48:63], v[90:93], v[110:113], v[48:63]
	ds_read_b128 v[90:93], v172 offset:36864
	ds_read_b128 v[118:121], v173 offset:36864
	s_waitcnt lgkmcnt(1)
	v_mfma_f32_32x32x16_bf16 v[0:15], v[90:93], v[98:101], v[0:15]
	v_mfma_f32_32x32x16_bf16 v[32:47], v[90:93], v[110:113], v[32:47]
	v_mfma_f32_32x32x16_bf16 v[16:31], v[102:105], v[106:109], v[16:31]
	v_mfma_f32_32x32x16_bf16 v[48:63], v[102:105], v[114:117], v[48:63]
	s_nop 0
	s_nop 0
	s_nop 0
	s_nop 0
	s_nop 0
	s_nop 0
	s_nop 0
	s_waitcnt lgkmcnt(0)
	s_waitcnt vmcnt(0)
	s_barrier
; DEVI int accrow(int r, int lane) { return (r & 3) + 8 * (r >> 2) + 4 * (lane >> 5); }
; DEVI void gemm_epi_ssd_in(const Params& p, f32x16 (&acc)[2][2], int rbase, int cbase, int lane) {
;     ...
;   } else {
;     float* dtr = (float*)(ar + S_DTRAW);
; #pragma unroll
;     for (int i = 0; i < 2; ++i)
; #pragma unroll
;       for (int r = 0; r < 16; ++r) {
;         const int row = rbase + i * 32 + accrow(r, lane);
;         if (row < M && cbase == 6144) dtr[(size_t)row * 32 + d] = acc[i][0][r];
;     ...
;   for (int kt = 0; kt < nk; kt += 2) {
;     if (kt + 2 < nk) G_LOAD(ra0, rb0, kt + 2);
;     if (kt + 1 < nk) G_STORE(ra1, rb1, As1, Bs1);
;     G_COMPUTE(As, Bs);
;     __syncthreads();
;     if (kt + 1 < nk) {
;       if (kt + 3 < nk) G_LOAD(ra1, rb1, kt + 3);
;       if (kt + 2 < nk) G_STORE(ra0, rb0, As, Bs);
;       G_COMPUTE(As1, Bs1);
;       __syncthreads();
;     }
;   }
;     ...
;   const int rbase = m0 + wm * 64, cbase = n0 + wn * 64;
;   switch (jb.epi) {
;     case EPI_SSD_IN: gemm_epi_ssd_in(p, acc, rbase, cbase, lane); break;
	v_lshl_add_u64 v[68:69], v[68:69], 0, s[96:97]
	s_add_u32 m0, s94, 0x8000
	s_nop 1
	global_load_lds_dwordx4 v[68:69], off
	v_lshl_add_u64 v[70:71], v[70:71], 0, s[96:97]
	s_add_u32 m0, s94, 0xc000
	s_nop 1
	global_load_lds_dwordx4 v[70:71], off
	v_lshl_add_u64 v[72:73], v[72:73], 0, s[96:97]
	s_add_u32 m0, s94, 0x9000
	s_nop 1
	global_load_lds_dwordx4 v[72:73], off
	v_lshl_add_u64 v[74:75], v[74:75], 0, s[96:97]
	s_add_u32 m0, s94, 0xd000
	s_nop 1
	global_load_lds_dwordx4 v[74:75], off
	v_lshl_add_u64 v[76:77], v[76:77], 0, s[96:97]
	s_add_u32 m0, s94, 0xa000
	s_nop 1
	global_load_lds_dwordx4 v[76:77], off
	v_lshl_add_u64 v[78:79], v[78:79], 0, s[96:97]
	s_add_u32 m0, s94, 0xe000
	s_nop 1
	global_load_lds_dwordx4 v[78:79], off
	v_lshl_add_u64 v[82:83], v[82:83], 0, s[96:97]
	s_add_u32 m0, s94, 0xb000
	s_nop 1
	global_load_lds_dwordx4 v[82:83], off
	v_lshl_add_u64 v[80:81], v[80:81], 0, s[96:97]
	s_add_u32 m0, s94, 0xf000
	s_nop 1
	global_load_lds_dwordx4 v[80:81], off
	v_mfma_f32_32x32x16_bf16 v[0:15], v[118:121], v[106:109], v[0:15]
	ds_read_b128 v[68:71], v170 offset:0
	ds_read_b128 v[72:75], v174 offset:16384
	ds_read_b128 v[76:79], v171 offset:0
	ds_read_b128 v[80:83], v175 offset:16384
	ds_read_b128 v[90:93], v174 offset:20480
	ds_read_b128 v[98:101], v175 offset:20480
	v_mfma_f32_32x32x16_bf16 v[32:47], v[118:121], v[114:117], v[32:47]
	s_waitcnt lgkmcnt(4)
	v_mfma_f32_32x32x16_bf16 v[16:31], v[68:71], v[72:75], v[16:31]
	s_waitcnt lgkmcnt(1)
	v_mfma_f32_32x32x16_bf16 v[48:63], v[68:71], v[90:93], v[48:63]
	ds_read_b128 v[68:71], v170 offset:4096
	ds_read_b128 v[102:105], v171 offset:4096
	s_waitcnt lgkmcnt(1)
	v_mfma_f32_32x32x16_bf16 v[0:15], v[68:71], v[72:75], v[0:15]
	v_mfma_f32_32x32x16_bf16 v[32:47], v[68:71], v[90:93], v[32:47]
	v_mfma_f32_32x32x16_bf16 v[16:31], v[76:79], v[80:83], v[16:31]
	v_mfma_f32_32x32x16_bf16 v[48:63], v[76:79], v[98:101], v[48:63]
	s_waitcnt lgkmcnt(0)
	v_mfma_f32_32x32x16_bf16 v[0:15], v[102:105], v[80:83], v[0:15]
	ds_read_b128 v[68:71], v172 offset:0
	ds_read_b128 v[72:75], v176 offset:16384
	ds_read_b128 v[76:79], v173 offset:0
	ds_read_b128 v[80:83], v177 offset:16384
	v_mfma_f32_32x32x16_bf16 v[32:47], v[102:105], v[98:101], v[32:47]
	ds_read_b128 v[90:93], v176 offset:20480
	ds_read_b128 v[98:101], v177 offset:20480
	s_waitcnt lgkmcnt(4)
	v_mfma_f32_32x32x16_bf16 v[16:31], v[68:71], v[72:75], v[16:31]
	s_waitcnt lgkmcnt(1)
	v_mfma_f32_32x32x16_bf16 v[48:63], v[68:71], v[90:93], v[48:63]
	ds_read_b128 v[68:71], v172 offset:4096
	ds_read_b128 v[102:105], v173 offset:4096
	s_waitcnt lgkmcnt(0)
	s_waitcnt vmcnt(0)
	s_barrier
	v_mfma_f32_32x32x16_bf16 v[0:15], v[68:71], v[72:75], v[0:15]
	v_mfma_f32_32x32x16_bf16 v[16:31], v[76:79], v[80:83], v[16:31]
	v_mfma_f32_32x32x16_bf16 v[48:63], v[76:79], v[98:101], v[48:63]
	v_mfma_f32_32x32x16_bf16 v[32:47], v[68:71], v[90:93], v[32:47]
	v_mfma_f32_32x32x16_bf16 v[0:15], v[102:105], v[80:83], v[0:15]
	ds_read_b128 v[68:71], v170 offset:32768
	ds_read_b128 v[72:75], v174 offset:49152
	ds_read_b128 v[76:79], v175 offset:49152
	ds_read_b128 v[80:83], v171 offset:32768
	ds_read_b128 v[90:93], v174 offset:53248
	s_waitcnt lgkmcnt(3)
	v_mfma_f32_32x32x16_bf16 v[16:31], v[68:71], v[72:75], v[16:31]
	s_waitcnt lgkmcnt(0)
	v_mfma_f32_32x32x16_bf16 v[48:63], v[68:71], v[90:93], v[48:63]
	ds_read_b128 v[68:71], v170 offset:36864
	v_mfma_f32_32x32x16_bf16 v[32:47], v[102:105], v[98:101], v[32:47]
	s_waitcnt lgkmcnt(0)
	v_mfma_f32_32x32x16_bf16 v[0:15], v[68:71], v[72:75], v[0:15]
	ds_read_b128 v[72:75], v171 offset:36864
	v_mfma_f32_32x32x16_bf16 v[32:47], v[68:71], v[90:93], v[32:47]
	ds_read_b128 v[68:71], v175 offset:53248
	v_mfma_f32_32x32x16_bf16 v[16:31], v[80:83], v[76:79], v[16:31]
	s_waitcnt lgkmcnt(0)
	v_mfma_f32_32x32x16_bf16 v[48:63], v[80:83], v[68:71], v[48:63]
	v_mfma_f32_32x32x16_bf16 v[0:15], v[72:75], v[76:79], v[0:15]
	v_mfma_f32_32x32x16_bf16 v[32:47], v[72:75], v[68:71], v[32:47]
	ds_read_b128 v[68:71], v172 offset:32768
	ds_read_b128 v[72:75], v176 offset:49152
	ds_read_b128 v[76:79], v176 offset:53248
	s_waitcnt lgkmcnt(1)
	v_mfma_f32_32x32x16_bf16 v[16:31], v[68:71], v[72:75], v[16:31]
	s_waitcnt lgkmcnt(0)
	v_mfma_f32_32x32x16_bf16 v[48:63], v[68:71], v[76:79], v[48:63]
	ds_read_b128 v[68:71], v172 offset:36864
	s_waitcnt lgkmcnt(0)
	v_mfma_f32_32x32x16_bf16 v[0:15], v[68:71], v[72:75], v[0:15]
	v_mfma_f32_32x32x16_bf16 v[32:47], v[68:71], v[76:79], v[32:47]
	ds_read_b128 v[68:71], v173 offset:32768
	ds_read_b128 v[72:75], v177 offset:49152
	ds_read_b128 v[76:79], v177 offset:53248
	ds_read_b128 v[80:83], v173 offset:36864
	v_and_b32_e32 v67, 63, v86
	v_and_or_b32 v66, v86, 64, s3
	s_waitcnt lgkmcnt(0)
	s_barrier
	v_mfma_f32_32x32x16_bf16 v[16:31], v[68:71], v[72:75], v[16:31]
	v_mfma_f32_32x32x16_bf16 v[48:63], v[68:71], v[76:79], v[48:63]
	v_add_u32_e32 v70, s2, v88
	s_movk_i32 s2, 0x17ff
	v_cmp_lt_i32_e32 vcc, s2, v66
	v_mfma_f32_32x32x16_bf16 v[0:15], v[80:83], v[72:75], v[0:15]
	v_lshrrev_b32_e32 v72, 3, v67
	v_and_b32_e32 v71, 4, v72
	v_mfma_f32_32x32x16_bf16 v[32:47], v[80:83], v[76:79], v[32:47]
	s_and_saveexec_b64 s[2:3], vcc
	s_xor_b64 s[2:3], exec, s[2:3]
	s_cbranch_execz .LBB0_4762
	s_movk_i32 s6, 0x1800
	v_lshlrev_b32_e32 v96, 2, v87
	v_cmp_eq_u32_e32 vcc, s6, v66
	s_nop 5
	v_lshl_add_u64 v[32:33], s[4:5], 0, v[96:97]
	s_mov_b64 s[6:7], 0x2cb5c000
	v_or_b32_e32 v34, v70, v71
	v_lshl_add_u64 v[32:33], v[32:33], 0, s[6:7]
	v_cmp_gt_i32_e64 s[6:7], s90, v34
	s_and_b64 s[12:13], vcc, s[6:7]
	s_and_saveexec_b64 s[6:7], s[12:13]
	s_cbranch_execz .LBB0_4699
	v_ashrrev_i32_e32 v35, 31, v34
	v_lshlrev_b64 v[34:35], 7, v[34:35]
	v_lshl_add_u64 v[34:35], v[32:33], 0, v[34:35]
	global_store_dword v[34:35], v16, off

; DEVI int TID() { int t = threadIdx.x; asm volatile("" : "+v"(t)); return t; }
;     ...
;   const int tid = TID(), lane = tid & 63, wave = tid >> 6, wm = wave >> 1, wn = wave & 1;
;   f32x16 acc[2][2];
; #pragma unroll
;   for (int i = 0; i < 2; ++i)
; #pragma unroll
;     for (int j = 0; j < 2; ++j) acc[i][j] = zero16();
;   const int lrow = tid >> 3, lkc = (tid & 7) * 8;
;   const bf16* Ag = jb.A + (size_t)max(m0 + lrow, 0) * jb.lda + lkc;
;   const bf16* Ag1 = jb.A + (ptrdiff_t)(m0 + lrow) * jb.lda + lkc;
;   const bf16* Bg = jb.Bt + (size_t)(n0 + lrow) * jb.K + lkc;
;   const size_t astep = (size_t)32 * jb.lda, bstep = (size_t)32 * jb.K;
;   if (kt1 < 0) kt1 = jb.K >> 6;
;   const int nk = kt1 - kt0;
;   Ag += (size_t)kt0 * 64; Ag1 += (size_t)kt0 * 64; Bg += (size_t)kt0 * 64;
;   u32x4 ra0[4], rb0[4], ra1[4], rb1[4];
;     ...
;   bf16* As1 = As + 2 * 128 * 72;
;   bf16* Bs1 = As1 + 128 * 72;
;   G_LOAD(ra0, rb0, 0);
;   if (nk > 1) G_LOAD(ra1, rb1, 1);
;   G_STORE(ra0, rb0, As, Bs);
;   __syncthreads();
; DEVI void gemm_single(const Params& p, const GJob& jb, int nt, char* smem) {
;     ...
;     for (int t = lb; t < nmt * nnt; t += nlb) {
;       const int mt = m_lo + t / nnt, ntg = n_lo + t % nnt;
;       gemm_tile(p, jb, fused ? mt * 126 - 2 : mt * 128, ntg * 128, smem);
.LBB0_4833:
	s_abs_i32 s3, s11
	s_mul_hi_u32 s4, s3, s18
	s_mul_i32 s5, s4, s14
	s_ashr_i32 s2, s11, 31
	s_sub_i32 s3, s3, s5
	s_xor_b32 s2, s2, s15
	s_add_i32 s5, s4, 1
	s_sub_i32 s6, s3, s14
	s_cmp_ge_u32 s3, s14
	s_cselect_b32 s4, s5, s4
	s_cselect_b32 s3, s6, s3
	s_add_i32 s5, s4, 1
	s_cmp_ge_u32 s3, s14
	s_cselect_b32 s3, s5, s4
	s_xor_b32 s3, s3, s2
	s_sub_i32 s3, s3, s2
	s_add_i32 s2, s3, s12
	v_mov_b32_e32 v86, v208
	s_lshl_b32 s2, s2, 7
	s_mul_i32 s3, s16, s3
	v_ashrrev_i32_e32 v84, 3, v86
	v_add_u32_e32 v0, s2, v84
	v_max_i32_e32 v96, 0, v0
	v_lshlrev_b32_e32 v1, 4, v86
	v_lshlrev_b64 v[2:3], 11, v[96:97]
	v_and_b32_e32 v96, 0x70, v1
	s_mov_b64 s[96:97], 0x80
	v_lshrrev_b32_e32 v178, 4, v208
	v_and_b32_e32 v178, 7, v178
	v_lshlrev_b32_e32 v178, 4, v178
	v_xor_b32_e32 v96, v96, v178
	v_lshrrev_b32_e32 v179, 6, v208
	v_lshlrev_b32_e32 v179, 10, v179
	v_lshrrev_b32_e32 v180, 5, v208
	v_lshrrev_b32_e32 v181, 1, v208
	v_xor_b32_e32 v180, v180, v181
	v_readfirstlane_b32 s94, v179
	v_and_b32_e32 v180, 1, v180
	v_lshlrev_b32_e32 v180, 4, v180
	v_and_b32_e32 v181, 31, v208
	v_lshlrev_b32_e32 v181, 7, v181
	v_or_b32_e32 v180, v180, v181
	v_lshrrev_b32_e32 v181, 7, v208
	v_lshlrev_b32_e32 v181, 13, v181
	v_or_b32_e32 v194, v180, v181
	v_bfe_u32 v181, v208, 6, 1
	v_lshlrev_b32_e32 v181, 13, v181
	v_or_b32_e32 v195, v180, v181
	v_bfe_u32 v178, v208, 2, 2
	v_xor_b32_e32 v179, 0, v178
	v_lshlrev_b32_e32 v179, 5, v179
	v_or_b32_e32 v170, v194, v179
	v_or_b32_e32 v174, v195, v179
	v_xor_b32_e32 v179, 1, v178
	v_lshlrev_b32_e32 v179, 5, v179
	v_or_b32_e32 v171, v194, v179
	v_or_b32_e32 v175, v195, v179
	v_xor_b32_e32 v179, 2, v178
	v_lshlrev_b32_e32 v179, 5, v179
	v_or_b32_e32 v172, v194, v179
	v_or_b32_e32 v176, v195, v179
	v_xor_b32_e32 v179, 3, v178
	v_lshlrev_b32_e32 v179, 5, v179
	v_or_b32_e32 v173, v194, v179
	v_or_b32_e32 v177, v195, v179
	v_ashrrev_i32_e32 v1, 31, v0
	v_lshlrev_b64 v[0:1], 11, v[0:1]
	v_lshl_add_u64 v[0:1], s[8:9], 0, v[0:1]
	v_lshl_add_u64 v[24:25], v[0:1], 0, v[96:97]
	v_subrev_u32_e32 v0, s3, v84
	v_add_u32_e32 v0, s17, v0
	v_ashrrev_i32_e32 v1, 31, v0
	v_lshlrev_b64 v[0:1], 11, v[0:1]
	v_lshl_add_u64 v[0:1], v[64:65], 0, v[0:1]
	v_add_co_u32_e32 v72, vcc, s63, v24
	v_lshl_add_u64 v[70:71], v[0:1], 0, v[96:97]
	s_nop 0
	v_addc_co_u32_e32 v73, vcc, 0, v25, vcc
	v_add_co_u32_e32 v74, vcc, s63, v70
	v_lshl_add_u64 v[2:3], s[8:9], 0, v[2:3]
	s_nop 0
	v_addc_co_u32_e32 v75, vcc, 0, v71, vcc
	v_add_co_u32_e32 v76, vcc, s64, v24
	v_lshl_add_u64 v[68:69], v[2:3], 0, v[96:97]
	s_nop 0
	v_addc_co_u32_e32 v77, vcc, 0, v25, vcc
	v_add_co_u32_e32 v78, vcc, s64, v70
	v_addc_co_u32_e32 v79, vcc, 0, v71, vcc
	v_add_co_u32_e32 v80, vcc, s65, v24
	s_nop 0
	v_addc_co_u32_e32 v81, vcc, 0, v25, vcc
	v_add_co_u32_e32 v82, vcc, s65, v70
	s_nop 0
	v_addc_co_u32_e32 v83, vcc, 0, v71, vcc
	v_ashrrev_i32_e32 v66, 1, v86
	v_and_b32_e32 v87, 31, v86
	v_lshrrev_b32_e32 v67, 1, v86
	v_and_b32_e32 v88, 0xffffffc0, v66
	v_and_b32_e32 v90, 16, v67
	v_or_b32_e32 v66, v88, v87
	v_mad_u64_u32 v[84:85], s[4:5], v84, s91, v[96:97]
	v_mad_u64_u32 v[66:67], s[4:5], v66, s91, v[90:91]
	v_add_u32_e32 v85, 0xd800, v84
	s_mov_b64 s[4:5], s[74:75]
	s_add_u32 m0, s94, 0x0
	s_nop 1
	global_load_lds_dwordx4 v[68:69], off
	s_add_u32 m0, s94, 0x4000
	s_nop 1
	global_load_lds_dwordx4 v[70:71], off
	s_add_u32 m0, s94, 0x1000
	s_nop 1
	global_load_lds_dwordx4 v[72:73], off
	s_add_u32 m0, s94, 0x5000
	s_nop 1
	global_load_lds_dwordx4 v[74:75], off
	s_add_u32 m0, s94, 0x2000
	s_nop 1
	global_load_lds_dwordx4 v[76:77], off
	s_add_u32 m0, s94, 0x6000
	s_nop 1
	global_load_lds_dwordx4 v[78:79], off
	s_add_u32 m0, s94, 0x3000
	s_nop 1
	global_load_lds_dwordx4 v[80:81], off
	s_add_u32 m0, s94, 0x7000
	s_nop 1
	global_load_lds_dwordx4 v[82:83], off
	s_waitcnt lgkmcnt(0)
	s_waitcnt vmcnt(0)
	s_barrier
	v_lshl_add_u64 v[68:69], v[68:69], 0, s[96:97]
	s_add_u32 m0, s94, 0x8000
	s_nop 1
	global_load_lds_dwordx4 v[68:69], off
	v_lshl_add_u64 v[70:71], v[70:71], 0, s[96:97]
	s_add_u32 m0, s94, 0xc000
	s_nop 1
	global_load_lds_dwordx4 v[70:71], off
	v_lshl_add_u64 v[72:73], v[72:73], 0, s[96:97]
	s_add_u32 m0, s94, 0x9000
	s_nop 1
	global_load_lds_dwordx4 v[72:73], off
	v_lshl_add_u64 v[74:75], v[74:75], 0, s[96:97]
	s_add_u32 m0, s94, 0xd000
	s_nop 1
	global_load_lds_dwordx4 v[74:75], off
	v_lshl_add_u64 v[76:77], v[76:77], 0, s[96:97]
	s_add_u32 m0, s94, 0xa000
	s_nop 1
	global_load_lds_dwordx4 v[76:77], off
	v_lshl_add_u64 v[78:79], v[78:79], 0, s[96:97]
	s_add_u32 m0, s94, 0xe000
	s_nop 1
	global_load_lds_dwordx4 v[78:79], off
	v_lshl_add_u64 v[80:81], v[80:81], 0, s[96:97]
	s_add_u32 m0, s94, 0xb000
	s_nop 1
	global_load_lds_dwordx4 v[80:81], off
	v_lshl_add_u64 v[82:83], v[82:83], 0, s[96:97]
	s_add_u32 m0, s94, 0xf000
	s_nop 1
	global_load_lds_dwordx4 v[82:83], off
	ds_read_b128 v[0:3], v170 offset:0
	v_and_b32_e32 v4, 0x5f, v86
	v_mad_u32_u24 v67, v4, s91, v90
	ds_read_b128 v[4:7], v174 offset:16384
	ds_read_b128 v[90:93], v171 offset:0
	ds_read_b128 v[98:101], v175 offset:16384
	ds_read_b128 v[32:35], v174 offset:20480
	ds_read_b128 v[102:105], v175 offset:20480
	s_waitcnt lgkmcnt(4)
	v_mfma_f32_32x32x16_bf16 v[16:31], v[0:3], v[4:7], 0
	ds_read_b128 v[36:39], v170 offset:4096
	ds_read_b128 v[106:109], v171 offset:4096
	s_waitcnt lgkmcnt(3)
	v_mfma_f32_32x32x16_bf16 v[48:63], v[0:3], v[32:35], 0
	s_waitcnt lgkmcnt(1)
	v_mfma_f32_32x32x16_bf16 v[0:15], v[36:39], v[4:7], 0
	v_mfma_f32_32x32x16_bf16 v[32:47], v[36:39], v[32:35], 0
	v_mfma_f32_32x32x16_bf16 v[16:31], v[90:93], v[98:101], v[16:31]
	v_mfma_f32_32x32x16_bf16 v[48:63], v[90:93], v[102:105], v[48:63]
	s_waitcnt lgkmcnt(0)
	v_mfma_f32_32x32x16_bf16 v[0:15], v[106:109], v[98:101], v[0:15]
	v_mfma_f32_32x32x16_bf16 v[32:47], v[106:109], v[102:105], v[32:47]
	ds_read_b128 v[90:93], v172 offset:0
	ds_read_b128 v[98:101], v176 offset:16384
	ds_read_b128 v[102:105], v173 offset:0
	ds_read_b128 v[106:109], v177 offset:16384
	ds_read_b128 v[110:113], v176 offset:20480
	ds_read_b128 v[114:117], v177 offset:20480
	s_waitcnt lgkmcnt(4)
	v_mfma_f32_32x32x16_bf16 v[16:31], v[90:93], v[98:101], v[16:31]
	s_waitcnt lgkmcnt(1)
	v_mfma_f32_32x32x16_bf16 v[48:63], v[90:93], v[110:113], v[48:63]
	ds_read_b128 v[90:93], v172 offset:4096
	ds_read_b128 v[118:121], v173 offset:4096
	s_waitcnt lgkmcnt(1)
	v_mfma_f32_32x32x16_bf16 v[0:15], v[90:93], v[98:101], v[0:15]
	v_mfma_f32_32x32x16_bf16 v[32:47], v[90:93], v[110:113], v[32:47]
	v_mfma_f32_32x32x16_bf16 v[16:31], v[102:105], v[106:109], v[16:31]
	v_mfma_f32_32x32x16_bf16 v[48:63], v[102:105], v[114:117], v[48:63]
	s_waitcnt lgkmcnt(0)
	v_mfma_f32_32x32x16_bf16 v[0:15], v[118:121], v[106:109], v[0:15]
	s_waitcnt vmcnt(0)
	s_barrier
;     ...
;   bf16* As1 = As + 2 * 128 * 72;
;   bf16* Bs1 = As1 + 128 * 72;
;   G_LOAD(ra0, rb0, 0);
;   if (nk > 1) G_LOAD(ra1, rb1, 1);
;   G_STORE(ra0, rb0, As, Bs);
;   __syncthreads();
;   for (int kt = 0; kt < nk; kt += 2) {
;     if (kt + 2 < nk) G_LOAD(ra0, rb0, kt + 2);
;     if (kt + 1 < nk) G_STORE(ra1, rb1, As1, Bs1);
;     G_COMPUTE(As, Bs);
;     __syncthreads();
;     if (kt + 1 < nk) {
;       if (kt + 3 < nk) G_LOAD(ra1, rb1, kt + 3);
;       if (kt + 2 < nk) G_STORE(ra0, rb0, As, Bs);
;       G_COMPUTE(As1, Bs1);
;       __syncthreads();
;     }
;   }
	v_lshl_add_u64 v[68:69], v[68:69], 0, s[96:97]
	s_add_u32 m0, s94, 0x0
	s_nop 1
	global_load_lds_dwordx4 v[68:69], off
	v_lshl_add_u64 v[70:71], v[70:71], 0, s[96:97]
	s_add_u32 m0, s94, 0x4000
	s_nop 1
	global_load_lds_dwordx4 v[70:71], off
	v_lshl_add_u64 v[72:73], v[72:73], 0, s[96:97]
	s_add_u32 m0, s94, 0x1000
	s_nop 1
	global_load_lds_dwordx4 v[72:73], off
	v_lshl_add_u64 v[74:75], v[74:75], 0, s[96:97]
	s_add_u32 m0, s94, 0x5000
	s_nop 1
	global_load_lds_dwordx4 v[74:75], off
	v_lshl_add_u64 v[76:77], v[76:77], 0, s[96:97]
	s_add_u32 m0, s94, 0x2000
	s_nop 1
	global_load_lds_dwordx4 v[76:77], off
	v_lshl_add_u64 v[78:79], v[78:79], 0, s[96:97]
	s_add_u32 m0, s94, 0x6000
	s_nop 1
	global_load_lds_dwordx4 v[78:79], off
	v_lshl_add_u64 v[80:81], v[80:81], 0, s[96:97]
	s_add_u32 m0, s94, 0x3000
	s_nop 1
	global_load_lds_dwordx4 v[80:81], off
	v_lshl_add_u64 v[82:83], v[82:83], 0, s[96:97]
	s_add_u32 m0, s94, 0x7000
	s_nop 1
	global_load_lds_dwordx4 v[82:83], off
	v_mfma_f32_32x32x16_bf16 v[32:47], v[118:121], v[114:117], v[32:47]
	ds_read_b128 v[90:93], v170 offset:32768
	ds_read_b128 v[98:101], v174 offset:49152
	ds_read_b128 v[102:105], v171 offset:32768
	ds_read_b128 v[106:109], v175 offset:49152
	ds_read_b128 v[110:113], v174 offset:53248
	ds_read_b128 v[114:117], v175 offset:53248
	s_waitcnt lgkmcnt(4)
	v_mfma_f32_32x32x16_bf16 v[16:31], v[90:93], v[98:101], v[16:31]
	s_waitcnt lgkmcnt(1)
	v_mfma_f32_32x32x16_bf16 v[48:63], v[90:93], v[110:113], v[48:63]
	ds_read_b128 v[90:93], v170 offset:36864
	ds_read_b128 v[118:121], v171 offset:36864
	s_waitcnt lgkmcnt(1)
	v_mfma_f32_32x32x16_bf16 v[0:15], v[90:93], v[98:101], v[0:15]
	v_mfma_f32_32x32x16_bf16 v[32:47], v[90:93], v[110:113], v[32:47]
	v_mfma_f32_32x32x16_bf16 v[16:31], v[102:105], v[106:109], v[16:31]
	v_mfma_f32_32x32x16_bf16 v[48:63], v[102:105], v[114:117], v[48:63]
	s_waitcnt lgkmcnt(0)
	v_mfma_f32_32x32x16_bf16 v[0:15], v[118:121], v[106:109], v[0:15]
	ds_read_b128 v[90:93], v172 offset:32768
	ds_read_b128 v[98:101], v176 offset:49152
	ds_read_b128 v[102:105], v173 offset:32768
	ds_read_b128 v[106:109], v177 offset:49152
	v_mfma_f32_32x32x16_bf16 v[32:47], v[118:121], v[114:117], v[32:47]
	ds_read_b128 v[110:113], v176 offset:53248
	ds_read_b128 v[114:117], v177 offset:53248
	s_waitcnt lgkmcnt(4)
	v_mfma_f32_32x32x16_bf16 v[16:31], v[90:93], v[98:101], v[16:31]
	s_waitcnt lgkmcnt(1)
	v_mfma_f32_32x32x16_bf16 v[48:63], v[90:93], v[110:113], v[48:63]
	ds_read_b128 v[90:93], v172 offset:36864
	ds_read_b128 v[118:121], v173 offset:36864
	s_waitcnt lgkmcnt(1)
	v_mfma_f32_32x32x16_bf16 v[0:15], v[90:93], v[98:101], v[0:15]
	v_mfma_f32_32x32x16_bf16 v[32:47], v[90:93], v[110:113], v[32:47]
	v_mfma_f32_32x32x16_bf16 v[16:31], v[102:105], v[106:109], v[16:31]
	v_mfma_f32_32x32x16_bf16 v[48:63], v[102:105], v[114:117], v[48:63]
	s_waitcnt lgkmcnt(0)
	v_mfma_f32_32x32x16_bf16 v[0:15], v[118:121], v[106:109], v[0:15]
	s_waitcnt vmcnt(0)
	s_barrier
	v_lshl_add_u64 v[68:69], v[68:69], 0, s[96:97]
	s_add_u32 m0, s94, 0x8000
	s_nop 1
	global_load_lds_dwordx4 v[68:69], off
	v_lshl_add_u64 v[70:71], v[70:71], 0, s[96:97]
	s_add_u32 m0, s94, 0xc000
	s_nop 1
	global_load_lds_dwordx4 v[70:71], off
	v_lshl_add_u64 v[72:73], v[72:73], 0, s[96:97]
	s_add_u32 m0, s94, 0x9000
	s_nop 1
	global_load_lds_dwordx4 v[72:73], off
	v_lshl_add_u64 v[74:75], v[74:75], 0, s[96:97]
	s_add_u32 m0, s94, 0xd000
	s_nop 1
	global_load_lds_dwordx4 v[74:75], off
	v_lshl_add_u64 v[76:77], v[76:77], 0, s[96:97]
	s_add_u32 m0, s94, 0xa000
	s_nop 1
	global_load_lds_dwordx4 v[76:77], off
	v_lshl_add_u64 v[78:79], v[78:79], 0, s[96:97]
	s_add_u32 m0, s94, 0xe000
	s_nop 1
	global_load_lds_dwordx4 v[78:79], off
	v_lshl_add_u64 v[80:81], v[80:81], 0, s[96:97]
	s_add_u32 m0, s94, 0xb000
	s_nop 1
	global_load_lds_dwordx4 v[80:81], off
	v_lshl_add_u64 v[82:83], v[82:83], 0, s[96:97]
	s_add_u32 m0, s94, 0xf000
	s_nop 1
	global_load_lds_dwordx4 v[82:83], off
	v_mfma_f32_32x32x16_bf16 v[32:47], v[118:121], v[114:117], v[32:47]
	ds_read_b128 v[90:93], v170 offset:0
	ds_read_b128 v[98:101], v174 offset:16384
	ds_read_b128 v[102:105], v171 offset:0
	ds_read_b128 v[106:109], v175 offset:16384
	ds_read_b128 v[110:113], v174 offset:20480
	ds_read_b128 v[114:117], v175 offset:20480
	s_waitcnt lgkmcnt(4)
	v_mfma_f32_32x32x16_bf16 v[16:31], v[90:93], v[98:101], v[16:31]
	s_waitcnt lgkmcnt(1)
	v_mfma_f32_32x32x16_bf16 v[48:63], v[90:93], v[110:113], v[48:63]
	ds_read_b128 v[90:93], v170 offset:4096
	ds_read_b128 v[118:121], v171 offset:4096
	s_waitcnt lgkmcnt(1)
	v_mfma_f32_32x32x16_bf16 v[0:15], v[90:93], v[98:101], v[0:15]
	v_mfma_f32_32x32x16_bf16 v[32:47], v[90:93], v[110:113], v[32:47]
	v_mfma_f32_32x32x16_bf16 v[16:31], v[102:105], v[106:109], v[16:31]
	v_mfma_f32_32x32x16_bf16 v[48:63], v[102:105], v[114:117], v[48:63]
	s_waitcnt lgkmcnt(0)
	v_mfma_f32_32x32x16_bf16 v[0:15], v[118:121], v[106:109], v[0:15]
	ds_read_b128 v[90:93], v172 offset:0
	ds_read_b128 v[98:101], v176 offset:16384
	ds_read_b128 v[102:105], v173 offset:0
	ds_read_b128 v[106:109], v177 offset:16384
	v_mfma_f32_32x32x16_bf16 v[32:47], v[118:121], v[114:117], v[32:47]
	ds_read_b128 v[110:113], v176 offset:20480
	ds_read_b128 v[114:117], v177 offset:20480
	s_waitcnt lgkmcnt(4)
	v_mfma_f32_32x32x16_bf16 v[16:31], v[90:93], v[98:101], v[16:31]
	s_waitcnt lgkmcnt(1)
	v_mfma_f32_32x32x16_bf16 v[48:63], v[90:93], v[110:113], v[48:63]
	ds_read_b128 v[90:93], v172 offset:4096
	ds_read_b128 v[118:121], v173 offset:4096
	s_waitcnt lgkmcnt(1)
	v_mfma_f32_32x32x16_bf16 v[0:15], v[90:93], v[98:101], v[0:15]
	v_mfma_f32_32x32x16_bf16 v[32:47], v[90:93], v[110:113], v[32:47]
	v_mfma_f32_32x32x16_bf16 v[16:31], v[102:105], v[106:109], v[16:31]
	v_mfma_f32_32x32x16_bf16 v[48:63], v[102:105], v[114:117], v[48:63]
	s_waitcnt lgkmcnt(0)
	v_mfma_f32_32x32x16_bf16 v[0:15], v[118:121], v[106:109], v[0:15]
	s_waitcnt vmcnt(0)
	s_barrier
;     ...
;   bf16* As1 = As + 2 * 128 * 72;
;   bf16* Bs1 = As1 + 128 * 72;
;   G_LOAD(ra0, rb0, 0);
;   if (nk > 1) G_LOAD(ra1, rb1, 1);
;   G_STORE(ra0, rb0, As, Bs);
;   __syncthreads();
;   for (int kt = 0; kt < nk; kt += 2) {
;     if (kt + 2 < nk) G_LOAD(ra0, rb0, kt + 2);
;     if (kt + 1 < nk) G_STORE(ra1, rb1, As1, Bs1);
;     G_COMPUTE(As, Bs);
;     __syncthreads();
;     if (kt + 1 < nk) {
;       if (kt + 3 < nk) G_LOAD(ra1, rb1, kt + 3);
;       if (kt + 2 < nk) G_STORE(ra0, rb0, As, Bs);
;       G_COMPUTE(As1, Bs1);
;       __syncthreads();
;     }
;   }
	v_lshl_add_u64 v[68:69], v[68:69], 0, s[96:97]
	s_add_u32 m0, s94, 0x0
	s_nop 1
	global_load_lds_dwordx4 v[68:69], off
	v_lshl_add_u64 v[70:71], v[70:71], 0, s[96:97]
	s_add_u32 m0, s94, 0x4000
	s_nop 1
	global_load_lds_dwordx4 v[70:71], off
	v_lshl_add_u64 v[72:73], v[72:73], 0, s[96:97]
	s_add_u32 m0, s94, 0x1000
	s_nop 1
	global_load_lds_dwordx4 v[72:73], off
	v_lshl_add_u64 v[74:75], v[74:75], 0, s[96:97]
	s_add_u32 m0, s94, 0x5000
	s_nop 1
	global_load_lds_dwordx4 v[74:75], off
	v_lshl_add_u64 v[76:77], v[76:77], 0, s[96:97]
	s_add_u32 m0, s94, 0x2000
	s_nop 1
	global_load_lds_dwordx4 v[76:77], off
	v_lshl_add_u64 v[78:79], v[78:79], 0, s[96:97]
	s_add_u32 m0, s94, 0x6000
	s_nop 1
	global_load_lds_dwordx4 v[78:79], off
	v_lshl_add_u64 v[80:81], v[80:81], 0, s[96:97]
	s_add_u32 m0, s94, 0x3000
	s_nop 1
	global_load_lds_dwordx4 v[80:81], off
	v_lshl_add_u64 v[82:83], v[82:83], 0, s[96:97]
	s_add_u32 m0, s94, 0x7000
	s_nop 1
	global_load_lds_dwordx4 v[82:83], off
	v_mfma_f32_32x32x16_bf16 v[32:47], v[118:121], v[114:117], v[32:47]
	ds_read_b128 v[90:93], v170 offset:32768
	ds_read_b128 v[98:101], v174 offset:49152
	ds_read_b128 v[102:105], v171 offset:32768
	ds_read_b128 v[106:109], v175 offset:49152
	ds_read_b128 v[110:113], v174 offset:53248
	ds_read_b128 v[114:117], v175 offset:53248
	s_waitcnt lgkmcnt(4)
	v_mfma_f32_32x32x16_bf16 v[16:31], v[90:93], v[98:101], v[16:31]
	s_waitcnt lgkmcnt(1)
	v_mfma_f32_32x32x16_bf16 v[48:63], v[90:93], v[110:113], v[48:63]
	ds_read_b128 v[90:93], v170 offset:36864
	ds_read_b128 v[118:121], v171 offset:36864
	s_waitcnt lgkmcnt(1)
	v_mfma_f32_32x32x16_bf16 v[0:15], v[90:93], v[98:101], v[0:15]
	v_mfma_f32_32x32x16_bf16 v[32:47], v[90:93], v[110:113], v[32:47]
	v_mfma_f32_32x32x16_bf16 v[16:31], v[102:105], v[106:109], v[16:31]
	v_mfma_f32_32x32x16_bf16 v[48:63], v[102:105], v[114:117], v[48:63]
	s_waitcnt lgkmcnt(0)
	v_mfma_f32_32x32x16_bf16 v[0:15], v[118:121], v[106:109], v[0:15]
	ds_read_b128 v[90:93], v172 offset:32768
	ds_read_b128 v[98:101], v176 offset:49152
	ds_read_b128 v[102:105], v173 offset:32768
	ds_read_b128 v[106:109], v177 offset:49152
	v_mfma_f32_32x32x16_bf16 v[32:47], v[118:121], v[114:117], v[32:47]
	ds_read_b128 v[110:113], v176 offset:53248
	ds_read_b128 v[114:117], v177 offset:53248
	s_waitcnt lgkmcnt(4)
	v_mfma_f32_32x32x16_bf16 v[16:31], v[90:93], v[98:101], v[16:31]
	s_waitcnt lgkmcnt(1)
	v_mfma_f32_32x32x16_bf16 v[48:63], v[90:93], v[110:113], v[48:63]
	ds_read_b128 v[90:93], v172 offset:36864
	ds_read_b128 v[118:121], v173 offset:36864
	s_waitcnt lgkmcnt(1)
	v_mfma_f32_32x32x16_bf16 v[0:15], v[90:93], v[98:101], v[0:15]
	v_mfma_f32_32x32x16_bf16 v[32:47], v[90:93], v[110:113], v[32:47]
	v_mfma_f32_32x32x16_bf16 v[16:31], v[102:105], v[106:109], v[16:31]
	v_mfma_f32_32x32x16_bf16 v[48:63], v[102:105], v[114:117], v[48:63]
	s_waitcnt lgkmcnt(0)
	v_mfma_f32_32x32x16_bf16 v[0:15], v[118:121], v[106:109], v[0:15]
	s_waitcnt vmcnt(0)
	s_barrier
	v_lshl_add_u64 v[68:69], v[68:69], 0, s[96:97]
	s_add_u32 m0, s94, 0x8000
	s_nop 1
	global_load_lds_dwordx4 v[68:69], off
	v_lshl_add_u64 v[70:71], v[70:71], 0, s[96:97]
	s_add_u32 m0, s94, 0xc000
	s_nop 1
	global_load_lds_dwordx4 v[70:71], off
	v_lshl_add_u64 v[72:73], v[72:73], 0, s[96:97]
	s_add_u32 m0, s94, 0x9000
	s_nop 1
	global_load_lds_dwordx4 v[72:73], off
	v_lshl_add_u64 v[74:75], v[74:75], 0, s[96:97]
	s_add_u32 m0, s94, 0xd000
	s_nop 1
	global_load_lds_dwordx4 v[74:75], off
	v_lshl_add_u64 v[76:77], v[76:77], 0, s[96:97]
	s_add_u32 m0, s94, 0xa000
	s_nop 1
	global_load_lds_dwordx4 v[76:77], off
	v_lshl_add_u64 v[78:79], v[78:79], 0, s[96:97]
	s_add_u32 m0, s94, 0xe000
	s_nop 1
	global_load_lds_dwordx4 v[78:79], off
	v_lshl_add_u64 v[80:81], v[80:81], 0, s[96:97]
	s_add_u32 m0, s94, 0xb000
	s_nop 1
	global_load_lds_dwordx4 v[80:81], off
	v_lshl_add_u64 v[82:83], v[82:83], 0, s[96:97]
	s_add_u32 m0, s94, 0xf000
	s_nop 1
	global_load_lds_dwordx4 v[82:83], off
	v_mfma_f32_32x32x16_bf16 v[32:47], v[118:121], v[114:117], v[32:47]
	ds_read_b128 v[90:93], v170 offset:0
	ds_read_b128 v[98:101], v174 offset:16384
	ds_read_b128 v[102:105], v171 offset:0
	ds_read_b128 v[106:109], v175 offset:16384
	ds_read_b128 v[110:113], v174 offset:20480
	ds_read_b128 v[114:117], v175 offset:20480
	s_waitcnt lgkmcnt(4)
	v_mfma_f32_32x32x16_bf16 v[16:31], v[90:93], v[98:101], v[16:31]
	s_waitcnt lgkmcnt(1)
	v_mfma_f32_32x32x16_bf16 v[48:63], v[90:93], v[110:113], v[48:63]
	ds_read_b128 v[90:93], v170 offset:4096
	ds_read_b128 v[118:121], v171 offset:4096
	s_waitcnt lgkmcnt(1)
	v_mfma_f32_32x32x16_bf16 v[0:15], v[90:93], v[98:101], v[0:15]
	v_mfma_f32_32x32x16_bf16 v[32:47], v[90:93], v[110:113], v[32:47]
	v_mfma_f32_32x32x16_bf16 v[16:31], v[102:105], v[106:109], v[16:31]
	v_mfma_f32_32x32x16_bf16 v[48:63], v[102:105], v[114:117], v[48:63]
	s_waitcnt lgkmcnt(0)
	v_mfma_f32_32x32x16_bf16 v[0:15], v[118:121], v[106:109], v[0:15]
	ds_read_b128 v[90:93], v172 offset:0
	ds_read_b128 v[98:101], v176 offset:16384
	ds_read_b128 v[102:105], v173 offset:0
	ds_read_b128 v[106:109], v177 offset:16384
	v_mfma_f32_32x32x16_bf16 v[32:47], v[118:121], v[114:117], v[32:47]
	ds_read_b128 v[110:113], v176 offset:20480
	ds_read_b128 v[114:117], v177 offset:20480
	s_waitcnt lgkmcnt(4)
	v_mfma_f32_32x32x16_bf16 v[16:31], v[90:93], v[98:101], v[16:31]
	s_waitcnt lgkmcnt(1)
	v_mfma_f32_32x32x16_bf16 v[48:63], v[90:93], v[110:113], v[48:63]
	ds_read_b128 v[90:93], v172 offset:4096
	ds_read_b128 v[118:121], v173 offset:4096
	s_waitcnt lgkmcnt(1)
	v_mfma_f32_32x32x16_bf16 v[0:15], v[90:93], v[98:101], v[0:15]
	v_mfma_f32_32x32x16_bf16 v[32:47], v[90:93], v[110:113], v[32:47]
	v_mfma_f32_32x32x16_bf16 v[16:31], v[102:105], v[106:109], v[16:31]
	v_mfma_f32_32x32x16_bf16 v[48:63], v[102:105], v[114:117], v[48:63]
	s_waitcnt lgkmcnt(0)
	v_mfma_f32_32x32x16_bf16 v[0:15], v[118:121], v[106:109], v[0:15]
	s_waitcnt vmcnt(0)
	s_barrier
;     ...
;   bf16* As1 = As + 2 * 128 * 72;
;   bf16* Bs1 = As1 + 128 * 72;
;   G_LOAD(ra0, rb0, 0);
;   if (nk > 1) G_LOAD(ra1, rb1, 1);
;   G_STORE(ra0, rb0, As, Bs);
;   __syncthreads();
;   for (int kt = 0; kt < nk; kt += 2) {
;     if (kt + 2 < nk) G_LOAD(ra0, rb0, kt + 2);
;     if (kt + 1 < nk) G_STORE(ra1, rb1, As1, Bs1);
;     G_COMPUTE(As, Bs);
;     __syncthreads();
;     if (kt + 1 < nk) {
;       if (kt + 3 < nk) G_LOAD(ra1, rb1, kt + 3);
;       if (kt + 2 < nk) G_STORE(ra0, rb0, As, Bs);
;       G_COMPUTE(As1, Bs1);
;       __syncthreads();
;     }
;   }
	v_lshl_add_u64 v[68:69], v[68:69], 0, s[96:97]
	s_add_u32 m0, s94, 0x0
	s_nop 1
	global_load_lds_dwordx4 v[68:69], off
	v_lshl_add_u64 v[70:71], v[70:71], 0, s[96:97]
	s_add_u32 m0, s94, 0x4000
	s_nop 1
	global_load_lds_dwordx4 v[70:71], off
	v_lshl_add_u64 v[72:73], v[72:73], 0, s[96:97]
	s_add_u32 m0, s94, 0x1000
	s_nop 1
	global_load_lds_dwordx4 v[72:73], off
	v_lshl_add_u64 v[74:75], v[74:75], 0, s[96:97]
	s_add_u32 m0, s94, 0x5000
	s_nop 1
	global_load_lds_dwordx4 v[74:75], off
	v_lshl_add_u64 v[76:77], v[76:77], 0, s[96:97]
	s_add_u32 m0, s94, 0x2000
	s_nop 1
	global_load_lds_dwordx4 v[76:77], off
	v_lshl_add_u64 v[78:79], v[78:79], 0, s[96:97]
	s_add_u32 m0, s94, 0x6000
	s_nop 1
	global_load_lds_dwordx4 v[78:79], off
	v_lshl_add_u64 v[80:81], v[80:81], 0, s[96:97]
	s_add_u32 m0, s94, 0x3000
	s_nop 1
	global_load_lds_dwordx4 v[80:81], off
	v_lshl_add_u64 v[82:83], v[82:83], 0, s[96:97]
	s_add_u32 m0, s94, 0x7000
	s_nop 1
	global_load_lds_dwordx4 v[82:83], off
	v_mfma_f32_32x32x16_bf16 v[32:47], v[118:121], v[114:117], v[32:47]
	ds_read_b128 v[90:93], v170 offset:32768
	ds_read_b128 v[98:101], v174 offset:49152
	ds_read_b128 v[102:105], v171 offset:32768
	ds_read_b128 v[106:109], v175 offset:49152
	ds_read_b128 v[110:113], v174 offset:53248
	ds_read_b128 v[114:117], v175 offset:53248
	s_waitcnt lgkmcnt(4)
	v_mfma_f32_32x32x16_bf16 v[16:31], v[90:93], v[98:101], v[16:31]
	s_waitcnt lgkmcnt(1)
	v_mfma_f32_32x32x16_bf16 v[48:63], v[90:93], v[110:113], v[48:63]
	ds_read_b128 v[90:93], v170 offset:36864
	ds_read_b128 v[118:121], v171 offset:36864
	s_waitcnt lgkmcnt(1)
	v_mfma_f32_32x32x16_bf16 v[0:15], v[90:93], v[98:101], v[0:15]
	v_mfma_f32_32x32x16_bf16 v[32:47], v[90:93], v[110:113], v[32:47]
	v_mfma_f32_32x32x16_bf16 v[16:31], v[102:105], v[106:109], v[16:31]
	v_mfma_f32_32x32x16_bf16 v[48:63], v[102:105], v[114:117], v[48:63]
	s_waitcnt lgkmcnt(0)
	v_mfma_f32_32x32x16_bf16 v[0:15], v[118:121], v[106:109], v[0:15]
	ds_read_b128 v[90:93], v172 offset:32768
	ds_read_b128 v[98:101], v176 offset:49152
	ds_read_b128 v[102:105], v173 offset:32768
	ds_read_b128 v[106:109], v177 offset:49152
	v_mfma_f32_32x32x16_bf16 v[32:47], v[118:121], v[114:117], v[32:47]
	ds_read_b128 v[110:113], v176 offset:53248
	ds_read_b128 v[114:117], v177 offset:53248
	s_waitcnt lgkmcnt(4)
	v_mfma_f32_32x32x16_bf16 v[16:31], v[90:93], v[98:101], v[16:31]
	s_waitcnt lgkmcnt(1)
	v_mfma_f32_32x32x16_bf16 v[48:63], v[90:93], v[110:113], v[48:63]
	ds_read_b128 v[90:93], v172 offset:36864
	ds_read_b128 v[118:121], v173 offset:36864
	s_waitcnt lgkmcnt(1)
	v_mfma_f32_32x32x16_bf16 v[0:15], v[90:93], v[98:101], v[0:15]
	v_mfma_f32_32x32x16_bf16 v[32:47], v[90:93], v[110:113], v[32:47]
	v_mfma_f32_32x32x16_bf16 v[16:31], v[102:105], v[106:109], v[16:31]
	v_mfma_f32_32x32x16_bf16 v[48:63], v[102:105], v[114:117], v[48:63]
	s_waitcnt lgkmcnt(0)
	v_mfma_f32_32x32x16_bf16 v[0:15], v[118:121], v[106:109], v[0:15]
	s_waitcnt vmcnt(0)
	s_barrier
	v_lshl_add_u64 v[68:69], v[68:69], 0, s[96:97]
	s_add_u32 m0, s94, 0x8000
	s_nop 1
	global_load_lds_dwordx4 v[68:69], off
	v_lshl_add_u64 v[70:71], v[70:71], 0, s[96:97]
	s_add_u32 m0, s94, 0xc000
	s_nop 1
	global_load_lds_dwordx4 v[70:71], off
	v_lshl_add_u64 v[72:73], v[72:73], 0, s[96:97]
	s_add_u32 m0, s94, 0x9000
	s_nop 1
	global_load_lds_dwordx4 v[72:73], off
	v_lshl_add_u64 v[74:75], v[74:75], 0, s[96:97]
	s_add_u32 m0, s94, 0xd000
	s_nop 1
	global_load_lds_dwordx4 v[74:75], off
	v_lshl_add_u64 v[76:77], v[76:77], 0, s[96:97]
	s_add_u32 m0, s94, 0xa000
	s_nop 1
	global_load_lds_dwordx4 v[76:77], off
	v_lshl_add_u64 v[78:79], v[78:79], 0, s[96:97]
	s_add_u32 m0, s94, 0xe000
	s_nop 1
	global_load_lds_dwordx4 v[78:79], off
	v_lshl_add_u64 v[80:81], v[80:81], 0, s[96:97]
	s_add_u32 m0, s94, 0xb000
	s_nop 1
	global_load_lds_dwordx4 v[80:81], off
	v_lshl_add_u64 v[82:83], v[82:83], 0, s[96:97]
	s_add_u32 m0, s94, 0xf000
	s_nop 1
	global_load_lds_dwordx4 v[82:83], off
	v_mfma_f32_32x32x16_bf16 v[32:47], v[118:121], v[114:117], v[32:47]
	ds_read_b128 v[90:93], v170 offset:0
	ds_read_b128 v[98:101], v174 offset:16384
	ds_read_b128 v[102:105], v171 offset:0
	ds_read_b128 v[106:109], v175 offset:16384
	ds_read_b128 v[110:113], v174 offset:20480
	ds_read_b128 v[114:117], v175 offset:20480
	s_waitcnt lgkmcnt(4)
	v_mfma_f32_32x32x16_bf16 v[16:31], v[90:93], v[98:101], v[16:31]
	s_waitcnt lgkmcnt(1)
	v_mfma_f32_32x32x16_bf16 v[48:63], v[90:93], v[110:113], v[48:63]
	ds_read_b128 v[90:93], v170 offset:4096
	ds_read_b128 v[118:121], v171 offset:4096
	s_waitcnt lgkmcnt(1)
	v_mfma_f32_32x32x16_bf16 v[0:15], v[90:93], v[98:101], v[0:15]
	v_mfma_f32_32x32x16_bf16 v[32:47], v[90:93], v[110:113], v[32:47]
	v_mfma_f32_32x32x16_bf16 v[16:31], v[102:105], v[106:109], v[16:31]
	v_mfma_f32_32x32x16_bf16 v[48:63], v[102:105], v[114:117], v[48:63]
	s_waitcnt lgkmcnt(0)
	v_mfma_f32_32x32x16_bf16 v[0:15], v[118:121], v[106:109], v[0:15]
	ds_read_b128 v[90:93], v172 offset:0
	ds_read_b128 v[98:101], v176 offset:16384
	ds_read_b128 v[102:105], v173 offset:0
	ds_read_b128 v[106:109], v177 offset:16384
	v_mfma_f32_32x32x16_bf16 v[32:47], v[118:121], v[114:117], v[32:47]
	ds_read_b128 v[110:113], v176 offset:20480
	ds_read_b128 v[114:117], v177 offset:20480
	s_waitcnt lgkmcnt(4)
	v_mfma_f32_32x32x16_bf16 v[16:31], v[90:93], v[98:101], v[16:31]
	s_waitcnt lgkmcnt(1)
	v_mfma_f32_32x32x16_bf16 v[48:63], v[90:93], v[110:113], v[48:63]
	ds_read_b128 v[90:93], v172 offset:4096
	ds_read_b128 v[118:121], v173 offset:4096
	s_waitcnt lgkmcnt(1)
	v_mfma_f32_32x32x16_bf16 v[0:15], v[90:93], v[98:101], v[0:15]
	v_mfma_f32_32x32x16_bf16 v[32:47], v[90:93], v[110:113], v[32:47]
	v_mfma_f32_32x32x16_bf16 v[16:31], v[102:105], v[106:109], v[16:31]
	v_mfma_f32_32x32x16_bf16 v[48:63], v[102:105], v[114:117], v[48:63]
	s_waitcnt lgkmcnt(0)
	v_mfma_f32_32x32x16_bf16 v[0:15], v[118:121], v[106:109], v[0:15]
	s_waitcnt vmcnt(0)
	s_barrier
;     ...
;   bf16* As1 = As + 2 * 128 * 72;
;   bf16* Bs1 = As1 + 128 * 72;
;   G_LOAD(ra0, rb0, 0);
;   if (nk > 1) G_LOAD(ra1, rb1, 1);
;   G_STORE(ra0, rb0, As, Bs);
;   __syncthreads();
;   for (int kt = 0; kt < nk; kt += 2) {
;     if (kt + 2 < nk) G_LOAD(ra0, rb0, kt + 2);
;     if (kt + 1 < nk) G_STORE(ra1, rb1, As1, Bs1);
;     G_COMPUTE(As, Bs);
;     __syncthreads();
;     if (kt + 1 < nk) {
;       if (kt + 3 < nk) G_LOAD(ra1, rb1, kt + 3);
;       if (kt + 2 < nk) G_STORE(ra0, rb0, As, Bs);
;       G_COMPUTE(As1, Bs1);
;       __syncthreads();
;     }
;   }
	v_lshl_add_u64 v[68:69], v[68:69], 0, s[96:97]
	s_add_u32 m0, s94, 0x0
	s_nop 1
	global_load_lds_dwordx4 v[68:69], off
	v_lshl_add_u64 v[70:71], v[70:71], 0, s[96:97]
	s_add_u32 m0, s94, 0x4000
	s_nop 1
	global_load_lds_dwordx4 v[70:71], off
	v_lshl_add_u64 v[72:73], v[72:73], 0, s[96:97]
	s_add_u32 m0, s94, 0x1000
	s_nop 1
	global_load_lds_dwordx4 v[72:73], off
	v_lshl_add_u64 v[74:75], v[74:75], 0, s[96:97]
	s_add_u32 m0, s94, 0x5000
	s_nop 1
	global_load_lds_dwordx4 v[74:75], off
	v_lshl_add_u64 v[76:77], v[76:77], 0, s[96:97]
	s_add_u32 m0, s94, 0x2000
	s_nop 1
	global_load_lds_dwordx4 v[76:77], off
	v_lshl_add_u64 v[78:79], v[78:79], 0, s[96:97]
	s_add_u32 m0, s94, 0x6000
	s_nop 1
	global_load_lds_dwordx4 v[78:79], off
	v_lshl_add_u64 v[80:81], v[80:81], 0, s[96:97]
	s_add_u32 m0, s94, 0x3000
	s_nop 1
	global_load_lds_dwordx4 v[80:81], off
	v_lshl_add_u64 v[82:83], v[82:83], 0, s[96:97]
	s_add_u32 m0, s94, 0x7000
	s_nop 1
	global_load_lds_dwordx4 v[82:83], off
	v_mfma_f32_32x32x16_bf16 v[32:47], v[118:121], v[114:117], v[32:47]
	ds_read_b128 v[90:93], v170 offset:32768
	ds_read_b128 v[98:101], v174 offset:49152
	ds_read_b128 v[102:105], v171 offset:32768
	ds_read_b128 v[106:109], v175 offset:49152
	ds_read_b128 v[110:113], v174 offset:53248
	ds_read_b128 v[114:117], v175 offset:53248
	s_waitcnt lgkmcnt(4)
	v_mfma_f32_32x32x16_bf16 v[16:31], v[90:93], v[98:101], v[16:31]
	s_waitcnt lgkmcnt(1)
	v_mfma_f32_32x32x16_bf16 v[48:63], v[90:93], v[110:113], v[48:63]
	ds_read_b128 v[90:93], v170 offset:36864
	ds_read_b128 v[118:121], v171 offset:36864
	s_waitcnt lgkmcnt(1)
	v_mfma_f32_32x32x16_bf16 v[0:15], v[90:93], v[98:101], v[0:15]
	v_mfma_f32_32x32x16_bf16 v[32:47], v[90:93], v[110:113], v[32:47]
	v_mfma_f32_32x32x16_bf16 v[16:31], v[102:105], v[106:109], v[16:31]
	v_mfma_f32_32x32x16_bf16 v[48:63], v[102:105], v[114:117], v[48:63]
	s_waitcnt lgkmcnt(0)
	v_mfma_f32_32x32x16_bf16 v[0:15], v[118:121], v[106:109], v[0:15]
	ds_read_b128 v[90:93], v172 offset:32768
	ds_read_b128 v[98:101], v176 offset:49152
	ds_read_b128 v[102:105], v173 offset:32768
	ds_read_b128 v[106:109], v177 offset:49152
	v_mfma_f32_32x32x16_bf16 v[32:47], v[118:121], v[114:117], v[32:47]
	ds_read_b128 v[110:113], v176 offset:53248
	ds_read_b128 v[114:117], v177 offset:53248
	s_waitcnt lgkmcnt(4)
	v_mfma_f32_32x32x16_bf16 v[16:31], v[90:93], v[98:101], v[16:31]
	s_waitcnt lgkmcnt(1)
	v_mfma_f32_32x32x16_bf16 v[48:63], v[90:93], v[110:113], v[48:63]
	ds_read_b128 v[90:93], v172 offset:36864
	ds_read_b128 v[118:121], v173 offset:36864
	s_waitcnt lgkmcnt(1)
	v_mfma_f32_32x32x16_bf16 v[0:15], v[90:93], v[98:101], v[0:15]
	v_mfma_f32_32x32x16_bf16 v[32:47], v[90:93], v[110:113], v[32:47]
	v_mfma_f32_32x32x16_bf16 v[16:31], v[102:105], v[106:109], v[16:31]
	v_mfma_f32_32x32x16_bf16 v[48:63], v[102:105], v[114:117], v[48:63]
	s_waitcnt lgkmcnt(0)
	v_mfma_f32_32x32x16_bf16 v[0:15], v[118:121], v[106:109], v[0:15]
	s_waitcnt vmcnt(0)
	s_barrier
	v_lshl_add_u64 v[68:69], v[68:69], 0, s[96:97]
	s_add_u32 m0, s94, 0x8000
	s_nop 1
	global_load_lds_dwordx4 v[68:69], off
	v_lshl_add_u64 v[70:71], v[70:71], 0, s[96:97]
	s_add_u32 m0, s94, 0xc000
	s_nop 1
	global_load_lds_dwordx4 v[70:71], off
	v_lshl_add_u64 v[72:73], v[72:73], 0, s[96:97]
	s_add_u32 m0, s94, 0x9000
	s_nop 1
	global_load_lds_dwordx4 v[72:73], off
	v_lshl_add_u64 v[74:75], v[74:75], 0, s[96:97]
	s_add_u32 m0, s94, 0xd000
	s_nop 1
	global_load_lds_dwordx4 v[74:75], off
	v_lshl_add_u64 v[76:77], v[76:77], 0, s[96:97]
	s_add_u32 m0, s94, 0xa000
	s_nop 1
	global_load_lds_dwordx4 v[76:77], off
	v_lshl_add_u64 v[78:79], v[78:79], 0, s[96:97]
	s_add_u32 m0, s94, 0xe000
	s_nop 1
	global_load_lds_dwordx4 v[78:79], off
	v_lshl_add_u64 v[80:81], v[80:81], 0, s[96:97]
	s_add_u32 m0, s94, 0xb000
	s_nop 1
	global_load_lds_dwordx4 v[80:81], off
	v_lshl_add_u64 v[82:83], v[82:83], 0, s[96:97]
	s_add_u32 m0, s94, 0xf000
	s_nop 1
	global_load_lds_dwordx4 v[82:83], off
	v_mfma_f32_32x32x16_bf16 v[32:47], v[118:121], v[114:117], v[32:47]
	ds_read_b128 v[90:93], v170 offset:0
	ds_read_b128 v[98:101], v174 offset:16384
	ds_read_b128 v[102:105], v171 offset:0
	ds_read_b128 v[106:109], v175 offset:16384
	ds_read_b128 v[110:113], v174 offset:20480
	ds_read_b128 v[114:117], v175 offset:20480
	s_waitcnt lgkmcnt(4)
	v_mfma_f32_32x32x16_bf16 v[16:31], v[90:93], v[98:101], v[16:31]
	s_waitcnt lgkmcnt(1)
	v_mfma_f32_32x32x16_bf16 v[48:63], v[90:93], v[110:113], v[48:63]
	ds_read_b128 v[90:93], v170 offset:4096
	ds_read_b128 v[118:121], v171 offset:4096
	s_waitcnt lgkmcnt(1)
	v_mfma_f32_32x32x16_bf16 v[0:15], v[90:93], v[98:101], v[0:15]
	v_mfma_f32_32x32x16_bf16 v[32:47], v[90:93], v[110:113], v[32:47]
	v_mfma_f32_32x32x16_bf16 v[16:31], v[102:105], v[106:109], v[16:31]
	v_mfma_f32_32x32x16_bf16 v[48:63], v[102:105], v[114:117], v[48:63]
	s_waitcnt lgkmcnt(0)
	v_mfma_f32_32x32x16_bf16 v[0:15], v[118:121], v[106:109], v[0:15]
	ds_read_b128 v[90:93], v172 offset:0
	ds_read_b128 v[98:101], v176 offset:16384
	ds_read_b128 v[102:105], v173 offset:0
	ds_read_b128 v[106:109], v177 offset:16384
	v_mfma_f32_32x32x16_bf16 v[32:47], v[118:121], v[114:117], v[32:47]
	ds_read_b128 v[110:113], v176 offset:20480
	ds_read_b128 v[114:117], v177 offset:20480
	s_waitcnt lgkmcnt(4)
	v_mfma_f32_32x32x16_bf16 v[16:31], v[90:93], v[98:101], v[16:31]
	s_waitcnt lgkmcnt(1)
	v_mfma_f32_32x32x16_bf16 v[48:63], v[90:93], v[110:113], v[48:63]
	ds_read_b128 v[90:93], v172 offset:4096
	ds_read_b128 v[118:121], v173 offset:4096
	s_waitcnt lgkmcnt(1)
	v_mfma_f32_32x32x16_bf16 v[0:15], v[90:93], v[98:101], v[0:15]
	v_mfma_f32_32x32x16_bf16 v[32:47], v[90:93], v[110:113], v[32:47]
	v_mfma_f32_32x32x16_bf16 v[16:31], v[102:105], v[106:109], v[16:31]
	v_mfma_f32_32x32x16_bf16 v[48:63], v[102:105], v[114:117], v[48:63]
	s_waitcnt lgkmcnt(0)
	v_mfma_f32_32x32x16_bf16 v[0:15], v[118:121], v[106:109], v[0:15]
	s_waitcnt vmcnt(0)
	s_barrier
;     ...
;   bf16* As1 = As + 2 * 128 * 72;
;   bf16* Bs1 = As1 + 128 * 72;
;   G_LOAD(ra0, rb0, 0);
;   if (nk > 1) G_LOAD(ra1, rb1, 1);
;   G_STORE(ra0, rb0, As, Bs);
;   __syncthreads();
;   for (int kt = 0; kt < nk; kt += 2) {
;     if (kt + 2 < nk) G_LOAD(ra0, rb0, kt + 2);
;     if (kt + 1 < nk) G_STORE(ra1, rb1, As1, Bs1);
;     G_COMPUTE(As, Bs);
;     __syncthreads();
;     if (kt + 1 < nk) {
;       if (kt + 3 < nk) G_LOAD(ra1, rb1, kt + 3);
;       if (kt + 2 < nk) G_STORE(ra0, rb0, As, Bs);
;       G_COMPUTE(As1, Bs1);
;       __syncthreads();
;     }
;   }
	v_lshl_add_u64 v[68:69], v[68:69], 0, s[96:97]
	s_add_u32 m0, s94, 0x0
	s_nop 1
	global_load_lds_dwordx4 v[68:69], off
	v_lshl_add_u64 v[70:71], v[70:71], 0, s[96:97]
	s_add_u32 m0, s94, 0x4000
	s_nop 1
	global_load_lds_dwordx4 v[70:71], off
	v_lshl_add_u64 v[72:73], v[72:73], 0, s[96:97]
	s_add_u32 m0, s94, 0x1000
	s_nop 1
	global_load_lds_dwordx4 v[72:73], off
	v_lshl_add_u64 v[74:75], v[74:75], 0, s[96:97]
	s_add_u32 m0, s94, 0x5000
	s_nop 1
	global_load_lds_dwordx4 v[74:75], off
	v_lshl_add_u64 v[76:77], v[76:77], 0, s[96:97]
	s_add_u32 m0, s94, 0x2000
	s_nop 1
	global_load_lds_dwordx4 v[76:77], off
	v_lshl_add_u64 v[78:79], v[78:79], 0, s[96:97]
	s_add_u32 m0, s94, 0x6000
	s_nop 1
	global_load_lds_dwordx4 v[78:79], off
	v_lshl_add_u64 v[80:81], v[80:81], 0, s[96:97]
	s_add_u32 m0, s94, 0x3000
	s_nop 1
	global_load_lds_dwordx4 v[80:81], off
	v_lshl_add_u64 v[82:83], v[82:83], 0, s[96:97]
	s_add_u32 m0, s94, 0x7000
	s_nop 1
	global_load_lds_dwordx4 v[82:83], off
	v_mfma_f32_32x32x16_bf16 v[32:47], v[118:121], v[114:117], v[32:47]
	ds_read_b128 v[90:93], v170 offset:32768
	ds_read_b128 v[98:101], v174 offset:49152
	ds_read_b128 v[102:105], v171 offset:32768
	ds_read_b128 v[106:109], v175 offset:49152
	ds_read_b128 v[110:113], v174 offset:53248
	ds_read_b128 v[114:117], v175 offset:53248
	s_waitcnt lgkmcnt(4)
	v_mfma_f32_32x32x16_bf16 v[16:31], v[90:93], v[98:101], v[16:31]
	s_waitcnt lgkmcnt(1)
	v_mfma_f32_32x32x16_bf16 v[48:63], v[90:93], v[110:113], v[48:63]
	ds_read_b128 v[90:93], v170 offset:36864
	ds_read_b128 v[118:121], v171 offset:36864
	s_waitcnt lgkmcnt(1)
	v_mfma_f32_32x32x16_bf16 v[0:15], v[90:93], v[98:101], v[0:15]
	v_mfma_f32_32x32x16_bf16 v[32:47], v[90:93], v[110:113], v[32:47]
	v_mfma_f32_32x32x16_bf16 v[16:31], v[102:105], v[106:109], v[16:31]
	v_mfma_f32_32x32x16_bf16 v[48:63], v[102:105], v[114:117], v[48:63]
	s_waitcnt lgkmcnt(0)
	v_mfma_f32_32x32x16_bf16 v[0:15], v[118:121], v[106:109], v[0:15]
	ds_read_b128 v[90:93], v172 offset:32768
	ds_read_b128 v[98:101], v176 offset:49152
	ds_read_b128 v[102:105], v173 offset:32768
	ds_read_b128 v[106:109], v177 offset:49152
	v_mfma_f32_32x32x16_bf16 v[32:47], v[118:121], v[114:117], v[32:47]
	ds_read_b128 v[110:113], v176 offset:53248
	ds_read_b128 v[114:117], v177 offset:53248
	s_waitcnt lgkmcnt(4)
	v_mfma_f32_32x32x16_bf16 v[16:31], v[90:93], v[98:101], v[16:31]
	s_waitcnt lgkmcnt(1)
	v_mfma_f32_32x32x16_bf16 v[48:63], v[90:93], v[110:113], v[48:63]
	ds_read_b128 v[90:93], v172 offset:36864
	ds_read_b128 v[118:121], v173 offset:36864
	s_waitcnt lgkmcnt(1)
	v_mfma_f32_32x32x16_bf16 v[0:15], v[90:93], v[98:101], v[0:15]
	v_mfma_f32_32x32x16_bf16 v[32:47], v[90:93], v[110:113], v[32:47]
	v_mfma_f32_32x32x16_bf16 v[16:31], v[102:105], v[106:109], v[16:31]
	v_mfma_f32_32x32x16_bf16 v[48:63], v[102:105], v[114:117], v[48:63]
	s_waitcnt lgkmcnt(0)
	v_mfma_f32_32x32x16_bf16 v[0:15], v[118:121], v[106:109], v[0:15]
	s_waitcnt vmcnt(0)
	s_barrier
	v_lshl_add_u64 v[68:69], v[68:69], 0, s[96:97]
	s_add_u32 m0, s94, 0x8000
	s_nop 1
	global_load_lds_dwordx4 v[68:69], off
	v_lshl_add_u64 v[70:71], v[70:71], 0, s[96:97]
	s_add_u32 m0, s94, 0xc000
	s_nop 1
	global_load_lds_dwordx4 v[70:71], off
	v_lshl_add_u64 v[72:73], v[72:73], 0, s[96:97]
	s_add_u32 m0, s94, 0x9000
	s_nop 1
	global_load_lds_dwordx4 v[72:73], off
	v_lshl_add_u64 v[74:75], v[74:75], 0, s[96:97]
	s_add_u32 m0, s94, 0xd000
	s_nop 1
	global_load_lds_dwordx4 v[74:75], off
	v_lshl_add_u64 v[76:77], v[76:77], 0, s[96:97]
	s_add_u32 m0, s94, 0xa000
	s_nop 1
	global_load_lds_dwordx4 v[76:77], off
	v_lshl_add_u64 v[78:79], v[78:79], 0, s[96:97]
	s_add_u32 m0, s94, 0xe000
	s_nop 1
	global_load_lds_dwordx4 v[78:79], off
	v_lshl_add_u64 v[80:81], v[80:81], 0, s[96:97]
	s_add_u32 m0, s94, 0xb000
	s_nop 1
	global_load_lds_dwordx4 v[80:81], off
	v_lshl_add_u64 v[82:83], v[82:83], 0, s[96:97]
	s_add_u32 m0, s94, 0xf000
	s_nop 1
	global_load_lds_dwordx4 v[82:83], off
	v_mfma_f32_32x32x16_bf16 v[32:47], v[118:121], v[114:117], v[32:47]
	ds_read_b128 v[90:93], v170 offset:0
	ds_read_b128 v[98:101], v174 offset:16384
	ds_read_b128 v[102:105], v171 offset:0
	ds_read_b128 v[106:109], v175 offset:16384
	ds_read_b128 v[110:113], v174 offset:20480
	ds_read_b128 v[114:117], v175 offset:20480
	s_waitcnt lgkmcnt(4)
	v_mfma_f32_32x32x16_bf16 v[16:31], v[90:93], v[98:101], v[16:31]
	s_waitcnt lgkmcnt(1)
	v_mfma_f32_32x32x16_bf16 v[48:63], v[90:93], v[110:113], v[48:63]
	ds_read_b128 v[90:93], v170 offset:4096
	ds_read_b128 v[118:121], v171 offset:4096
	s_waitcnt lgkmcnt(1)
	v_mfma_f32_32x32x16_bf16 v[0:15], v[90:93], v[98:101], v[0:15]
	v_mfma_f32_32x32x16_bf16 v[32:47], v[90:93], v[110:113], v[32:47]
	v_mfma_f32_32x32x16_bf16 v[16:31], v[102:105], v[106:109], v[16:31]
	v_mfma_f32_32x32x16_bf16 v[48:63], v[102:105], v[114:117], v[48:63]
	s_waitcnt lgkmcnt(0)
	v_mfma_f32_32x32x16_bf16 v[0:15], v[118:121], v[106:109], v[0:15]
	ds_read_b128 v[90:93], v172 offset:0
	ds_read_b128 v[98:101], v176 offset:16384
	ds_read_b128 v[102:105], v173 offset:0
	ds_read_b128 v[106:109], v177 offset:16384
	v_mfma_f32_32x32x16_bf16 v[32:47], v[118:121], v[114:117], v[32:47]
	ds_read_b128 v[110:113], v176 offset:20480
	ds_read_b128 v[114:117], v177 offset:20480
	s_waitcnt lgkmcnt(4)
	v_mfma_f32_32x32x16_bf16 v[16:31], v[90:93], v[98:101], v[16:31]
	s_waitcnt lgkmcnt(1)
	v_mfma_f32_32x32x16_bf16 v[48:63], v[90:93], v[110:113], v[48:63]
	ds_read_b128 v[90:93], v172 offset:4096
	ds_read_b128 v[118:121], v173 offset:4096
	s_waitcnt lgkmcnt(1)
	v_mfma_f32_32x32x16_bf16 v[0:15], v[90:93], v[98:101], v[0:15]
	v_mfma_f32_32x32x16_bf16 v[32:47], v[90:93], v[110:113], v[32:47]
	v_mfma_f32_32x32x16_bf16 v[16:31], v[102:105], v[106:109], v[16:31]
	v_mfma_f32_32x32x16_bf16 v[48:63], v[102:105], v[114:117], v[48:63]
	s_waitcnt lgkmcnt(0)
	v_mfma_f32_32x32x16_bf16 v[0:15], v[118:121], v[106:109], v[0:15]
	s_waitcnt vmcnt(0)
	s_barrier
;     ...
;   bf16* As1 = As + 2 * 128 * 72;
;   bf16* Bs1 = As1 + 128 * 72;
;   G_LOAD(ra0, rb0, 0);
;   if (nk > 1) G_LOAD(ra1, rb1, 1);
;   G_STORE(ra0, rb0, As, Bs);
;   __syncthreads();
;   for (int kt = 0; kt < nk; kt += 2) {
;     if (kt + 2 < nk) G_LOAD(ra0, rb0, kt + 2);
;     if (kt + 1 < nk) G_STORE(ra1, rb1, As1, Bs1);
;     G_COMPUTE(As, Bs);
;     __syncthreads();
;     if (kt + 1 < nk) {
;       if (kt + 3 < nk) G_LOAD(ra1, rb1, kt + 3);
;       if (kt + 2 < nk) G_STORE(ra0, rb0, As, Bs);
;       G_COMPUTE(As1, Bs1);
;       __syncthreads();
;     }
;   }
	v_lshl_add_u64 v[68:69], v[68:69], 0, s[96:97]
	s_add_u32 m0, s94, 0x0
	s_nop 1
	global_load_lds_dwordx4 v[68:69], off
	v_lshl_add_u64 v[70:71], v[70:71], 0, s[96:97]
	s_add_u32 m0, s94, 0x4000
	s_nop 1
	global_load_lds_dwordx4 v[70:71], off
	v_lshl_add_u64 v[72:73], v[72:73], 0, s[96:97]
	s_add_u32 m0, s94, 0x1000
	s_nop 1
	global_load_lds_dwordx4 v[72:73], off
	v_lshl_add_u64 v[74:75], v[74:75], 0, s[96:97]
	s_add_u32 m0, s94, 0x5000
	s_nop 1
	global_load_lds_dwordx4 v[74:75], off
	v_lshl_add_u64 v[76:77], v[76:77], 0, s[96:97]
	s_add_u32 m0, s94, 0x2000
	s_nop 1
	global_load_lds_dwordx4 v[76:77], off
	v_lshl_add_u64 v[78:79], v[78:79], 0, s[96:97]
	s_add_u32 m0, s94, 0x6000
	s_nop 1
	global_load_lds_dwordx4 v[78:79], off
	v_lshl_add_u64 v[80:81], v[80:81], 0, s[96:97]
	s_add_u32 m0, s94, 0x3000
	s_nop 1
	global_load_lds_dwordx4 v[80:81], off
	v_lshl_add_u64 v[82:83], v[82:83], 0, s[96:97]
	s_add_u32 m0, s94, 0x7000
	s_nop 1
	global_load_lds_dwordx4 v[82:83], off
	v_mfma_f32_32x32x16_bf16 v[32:47], v[118:121], v[114:117], v[32:47]
	ds_read_b128 v[90:93], v170 offset:32768
	ds_read_b128 v[98:101], v174 offset:49152
	ds_read_b128 v[102:105], v171 offset:32768
	ds_read_b128 v[106:109], v175 offset:49152
	ds_read_b128 v[110:113], v174 offset:53248
	ds_read_b128 v[114:117], v175 offset:53248
	s_waitcnt lgkmcnt(4)
	v_mfma_f32_32x32x16_bf16 v[16:31], v[90:93], v[98:101], v[16:31]
	s_waitcnt lgkmcnt(1)
	v_mfma_f32_32x32x16_bf16 v[48:63], v[90:93], v[110:113], v[48:63]
	ds_read_b128 v[90:93], v170 offset:36864
	ds_read_b128 v[118:121], v171 offset:36864
	s_waitcnt lgkmcnt(1)
	v_mfma_f32_32x32x16_bf16 v[0:15], v[90:93], v[98:101], v[0:15]
	v_mfma_f32_32x32x16_bf16 v[32:47], v[90:93], v[110:113], v[32:47]
	v_mfma_f32_32x32x16_bf16 v[16:31], v[102:105], v[106:109], v[16:31]
	v_mfma_f32_32x32x16_bf16 v[48:63], v[102:105], v[114:117], v[48:63]
	s_waitcnt lgkmcnt(0)
	v_mfma_f32_32x32x16_bf16 v[0:15], v[118:121], v[106:109], v[0:15]
	ds_read_b128 v[90:93], v172 offset:32768
	ds_read_b128 v[98:101], v176 offset:49152
	ds_read_b128 v[102:105], v173 offset:32768
	ds_read_b128 v[106:109], v177 offset:49152
	v_mfma_f32_32x32x16_bf16 v[32:47], v[118:121], v[114:117], v[32:47]
	ds_read_b128 v[110:113], v176 offset:53248
	ds_read_b128 v[114:117], v177 offset:53248
	s_waitcnt lgkmcnt(4)
	v_mfma_f32_32x32x16_bf16 v[16:31], v[90:93], v[98:101], v[16:31]
	s_waitcnt lgkmcnt(1)
	v_mfma_f32_32x32x16_bf16 v[48:63], v[90:93], v[110:113], v[48:63]
	ds_read_b128 v[90:93], v172 offset:36864
	ds_read_b128 v[118:121], v173 offset:36864
	s_waitcnt lgkmcnt(1)
	v_mfma_f32_32x32x16_bf16 v[0:15], v[90:93], v[98:101], v[0:15]
	v_mfma_f32_32x32x16_bf16 v[32:47], v[90:93], v[110:113], v[32:47]
	v_mfma_f32_32x32x16_bf16 v[16:31], v[102:105], v[106:109], v[16:31]
	v_mfma_f32_32x32x16_bf16 v[48:63], v[102:105], v[114:117], v[48:63]
	s_waitcnt lgkmcnt(0)
	v_mfma_f32_32x32x16_bf16 v[0:15], v[118:121], v[106:109], v[0:15]
	s_waitcnt vmcnt(0)
	s_barrier
	v_lshl_add_u64 v[68:69], v[68:69], 0, s[96:97]
	s_add_u32 m0, s94, 0x8000
	s_nop 1
	global_load_lds_dwordx4 v[68:69], off
	v_lshl_add_u64 v[70:71], v[70:71], 0, s[96:97]
	s_add_u32 m0, s94, 0xc000
	s_nop 1
	global_load_lds_dwordx4 v[70:71], off
	v_lshl_add_u64 v[72:73], v[72:73], 0, s[96:97]
	s_add_u32 m0, s94, 0x9000
	s_nop 1
	global_load_lds_dwordx4 v[72:73], off
	v_lshl_add_u64 v[74:75], v[74:75], 0, s[96:97]
	s_add_u32 m0, s94, 0xd000
	s_nop 1
	global_load_lds_dwordx4 v[74:75], off
	v_lshl_add_u64 v[76:77], v[76:77], 0, s[96:97]
	s_add_u32 m0, s94, 0xa000
	s_nop 1
	global_load_lds_dwordx4 v[76:77], off
	v_lshl_add_u64 v[78:79], v[78:79], 0, s[96:97]
	s_add_u32 m0, s94, 0xe000
	s_nop 1
	global_load_lds_dwordx4 v[78:79], off
	v_lshl_add_u64 v[80:81], v[80:81], 0, s[96:97]
	s_add_u32 m0, s94, 0xb000
	s_nop 1
	global_load_lds_dwordx4 v[80:81], off
	v_lshl_add_u64 v[82:83], v[82:83], 0, s[96:97]
	s_add_u32 m0, s94, 0xf000
	s_nop 1
	global_load_lds_dwordx4 v[82:83], off
	v_mfma_f32_32x32x16_bf16 v[32:47], v[118:121], v[114:117], v[32:47]
	ds_read_b128 v[90:93], v170 offset:0
	ds_read_b128 v[98:101], v174 offset:16384
	ds_read_b128 v[102:105], v171 offset:0
	ds_read_b128 v[106:109], v175 offset:16384
	ds_read_b128 v[110:113], v174 offset:20480
	ds_read_b128 v[114:117], v175 offset:20480
	s_waitcnt lgkmcnt(4)
	v_mfma_f32_32x32x16_bf16 v[16:31], v[90:93], v[98:101], v[16:31]
	s_waitcnt lgkmcnt(1)
	v_mfma_f32_32x32x16_bf16 v[48:63], v[90:93], v[110:113], v[48:63]
	ds_read_b128 v[90:93], v170 offset:4096
	ds_read_b128 v[118:121], v171 offset:4096
	s_waitcnt lgkmcnt(1)
	v_mfma_f32_32x32x16_bf16 v[0:15], v[90:93], v[98:101], v[0:15]
	v_mfma_f32_32x32x16_bf16 v[32:47], v[90:93], v[110:113], v[32:47]
	v_mfma_f32_32x32x16_bf16 v[16:31], v[102:105], v[106:109], v[16:31]
	v_mfma_f32_32x32x16_bf16 v[48:63], v[102:105], v[114:117], v[48:63]
	s_waitcnt lgkmcnt(0)
	v_mfma_f32_32x32x16_bf16 v[0:15], v[118:121], v[106:109], v[0:15]
	ds_read_b128 v[90:93], v172 offset:0
	ds_read_b128 v[98:101], v176 offset:16384
	ds_read_b128 v[102:105], v173 offset:0
	ds_read_b128 v[106:109], v177 offset:16384
	v_mfma_f32_32x32x16_bf16 v[32:47], v[118:121], v[114:117], v[32:47]
	ds_read_b128 v[110:113], v176 offset:20480
	ds_read_b128 v[114:117], v177 offset:20480
	s_waitcnt lgkmcnt(4)
	v_mfma_f32_32x32x16_bf16 v[16:31], v[90:93], v[98:101], v[16:31]
	s_waitcnt lgkmcnt(1)
	v_mfma_f32_32x32x16_bf16 v[48:63], v[90:93], v[110:113], v[48:63]
	ds_read_b128 v[90:93], v172 offset:4096
	ds_read_b128 v[118:121], v173 offset:4096
	s_waitcnt lgkmcnt(1)
	v_mfma_f32_32x32x16_bf16 v[0:15], v[90:93], v[98:101], v[0:15]
	v_mfma_f32_32x32x16_bf16 v[32:47], v[90:93], v[110:113], v[32:47]
	v_mfma_f32_32x32x16_bf16 v[16:31], v[102:105], v[106:109], v[16:31]
	v_mfma_f32_32x32x16_bf16 v[48:63], v[102:105], v[114:117], v[48:63]
	s_waitcnt lgkmcnt(0)
	v_mfma_f32_32x32x16_bf16 v[0:15], v[118:121], v[106:109], v[0:15]
	s_waitcnt vmcnt(0)
	s_barrier
;     ...
;   bf16* As1 = As + 2 * 128 * 72;
;   bf16* Bs1 = As1 + 128 * 72;
;   G_LOAD(ra0, rb0, 0);
;   if (nk > 1) G_LOAD(ra1, rb1, 1);
;   G_STORE(ra0, rb0, As, Bs);
;   __syncthreads();
;   for (int kt = 0; kt < nk; kt += 2) {
;     if (kt + 2 < nk) G_LOAD(ra0, rb0, kt + 2);
;     if (kt + 1 < nk) G_STORE(ra1, rb1, As1, Bs1);
;     G_COMPUTE(As, Bs);
;     __syncthreads();
;     if (kt + 1 < nk) {
;       if (kt + 3 < nk) G_LOAD(ra1, rb1, kt + 3);
;       if (kt + 2 < nk) G_STORE(ra0, rb0, As, Bs);
;       G_COMPUTE(As1, Bs1);
;       __syncthreads();
;     }
;   }
	v_lshl_add_u64 v[68:69], v[68:69], 0, s[96:97]
	s_add_u32 m0, s94, 0x0
	s_nop 1
	global_load_lds_dwordx4 v[68:69], off
	v_lshl_add_u64 v[70:71], v[70:71], 0, s[96:97]
	s_add_u32 m0, s94, 0x4000
	s_nop 1
	global_load_lds_dwordx4 v[70:71], off
	v_lshl_add_u64 v[72:73], v[72:73], 0, s[96:97]
	s_add_u32 m0, s94, 0x1000
	s_nop 1
	global_load_lds_dwordx4 v[72:73], off
	v_lshl_add_u64 v[74:75], v[74:75], 0, s[96:97]
	s_add_u32 m0, s94, 0x5000
	s_nop 1
	global_load_lds_dwordx4 v[74:75], off
	v_lshl_add_u64 v[76:77], v[76:77], 0, s[96:97]
	s_add_u32 m0, s94, 0x2000
	s_nop 1
	global_load_lds_dwordx4 v[76:77], off
	v_lshl_add_u64 v[78:79], v[78:79], 0, s[96:97]
	s_add_u32 m0, s94, 0x6000
	s_nop 1
	global_load_lds_dwordx4 v[78:79], off
	v_lshl_add_u64 v[80:81], v[80:81], 0, s[96:97]
	s_add_u32 m0, s94, 0x3000
	s_nop 1
	global_load_lds_dwordx4 v[80:81], off
	v_lshl_add_u64 v[82:83], v[82:83], 0, s[96:97]
	s_add_u32 m0, s94, 0x7000
	s_nop 1
	global_load_lds_dwordx4 v[82:83], off
	v_mfma_f32_32x32x16_bf16 v[32:47], v[118:121], v[114:117], v[32:47]
	ds_read_b128 v[90:93], v170 offset:32768
	ds_read_b128 v[98:101], v174 offset:49152
	ds_read_b128 v[102:105], v171 offset:32768
	ds_read_b128 v[106:109], v175 offset:49152
	ds_read_b128 v[110:113], v174 offset:53248
	ds_read_b128 v[114:117], v175 offset:53248
	s_waitcnt lgkmcnt(4)
	v_mfma_f32_32x32x16_bf16 v[16:31], v[90:93], v[98:101], v[16:31]
	s_waitcnt lgkmcnt(1)
	v_mfma_f32_32x32x16_bf16 v[48:63], v[90:93], v[110:113], v[48:63]
	ds_read_b128 v[90:93], v170 offset:36864
	ds_read_b128 v[118:121], v171 offset:36864
	s_waitcnt lgkmcnt(1)
	v_mfma_f32_32x32x16_bf16 v[0:15], v[90:93], v[98:101], v[0:15]
	v_mfma_f32_32x32x16_bf16 v[32:47], v[90:93], v[110:113], v[32:47]
	v_mfma_f32_32x32x16_bf16 v[16:31], v[102:105], v[106:109], v[16:31]
	v_mfma_f32_32x32x16_bf16 v[48:63], v[102:105], v[114:117], v[48:63]
	s_waitcnt lgkmcnt(0)
	v_mfma_f32_32x32x16_bf16 v[0:15], v[118:121], v[106:109], v[0:15]
	ds_read_b128 v[90:93], v172 offset:32768
	ds_read_b128 v[98:101], v176 offset:49152
	ds_read_b128 v[102:105], v173 offset:32768
	ds_read_b128 v[106:109], v177 offset:49152
	v_mfma_f32_32x32x16_bf16 v[32:47], v[118:121], v[114:117], v[32:47]
	ds_read_b128 v[110:113], v176 offset:53248
	ds_read_b128 v[114:117], v177 offset:53248
	s_waitcnt lgkmcnt(4)
	v_mfma_f32_32x32x16_bf16 v[16:31], v[90:93], v[98:101], v[16:31]
	s_waitcnt lgkmcnt(1)
	v_mfma_f32_32x32x16_bf16 v[48:63], v[90:93], v[110:113], v[48:63]
	ds_read_b128 v[90:93], v172 offset:36864
	ds_read_b128 v[118:121], v173 offset:36864
	s_waitcnt lgkmcnt(1)
	v_mfma_f32_32x32x16_bf16 v[0:15], v[90:93], v[98:101], v[0:15]
	v_mfma_f32_32x32x16_bf16 v[32:47], v[90:93], v[110:113], v[32:47]
	v_mfma_f32_32x32x16_bf16 v[16:31], v[102:105], v[106:109], v[16:31]
	v_mfma_f32_32x32x16_bf16 v[48:63], v[102:105], v[114:117], v[48:63]
	s_nop 0
	s_nop 0
	s_nop 0
	s_nop 0
	s_nop 0
	s_nop 0
	s_nop 0
	s_waitcnt lgkmcnt(0)
	s_waitcnt vmcnt(0)
	s_barrier
	v_lshl_add_u64 v[68:69], v[68:69], 0, s[96:97]
	s_add_u32 m0, s94, 0x8000
	s_nop 1
	global_load_lds_dwordx4 v[68:69], off
	v_lshl_add_u64 v[70:71], v[70:71], 0, s[96:97]
	s_add_u32 m0, s94, 0xc000
	s_nop 1
	global_load_lds_dwordx4 v[70:71], off
	v_lshl_add_u64 v[72:73], v[72:73], 0, s[96:97]
	s_add_u32 m0, s94, 0x9000
	s_nop 1
	global_load_lds_dwordx4 v[72:73], off
	v_lshl_add_u64 v[74:75], v[74:75], 0, s[96:97]
	s_add_u32 m0, s94, 0xd000
	s_nop 1
	global_load_lds_dwordx4 v[74:75], off
	v_lshl_add_u64 v[76:77], v[76:77], 0, s[96:97]
	s_add_u32 m0, s94, 0xa000
	s_nop 1
	global_load_lds_dwordx4 v[76:77], off
	v_lshl_add_u64 v[78:79], v[78:79], 0, s[96:97]
	s_add_u32 m0, s94, 0xe000
	s_nop 1
	global_load_lds_dwordx4 v[78:79], off
	v_lshl_add_u64 v[80:81], v[80:81], 0, s[96:97]
	s_add_u32 m0, s94, 0xb000
	s_nop 1
	global_load_lds_dwordx4 v[80:81], off
	v_lshl_add_u64 v[82:83], v[82:83], 0, s[96:97]
	s_add_u32 m0, s94, 0xf000
	s_nop 1
	global_load_lds_dwordx4 v[82:83], off
	v_mfma_f32_32x32x16_bf16 v[0:15], v[118:121], v[106:109], v[0:15]
	ds_read_b128 v[68:71], v170 offset:0
	ds_read_b128 v[72:75], v174 offset:16384
	ds_read_b128 v[76:79], v171 offset:0
	ds_read_b128 v[80:83], v175 offset:16384
	ds_read_b128 v[90:93], v174 offset:20480
	ds_read_b128 v[98:101], v175 offset:20480
	v_mfma_f32_32x32x16_bf16 v[32:47], v[118:121], v[114:117], v[32:47]
	s_waitcnt lgkmcnt(4)
	v_mfma_f32_32x32x16_bf16 v[16:31], v[68:71], v[72:75], v[16:31]
	s_waitcnt lgkmcnt(1)
	v_mfma_f32_32x32x16_bf16 v[48:63], v[68:71], v[90:93], v[48:63]
	ds_read_b128 v[68:71], v170 offset:4096
	ds_read_b128 v[102:105], v171 offset:4096
	s_waitcnt lgkmcnt(1)
	v_mfma_f32_32x32x16_bf16 v[0:15], v[68:71], v[72:75], v[0:15]
	v_mfma_f32_32x32x16_bf16 v[32:47], v[68:71], v[90:93], v[32:47]
	v_mfma_f32_32x32x16_bf16 v[16:31], v[76:79], v[80:83], v[16:31]
	v_mfma_f32_32x32x16_bf16 v[48:63], v[76:79], v[98:101], v[48:63]
	s_waitcnt lgkmcnt(0)
	v_mfma_f32_32x32x16_bf16 v[0:15], v[102:105], v[80:83], v[0:15]
	ds_read_b128 v[68:71], v172 offset:0
	ds_read_b128 v[72:75], v176 offset:16384
	ds_read_b128 v[76:79], v173 offset:0
	ds_read_b128 v[80:83], v177 offset:16384
	v_mfma_f32_32x32x16_bf16 v[32:47], v[102:105], v[98:101], v[32:47]
	ds_read_b128 v[90:93], v176 offset:20480
	ds_read_b128 v[98:101], v177 offset:20480
	s_waitcnt lgkmcnt(4)
	v_mfma_f32_32x32x16_bf16 v[16:31], v[68:71], v[72:75], v[16:31]
	s_waitcnt lgkmcnt(1)
	v_mfma_f32_32x32x16_bf16 v[48:63], v[68:71], v[90:93], v[48:63]
	ds_read_b128 v[68:71], v172 offset:4096
	ds_read_b128 v[102:105], v173 offset:4096
	s_waitcnt lgkmcnt(0)
	s_waitcnt vmcnt(0)
	s_barrier
; DEVI int accrow(int r, int lane) { return (r & 3) + 8 * (r >> 2) + 4 * (lane >> 5); }
; DEVI void gemm_epi_ssd_in(const Params& p, f32x16 (&acc)[2][2], int rbase, int cbase, int lane) {
;     ...
;   } else {
;     float* dtr = (float*)(ar + S_DTRAW);
; #pragma unroll
;     for (int i = 0; i < 2; ++i)
; #pragma unroll
;       for (int r = 0; r < 16; ++r) {
;         const int row = rbase + i * 32 + accrow(r, lane);
;         if (row < M && cbase == 6144) dtr[(size_t)row * 32 + d] = acc[i][0][r];
;     ...
;   for (int kt = 0; kt < nk; kt += 2) {
;     if (kt + 2 < nk) G_LOAD(ra0, rb0, kt + 2);
;     if (kt + 1 < nk) G_STORE(ra1, rb1, As1, Bs1);
;     G_COMPUTE(As, Bs);
;     __syncthreads();
;     if (kt + 1 < nk) {
;       if (kt + 3 < nk) G_LOAD(ra1, rb1, kt + 3);
;       if (kt + 2 < nk) G_STORE(ra0, rb0, As, Bs);
;       G_COMPUTE(As1, Bs1);
;       __syncthreads();
;     }
;   }
	v_mfma_f32_32x32x16_bf16 v[0:15], v[68:71], v[72:75], v[0:15]
	v_mfma_f32_32x32x16_bf16 v[16:31], v[76:79], v[80:83], v[16:31]
	v_mfma_f32_32x32x16_bf16 v[48:63], v[76:79], v[98:101], v[48:63]
	v_mfma_f32_32x32x16_bf16 v[32:47], v[68:71], v[90:93], v[32:47]
	v_mfma_f32_32x32x16_bf16 v[0:15], v[102:105], v[80:83], v[0:15]
	ds_read_b128 v[68:71], v170 offset:32768
	ds_read_b128 v[72:75], v174 offset:49152
	ds_read_b128 v[76:79], v175 offset:49152
	ds_read_b128 v[80:83], v171 offset:32768
	ds_read_b128 v[90:93], v174 offset:53248
	s_waitcnt lgkmcnt(3)
	v_mfma_f32_32x32x16_bf16 v[16:31], v[68:71], v[72:75], v[16:31]
	s_waitcnt lgkmcnt(0)
	v_mfma_f32_32x32x16_bf16 v[48:63], v[68:71], v[90:93], v[48:63]
	ds_read_b128 v[68:71], v170 offset:36864
	v_mfma_f32_32x32x16_bf16 v[32:47], v[102:105], v[98:101], v[32:47]
	s_waitcnt lgkmcnt(0)
	v_mfma_f32_32x32x16_bf16 v[0:15], v[68:71], v[72:75], v[0:15]
	ds_read_b128 v[72:75], v171 offset:36864
	v_mfma_f32_32x32x16_bf16 v[32:47], v[68:71], v[90:93], v[32:47]
	ds_read_b128 v[68:71], v175 offset:53248
	v_mfma_f32_32x32x16_bf16 v[16:31], v[80:83], v[76:79], v[16:31]
	s_waitcnt lgkmcnt(0)
	v_mfma_f32_32x32x16_bf16 v[48:63], v[80:83], v[68:71], v[48:63]
	v_mfma_f32_32x32x16_bf16 v[0:15], v[72:75], v[76:79], v[0:15]
	v_mfma_f32_32x32x16_bf16 v[32:47], v[72:75], v[68:71], v[32:47]
	ds_read_b128 v[68:71], v172 offset:32768
	ds_read_b128 v[72:75], v176 offset:49152
	ds_read_b128 v[76:79], v176 offset:53248
	s_waitcnt lgkmcnt(1)
	v_mfma_f32_32x32x16_bf16 v[16:31], v[68:71], v[72:75], v[16:31]
	s_waitcnt lgkmcnt(0)
	v_mfma_f32_32x32x16_bf16 v[48:63], v[68:71], v[76:79], v[48:63]
	ds_read_b128 v[68:71], v172 offset:36864
	s_waitcnt lgkmcnt(0)
	v_mfma_f32_32x32x16_bf16 v[0:15], v[68:71], v[72:75], v[0:15]
	v_mfma_f32_32x32x16_bf16 v[32:47], v[68:71], v[76:79], v[32:47]
	ds_read_b128 v[68:71], v173 offset:32768
	ds_read_b128 v[72:75], v177 offset:49152
	ds_read_b128 v[76:79], v177 offset:53248
	ds_read_b128 v[80:83], v173 offset:36864
	v_and_b32_e32 v66, 64, v86
	v_and_b32_e32 v67, 63, v86
	v_subrev_u32_e32 v66, s3, v66
	v_add_u32_e32 v66, s17, v66
	s_waitcnt lgkmcnt(2)
	v_mfma_f32_32x32x16_bf16 v[16:31], v[68:71], v[72:75], v[16:31]
	s_waitcnt lgkmcnt(0)
	s_barrier
	v_mfma_f32_32x32x16_bf16 v[48:63], v[68:71], v[76:79], v[48:63]
	v_add_u32_e32 v70, s2, v88
	s_movk_i32 s2, 0x17ff
	v_cmp_lt_i32_e32 vcc, s2, v66
	v_mfma_f32_32x32x16_bf16 v[0:15], v[80:83], v[72:75], v[0:15]
	v_lshrrev_b32_e32 v72, 3, v67
	v_and_b32_e32 v71, 4, v72
	v_mfma_f32_32x32x16_bf16 v[32:47], v[80:83], v[76:79], v[32:47]
	s_and_saveexec_b64 s[2:3], vcc
	s_xor_b64 s[2:3], exec, s[2:3]
	s_cbranch_execz .LBB0_4899
	s_movk_i32 s6, 0x1800
	v_lshlrev_b32_e32 v96, 2, v87
	v_cmp_eq_u32_e32 vcc, s6, v66
	s_nop 5
	v_lshl_add_u64 v[32:33], s[4:5], 0, v[96:97]
	s_mov_b64 s[6:7], 0x2cb5c000
	v_or_b32_e32 v34, v70, v71
	v_lshl_add_u64 v[32:33], v[32:33], 0, s[6:7]
	v_cmp_gt_i32_e64 s[6:7], s90, v34
	s_and_b64 s[20:21], vcc, s[6:7]
	s_and_saveexec_b64 s[6:7], s[20:21]
	s_cbranch_execz .LBB0_4836
	v_ashrrev_i32_e32 v35, 31, v34
	v_lshlrev_b64 v[34:35], 7, v[34:35]
	v_lshl_add_u64 v[34:35], v[32:33], 0, v[34:35]
	global_store_dword v[34:35], v16, off
